# merged-phase K-loops without the extra m0 pads and read-burst split
# speedup vs baseline: 1.0149x; 1.0022x over previous
; #define PG8_STAGE(bufoff, gbase, voff) do { _Pragma("unroll") for (int _i = 0; _i < 2; ++_i) \
;         __builtin_amdgcn_global_load_lds((const unsigned*)((const char*)(gbase) + (voff)[_i]), (PG8_LAS unsigned*)(lds + (bufoff) + ldsw + _i * 8192), 16, 0, 0); } while (0)
; #define PG8_LDA(dst, b, h) do { _Pragma("unroll") for (int m = 0; m < 4; ++m) _Pragma("unroll") for (int k = 0; k < 2; ++k) dst[m][k] = *(const PG8_LAS bf16x8*)(lds + PG8_SA(b, h) + aoff + m * 2048 + k * 1024); } while (0)
; #define PG8_LDB(dst, b, h) do { _Pragma("unroll") for (int n = 0; n < 2; ++n) _Pragma("unroll") for (int k = 0; k < 2; ++k) dst[n][k] = *(const PG8_LAS bf16x8*)(lds + PG8_SB(b, h) + boff + n * 2048 + k * 1024); } while (0)
; #define PG8_MMA(ai, bj, At, Bt) do { __builtin_amdgcn_s_setprio(1); _Pragma("unroll") for (int m = 0; m < 4; ++m) _Pragma("unroll") for (int n = 0; n < 2; ++n) _Pragma("unroll") for (int k = 0; k < 2; ++k) \
;         acc[ai][bj][m][n] = __builtin_amdgcn_mfma_f32_16x16x32_bf16(Bt[n][k], At[m][k], acc[ai][bj][m][n], 0, 0, 0); __builtin_amdgcn_s_setprio(0); } while (0)
; #define PG8_WAIT_V(n) asm volatile("s_waitcnt vmcnt(" #n ")" ::: "memory")
; #define PG8_WAIT_L(n) asm volatile("s_waitcnt lgkmcnt(" #n ")" ::: "memory")
; #define PG8_BAR __builtin_amdgcn_s_barrier()
; #define PG8_SCHED __builtin_amdgcn_sched_barrier(0)
; template <class Epi, class Sched>
; __device__ __forceinline__ void gemm_phase(PG8_LAS unsigned char* lds, const Gemm g, const Sched& S, const Epi& E) {
;     ...
;             PG8_LDB(B0, 0, 0); PG8_SCHED; PG8_LDA(At, 0, 0); PG8_STAGE(PG8_SA(1, 1), a1 + hstep, voffA);
;             PG8_WAIT_L(8); PG8_BAR; PG8_WAIT_L(0); PG8_MMA(0, 0, At, B0); PG8_BAR; PG8_SCHED;
;             PG8_LDB(B1, 0, 1); PG8_STAGE(PG8_SB(0, 0), b2, voffB);
;             PG8_BAR; PG8_WAIT_L(0); PG8_MMA(0, 1, At, B1); PG8_BAR;
;             PG8_LDA(At, 0, 1); PG8_STAGE(PG8_SA(0, 0), a2, voffA);
;             PG8_BAR; PG8_WAIT_L(0); PG8_MMA(1, 0, At, B0); PG8_BAR; PG8_SCHED;
;             PG8_STAGE(PG8_SB(0, 1), b2 + hstep, voffB);
;             PG8_WAIT_V(6); PG8_BAR; PG8_MMA(1, 1, At, B1); PG8_BAR;
.LBB0_195:
	ds_read_b128 v[144:147], v151
	ds_read_b128 v[156:159], v151 offset:1024
	ds_read_b128 v[160:163], v151 offset:2048
	ds_read_b128 v[166:169], v151 offset:3072
	s_add_u32 s30, s28, 0xfffc0080
	s_addc_u32 s31, s29, -1
	s_cmp_eq_u32 s58, 12
	s_cselect_b32 s35, s17, s31
	s_cselect_b32 s34, s54, s30
	s_cselect_b32 s31, s15, s57
	s_cselect_b32 s30, s55, s56
	v_lshl_add_u64 v[174:175], s[28:29], 0, v[136:137]
	s_add_i32 m0, s27, 0xc000
	ds_read_b128 v[170:173], v153
	ds_read_b128 v[182:185], v153 offset:1024
	ds_read_b128 v[190:193], v153 offset:2048
	ds_read_b128 v[194:197], v153 offset:3072
	ds_read_b128 v[198:201], v153 offset:4096
	ds_read_b128 v[202:205], v153 offset:5120
	ds_read_b128 v[206:209], v153 offset:6144
	ds_read_b128 v[210:213], v153 offset:7168
	global_load_lds_dwordx4 v[174:175], off
	v_lshl_add_u64 v[174:175], s[28:29], 0, v[138:139]
	s_add_i32 m0, s27, 0xe000
	s_nop 0
	global_load_lds_dwordx4 v[174:175], off
	ds_read_b128 v[214:217], v154
	ds_read_b128 v[218:221], v154 offset:1024
	ds_read_b128 v[222:225], v154 offset:2048
	ds_read_b128 v[226:229], v154 offset:3072
	s_waitcnt vmcnt(8) lgkmcnt(0)
	s_barrier
	v_mfma_f32_16x16x32_bf16 v[124:127], v[144:147], v[170:173], v[124:127]
	v_mfma_f32_16x16x32_bf16 v[120:123], v[160:163], v[170:173], v[120:123]
	v_mfma_f32_16x16x32_bf16 v[108:111], v[144:147], v[190:193], v[108:111]
	v_mfma_f32_16x16x32_bf16 v[104:107], v[160:163], v[190:193], v[104:107]
	v_mfma_f32_16x16x32_bf16 v[92:95], v[144:147], v[198:201], v[92:95]
	v_mfma_f32_16x16x32_bf16 v[88:91], v[160:163], v[198:201], v[88:91]
	v_mfma_f32_16x16x32_bf16 v[76:79], v[144:147], v[206:209], v[76:79]
	v_mfma_f32_16x16x32_bf16 v[72:75], v[160:163], v[206:209], v[72:75]
	v_mfma_f32_16x16x32_bf16 v[124:127], v[156:159], v[182:185], v[124:127]
	v_mfma_f32_16x16x32_bf16 v[120:123], v[166:169], v[182:185], v[120:123]
	v_mfma_f32_16x16x32_bf16 v[108:111], v[156:159], v[194:197], v[108:111]
	v_mfma_f32_16x16x32_bf16 v[104:107], v[166:169], v[194:197], v[104:107]
	v_mfma_f32_16x16x32_bf16 v[92:95], v[156:159], v[202:205], v[92:95]
	v_mfma_f32_16x16x32_bf16 v[88:91], v[166:169], v[202:205], v[88:91]
	v_mfma_f32_16x16x32_bf16 v[76:79], v[156:159], v[210:213], v[76:79]
	v_mfma_f32_16x16x32_bf16 v[72:75], v[166:169], v[210:213], v[72:75]
	v_mfma_f32_16x16x32_bf16 v[116:119], v[214:217], v[170:173], v[116:119]
	v_mfma_f32_16x16x32_bf16 v[112:115], v[222:225], v[170:173], v[112:115]
	v_mfma_f32_16x16x32_bf16 v[100:103], v[214:217], v[190:193], v[100:103]
	v_mfma_f32_16x16x32_bf16 v[96:99], v[222:225], v[190:193], v[96:99]
	v_mfma_f32_16x16x32_bf16 v[84:87], v[214:217], v[198:201], v[84:87]
	v_mfma_f32_16x16x32_bf16 v[80:83], v[222:225], v[198:201], v[80:83]
	v_mfma_f32_16x16x32_bf16 v[68:71], v[214:217], v[206:209], v[68:71]
	v_mfma_f32_16x16x32_bf16 v[64:67], v[222:225], v[206:209], v[64:67]
	v_mfma_f32_16x16x32_bf16 v[116:119], v[218:221], v[182:185], v[116:119]
	v_mfma_f32_16x16x32_bf16 v[112:115], v[226:229], v[182:185], v[112:115]
	v_mfma_f32_16x16x32_bf16 v[100:103], v[218:221], v[194:197], v[100:103]
	v_mfma_f32_16x16x32_bf16 v[96:99], v[226:229], v[194:197], v[96:99]
	v_mfma_f32_16x16x32_bf16 v[84:87], v[218:221], v[202:205], v[84:87]
	v_mfma_f32_16x16x32_bf16 v[80:83], v[226:229], v[202:205], v[80:83]
	v_mfma_f32_16x16x32_bf16 v[68:71], v[218:221], v[210:213], v[68:71]
	v_mfma_f32_16x16x32_bf16 v[64:67], v[226:229], v[210:213], v[64:67]
	s_barrier
	ds_read_b128 v[170:173], v153 offset:16384
	ds_read_b128 v[182:185], v153 offset:17408
	ds_read_b128 v[190:193], v153 offset:18432
	ds_read_b128 v[194:197], v153 offset:19456
	ds_read_b128 v[198:201], v153 offset:20480
	ds_read_b128 v[202:205], v153 offset:21504
	ds_read_b128 v[206:209], v153 offset:22528
	ds_read_b128 v[210:213], v153 offset:23552
	s_add_i32 s59, s50, s40
	v_lshl_add_u64 v[174:175], s[30:31], 0, v[132:133]
	s_mov_b32 m0, s59
	s_nop 0
	global_load_lds_dwordx4 v[174:175], off
	v_lshl_add_u64 v[178:179], s[30:31], 0, v[128:129]
	s_add_i32 m0, s59, 0x2000
	s_nop 0
	global_load_lds_dwordx4 v[178:179], off
	s_mov_b32 m0, s27
	v_lshl_add_u64 v[186:187], s[34:35], 0, v[134:135]
	global_load_lds_dwordx4 v[186:187], off
	v_lshl_add_u64 v[230:231], s[34:35], 0, v[130:131]
	s_mov_b32 m0, s43
	s_nop 0
	global_load_lds_dwordx4 v[230:231], off
	s_add_u32 s60, s30, 0x40000
	s_addc_u32 s61, s31, 0
	s_add_i32 s59, s51, s40
	v_lshl_add_u64 v[246:247], s[60:61], 0, v[132:133]
	s_mov_b32 m0, s59
	s_nop 0
	global_load_lds_dwordx4 v[246:247], off
	v_lshl_add_u64 v[246:247], s[60:61], 0, v[128:129]
	s_add_i32 m0, s59, 0x2000
	s_nop 0
	global_load_lds_dwordx4 v[246:247], off
	s_waitcnt vmcnt(8) lgkmcnt(0)
	s_barrier
; #define PG8_STAGE(bufoff, gbase, voff) do { _Pragma("unroll") for (int _i = 0; _i < 2; ++_i) \
;         __builtin_amdgcn_global_load_lds((const unsigned*)((const char*)(gbase) + (voff)[_i]), (PG8_LAS unsigned*)(lds + (bufoff) + ldsw + _i * 8192), 16, 0, 0); } while (0)
; #define PG8_LDA(dst, b, h) do { _Pragma("unroll") for (int m = 0; m < 4; ++m) _Pragma("unroll") for (int k = 0; k < 2; ++k) dst[m][k] = *(const PG8_LAS bf16x8*)(lds + PG8_SA(b, h) + aoff + m * 2048 + k * 1024); } while (0)
; #define PG8_LDB(dst, b, h) do { _Pragma("unroll") for (int n = 0; n < 2; ++n) _Pragma("unroll") for (int k = 0; k < 2; ++k) dst[n][k] = *(const PG8_LAS bf16x8*)(lds + PG8_SB(b, h) + boff + n * 2048 + k * 1024); } while (0)
; #define PG8_MMA(ai, bj, At, Bt) do { __builtin_amdgcn_s_setprio(1); _Pragma("unroll") for (int m = 0; m < 4; ++m) _Pragma("unroll") for (int n = 0; n < 2; ++n) _Pragma("unroll") for (int k = 0; k < 2; ++k) \
;         acc[ai][bj][m][n] = __builtin_amdgcn_mfma_f32_16x16x32_bf16(Bt[n][k], At[m][k], acc[ai][bj][m][n], 0, 0, 0); __builtin_amdgcn_s_setprio(0); } while (0)
; #define PG8_WAIT_V(n) asm volatile("s_waitcnt vmcnt(" #n ")" ::: "memory")
; #define PG8_WAIT_L(n) asm volatile("s_waitcnt lgkmcnt(" #n ")" ::: "memory")
; #define PG8_BAR __builtin_amdgcn_s_barrier()
; #define PG8_SCHED __builtin_amdgcn_sched_barrier(0)
; template <class Epi, class Sched>
; __device__ __forceinline__ void gemm_phase(PG8_LAS unsigned char* lds, const Gemm g, const Sched& S, const Epi& E) {
;     ...
;             PG8_LDA(At, 0, 1); PG8_STAGE(PG8_SA(0, 0), a2, voffA);
;             PG8_BAR; PG8_WAIT_L(0); PG8_MMA(1, 0, At, B0); PG8_BAR; PG8_SCHED;
;             PG8_STAGE(PG8_SB(0, 1), b2 + hstep, voffB);
;             PG8_WAIT_V(6); PG8_BAR; PG8_MMA(1, 1, At, B1); PG8_BAR;
;             PG8_LDB(B0, 1, 0); PG8_SCHED; PG8_LDA(At, 1, 0); PG8_STAGE(PG8_SA(0, 1), a2 + hstep, voffA);
;             PG8_WAIT_L(8); PG8_BAR; PG8_WAIT_L(0); PG8_MMA(0, 0, At, B0); PG8_BAR; PG8_SCHED;
;             PG8_LDB(B1, 1, 1); PG8_STAGE(PG8_SB(1, 0), b3, voffB);
;             PG8_BAR; PG8_WAIT_L(0); PG8_MMA(0, 1, At, B1); PG8_BAR;
	v_mfma_f32_16x16x32_bf16 v[60:63], v[144:147], v[170:173], v[60:63]
	v_mfma_f32_16x16x32_bf16 v[56:59], v[160:163], v[170:173], v[56:59]
	v_mfma_f32_16x16x32_bf16 v[44:47], v[144:147], v[190:193], v[44:47]
	v_mfma_f32_16x16x32_bf16 v[40:43], v[160:163], v[190:193], v[40:43]
	v_mfma_f32_16x16x32_bf16 v[28:31], v[144:147], v[198:201], v[28:31]
	v_mfma_f32_16x16x32_bf16 v[24:27], v[160:163], v[198:201], v[24:27]
	v_mfma_f32_16x16x32_bf16 v[12:15], v[144:147], v[206:209], v[12:15]
	v_mfma_f32_16x16x32_bf16 v[8:11], v[160:163], v[206:209], v[8:11]
	v_mfma_f32_16x16x32_bf16 v[60:63], v[156:159], v[182:185], v[60:63]
	v_mfma_f32_16x16x32_bf16 v[56:59], v[166:169], v[182:185], v[56:59]
	v_mfma_f32_16x16x32_bf16 v[44:47], v[156:159], v[194:197], v[44:47]
	v_mfma_f32_16x16x32_bf16 v[40:43], v[166:169], v[194:197], v[40:43]
	v_mfma_f32_16x16x32_bf16 v[28:31], v[156:159], v[202:205], v[28:31]
	v_mfma_f32_16x16x32_bf16 v[24:27], v[166:169], v[202:205], v[24:27]
	v_mfma_f32_16x16x32_bf16 v[12:15], v[156:159], v[210:213], v[12:15]
	v_mfma_f32_16x16x32_bf16 v[8:11], v[166:169], v[210:213], v[8:11]
	v_mfma_f32_16x16x32_bf16 v[52:55], v[214:217], v[170:173], v[52:55]
	v_mfma_f32_16x16x32_bf16 v[48:51], v[222:225], v[170:173], v[48:51]
	v_mfma_f32_16x16x32_bf16 v[36:39], v[214:217], v[190:193], v[36:39]
	v_mfma_f32_16x16x32_bf16 v[32:35], v[222:225], v[190:193], v[32:35]
	v_mfma_f32_16x16x32_bf16 v[20:23], v[214:217], v[198:201], v[20:23]
	v_mfma_f32_16x16x32_bf16 v[16:19], v[222:225], v[198:201], v[16:19]
	v_mfma_f32_16x16x32_bf16 v[4:7], v[214:217], v[206:209], v[4:7]
	v_mfma_f32_16x16x32_bf16 v[0:3], v[222:225], v[206:209], v[0:3]
	v_mfma_f32_16x16x32_bf16 v[52:55], v[218:221], v[182:185], v[52:55]
	v_mfma_f32_16x16x32_bf16 v[48:51], v[226:229], v[182:185], v[48:51]
	v_mfma_f32_16x16x32_bf16 v[36:39], v[218:221], v[194:197], v[36:39]
	v_mfma_f32_16x16x32_bf16 v[32:35], v[226:229], v[194:197], v[32:35]
	v_mfma_f32_16x16x32_bf16 v[20:23], v[218:221], v[202:205], v[20:23]
	v_mfma_f32_16x16x32_bf16 v[16:19], v[226:229], v[202:205], v[16:19]
	v_mfma_f32_16x16x32_bf16 v[4:7], v[218:221], v[210:213], v[4:7]
	v_mfma_f32_16x16x32_bf16 v[0:3], v[226:229], v[210:213], v[0:3]
	s_barrier
	s_add_i32 s59, 0, 0x18000
	v_add_u32_e32 v155, s59, v149
	ds_read_b128 v[144:147], v155
	ds_read_b128 v[156:159], v155 offset:1024
	ds_read_b128 v[160:163], v155 offset:2048
	ds_read_b128 v[166:169], v155 offset:3072
	s_add_u32 s34, s34, 0x40000
	s_addc_u32 s35, s35, 0
	s_mov_b32 m0, s44
	v_lshl_add_u64 v[214:215], s[34:35], 0, v[134:135]
	ds_read_b128 v[170:173], v153 offset:32768
	ds_read_b128 v[182:185], v153 offset:33792
	ds_read_b128 v[190:193], v153 offset:34816
	ds_read_b128 v[194:197], v153 offset:35840
	ds_read_b128 v[198:201], v153 offset:36864
	ds_read_b128 v[202:205], v153 offset:37888
	ds_read_b128 v[206:209], v153 offset:38912
	ds_read_b128 v[210:213], v153 offset:39936
	global_load_lds_dwordx4 v[214:215], off
	v_lshl_add_u64 v[214:215], s[34:35], 0, v[130:131]
	s_mov_b32 m0, s45
	s_nop 0
	global_load_lds_dwordx4 v[214:215], off
	s_add_i32 s34, 0, 0x1c000
	v_add_u32_e32 v155, s34, v149
	ds_read_b128 v[214:217], v155
	ds_read_b128 v[218:221], v155 offset:1024
	ds_read_b128 v[222:225], v155 offset:2048
	ds_read_b128 v[226:229], v155 offset:3072
	s_waitcnt vmcnt(8) lgkmcnt(0)
	s_barrier
	v_mfma_f32_16x16x32_bf16 v[124:127], v[144:147], v[170:173], v[124:127]
	v_mfma_f32_16x16x32_bf16 v[120:123], v[160:163], v[170:173], v[120:123]
	v_mfma_f32_16x16x32_bf16 v[108:111], v[144:147], v[190:193], v[108:111]
	v_mfma_f32_16x16x32_bf16 v[104:107], v[160:163], v[190:193], v[104:107]
	v_mfma_f32_16x16x32_bf16 v[92:95], v[144:147], v[198:201], v[92:95]
	v_mfma_f32_16x16x32_bf16 v[88:91], v[160:163], v[198:201], v[88:91]
	v_mfma_f32_16x16x32_bf16 v[76:79], v[144:147], v[206:209], v[76:79]
	v_mfma_f32_16x16x32_bf16 v[72:75], v[160:163], v[206:209], v[72:75]
	v_mfma_f32_16x16x32_bf16 v[124:127], v[156:159], v[182:185], v[124:127]
	v_mfma_f32_16x16x32_bf16 v[120:123], v[166:169], v[182:185], v[120:123]
	v_mfma_f32_16x16x32_bf16 v[108:111], v[156:159], v[194:197], v[108:111]
	v_mfma_f32_16x16x32_bf16 v[104:107], v[166:169], v[194:197], v[104:107]
	v_mfma_f32_16x16x32_bf16 v[92:95], v[156:159], v[202:205], v[92:95]
	v_mfma_f32_16x16x32_bf16 v[88:91], v[166:169], v[202:205], v[88:91]
	v_mfma_f32_16x16x32_bf16 v[76:79], v[156:159], v[210:213], v[76:79]
	v_mfma_f32_16x16x32_bf16 v[72:75], v[166:169], v[210:213], v[72:75]
	v_mfma_f32_16x16x32_bf16 v[116:119], v[214:217], v[170:173], v[116:119]
	v_mfma_f32_16x16x32_bf16 v[112:115], v[222:225], v[170:173], v[112:115]
	v_mfma_f32_16x16x32_bf16 v[100:103], v[214:217], v[190:193], v[100:103]
	v_mfma_f32_16x16x32_bf16 v[96:99], v[222:225], v[190:193], v[96:99]
	v_mfma_f32_16x16x32_bf16 v[84:87], v[214:217], v[198:201], v[84:87]
	v_mfma_f32_16x16x32_bf16 v[80:83], v[222:225], v[198:201], v[80:83]
	v_mfma_f32_16x16x32_bf16 v[68:71], v[214:217], v[206:209], v[68:71]
	v_mfma_f32_16x16x32_bf16 v[64:67], v[222:225], v[206:209], v[64:67]
	v_mfma_f32_16x16x32_bf16 v[116:119], v[218:221], v[182:185], v[116:119]
	v_mfma_f32_16x16x32_bf16 v[112:115], v[226:229], v[182:185], v[112:115]
	v_mfma_f32_16x16x32_bf16 v[100:103], v[218:221], v[194:197], v[100:103]
	v_mfma_f32_16x16x32_bf16 v[96:99], v[226:229], v[194:197], v[96:99]
	v_mfma_f32_16x16x32_bf16 v[84:87], v[218:221], v[202:205], v[84:87]
	v_mfma_f32_16x16x32_bf16 v[80:83], v[226:229], v[202:205], v[80:83]
	v_mfma_f32_16x16x32_bf16 v[68:71], v[218:221], v[210:213], v[68:71]
	v_mfma_f32_16x16x32_bf16 v[64:67], v[226:229], v[210:213], v[64:67]
	s_barrier
; #define PG8_STAGE(bufoff, gbase, voff) do { _Pragma("unroll") for (int _i = 0; _i < 2; ++_i) \
;         __builtin_amdgcn_global_load_lds((const unsigned*)((const char*)(gbase) + (voff)[_i]), (PG8_LAS unsigned*)(lds + (bufoff) + ldsw + _i * 8192), 16, 0, 0); } while (0)
; #define PG8_LDA(dst, b, h) do { _Pragma("unroll") for (int m = 0; m < 4; ++m) _Pragma("unroll") for (int k = 0; k < 2; ++k) dst[m][k] = *(const PG8_LAS bf16x8*)(lds + PG8_SA(b, h) + aoff + m * 2048 + k * 1024); } while (0)
; #define PG8_MMA(ai, bj, At, Bt) do { __builtin_amdgcn_s_setprio(1); _Pragma("unroll") for (int m = 0; m < 4; ++m) _Pragma("unroll") for (int n = 0; n < 2; ++n) _Pragma("unroll") for (int k = 0; k < 2; ++k) \
;         acc[ai][bj][m][n] = __builtin_amdgcn_mfma_f32_16x16x32_bf16(Bt[n][k], At[m][k], acc[ai][bj][m][n], 0, 0, 0); __builtin_amdgcn_s_setprio(0); } while (0)
; #define PG8_WAIT_V(n) asm volatile("s_waitcnt vmcnt(" #n ")" ::: "memory")
; #define PG8_WAIT_L(n) asm volatile("s_waitcnt lgkmcnt(" #n ")" ::: "memory")
; #define PG8_BAR __builtin_amdgcn_s_barrier()
; #define PG8_SCHED __builtin_amdgcn_sched_barrier(0)
; __device__ __forceinline__ f32x4 sigmoid4(f32x4 x) {
;     f32x4 d;
; #pragma unroll
;     for (int j = 0; j < 4; ++j) d[j] = 1.0f + __expf(-fmaxf(x[j], -20.0f));
;     const float p01 = d[0] * d[1], p23 = d[2] * d[3], r = __builtin_amdgcn_rcpf(p01 * p23), r01 = r * p23, r23 = r * p01;
;     return (f32x4){r01 * d[1], r01 * d[0], r23 * d[3], r23 * d[2]};
; }
; template <class Epi, class Sched>
; __device__ __forceinline__ void gemm_phase(PG8_LAS unsigned char* lds, const Gemm g, const Sched& S, const Epi& E) {
;     ...
;             PG8_LDA(At, 1, 1); PG8_STAGE(PG8_SA(1, 0), a3, voffA);
;             PG8_BAR; PG8_WAIT_L(0); PG8_MMA(1, 0, At, B0); PG8_BAR; PG8_SCHED;
;             PG8_STAGE(PG8_SB(1, 1), b3 + hstep, voffB);
;             PG8_WAIT_V(6); PG8_BAR; PG8_MMA(1, 1, At, B1); PG8_BAR;
;         }
	ds_read_b128 v[170:173], v153 offset:49152
	ds_read_b128 v[182:185], v153 offset:50176
	ds_read_b128 v[190:193], v153 offset:51200
	ds_read_b128 v[194:197], v153 offset:52224
	ds_read_b128 v[198:201], v153 offset:53248
	ds_read_b128 v[202:205], v153 offset:54272
	ds_read_b128 v[206:209], v153 offset:55296
	ds_read_b128 v[210:213], v153 offset:56320
	s_add_i32 s35, s59, s40
	v_lshl_add_u64 v[174:175], v[174:175], 0, s[10:11]
	s_mov_b32 m0, s35
	s_nop 0
	global_load_lds_dwordx4 v[174:175], off
	v_lshl_add_u64 v[174:175], v[178:179], 0, s[10:11]
	s_add_i32 m0, s35, 0x2000
	s_nop 0
	global_load_lds_dwordx4 v[174:175], off
	s_mov_b32 m0, s47
	v_lshl_add_u64 v[174:175], v[186:187], 0, s[10:11]
	global_load_lds_dwordx4 v[174:175], off
	v_lshl_add_u64 v[174:175], v[230:231], 0, s[10:11]
	s_mov_b32 m0, s48
	s_nop 0
	global_load_lds_dwordx4 v[174:175], off
	s_add_u32 s30, s30, 0x40080
	s_addc_u32 s31, s31, 0
	s_add_i32 s34, s34, s40
	v_lshl_add_u64 v[246:247], s[30:31], 0, v[132:133]
	s_mov_b32 m0, s34
	s_nop 0
	global_load_lds_dwordx4 v[246:247], off
	v_lshl_add_u64 v[246:247], s[30:31], 0, v[128:129]
	s_add_i32 m0, s34, 0x2000
	s_nop 0
	global_load_lds_dwordx4 v[246:247], off
	s_waitcnt vmcnt(8) lgkmcnt(0)
	s_barrier
	v_mfma_f32_16x16x32_bf16 v[60:63], v[144:147], v[170:173], v[60:63]
	v_mfma_f32_16x16x32_bf16 v[56:59], v[160:163], v[170:173], v[56:59]
	v_mfma_f32_16x16x32_bf16 v[44:47], v[144:147], v[190:193], v[44:47]
	v_mfma_f32_16x16x32_bf16 v[40:43], v[160:163], v[190:193], v[40:43]
	v_mfma_f32_16x16x32_bf16 v[28:31], v[144:147], v[198:201], v[28:31]
	v_mfma_f32_16x16x32_bf16 v[24:27], v[160:163], v[198:201], v[24:27]
	v_mfma_f32_16x16x32_bf16 v[12:15], v[144:147], v[206:209], v[12:15]
	v_mfma_f32_16x16x32_bf16 v[8:11], v[160:163], v[206:209], v[8:11]
	v_mfma_f32_16x16x32_bf16 v[60:63], v[156:159], v[182:185], v[60:63]
	v_mfma_f32_16x16x32_bf16 v[56:59], v[166:169], v[182:185], v[56:59]
	v_mfma_f32_16x16x32_bf16 v[44:47], v[156:159], v[194:197], v[44:47]
	v_mfma_f32_16x16x32_bf16 v[40:43], v[166:169], v[194:197], v[40:43]
	v_mfma_f32_16x16x32_bf16 v[28:31], v[156:159], v[202:205], v[28:31]
	v_mfma_f32_16x16x32_bf16 v[24:27], v[166:169], v[202:205], v[24:27]
	v_mfma_f32_16x16x32_bf16 v[12:15], v[156:159], v[210:213], v[12:15]
	v_mfma_f32_16x16x32_bf16 v[8:11], v[166:169], v[210:213], v[8:11]
	v_mfma_f32_16x16x32_bf16 v[52:55], v[214:217], v[170:173], v[52:55]
	v_mfma_f32_16x16x32_bf16 v[48:51], v[222:225], v[170:173], v[48:51]
	v_mfma_f32_16x16x32_bf16 v[36:39], v[214:217], v[190:193], v[36:39]
	v_mfma_f32_16x16x32_bf16 v[32:35], v[222:225], v[190:193], v[32:35]
	v_mfma_f32_16x16x32_bf16 v[20:23], v[214:217], v[198:201], v[20:23]
	v_mfma_f32_16x16x32_bf16 v[16:19], v[222:225], v[198:201], v[16:19]
	v_mfma_f32_16x16x32_bf16 v[4:7], v[214:217], v[206:209], v[4:7]
	v_mfma_f32_16x16x32_bf16 v[0:3], v[222:225], v[206:209], v[0:3]
	v_mfma_f32_16x16x32_bf16 v[52:55], v[218:221], v[182:185], v[52:55]
	v_mfma_f32_16x16x32_bf16 v[48:51], v[226:229], v[182:185], v[48:51]
	v_mfma_f32_16x16x32_bf16 v[36:39], v[218:221], v[194:197], v[36:39]
	v_mfma_f32_16x16x32_bf16 v[32:35], v[226:229], v[194:197], v[32:35]
	v_mfma_f32_16x16x32_bf16 v[20:23], v[218:221], v[202:205], v[20:23]
	v_mfma_f32_16x16x32_bf16 v[16:19], v[226:229], v[202:205], v[16:19]
	v_mfma_f32_16x16x32_bf16 v[4:7], v[218:221], v[210:213], v[4:7]
	v_mfma_f32_16x16x32_bf16 v[0:3], v[226:229], v[210:213], v[0:3]
	s_barrier
	s_add_i32 s58, s58, 2
	s_add_u32 s28, s28, 0x100
	s_addc_u32 s29, s29, 0
	s_add_u32 s56, s56, 0x100
	s_addc_u32 s57, s57, 0
	s_cmp_gt_u32 s58, 13
	s_cbranch_scc0 .LBB0_195
	v_max_f32_e32 v144, v124, v124
	v_max_f32_e32 v144, 0xc1a00000, v144
	v_mul_f32_e32 v144, 0xbfb8aa3b, v144
	v_exp_f32_e32 v157, v144
	v_max_f32_e32 v144, v125, v125
	v_max_f32_e32 v144, 0xc1a00000, v144
	v_mul_f32_e32 v144, 0xbfb8aa3b, v144
	v_exp_f32_e32 v156, v144
	v_max_f32_e32 v144, v126, v126
	v_max_f32_e32 v144, 0xc1a00000, v144
	v_mul_f32_e32 v144, 0xbfb8aa3b, v144
	v_exp_f32_e32 v159, v144
	v_max_f32_e32 v144, v127, v127
	v_max_f32_e32 v144, 0xc1a00000, v144
	v_mul_f32_e32 v144, 0xbfb8aa3b, v144
	v_exp_f32_e32 v158, v144
	v_pk_add_f32 v[156:157], v[156:157], 1.0 op_sel_hi:[1,0]
	v_lshl_or_b32 v146, s53, 7, v150
	v_mov_b32_e32 v160, v157
	v_pk_add_f32 v[158:159], v[158:159], 1.0 op_sel_hi:[1,0]
	v_mov_b32_e32 v162, v156
	v_mov_b32_e32 v161, v159
	v_mov_b32_e32 v163, v158
	v_pk_mul_f32 v[160:161], v[160:161], v[162:163]
	v_lshl_add_u32 v155, s26, 8, v148
	v_mul_f32_e32 v162, v160, v161
	v_rcp_f32_e32 v166, v162
	v_ashrrev_i32_e32 v147, 31, v146
	v_mov_b64_e32 v[144:145], s[4:5]
	v_mad_i64_i32 v[162:163], s[28:29], v155, s52, v[144:145]
	v_mul_f32_e32 v160, v160, v166
	v_mul_f32_e32 v164, v161, v166
	v_pk_mul_f32 v[158:159], v[158:159], v[160:161] op_sel_hi:[1,0]
	v_max_f32_e32 v160, v120, v120
	v_max_f32_e32 v166, v122, v122
	v_max_f32_e32 v160, 0xc1a00000, v160
	v_max_f32_e32 v166, 0xc1a00000, v166
	v_mul_f32_e32 v160, 0xbfb8aa3b, v160
	v_mul_f32_e32 v166, 0xbfb8aa3b, v166
	v_exp_f32_e32 v161, v160
	v_max_f32_e32 v160, v121, v121
	v_exp_f32_e32 v167, v166
	v_max_f32_e32 v166, v123, v123
	v_max_f32_e32 v160, 0xc1a00000, v160
	v_max_f32_e32 v166, 0xc1a00000, v166
	v_mul_f32_e32 v160, 0xbfb8aa3b, v160
	v_mul_f32_e32 v166, 0xbfb8aa3b, v166
	v_exp_f32_e32 v160, v160
	v_exp_f32_e32 v166, v166
	v_pk_mul_f32 v[156:157], v[156:157], v[164:165] op_sel_hi:[1,0]
	v_pk_mul_f32 v[126:127], v[126:127], v[158:159]
	v_pk_mul_f32 v[124:125], v[124:125], v[156:157]
	v_pk_add_f32 v[156:157], v[160:161], 1.0 op_sel_hi:[1,0]
	v_pk_add_f32 v[160:161], v[166:167], 1.0 op_sel_hi:[1,0]
	v_mov_b32_e32 v166, v157
; __device__ __forceinline__ unsigned cvt_pk_bf16(float lo, float hi) { unsigned r; asm volatile("v_cvt_pk_bf16_f32 %0, %1, %2" : "=v"(r) : "v"(lo), "v"(hi)); return r; }
; __device__ __forceinline__ f32x4 sigmoid4(f32x4 x) {
;     f32x4 d;
; #pragma unroll
;     for (int j = 0; j < 4; ++j) d[j] = 1.0f + __expf(-fmaxf(x[j], -20.0f));
;     const float p01 = d[0] * d[1], p23 = d[2] * d[3], r = __builtin_amdgcn_rcpf(p01 * p23), r01 = r * p23, r23 = r * p01;
;     return (f32x4){r01 * d[1], r01 * d[0], r23 * d[3], r23 * d[2]};
; }
;     __device__ __forceinline__ void operator()(const f32x4 (&acc)[2][2][4][2], const Unit& u, int wr, int wc, int fr, int fq) const {
;         const int row0 = u.pm * BM + wr * 64 + fr, col0 = u.pn * HALF + wc * 32 + 8 * fq;
; #pragma unroll
;         for (int ai = 0; ai < 2; ++ai)
; #pragma unroll
;             for (int m = 0; m < 4; ++m) { bf16_t* rowp = O + (size_t)(row0 + ai * HALF + m * 16) * ldc + col0;
;                 f32x4 v0, v1;
; #pragma unroll
;                 for (int j = 0; j < 1; ++j) { v0 = acc[ai][0][m][0] * sigmoid4(acc[ai][0][m][0]) * acc[ai][1][m][0]; v1 = acc[ai][0][m][1] * sigmoid4(acc[ai][0][m][1]) * acc[ai][1][m][1]; }
;                 u32x4 w; w.x = cvt_pk_bf16(v0[0], v0[1]); w.y = cvt_pk_bf16(v0[2], v0[3]); w.z = cvt_pk_bf16(v1[0], v1[1]); w.w = cvt_pk_bf16(v1[2], v1[3]);
;                 *(u32x4*)rowp = w; }
	v_mov_b32_e32 v167, v161
	v_mov_b32_e32 v168, v156
	v_mov_b32_e32 v169, v160
	v_pk_mul_f32 v[166:167], v[166:167], v[168:169]
	v_pk_mul_f32 v[118:119], v[126:127], v[118:119]
	v_mul_f32_e32 v164, v166, v167
	v_rcp_f32_e32 v164, v164
	v_pk_mul_f32 v[116:117], v[124:125], v[116:117]
	v_lshlrev_b64 v[146:147], 1, v[146:147]
	v_lshl_add_u64 v[162:163], v[162:163], 0, v[146:147]
	v_mul_f32_e32 v124, v167, v164
	v_mul_f32_e32 v126, v166, v164
	v_pk_mul_f32 v[126:127], v[160:161], v[126:127] op_sel_hi:[1,0]
	v_pk_mul_f32 v[124:125], v[156:157], v[124:125] op_sel_hi:[1,0]
	v_pk_mul_f32 v[122:123], v[122:123], v[126:127]
	v_pk_mul_f32 v[120:121], v[120:121], v[124:125]
	v_pk_mul_f32 v[122:123], v[122:123], v[114:115]
	v_pk_mul_f32 v[114:115], v[120:121], v[112:113]
	v_cvt_pk_bf16_f32 v112, v116, v117
	v_cvt_pk_bf16_f32 v113, v118, v119
	v_max_f32_e32 v116, v108, v108
	v_max_f32_e32 v118, v110, v110
	v_max_f32_e32 v116, 0xc1a00000, v116
	v_max_f32_e32 v118, 0xc1a00000, v118
	v_mul_f32_e32 v116, 0xbfb8aa3b, v116
	v_mul_f32_e32 v118, 0xbfb8aa3b, v118
	v_exp_f32_e32 v117, v116
	v_max_f32_e32 v116, v109, v109
	v_exp_f32_e32 v119, v118
	v_max_f32_e32 v118, v111, v111
	v_max_f32_e32 v116, 0xc1a00000, v116
	v_max_f32_e32 v118, 0xc1a00000, v118
	v_mul_f32_e32 v116, 0xbfb8aa3b, v116
	v_mul_f32_e32 v118, 0xbfb8aa3b, v118
	v_exp_f32_e32 v116, v116
	v_exp_f32_e32 v118, v118
	v_cvt_pk_bf16_f32 v114, v114, v115
	v_cvt_pk_bf16_f32 v115, v122, v123
	global_store_dwordx4 v[162:163], v[112:115], off
	v_or_b32_e32 v120, 16, v155
	s_and_b64 vcc, exec, s[2:3]
	v_pk_add_f32 v[112:113], v[116:117], 1.0 op_sel_hi:[1,0]
	v_pk_add_f32 v[114:115], v[118:119], 1.0 op_sel_hi:[1,0]
	v_mov_b32_e32 v116, v113
	v_mov_b32_e32 v117, v115
	v_mov_b32_e32 v118, v112
	v_mov_b32_e32 v119, v114
	v_pk_mul_f32 v[116:117], v[116:117], v[118:119]
	s_mov_b32 s53, s14
	v_mul_f32_e32 v118, v116, v117
	v_rcp_f32_e32 v121, v118
	v_mad_i64_i32 v[118:119], s[28:29], v120, s52, v[144:145]
	v_lshl_add_u64 v[118:119], v[118:119], 0, v[146:147]
	v_mul_f32_e32 v116, v116, v121
	v_mul_f32_e32 v120, v117, v121
	v_pk_mul_f32 v[114:115], v[114:115], v[116:117] op_sel_hi:[1,0]
	v_max_f32_e32 v116, v104, v104
	v_max_f32_e32 v121, v106, v106
	v_max_f32_e32 v116, 0xc1a00000, v116
	v_max_f32_e32 v121, 0xc1a00000, v121
	v_mul_f32_e32 v116, 0xbfb8aa3b, v116
	v_mul_f32_e32 v121, 0xbfb8aa3b, v121
	v_exp_f32_e32 v117, v116
	v_max_f32_e32 v116, v105, v105
	v_exp_f32_e32 v123, v121
	v_max_f32_e32 v121, v107, v107
	v_max_f32_e32 v116, 0xc1a00000, v116
	v_max_f32_e32 v121, 0xc1a00000, v121
	v_mul_f32_e32 v116, 0xbfb8aa3b, v116
	v_mul_f32_e32 v121, 0xbfb8aa3b, v121
	v_exp_f32_e32 v116, v116
	v_exp_f32_e32 v122, v121
	v_pk_mul_f32 v[112:113], v[112:113], v[120:121] op_sel_hi:[1,0]
	v_pk_mul_f32 v[110:111], v[110:111], v[114:115]
	v_pk_mul_f32 v[108:109], v[108:109], v[112:113]
	v_pk_add_f32 v[112:113], v[116:117], 1.0 op_sel_hi:[1,0]
	v_pk_add_f32 v[116:117], v[122:123], 1.0 op_sel_hi:[1,0]
	v_mov_b32_e32 v120, v113
	v_mov_b32_e32 v121, v117
	v_mov_b32_e32 v122, v112
	v_mov_b32_e32 v123, v116
	v_pk_mul_f32 v[120:121], v[120:121], v[122:123]
	v_pk_mul_f32 v[102:103], v[110:111], v[102:103]
	v_mul_f32_e32 v122, v120, v121
	v_rcp_f32_e32 v122, v122
	v_pk_mul_f32 v[100:101], v[108:109], v[100:101]
	s_mov_b32 s26, s16
	s_mov_b64 s[30:31], s[24:25]
	v_mul_f32_e32 v108, v121, v122
	v_mul_f32_e32 v110, v120, v122
	v_pk_mul_f32 v[110:111], v[116:117], v[110:111] op_sel_hi:[1,0]
	v_pk_mul_f32 v[108:109], v[112:113], v[108:109] op_sel_hi:[1,0]
	v_pk_mul_f32 v[106:107], v[106:107], v[110:111]
	v_pk_mul_f32 v[104:105], v[104:105], v[108:109]
	v_pk_mul_f32 v[106:107], v[106:107], v[98:99]
	v_pk_mul_f32 v[98:99], v[104:105], v[96:97]
	v_cvt_pk_bf16_f32 v96, v100, v101
	v_cvt_pk_bf16_f32 v97, v102, v103
	v_max_f32_e32 v100, v92, v92
	v_max_f32_e32 v102, v94, v94
	v_max_f32_e32 v100, 0xc1a00000, v100
	v_max_f32_e32 v102, 0xc1a00000, v102
	v_mul_f32_e32 v100, 0xbfb8aa3b, v100
	v_mul_f32_e32 v102, 0xbfb8aa3b, v102
	v_exp_f32_e32 v101, v100
	v_max_f32_e32 v100, v93, v93
	v_exp_f32_e32 v103, v102
	v_max_f32_e32 v102, v95, v95
	v_max_f32_e32 v100, 0xc1a00000, v100
	v_max_f32_e32 v102, 0xc1a00000, v102
	v_mul_f32_e32 v100, 0xbfb8aa3b, v100
	v_mul_f32_e32 v102, 0xbfb8aa3b, v102
	v_exp_f32_e32 v100, v100
	v_exp_f32_e32 v102, v102
	v_cvt_pk_bf16_f32 v98, v98, v99
	v_cvt_pk_bf16_f32 v99, v106, v107
	global_store_dwordx4 v[118:119], v[96:99], off
	v_or_b32_e32 v104, 32, v155
	s_nop 0
	v_pk_add_f32 v[96:97], v[100:101], 1.0 op_sel_hi:[1,0]
	v_pk_add_f32 v[98:99], v[102:103], 1.0 op_sel_hi:[1,0]
	v_mov_b32_e32 v100, v97
	v_mov_b32_e32 v101, v99
	v_mov_b32_e32 v102, v96
	v_mov_b32_e32 v103, v98
	v_pk_mul_f32 v[100:101], v[100:101], v[102:103]
	s_nop 0
	v_mul_f32_e32 v102, v100, v101
	v_rcp_f32_e32 v105, v102
	v_mad_i64_i32 v[102:103], s[28:29], v104, s52, v[144:145]
	v_lshl_add_u64 v[102:103], v[102:103], 0, v[146:147]
	v_mul_f32_e32 v100, v100, v105
	v_mul_f32_e32 v104, v101, v105
	v_pk_mul_f32 v[98:99], v[98:99], v[100:101] op_sel_hi:[1,0]
	v_max_f32_e32 v100, v88, v88
	v_max_f32_e32 v105, v90, v90
	v_max_f32_e32 v100, 0xc1a00000, v100
	v_max_f32_e32 v105, 0xc1a00000, v105
	v_mul_f32_e32 v100, 0xbfb8aa3b, v100
	v_mul_f32_e32 v105, 0xbfb8aa3b, v105
	v_exp_f32_e32 v101, v100
	v_max_f32_e32 v100, v89, v89
	v_exp_f32_e32 v107, v105
	v_max_f32_e32 v105, v91, v91
	v_max_f32_e32 v100, 0xc1a00000, v100
	v_max_f32_e32 v105, 0xc1a00000, v105
	v_mul_f32_e32 v100, 0xbfb8aa3b, v100
	v_mul_f32_e32 v105, 0xbfb8aa3b, v105
	v_exp_f32_e32 v100, v100
	v_exp_f32_e32 v106, v105
	v_pk_mul_f32 v[96:97], v[96:97], v[104:105] op_sel_hi:[1,0]
	v_pk_mul_f32 v[94:95], v[94:95], v[98:99]
; __device__ __forceinline__ unsigned cvt_pk_bf16(float lo, float hi) { unsigned r; asm volatile("v_cvt_pk_bf16_f32 %0, %1, %2" : "=v"(r) : "v"(lo), "v"(hi)); return r; }
; __device__ __forceinline__ f32x4 sigmoid4(f32x4 x) {
;     f32x4 d;
; #pragma unroll
;     for (int j = 0; j < 4; ++j) d[j] = 1.0f + __expf(-fmaxf(x[j], -20.0f));
;     const float p01 = d[0] * d[1], p23 = d[2] * d[3], r = __builtin_amdgcn_rcpf(p01 * p23), r01 = r * p23, r23 = r * p01;
;     return (f32x4){r01 * d[1], r01 * d[0], r23 * d[3], r23 * d[2]};
; }
;     __device__ __forceinline__ void operator()(const f32x4 (&acc)[2][2][4][2], const Unit& u, int wr, int wc, int fr, int fq) const {
;         const int row0 = u.pm * BM + wr * 64 + fr, col0 = u.pn * HALF + wc * 32 + 8 * fq;
; #pragma unroll
;         for (int ai = 0; ai < 2; ++ai)
; #pragma unroll
;             for (int m = 0; m < 4; ++m) { bf16_t* rowp = O + (size_t)(row0 + ai * HALF + m * 16) * ldc + col0;
;                 f32x4 v0, v1;
; #pragma unroll
;                 for (int j = 0; j < 1; ++j) { v0 = acc[ai][0][m][0] * sigmoid4(acc[ai][0][m][0]) * acc[ai][1][m][0]; v1 = acc[ai][0][m][1] * sigmoid4(acc[ai][0][m][1]) * acc[ai][1][m][1]; }
;                 u32x4 w; w.x = cvt_pk_bf16(v0[0], v0[1]); w.y = cvt_pk_bf16(v0[2], v0[3]); w.z = cvt_pk_bf16(v1[0], v1[1]); w.w = cvt_pk_bf16(v1[2], v1[3]);
;                 *(u32x4*)rowp = w; }
	v_pk_mul_f32 v[92:93], v[92:93], v[96:97]
	v_pk_add_f32 v[96:97], v[100:101], 1.0 op_sel_hi:[1,0]
	v_pk_add_f32 v[100:101], v[106:107], 1.0 op_sel_hi:[1,0]
	v_mov_b32_e32 v104, v97
	v_mov_b32_e32 v105, v101
	v_mov_b32_e32 v106, v96
	v_mov_b32_e32 v107, v100
	v_pk_mul_f32 v[104:105], v[104:105], v[106:107]
	v_pk_mul_f32 v[86:87], v[94:95], v[86:87]
	v_mul_f32_e32 v106, v104, v105
	v_rcp_f32_e32 v106, v106
	v_pk_mul_f32 v[84:85], v[92:93], v[84:85]
	v_mul_f32_e32 v92, v105, v106
	v_mul_f32_e32 v94, v104, v106
	v_pk_mul_f32 v[94:95], v[100:101], v[94:95] op_sel_hi:[1,0]
	v_pk_mul_f32 v[92:93], v[96:97], v[92:93] op_sel_hi:[1,0]
	v_pk_mul_f32 v[90:91], v[90:91], v[94:95]
	v_pk_mul_f32 v[88:89], v[88:89], v[92:93]
	v_pk_mul_f32 v[90:91], v[90:91], v[82:83]
	v_pk_mul_f32 v[82:83], v[88:89], v[80:81]
	v_cvt_pk_bf16_f32 v80, v84, v85
	v_cvt_pk_bf16_f32 v81, v86, v87
	v_max_f32_e32 v84, v76, v76
	v_max_f32_e32 v86, v78, v78
	v_max_f32_e32 v84, 0xc1a00000, v84
	v_max_f32_e32 v86, 0xc1a00000, v86
	v_mul_f32_e32 v84, 0xbfb8aa3b, v84
	v_mul_f32_e32 v86, 0xbfb8aa3b, v86
	v_exp_f32_e32 v85, v84
	v_max_f32_e32 v84, v77, v77
	v_exp_f32_e32 v87, v86
	v_max_f32_e32 v86, v79, v79
	v_max_f32_e32 v84, 0xc1a00000, v84
	v_max_f32_e32 v86, 0xc1a00000, v86
	v_mul_f32_e32 v84, 0xbfb8aa3b, v84
	v_mul_f32_e32 v86, 0xbfb8aa3b, v86
	v_exp_f32_e32 v84, v84
	v_exp_f32_e32 v86, v86
	v_cvt_pk_bf16_f32 v82, v82, v83
	v_cvt_pk_bf16_f32 v83, v90, v91
	global_store_dwordx4 v[102:103], v[80:83], off
	v_or_b32_e32 v88, 48, v155
	s_nop 0
	v_pk_add_f32 v[80:81], v[84:85], 1.0 op_sel_hi:[1,0]
	v_pk_add_f32 v[82:83], v[86:87], 1.0 op_sel_hi:[1,0]
	v_mov_b32_e32 v84, v81
	v_mov_b32_e32 v85, v83
	v_mov_b32_e32 v86, v80
	v_mov_b32_e32 v87, v82
	v_pk_mul_f32 v[84:85], v[84:85], v[86:87]
	s_nop 0
	v_mul_f32_e32 v86, v84, v85
	v_rcp_f32_e32 v89, v86
	v_mad_i64_i32 v[86:87], s[28:29], v88, s52, v[144:145]
	v_lshl_add_u64 v[86:87], v[86:87], 0, v[146:147]
	v_mul_f32_e32 v84, v84, v89
	v_mul_f32_e32 v88, v85, v89
	v_pk_mul_f32 v[82:83], v[82:83], v[84:85] op_sel_hi:[1,0]
	v_max_f32_e32 v84, v72, v72
	v_max_f32_e32 v89, v74, v74
	v_max_f32_e32 v84, 0xc1a00000, v84
	v_max_f32_e32 v89, 0xc1a00000, v89
	v_mul_f32_e32 v84, 0xbfb8aa3b, v84
	v_mul_f32_e32 v89, 0xbfb8aa3b, v89
	v_exp_f32_e32 v85, v84
	v_max_f32_e32 v84, v73, v73
	v_exp_f32_e32 v91, v89
	v_max_f32_e32 v89, v75, v75
	v_max_f32_e32 v84, 0xc1a00000, v84
	v_max_f32_e32 v89, 0xc1a00000, v89
	v_mul_f32_e32 v84, 0xbfb8aa3b, v84
	v_mul_f32_e32 v89, 0xbfb8aa3b, v89
	v_exp_f32_e32 v84, v84
	v_exp_f32_e32 v90, v89
	v_pk_mul_f32 v[80:81], v[80:81], v[88:89] op_sel_hi:[1,0]
	v_pk_mul_f32 v[78:79], v[78:79], v[82:83]
	v_pk_mul_f32 v[76:77], v[76:77], v[80:81]
	v_pk_add_f32 v[80:81], v[84:85], 1.0 op_sel_hi:[1,0]
	v_pk_add_f32 v[84:85], v[90:91], 1.0 op_sel_hi:[1,0]
	v_mov_b32_e32 v88, v81
	v_mov_b32_e32 v89, v85
	v_mov_b32_e32 v90, v80
	v_mov_b32_e32 v91, v84
	v_pk_mul_f32 v[88:89], v[88:89], v[90:91]
	v_pk_mul_f32 v[70:71], v[78:79], v[70:71]
	v_mul_f32_e32 v90, v88, v89
	v_rcp_f32_e32 v90, v90
	v_pk_mul_f32 v[68:69], v[76:77], v[68:69]
	v_mul_f32_e32 v76, v89, v90
	v_mul_f32_e32 v78, v88, v90
	v_pk_mul_f32 v[78:79], v[84:85], v[78:79] op_sel_hi:[1,0]
	v_pk_mul_f32 v[76:77], v[80:81], v[76:77] op_sel_hi:[1,0]
	v_pk_mul_f32 v[74:75], v[74:75], v[78:79]
	v_pk_mul_f32 v[72:73], v[72:73], v[76:77]
	v_pk_mul_f32 v[74:75], v[74:75], v[66:67]
	v_pk_mul_f32 v[66:67], v[72:73], v[64:65]
	v_cvt_pk_bf16_f32 v64, v68, v69
	v_cvt_pk_bf16_f32 v65, v70, v71
	v_max_f32_e32 v68, v60, v60
	v_max_f32_e32 v70, v62, v62
	v_max_f32_e32 v68, 0xc1a00000, v68
	v_max_f32_e32 v70, 0xc1a00000, v70
	v_mul_f32_e32 v68, 0xbfb8aa3b, v68
	v_mul_f32_e32 v70, 0xbfb8aa3b, v70
	v_exp_f32_e32 v69, v68
	v_max_f32_e32 v68, v61, v61
	v_exp_f32_e32 v71, v70
	v_max_f32_e32 v70, v63, v63
	v_max_f32_e32 v68, 0xc1a00000, v68
	v_max_f32_e32 v70, 0xc1a00000, v70
	v_mul_f32_e32 v68, 0xbfb8aa3b, v68
	v_mul_f32_e32 v70, 0xbfb8aa3b, v70
	v_exp_f32_e32 v68, v68
	v_exp_f32_e32 v70, v70
	v_cvt_pk_bf16_f32 v66, v66, v67
	v_cvt_pk_bf16_f32 v67, v74, v75
	global_store_dwordx4 v[86:87], v[64:67], off
	v_add_u32_e32 v72, 0x80, v155
	s_nop 0
	v_pk_add_f32 v[64:65], v[68:69], 1.0 op_sel_hi:[1,0]
	v_pk_add_f32 v[66:67], v[70:71], 1.0 op_sel_hi:[1,0]
	v_mov_b32_e32 v68, v65
	v_mov_b32_e32 v69, v67
	v_mov_b32_e32 v70, v64
	v_mov_b32_e32 v71, v66
	v_pk_mul_f32 v[68:69], v[68:69], v[70:71]
	s_nop 0
	v_mul_f32_e32 v70, v68, v69
	v_rcp_f32_e32 v73, v70
	v_mad_i64_i32 v[70:71], s[28:29], v72, s52, v[144:145]
	v_lshl_add_u64 v[70:71], v[70:71], 0, v[146:147]
	v_mul_f32_e32 v68, v68, v73
	v_mul_f32_e32 v72, v69, v73
	v_pk_mul_f32 v[66:67], v[66:67], v[68:69] op_sel_hi:[1,0]
	v_max_f32_e32 v68, v56, v56
	v_max_f32_e32 v73, v58, v58
	v_max_f32_e32 v68, 0xc1a00000, v68
	v_max_f32_e32 v73, 0xc1a00000, v73
	v_mul_f32_e32 v68, 0xbfb8aa3b, v68
	v_mul_f32_e32 v73, 0xbfb8aa3b, v73
	v_exp_f32_e32 v69, v68
	v_max_f32_e32 v68, v57, v57
	v_exp_f32_e32 v75, v73
	v_max_f32_e32 v73, v59, v59
	v_max_f32_e32 v68, 0xc1a00000, v68
	v_max_f32_e32 v73, 0xc1a00000, v73
	v_mul_f32_e32 v68, 0xbfb8aa3b, v68
	v_mul_f32_e32 v73, 0xbfb8aa3b, v73
	v_exp_f32_e32 v68, v68
	v_exp_f32_e32 v74, v73
	v_pk_mul_f32 v[64:65], v[64:65], v[72:73] op_sel_hi:[1,0]
	v_pk_mul_f32 v[62:63], v[62:63], v[66:67]
	v_pk_mul_f32 v[60:61], v[60:61], v[64:65]
	v_pk_add_f32 v[64:65], v[68:69], 1.0 op_sel_hi:[1,0]
	v_pk_add_f32 v[68:69], v[74:75], 1.0 op_sel_hi:[1,0]
	v_mov_b32_e32 v72, v65
	v_mov_b32_e32 v73, v69
	v_mov_b32_e32 v74, v64
	v_mov_b32_e32 v75, v68
	v_pk_mul_f32 v[72:73], v[72:73], v[74:75]
	v_pk_mul_f32 v[54:55], v[62:63], v[54:55]
	v_mul_f32_e32 v74, v72, v73
; __device__ __forceinline__ unsigned cvt_pk_bf16(float lo, float hi) { unsigned r; asm volatile("v_cvt_pk_bf16_f32 %0, %1, %2" : "=v"(r) : "v"(lo), "v"(hi)); return r; }
; __device__ __forceinline__ f32x4 sigmoid4(f32x4 x) {
;     f32x4 d;
; #pragma unroll
;     for (int j = 0; j < 4; ++j) d[j] = 1.0f + __expf(-fmaxf(x[j], -20.0f));
;     const float p01 = d[0] * d[1], p23 = d[2] * d[3], r = __builtin_amdgcn_rcpf(p01 * p23), r01 = r * p23, r23 = r * p01;
;     return (f32x4){r01 * d[1], r01 * d[0], r23 * d[3], r23 * d[2]};
; }
;     __device__ __forceinline__ void operator()(const f32x4 (&acc)[2][2][4][2], const Unit& u, int wr, int wc, int fr, int fq) const {
;         const int row0 = u.pm * BM + wr * 64 + fr, col0 = u.pn * HALF + wc * 32 + 8 * fq;
; #pragma unroll
;         for (int ai = 0; ai < 2; ++ai)
; #pragma unroll
;             for (int m = 0; m < 4; ++m) { bf16_t* rowp = O + (size_t)(row0 + ai * HALF + m * 16) * ldc + col0;
;                 f32x4 v0, v1;
; #pragma unroll
;                 for (int j = 0; j < 1; ++j) { v0 = acc[ai][0][m][0] * sigmoid4(acc[ai][0][m][0]) * acc[ai][1][m][0]; v1 = acc[ai][0][m][1] * sigmoid4(acc[ai][0][m][1]) * acc[ai][1][m][1]; }
;                 u32x4 w; w.x = cvt_pk_bf16(v0[0], v0[1]); w.y = cvt_pk_bf16(v0[2], v0[3]); w.z = cvt_pk_bf16(v1[0], v1[1]); w.w = cvt_pk_bf16(v1[2], v1[3]);
;                 *(u32x4*)rowp = w; }
	v_rcp_f32_e32 v74, v74
	v_pk_mul_f32 v[52:53], v[60:61], v[52:53]
	v_mul_f32_e32 v60, v73, v74
	v_mul_f32_e32 v62, v72, v74
	v_pk_mul_f32 v[62:63], v[68:69], v[62:63] op_sel_hi:[1,0]
	v_pk_mul_f32 v[60:61], v[64:65], v[60:61] op_sel_hi:[1,0]
	v_pk_mul_f32 v[58:59], v[58:59], v[62:63]
	v_pk_mul_f32 v[56:57], v[56:57], v[60:61]
	v_pk_mul_f32 v[58:59], v[58:59], v[50:51]
	v_pk_mul_f32 v[50:51], v[56:57], v[48:49]
	v_cvt_pk_bf16_f32 v48, v52, v53
	v_cvt_pk_bf16_f32 v49, v54, v55
	v_max_f32_e32 v52, v44, v44
	v_max_f32_e32 v54, v46, v46
	v_max_f32_e32 v52, 0xc1a00000, v52
	v_max_f32_e32 v54, 0xc1a00000, v54
	v_mul_f32_e32 v52, 0xbfb8aa3b, v52
	v_mul_f32_e32 v54, 0xbfb8aa3b, v54
	v_exp_f32_e32 v53, v52
	v_max_f32_e32 v52, v45, v45
	v_exp_f32_e32 v55, v54
	v_max_f32_e32 v54, v47, v47
	v_max_f32_e32 v52, 0xc1a00000, v52
	v_max_f32_e32 v54, 0xc1a00000, v54
	v_mul_f32_e32 v52, 0xbfb8aa3b, v52
	v_mul_f32_e32 v54, 0xbfb8aa3b, v54
	v_exp_f32_e32 v52, v52
	v_exp_f32_e32 v54, v54
	v_cvt_pk_bf16_f32 v50, v50, v51
	v_cvt_pk_bf16_f32 v51, v58, v59
	global_store_dwordx4 v[70:71], v[48:51], off
	v_add_u32_e32 v56, 0x90, v155
	s_nop 0
	v_pk_add_f32 v[48:49], v[52:53], 1.0 op_sel_hi:[1,0]
	v_pk_add_f32 v[50:51], v[54:55], 1.0 op_sel_hi:[1,0]
	v_mov_b32_e32 v52, v49
	v_mov_b32_e32 v53, v51
	v_mov_b32_e32 v54, v48
	v_mov_b32_e32 v55, v50
	v_pk_mul_f32 v[52:53], v[52:53], v[54:55]
	s_nop 0
	v_mul_f32_e32 v54, v52, v53
	v_rcp_f32_e32 v57, v54
	v_mad_i64_i32 v[54:55], s[28:29], v56, s52, v[144:145]
	v_lshl_add_u64 v[54:55], v[54:55], 0, v[146:147]
	v_mul_f32_e32 v52, v52, v57
	v_mul_f32_e32 v56, v53, v57
	v_pk_mul_f32 v[50:51], v[50:51], v[52:53] op_sel_hi:[1,0]
	v_max_f32_e32 v52, v40, v40
	v_max_f32_e32 v57, v42, v42
	v_max_f32_e32 v52, 0xc1a00000, v52
	v_max_f32_e32 v57, 0xc1a00000, v57
	v_mul_f32_e32 v52, 0xbfb8aa3b, v52
	v_mul_f32_e32 v57, 0xbfb8aa3b, v57
	v_exp_f32_e32 v53, v52
	v_max_f32_e32 v52, v41, v41
	v_exp_f32_e32 v59, v57
	v_max_f32_e32 v57, v43, v43
	v_max_f32_e32 v52, 0xc1a00000, v52
	v_max_f32_e32 v57, 0xc1a00000, v57
	v_mul_f32_e32 v52, 0xbfb8aa3b, v52
	v_mul_f32_e32 v57, 0xbfb8aa3b, v57
	v_exp_f32_e32 v52, v52
	v_exp_f32_e32 v58, v57
	v_pk_mul_f32 v[48:49], v[48:49], v[56:57] op_sel_hi:[1,0]
	v_pk_mul_f32 v[46:47], v[46:47], v[50:51]
	v_pk_mul_f32 v[44:45], v[44:45], v[48:49]
	v_pk_add_f32 v[48:49], v[52:53], 1.0 op_sel_hi:[1,0]
	v_pk_add_f32 v[52:53], v[58:59], 1.0 op_sel_hi:[1,0]
	v_mov_b32_e32 v56, v49
	v_mov_b32_e32 v57, v53
	v_mov_b32_e32 v58, v48
	v_mov_b32_e32 v59, v52
	v_pk_mul_f32 v[56:57], v[56:57], v[58:59]
	v_pk_mul_f32 v[38:39], v[46:47], v[38:39]
	v_mul_f32_e32 v58, v56, v57
	v_rcp_f32_e32 v58, v58
	v_pk_mul_f32 v[36:37], v[44:45], v[36:37]
	v_mul_f32_e32 v44, v57, v58
	v_mul_f32_e32 v46, v56, v58
	v_pk_mul_f32 v[46:47], v[52:53], v[46:47] op_sel_hi:[1,0]
	v_pk_mul_f32 v[44:45], v[48:49], v[44:45] op_sel_hi:[1,0]
	v_pk_mul_f32 v[42:43], v[42:43], v[46:47]
	v_pk_mul_f32 v[40:41], v[40:41], v[44:45]
	v_pk_mul_f32 v[42:43], v[42:43], v[34:35]
	v_pk_mul_f32 v[34:35], v[40:41], v[32:33]
	v_cvt_pk_bf16_f32 v32, v36, v37
	v_cvt_pk_bf16_f32 v33, v38, v39
	v_max_f32_e32 v36, v28, v28
	v_max_f32_e32 v38, v30, v30
	v_max_f32_e32 v36, 0xc1a00000, v36
	v_max_f32_e32 v38, 0xc1a00000, v38
	v_mul_f32_e32 v36, 0xbfb8aa3b, v36
	v_mul_f32_e32 v38, 0xbfb8aa3b, v38
	v_exp_f32_e32 v37, v36
	v_max_f32_e32 v36, v29, v29
	v_exp_f32_e32 v39, v38
	v_max_f32_e32 v38, v31, v31
	v_max_f32_e32 v36, 0xc1a00000, v36
	v_max_f32_e32 v38, 0xc1a00000, v38
	v_mul_f32_e32 v36, 0xbfb8aa3b, v36
	v_mul_f32_e32 v38, 0xbfb8aa3b, v38
	v_exp_f32_e32 v36, v36
	v_exp_f32_e32 v38, v38
	v_cvt_pk_bf16_f32 v34, v34, v35
	v_cvt_pk_bf16_f32 v35, v42, v43
	global_store_dwordx4 v[54:55], v[32:35], off
	v_add_u32_e32 v40, 0xa0, v155
	s_nop 0
	v_pk_add_f32 v[32:33], v[36:37], 1.0 op_sel_hi:[1,0]
	v_pk_add_f32 v[34:35], v[38:39], 1.0 op_sel_hi:[1,0]
	v_mov_b32_e32 v36, v33
	v_mov_b32_e32 v37, v35
	v_mov_b32_e32 v38, v32
	v_mov_b32_e32 v39, v34
	v_pk_mul_f32 v[36:37], v[36:37], v[38:39]
	s_nop 0
	v_mul_f32_e32 v38, v36, v37
	v_rcp_f32_e32 v41, v38
	v_mad_i64_i32 v[38:39], s[28:29], v40, s52, v[144:145]
	v_lshl_add_u64 v[38:39], v[38:39], 0, v[146:147]
	v_mul_f32_e32 v36, v36, v41
	v_mul_f32_e32 v40, v37, v41
	v_pk_mul_f32 v[34:35], v[34:35], v[36:37] op_sel_hi:[1,0]
; __device__ __forceinline__ unsigned cvt_pk_bf16(float lo, float hi) { unsigned r; asm volatile("v_cvt_pk_bf16_f32 %0, %1, %2" : "=v"(r) : "v"(lo), "v"(hi)); return r; }
; #define PG8_WAIT_V(n) asm volatile("s_waitcnt vmcnt(" #n ")" ::: "memory")
; #define PG8_BAR __builtin_amdgcn_s_barrier()
;     __device__ __forceinline__ void operator()(const f32x4 (&acc)[2][2][4][2], const Unit& u, int wr, int wc, int fr, int fq) const {
;         const int row0 = u.pm * BM + wr * 64 + fr, col0 = u.pn * HALF + wc * 32 + 8 * fq;
; #pragma unroll
;         for (int ai = 0; ai < 2; ++ai)
; #pragma unroll
;             for (int m = 0; m < 4; ++m) { bf16_t* rowp = O + (size_t)(row0 + ai * HALF + m * 16) * ldc + col0;
;                 f32x4 v0, v1;
; #pragma unroll
;                 for (int j = 0; j < 1; ++j) { v0 = acc[ai][0][m][0] * sigmoid4(acc[ai][0][m][0]) * acc[ai][1][m][0]; v1 = acc[ai][0][m][1] * sigmoid4(acc[ai][0][m][1]) * acc[ai][1][m][1]; }
;                 u32x4 w; w.x = cvt_pk_bf16(v0[0], v0[1]); w.y = cvt_pk_bf16(v0[2], v0[3]); w.z = cvt_pk_bf16(v1[0], v1[1]); w.w = cvt_pk_bf16(v1[2], v1[3]);
;                 *(u32x4*)rowp = w; }
; template <class Epi, class Sched>
; __device__ __forceinline__ void gemm_phase(PG8_LAS unsigned char* lds, const Gemm g, const Sched& S, const Epi& E) {
;     ...
;         if (!has_next) break;
; #pragma unroll
;         for (int a = 0; a < 2; ++a)
; #pragma unroll
;             for (int b = 0; b < 2; ++b)
; #pragma unroll
;                 for (int m = 0; m < 4; ++m)
; #pragma unroll
;                     for (int n = 0; n < 2; ++n) acc[a][b][m][n] = (f32x4){0.f, 0.f, 0.f, 0.f};
;         cur = nxt; cA = nA; cB = nB; ++ui;
;     }
;     PG8_WAIT_V(0);
;     if (wr == 0) PG8_BAR;
;     PG8_BAR;
	v_max_f32_e32 v36, v24, v24
	v_max_f32_e32 v41, v26, v26
	v_max_f32_e32 v36, 0xc1a00000, v36
	v_max_f32_e32 v41, 0xc1a00000, v41
	v_mul_f32_e32 v36, 0xbfb8aa3b, v36
	v_mul_f32_e32 v41, 0xbfb8aa3b, v41
	v_exp_f32_e32 v37, v36
	v_max_f32_e32 v36, v25, v25
	v_exp_f32_e32 v43, v41
	v_max_f32_e32 v41, v27, v27
	v_max_f32_e32 v36, 0xc1a00000, v36
	v_max_f32_e32 v41, 0xc1a00000, v41
	v_mul_f32_e32 v36, 0xbfb8aa3b, v36
	v_mul_f32_e32 v41, 0xbfb8aa3b, v41
	v_exp_f32_e32 v36, v36
	v_exp_f32_e32 v42, v41
	v_pk_mul_f32 v[32:33], v[32:33], v[40:41] op_sel_hi:[1,0]
	v_pk_mul_f32 v[30:31], v[30:31], v[34:35]
	v_pk_mul_f32 v[28:29], v[28:29], v[32:33]
	v_pk_add_f32 v[32:33], v[36:37], 1.0 op_sel_hi:[1,0]
	v_pk_add_f32 v[36:37], v[42:43], 1.0 op_sel_hi:[1,0]
	v_mov_b32_e32 v40, v33
	v_mov_b32_e32 v41, v37
	v_mov_b32_e32 v42, v32
	v_mov_b32_e32 v43, v36
	v_pk_mul_f32 v[40:41], v[40:41], v[42:43]
	v_pk_mul_f32 v[22:23], v[30:31], v[22:23]
	v_mul_f32_e32 v42, v40, v41
	v_rcp_f32_e32 v42, v42
	v_pk_mul_f32 v[20:21], v[28:29], v[20:21]
	v_mul_f32_e32 v28, v41, v42
	v_mul_f32_e32 v30, v40, v42
	v_pk_mul_f32 v[30:31], v[36:37], v[30:31] op_sel_hi:[1,0]
	v_pk_mul_f32 v[28:29], v[32:33], v[28:29] op_sel_hi:[1,0]
	v_pk_mul_f32 v[26:27], v[26:27], v[30:31]
	v_pk_mul_f32 v[24:25], v[24:25], v[28:29]
	v_pk_mul_f32 v[26:27], v[26:27], v[18:19]
	v_pk_mul_f32 v[18:19], v[24:25], v[16:17]
	v_cvt_pk_bf16_f32 v16, v20, v21
	v_cvt_pk_bf16_f32 v17, v22, v23
	v_max_f32_e32 v20, v12, v12
	v_max_f32_e32 v22, v14, v14
	v_max_f32_e32 v20, 0xc1a00000, v20
	v_max_f32_e32 v22, 0xc1a00000, v22
	v_mul_f32_e32 v20, 0xbfb8aa3b, v20
	v_mul_f32_e32 v22, 0xbfb8aa3b, v22
	v_exp_f32_e32 v21, v20
	v_max_f32_e32 v20, v13, v13
	v_exp_f32_e32 v23, v22
	v_max_f32_e32 v22, v15, v15
	v_max_f32_e32 v20, 0xc1a00000, v20
	v_max_f32_e32 v22, 0xc1a00000, v22
	v_mul_f32_e32 v20, 0xbfb8aa3b, v20
	v_mul_f32_e32 v22, 0xbfb8aa3b, v22
	v_exp_f32_e32 v20, v20
	v_exp_f32_e32 v22, v22
	v_cvt_pk_bf16_f32 v18, v18, v19
	v_cvt_pk_bf16_f32 v19, v26, v27
	global_store_dwordx4 v[38:39], v[16:19], off
	v_add_u32_e32 v24, 0xb0, v155
	s_nop 0
	v_pk_add_f32 v[16:17], v[20:21], 1.0 op_sel_hi:[1,0]
	v_pk_add_f32 v[18:19], v[22:23], 1.0 op_sel_hi:[1,0]
	v_mov_b32_e32 v20, v17
	v_mov_b32_e32 v21, v19
	v_mov_b32_e32 v22, v16
	v_mov_b32_e32 v23, v18
	v_pk_mul_f32 v[20:21], v[20:21], v[22:23]
	s_nop 0
	v_mul_f32_e32 v22, v20, v21
	v_rcp_f32_e32 v25, v22
	v_mad_i64_i32 v[22:23], s[28:29], v24, s52, v[144:145]
	v_lshl_add_u64 v[22:23], v[22:23], 0, v[146:147]
	v_mul_f32_e32 v20, v20, v25
	v_mul_f32_e32 v24, v21, v25
	v_pk_mul_f32 v[18:19], v[18:19], v[20:21] op_sel_hi:[1,0]
	v_max_f32_e32 v20, v8, v8
	v_max_f32_e32 v25, v10, v10
	v_max_f32_e32 v20, 0xc1a00000, v20
	v_max_f32_e32 v25, 0xc1a00000, v25
	v_mul_f32_e32 v20, 0xbfb8aa3b, v20
	v_mul_f32_e32 v25, 0xbfb8aa3b, v25
	v_exp_f32_e32 v21, v20
	v_max_f32_e32 v20, v9, v9
	v_exp_f32_e32 v27, v25
	v_max_f32_e32 v25, v11, v11
	v_max_f32_e32 v20, 0xc1a00000, v20
	v_max_f32_e32 v25, 0xc1a00000, v25
	v_mul_f32_e32 v20, 0xbfb8aa3b, v20
	v_mul_f32_e32 v25, 0xbfb8aa3b, v25
	v_exp_f32_e32 v20, v20
	v_exp_f32_e32 v26, v25
	v_pk_mul_f32 v[16:17], v[16:17], v[24:25] op_sel_hi:[1,0]
	v_pk_mul_f32 v[14:15], v[14:15], v[18:19]
	v_pk_mul_f32 v[12:13], v[12:13], v[16:17]
	v_pk_add_f32 v[16:17], v[20:21], 1.0 op_sel_hi:[1,0]
	v_pk_add_f32 v[20:21], v[26:27], 1.0 op_sel_hi:[1,0]
	v_mov_b32_e32 v24, v17
	v_mov_b32_e32 v25, v21
	v_mov_b32_e32 v26, v16
	v_mov_b32_e32 v27, v20
	v_pk_mul_f32 v[24:25], v[24:25], v[26:27]
	v_pk_mul_f32 v[6:7], v[14:15], v[6:7]
	v_mul_f32_e32 v26, v24, v25
	v_rcp_f32_e32 v26, v26
	v_pk_mul_f32 v[4:5], v[12:13], v[4:5]
	s_mov_b64 s[28:29], s[18:19]
	v_mul_f32_e32 v12, v25, v26
	v_mul_f32_e32 v14, v24, v26
	v_pk_mul_f32 v[14:15], v[20:21], v[14:15] op_sel_hi:[1,0]
	v_pk_mul_f32 v[12:13], v[16:17], v[12:13] op_sel_hi:[1,0]
	v_pk_mul_f32 v[10:11], v[10:11], v[14:15]
	v_pk_mul_f32 v[8:9], v[8:9], v[12:13]
	v_pk_mul_f32 v[10:11], v[10:11], v[2:3]
	v_pk_mul_f32 v[2:3], v[8:9], v[0:1]
	v_cvt_pk_bf16_f32 v0, v4, v5
	v_cvt_pk_bf16_f32 v1, v6, v7
	s_nop 0
	v_cvt_pk_bf16_f32 v2, v2, v3
	v_cvt_pk_bf16_f32 v3, v10, v11
	global_store_dwordx4 v[22:23], v[0:3], off
	s_cbranch_vccz .LBB0_192
	s_waitcnt vmcnt(0)
	s_cmpk_gt_u32 s37, 0xff
	s_cbranch_scc1 .LBB0_199
	s_barrier

; #define PG8_STAGE(bufoff, gbase, voff) do { _Pragma("unroll") for (int _i = 0; _i < 2; ++_i) \
;         __builtin_amdgcn_global_load_lds((const unsigned*)((const char*)(gbase) + (voff)[_i]), (PG8_LAS unsigned*)(lds + (bufoff) + ldsw + _i * 8192), 16, 0, 0); } while (0)
; #define PG8_LDA(dst, b, h) do { _Pragma("unroll") for (int m = 0; m < 4; ++m) _Pragma("unroll") for (int k = 0; k < 2; ++k) dst[m][k] = *(const PG8_LAS bf16x8*)(lds + PG8_SA(b, h) + aoff + m * 2048 + k * 1024); } while (0)
; #define PG8_LDB(dst, b, h) do { _Pragma("unroll") for (int n = 0; n < 2; ++n) _Pragma("unroll") for (int k = 0; k < 2; ++k) dst[n][k] = *(const PG8_LAS bf16x8*)(lds + PG8_SB(b, h) + boff + n * 2048 + k * 1024); } while (0)
; #define PG8_MMA(ai, bj, At, Bt) do { __builtin_amdgcn_s_setprio(1); _Pragma("unroll") for (int m = 0; m < 4; ++m) _Pragma("unroll") for (int n = 0; n < 2; ++n) _Pragma("unroll") for (int k = 0; k < 2; ++k) \
;         acc[ai][bj][m][n] = __builtin_amdgcn_mfma_f32_16x16x32_bf16(Bt[n][k], At[m][k], acc[ai][bj][m][n], 0, 0, 0); __builtin_amdgcn_s_setprio(0); } while (0)
; #define PG8_WAIT_V(n) asm volatile("s_waitcnt vmcnt(" #n ")" ::: "memory")
; #define PG8_WAIT_L(n) asm volatile("s_waitcnt lgkmcnt(" #n ")" ::: "memory")
; template <class Epi, class Sched>
; __device__ __forceinline__ void gemm_phase(PG8_LAS unsigned char* lds, const Gemm g, const Sched& S, const Epi& E) {
;     ...
;             const bool last = (t == nt - 2);
;             const char* a1 = cA + (size_t)(t + 1) * kstep;
;             const char* a2 = last ? nA : cA + (size_t)(t + 2) * kstep; const char* b2 = last ? nB : cB + (size_t)(t + 2) * kstep;
;             const char* a3 = a2 + kstep; const char* b3 = b2 + kstep;
;             if (last && has_next) S.a_ready(nxt);
;             PG8_LDB(B0, 0, 0); PG8_SCHED; PG8_LDA(At, 0, 0); PG8_STAGE(PG8_SA(1, 1), a1 + hstep, voffA);
;             PG8_WAIT_L(8); PG8_BAR; PG8_WAIT_L(0); PG8_MMA(0, 0, At, B0); PG8_BAR; PG8_SCHED;
;             PG8_LDB(B1, 0, 1); PG8_STAGE(PG8_SB(0, 0), b2, voffB);
;             PG8_BAR; PG8_WAIT_L(0); PG8_MMA(0, 1, At, B1); PG8_BAR;
;             PG8_LDA(At, 0, 1); PG8_STAGE(PG8_SA(0, 0), a2, voffA);
;             PG8_BAR; PG8_WAIT_L(0); PG8_MMA(1, 0, At, B0); PG8_BAR; PG8_SCHED;
;             PG8_STAGE(PG8_SB(0, 1), b2 + hstep, voffB);
;             PG8_WAIT_V(6); PG8_BAR; PG8_MMA(1, 1, At, B1); PG8_BAR;
.LBB0_286:
	ds_read_b128 v[154:157], v149
	ds_read_b128 v[158:161], v149 offset:1024
	ds_read_b128 v[166:169], v149 offset:2048
	ds_read_b128 v[170:173], v149 offset:3072
	s_add_u32 s24, s22, 0x100
	s_addc_u32 s25, s23, 0
	s_cmp_eq_u32 s57, 40
	s_cselect_b32 s29, s1, s25
	s_cselect_b32 s28, s0, s24
	s_cselect_b32 s27, s5, s56
	s_cselect_b32 s26, s4, s55
	v_lshl_add_u64 v[144:145], s[22:23], 0, v[136:137]
	s_add_i32 m0, s38, 0xc000
	ds_read_b128 v[182:185], v150
	ds_read_b128 v[190:193], v150 offset:1024
	ds_read_b128 v[194:197], v150 offset:2048
	ds_read_b128 v[198:201], v150 offset:3072
	ds_read_b128 v[202:205], v150 offset:4096
	ds_read_b128 v[206:209], v150 offset:5120
	ds_read_b128 v[210:213], v150 offset:6144
	ds_read_b128 v[214:217], v150 offset:7168
	global_load_lds_dwordx4 v[144:145], off
	v_lshl_add_u64 v[144:145], s[22:23], 0, v[138:139]
	s_add_i32 m0, s38, 0xe000
	s_nop 0
	global_load_lds_dwordx4 v[144:145], off
	ds_read_b128 v[218:221], v151
	ds_read_b128 v[222:225], v151 offset:1024
	ds_read_b128 v[226:229], v151 offset:2048
	ds_read_b128 v[230:233], v151 offset:3072
	s_waitcnt vmcnt(8) lgkmcnt(0)
	s_barrier
	v_mfma_f32_16x16x32_bf16 v[124:127], v[154:157], v[182:185], v[124:127]
	v_mfma_f32_16x16x32_bf16 v[120:123], v[166:169], v[182:185], v[120:123]
	v_mfma_f32_16x16x32_bf16 v[108:111], v[154:157], v[194:197], v[108:111]
	v_mfma_f32_16x16x32_bf16 v[104:107], v[166:169], v[194:197], v[104:107]
	v_mfma_f32_16x16x32_bf16 v[92:95], v[154:157], v[202:205], v[92:95]
	v_mfma_f32_16x16x32_bf16 v[88:91], v[166:169], v[202:205], v[88:91]
	v_mfma_f32_16x16x32_bf16 v[76:79], v[154:157], v[210:213], v[76:79]
	v_mfma_f32_16x16x32_bf16 v[72:75], v[166:169], v[210:213], v[72:75]
	v_mfma_f32_16x16x32_bf16 v[124:127], v[158:161], v[190:193], v[124:127]
	v_mfma_f32_16x16x32_bf16 v[120:123], v[170:173], v[190:193], v[120:123]
	v_mfma_f32_16x16x32_bf16 v[108:111], v[158:161], v[198:201], v[108:111]
	v_mfma_f32_16x16x32_bf16 v[104:107], v[170:173], v[198:201], v[104:107]
	v_mfma_f32_16x16x32_bf16 v[92:95], v[158:161], v[206:209], v[92:95]
	v_mfma_f32_16x16x32_bf16 v[88:91], v[170:173], v[206:209], v[88:91]
	v_mfma_f32_16x16x32_bf16 v[76:79], v[158:161], v[214:217], v[76:79]
	v_mfma_f32_16x16x32_bf16 v[72:75], v[170:173], v[214:217], v[72:75]
	v_mfma_f32_16x16x32_bf16 v[116:119], v[218:221], v[182:185], v[116:119]
	v_mfma_f32_16x16x32_bf16 v[112:115], v[226:229], v[182:185], v[112:115]
	v_mfma_f32_16x16x32_bf16 v[100:103], v[218:221], v[194:197], v[100:103]
	v_mfma_f32_16x16x32_bf16 v[96:99], v[226:229], v[194:197], v[96:99]
	v_mfma_f32_16x16x32_bf16 v[84:87], v[218:221], v[202:205], v[84:87]
	v_mfma_f32_16x16x32_bf16 v[80:83], v[226:229], v[202:205], v[80:83]
	v_mfma_f32_16x16x32_bf16 v[68:71], v[218:221], v[210:213], v[68:71]
	v_mfma_f32_16x16x32_bf16 v[64:67], v[226:229], v[210:213], v[64:67]
	v_mfma_f32_16x16x32_bf16 v[116:119], v[222:225], v[190:193], v[116:119]
	v_mfma_f32_16x16x32_bf16 v[112:115], v[230:233], v[190:193], v[112:115]
	v_mfma_f32_16x16x32_bf16 v[100:103], v[222:225], v[198:201], v[100:103]
	v_mfma_f32_16x16x32_bf16 v[96:99], v[230:233], v[198:201], v[96:99]
	v_mfma_f32_16x16x32_bf16 v[84:87], v[222:225], v[206:209], v[84:87]
	v_mfma_f32_16x16x32_bf16 v[80:83], v[230:233], v[206:209], v[80:83]
	v_mfma_f32_16x16x32_bf16 v[68:71], v[222:225], v[214:217], v[68:71]
	v_mfma_f32_16x16x32_bf16 v[64:67], v[230:233], v[214:217], v[64:67]
	s_barrier
	ds_read_b128 v[182:185], v150 offset:16384
	ds_read_b128 v[190:193], v150 offset:17408
	ds_read_b128 v[194:197], v150 offset:18432
	ds_read_b128 v[198:201], v150 offset:19456
	ds_read_b128 v[202:205], v150 offset:20480
	ds_read_b128 v[206:209], v150 offset:21504
	ds_read_b128 v[210:213], v150 offset:22528
	ds_read_b128 v[214:217], v150 offset:23552
	s_add_i32 s22, s46, s37
	v_lshl_add_u64 v[144:145], s[26:27], 0, v[130:131]
	s_mov_b32 m0, s22
	s_nop 0
	global_load_lds_dwordx4 v[144:145], off
	v_lshl_add_u64 v[162:163], s[26:27], 0, v[134:135]
	s_add_i32 m0, s22, 0x2000
	s_nop 0
	global_load_lds_dwordx4 v[162:163], off
	s_mov_b32 m0, s38
	v_lshl_add_u64 v[174:175], s[28:29], 0, v[128:129]
	global_load_lds_dwordx4 v[174:175], off
	v_lshl_add_u64 v[178:179], s[28:29], 0, v[132:133]
	s_mov_b32 m0, s39
	s_nop 0
	global_load_lds_dwordx4 v[178:179], off
	s_add_u32 s22, s26, 0xb0000
	s_addc_u32 s23, s27, 0
	s_add_i32 s58, s47, s37
	v_lshl_add_u64 v[246:247], s[22:23], 0, v[130:131]
	s_mov_b32 m0, s58
	s_nop 0
	global_load_lds_dwordx4 v[246:247], off
	v_lshl_add_u64 v[246:247], s[22:23], 0, v[134:135]
	s_add_i32 m0, s58, 0x2000
	s_nop 0
	global_load_lds_dwordx4 v[246:247], off
	s_waitcnt vmcnt(8) lgkmcnt(0)
	s_barrier
; #define PG8_STAGE(bufoff, gbase, voff) do { _Pragma("unroll") for (int _i = 0; _i < 2; ++_i) \
;         __builtin_amdgcn_global_load_lds((const unsigned*)((const char*)(gbase) + (voff)[_i]), (PG8_LAS unsigned*)(lds + (bufoff) + ldsw + _i * 8192), 16, 0, 0); } while (0)
; #define PG8_LDA(dst, b, h) do { _Pragma("unroll") for (int m = 0; m < 4; ++m) _Pragma("unroll") for (int k = 0; k < 2; ++k) dst[m][k] = *(const PG8_LAS bf16x8*)(lds + PG8_SA(b, h) + aoff + m * 2048 + k * 1024); } while (0)
; #define PG8_LDB(dst, b, h) do { _Pragma("unroll") for (int n = 0; n < 2; ++n) _Pragma("unroll") for (int k = 0; k < 2; ++k) dst[n][k] = *(const PG8_LAS bf16x8*)(lds + PG8_SB(b, h) + boff + n * 2048 + k * 1024); } while (0)
; #define PG8_MMA(ai, bj, At, Bt) do { __builtin_amdgcn_s_setprio(1); _Pragma("unroll") for (int m = 0; m < 4; ++m) _Pragma("unroll") for (int n = 0; n < 2; ++n) _Pragma("unroll") for (int k = 0; k < 2; ++k) \
;         acc[ai][bj][m][n] = __builtin_amdgcn_mfma_f32_16x16x32_bf16(Bt[n][k], At[m][k], acc[ai][bj][m][n], 0, 0, 0); __builtin_amdgcn_s_setprio(0); } while (0)
; #define PG8_WAIT_V(n) asm volatile("s_waitcnt vmcnt(" #n ")" ::: "memory")
; #define PG8_WAIT_L(n) asm volatile("s_waitcnt lgkmcnt(" #n ")" ::: "memory")
; #define PG8_BAR __builtin_amdgcn_s_barrier()
; #define PG8_SCHED __builtin_amdgcn_sched_barrier(0)
; template <class Epi, class Sched>
; __device__ __forceinline__ void gemm_phase(PG8_LAS unsigned char* lds, const Gemm g, const Sched& S, const Epi& E) {
;     ...
;             PG8_BAR; PG8_WAIT_L(0); PG8_MMA(1, 0, At, B0); PG8_BAR; PG8_SCHED;
;             PG8_STAGE(PG8_SB(0, 1), b2 + hstep, voffB);
;             PG8_WAIT_V(6); PG8_BAR; PG8_MMA(1, 1, At, B1); PG8_BAR;
;             PG8_LDB(B0, 1, 0); PG8_SCHED; PG8_LDA(At, 1, 0); PG8_STAGE(PG8_SA(0, 1), a2 + hstep, voffA);
;             PG8_WAIT_L(8); PG8_BAR; PG8_WAIT_L(0); PG8_MMA(0, 0, At, B0); PG8_BAR; PG8_SCHED;
;             PG8_LDB(B1, 1, 1); PG8_STAGE(PG8_SB(1, 0), b3, voffB);
;             PG8_BAR; PG8_WAIT_L(0); PG8_MMA(0, 1, At, B1); PG8_BAR;
	v_mfma_f32_16x16x32_bf16 v[60:63], v[154:157], v[182:185], v[60:63]
	v_mfma_f32_16x16x32_bf16 v[56:59], v[166:169], v[182:185], v[56:59]
	v_mfma_f32_16x16x32_bf16 v[48:51], v[154:157], v[194:197], v[48:51]
	v_mfma_f32_16x16x32_bf16 v[40:43], v[166:169], v[194:197], v[40:43]
	v_mfma_f32_16x16x32_bf16 v[32:35], v[154:157], v[202:205], v[32:35]
	v_mfma_f32_16x16x32_bf16 v[24:27], v[166:169], v[202:205], v[24:27]
	v_mfma_f32_16x16x32_bf16 v[16:19], v[154:157], v[210:213], v[16:19]
	v_mfma_f32_16x16x32_bf16 v[8:11], v[166:169], v[210:213], v[8:11]
	v_mfma_f32_16x16x32_bf16 v[60:63], v[158:161], v[190:193], v[60:63]
	v_mfma_f32_16x16x32_bf16 v[56:59], v[170:173], v[190:193], v[56:59]
	v_mfma_f32_16x16x32_bf16 v[48:51], v[158:161], v[198:201], v[48:51]
	v_mfma_f32_16x16x32_bf16 v[40:43], v[170:173], v[198:201], v[40:43]
	v_mfma_f32_16x16x32_bf16 v[32:35], v[158:161], v[206:209], v[32:35]
	v_mfma_f32_16x16x32_bf16 v[24:27], v[170:173], v[206:209], v[24:27]
	v_mfma_f32_16x16x32_bf16 v[16:19], v[158:161], v[214:217], v[16:19]
	v_mfma_f32_16x16x32_bf16 v[8:11], v[170:173], v[214:217], v[8:11]
	v_mfma_f32_16x16x32_bf16 v[52:55], v[218:221], v[182:185], v[52:55]
	v_mfma_f32_16x16x32_bf16 v[44:47], v[226:229], v[182:185], v[44:47]
	v_mfma_f32_16x16x32_bf16 v[36:39], v[218:221], v[194:197], v[36:39]
	v_mfma_f32_16x16x32_bf16 v[28:31], v[226:229], v[194:197], v[28:31]
	v_mfma_f32_16x16x32_bf16 v[20:23], v[218:221], v[202:205], v[20:23]
	v_mfma_f32_16x16x32_bf16 v[12:15], v[226:229], v[202:205], v[12:15]
	v_mfma_f32_16x16x32_bf16 v[4:7], v[218:221], v[210:213], v[4:7]
	v_mfma_f32_16x16x32_bf16 v[0:3], v[226:229], v[210:213], v[0:3]
	v_mfma_f32_16x16x32_bf16 v[52:55], v[222:225], v[190:193], v[52:55]
	v_mfma_f32_16x16x32_bf16 v[44:47], v[230:233], v[190:193], v[44:47]
	v_mfma_f32_16x16x32_bf16 v[36:39], v[222:225], v[198:201], v[36:39]
	v_mfma_f32_16x16x32_bf16 v[28:31], v[230:233], v[198:201], v[28:31]
	v_mfma_f32_16x16x32_bf16 v[20:23], v[222:225], v[206:209], v[20:23]
	v_mfma_f32_16x16x32_bf16 v[12:15], v[230:233], v[206:209], v[12:15]
	v_mfma_f32_16x16x32_bf16 v[4:7], v[222:225], v[214:217], v[4:7]
	v_mfma_f32_16x16x32_bf16 v[0:3], v[230:233], v[214:217], v[0:3]
	s_barrier
	s_add_i32 s58, 0, 0x18000
	v_add_u32_e32 v153, s58, v147
	ds_read_b128 v[154:157], v153
	ds_read_b128 v[158:161], v153 offset:1024
	ds_read_b128 v[166:169], v153 offset:2048
	ds_read_b128 v[170:173], v153 offset:3072
	s_add_u32 s22, s28, 0xb0000
	s_addc_u32 s23, s29, 0
	s_mov_b32 m0, s40
	v_lshl_add_u64 v[186:187], s[22:23], 0, v[128:129]
	ds_read_b128 v[182:185], v150 offset:32768
	ds_read_b128 v[190:193], v150 offset:33792
	ds_read_b128 v[194:197], v150 offset:34816
	ds_read_b128 v[198:201], v150 offset:35840
	ds_read_b128 v[202:205], v150 offset:36864
	ds_read_b128 v[206:209], v150 offset:37888
	ds_read_b128 v[210:213], v150 offset:38912
	ds_read_b128 v[214:217], v150 offset:39936
	global_load_lds_dwordx4 v[186:187], off
	v_lshl_add_u64 v[186:187], s[22:23], 0, v[132:133]
	s_mov_b32 m0, s41
	s_nop 0
	global_load_lds_dwordx4 v[186:187], off
	s_add_i32 s28, 0, 0x1c000
	v_add_u32_e32 v153, s28, v147
	ds_read_b128 v[218:221], v153
	ds_read_b128 v[222:225], v153 offset:1024
	ds_read_b128 v[226:229], v153 offset:2048
	ds_read_b128 v[230:233], v153 offset:3072
	s_waitcnt vmcnt(8) lgkmcnt(0)
	s_barrier
	v_mfma_f32_16x16x32_bf16 v[124:127], v[154:157], v[182:185], v[124:127]
	v_mfma_f32_16x16x32_bf16 v[120:123], v[166:169], v[182:185], v[120:123]
	v_mfma_f32_16x16x32_bf16 v[108:111], v[154:157], v[194:197], v[108:111]
	v_mfma_f32_16x16x32_bf16 v[104:107], v[166:169], v[194:197], v[104:107]
	v_mfma_f32_16x16x32_bf16 v[92:95], v[154:157], v[202:205], v[92:95]
	v_mfma_f32_16x16x32_bf16 v[88:91], v[166:169], v[202:205], v[88:91]
	v_mfma_f32_16x16x32_bf16 v[76:79], v[154:157], v[210:213], v[76:79]
	v_mfma_f32_16x16x32_bf16 v[72:75], v[166:169], v[210:213], v[72:75]
	v_mfma_f32_16x16x32_bf16 v[124:127], v[158:161], v[190:193], v[124:127]
	v_mfma_f32_16x16x32_bf16 v[120:123], v[170:173], v[190:193], v[120:123]
	v_mfma_f32_16x16x32_bf16 v[108:111], v[158:161], v[198:201], v[108:111]
	v_mfma_f32_16x16x32_bf16 v[104:107], v[170:173], v[198:201], v[104:107]
	v_mfma_f32_16x16x32_bf16 v[92:95], v[158:161], v[206:209], v[92:95]
	v_mfma_f32_16x16x32_bf16 v[88:91], v[170:173], v[206:209], v[88:91]
	v_mfma_f32_16x16x32_bf16 v[76:79], v[158:161], v[214:217], v[76:79]
	v_mfma_f32_16x16x32_bf16 v[72:75], v[170:173], v[214:217], v[72:75]
	v_mfma_f32_16x16x32_bf16 v[116:119], v[218:221], v[182:185], v[116:119]
	v_mfma_f32_16x16x32_bf16 v[112:115], v[226:229], v[182:185], v[112:115]
	v_mfma_f32_16x16x32_bf16 v[100:103], v[218:221], v[194:197], v[100:103]
	v_mfma_f32_16x16x32_bf16 v[96:99], v[226:229], v[194:197], v[96:99]
	v_mfma_f32_16x16x32_bf16 v[84:87], v[218:221], v[202:205], v[84:87]
	v_mfma_f32_16x16x32_bf16 v[80:83], v[226:229], v[202:205], v[80:83]
	v_mfma_f32_16x16x32_bf16 v[68:71], v[218:221], v[210:213], v[68:71]
	v_mfma_f32_16x16x32_bf16 v[64:67], v[226:229], v[210:213], v[64:67]
	v_mfma_f32_16x16x32_bf16 v[116:119], v[222:225], v[190:193], v[116:119]
	v_mfma_f32_16x16x32_bf16 v[112:115], v[230:233], v[190:193], v[112:115]
	v_mfma_f32_16x16x32_bf16 v[100:103], v[222:225], v[198:201], v[100:103]
	v_mfma_f32_16x16x32_bf16 v[96:99], v[230:233], v[198:201], v[96:99]
	v_mfma_f32_16x16x32_bf16 v[84:87], v[222:225], v[206:209], v[84:87]
	v_mfma_f32_16x16x32_bf16 v[80:83], v[230:233], v[206:209], v[80:83]
	v_mfma_f32_16x16x32_bf16 v[68:71], v[222:225], v[214:217], v[68:71]
	v_mfma_f32_16x16x32_bf16 v[64:67], v[230:233], v[214:217], v[64:67]
	s_barrier
; __device__ __forceinline__ unsigned cvt_pk_bf16(float lo, float hi) { unsigned r; asm volatile("v_cvt_pk_bf16_f32 %0, %1, %2" : "=v"(r) : "v"(lo), "v"(hi)); return r; }
; __device__ __forceinline__ float flogsig16(float x) { return (fminf(x, 0.f) - __logf(1.0f + __expf(-fabsf(x)))) * 0.0625f; }
; #define PG8_WAIT_V(n) asm volatile("s_waitcnt vmcnt(" #n ")" ::: "memory")
;     __device__ __forceinline__ void operator()(const f32x4 (&acc)[2][2][4][2], const Unit& u, int wr, int wc, int fr, int fq) const {
;     ...
;         const int row0 = u.pm * BM + wr * 64 + fr, col0 = u.pn * BM + wc * 32 + 8 * fq, bcol0 = wc * 32 + 8 * fq;
;         f32x4 bv[2][2];
; #pragma unroll
;         for (int bj = 0; bj < 2; ++bj)
; #pragma unroll
;             for (int n = 0; n < 2; ++n) bv[bj][n] = bias ? *(const f32x4*)(bias + bcol0 + bj * HALF + 4 * n) : (f32x4){0.f, 0.f, 0.f, 0.f};
; #pragma unroll
;         for (int ai = 0; ai < 2; ++ai)
; #pragma unroll
;             for (int m = 0; m < 4; ++m) { bf16_t* rowp = O + (size_t)(row0 + ai * HALF + m * 16) * ldc + col0;
; #pragma unroll
;                 for (int bj = 0; bj < 2; ++bj) { f32x4 v0 = acc[ai][bj][m][0] + bv[bj][0], v1 = acc[ai][bj][m][1] + bv[bj][1];
;                     if (act == 1) {
; #pragma unroll
;                         for (int j = 0; j < 1; ++j) { v0 = v0 * sigmoid4(v0); v1 = v1 * sigmoid4(v1); } }
;                     else if (act == 2) {
; #pragma unroll
;                         for (int j = 0; j < 1; ++j) { v0 = sigmoid4(v0); v1 = sigmoid4(v1); } }
;                     else if (act == 3) {
; #pragma unroll
;                         for (int j = 0; j < 4; ++j) { v0[j] = flogsig16(v0[j]); v1[j] = flogsig16(v1[j]); } }
;                     u32x4 w; w.x = cvt_pk_bf16(v0[0], v0[1]); w.y = cvt_pk_bf16(v0[2], v0[3]); w.z = cvt_pk_bf16(v1[0], v1[1]); w.w = cvt_pk_bf16(v1[2], v1[3]);
;                     *(u32x4*)(rowp + bj * HALF) = w; } }
; template <class Epi, class Sched>
; __device__ __forceinline__ void gemm_phase(PG8_LAS unsigned char* lds, const Gemm g, const Sched& S, const Epi& E) {
;     ...
;             PG8_LDA(At, 1, 1); PG8_STAGE(PG8_SA(1, 0), a3, voffA);
;             PG8_BAR; PG8_WAIT_L(0); PG8_MMA(1, 0, At, B0); PG8_BAR; PG8_SCHED;
;             PG8_STAGE(PG8_SB(1, 1), b3 + hstep, voffB);
;             PG8_WAIT_V(6); PG8_BAR; PG8_MMA(1, 1, At, B1); PG8_BAR;
;         }
	ds_read_b128 v[182:185], v150 offset:49152
	ds_read_b128 v[190:193], v150 offset:50176
	ds_read_b128 v[194:197], v150 offset:51200
	ds_read_b128 v[198:201], v150 offset:52224
	ds_read_b128 v[202:205], v150 offset:53248
	ds_read_b128 v[206:209], v150 offset:54272
	ds_read_b128 v[210:213], v150 offset:55296
	ds_read_b128 v[214:217], v150 offset:56320
	s_add_i32 s22, s58, s37
	v_lshl_add_u64 v[144:145], v[144:145], 0, s[14:15]
	s_mov_b32 m0, s22
	s_nop 0
	global_load_lds_dwordx4 v[144:145], off
	v_lshl_add_u64 v[144:145], v[162:163], 0, s[14:15]
	s_add_i32 m0, s22, 0x2000
	s_nop 0
	global_load_lds_dwordx4 v[144:145], off
	s_mov_b32 m0, s43
	v_lshl_add_u64 v[144:145], v[174:175], 0, s[14:15]
	global_load_lds_dwordx4 v[144:145], off
	v_lshl_add_u64 v[144:145], v[178:179], 0, s[14:15]
	s_mov_b32 m0, s44
	s_nop 0
	global_load_lds_dwordx4 v[144:145], off
	s_add_u32 s22, s26, 0xb0080
	s_addc_u32 s23, s27, 0
	s_add_i32 s26, s28, s37
	v_lshl_add_u64 v[144:145], s[22:23], 0, v[130:131]
	s_mov_b32 m0, s26
	s_nop 0
	global_load_lds_dwordx4 v[144:145], off
	v_lshl_add_u64 v[144:145], s[22:23], 0, v[134:135]
	s_add_i32 m0, s26, 0x2000
	s_nop 0
	global_load_lds_dwordx4 v[144:145], off
	s_waitcnt vmcnt(8) lgkmcnt(0)
	s_barrier
	v_mfma_f32_16x16x32_bf16 v[60:63], v[154:157], v[182:185], v[60:63]
	v_mfma_f32_16x16x32_bf16 v[56:59], v[166:169], v[182:185], v[56:59]
	v_mfma_f32_16x16x32_bf16 v[48:51], v[154:157], v[194:197], v[48:51]
	v_mfma_f32_16x16x32_bf16 v[40:43], v[166:169], v[194:197], v[40:43]
	v_mfma_f32_16x16x32_bf16 v[32:35], v[154:157], v[202:205], v[32:35]
	v_mfma_f32_16x16x32_bf16 v[24:27], v[166:169], v[202:205], v[24:27]
	v_mfma_f32_16x16x32_bf16 v[16:19], v[154:157], v[210:213], v[16:19]
	v_mfma_f32_16x16x32_bf16 v[8:11], v[166:169], v[210:213], v[8:11]
	v_mfma_f32_16x16x32_bf16 v[60:63], v[158:161], v[190:193], v[60:63]
	v_mfma_f32_16x16x32_bf16 v[56:59], v[170:173], v[190:193], v[56:59]
	v_mfma_f32_16x16x32_bf16 v[48:51], v[158:161], v[198:201], v[48:51]
	v_mfma_f32_16x16x32_bf16 v[40:43], v[170:173], v[198:201], v[40:43]
	v_mfma_f32_16x16x32_bf16 v[32:35], v[158:161], v[206:209], v[32:35]
	v_mfma_f32_16x16x32_bf16 v[24:27], v[170:173], v[206:209], v[24:27]
	v_mfma_f32_16x16x32_bf16 v[16:19], v[158:161], v[214:217], v[16:19]
	v_mfma_f32_16x16x32_bf16 v[8:11], v[170:173], v[214:217], v[8:11]
	v_mfma_f32_16x16x32_bf16 v[52:55], v[218:221], v[182:185], v[52:55]
	v_mfma_f32_16x16x32_bf16 v[44:47], v[226:229], v[182:185], v[44:47]
	v_mfma_f32_16x16x32_bf16 v[36:39], v[218:221], v[194:197], v[36:39]
	v_mfma_f32_16x16x32_bf16 v[28:31], v[226:229], v[194:197], v[28:31]
	v_mfma_f32_16x16x32_bf16 v[20:23], v[218:221], v[202:205], v[20:23]
	v_mfma_f32_16x16x32_bf16 v[12:15], v[226:229], v[202:205], v[12:15]
	v_mfma_f32_16x16x32_bf16 v[4:7], v[218:221], v[210:213], v[4:7]
	v_mfma_f32_16x16x32_bf16 v[0:3], v[226:229], v[210:213], v[0:3]
	v_mfma_f32_16x16x32_bf16 v[52:55], v[222:225], v[190:193], v[52:55]
	v_mfma_f32_16x16x32_bf16 v[44:47], v[230:233], v[190:193], v[44:47]
	v_mfma_f32_16x16x32_bf16 v[36:39], v[222:225], v[198:201], v[36:39]
	v_mfma_f32_16x16x32_bf16 v[28:31], v[230:233], v[198:201], v[28:31]
	v_mfma_f32_16x16x32_bf16 v[20:23], v[222:225], v[206:209], v[20:23]
	v_mfma_f32_16x16x32_bf16 v[12:15], v[230:233], v[206:209], v[12:15]
	v_mfma_f32_16x16x32_bf16 v[4:7], v[222:225], v[214:217], v[4:7]
	v_mfma_f32_16x16x32_bf16 v[0:3], v[230:233], v[214:217], v[0:3]
	s_barrier
	s_add_i32 s57, s57, 2
	s_add_u32 s55, s55, 0x100
	s_addc_u32 s56, s56, 0
	s_cmp_gt_u32 s57, 41
	s_mov_b64 s[22:23], s[24:25]
	s_cbranch_scc0 .LBB0_286
	v_lshl_add_u32 v154, s53, 8, v146
	v_lshl_or_b32 v144, s54, 8, v148
	v_ashrrev_i32_e32 v155, 31, v154
	v_ashrrev_i32_e32 v145, 31, v144
	v_lshlrev_b64 v[156:157], 11, v[154:155]
	v_lshl_add_u64 v[156:157], s[10:11], 0, v[156:157]
	v_lshlrev_b64 v[158:159], 1, v[144:145]
	v_lshl_add_u64 v[144:145], v[156:157], 0, v[158:159]
	v_pk_add_f32 v[126:127], v[126:127], 0 op_sel_hi:[1,0]
	v_pk_add_f32 v[124:125], v[124:125], 0 op_sel_hi:[1,0]
	v_pk_add_f32 v[156:157], v[122:123], 0 op_sel_hi:[1,0]
	v_pk_add_f32 v[122:123], v[120:121], 0 op_sel_hi:[1,0]
	v_cvt_pk_bf16_f32 v120, v124, v125
	v_cvt_pk_bf16_f32 v121, v126, v127
	v_pk_add_f32 v[116:117], v[116:117], 0 op_sel_hi:[1,0]
	v_cvt_pk_bf16_f32 v122, v122, v123
	v_cvt_pk_bf16_f32 v123, v156, v157
	global_store_dwordx4 v[144:145], v[120:123], off
	v_pk_add_f32 v[118:119], v[118:119], 0 op_sel_hi:[1,0]
	v_pk_add_f32 v[110:111], v[110:111], 0 op_sel_hi:[1,0]
	v_pk_add_f32 v[120:121], v[114:115], 0 op_sel_hi:[1,0]
	v_pk_add_f32 v[114:115], v[112:113], 0 op_sel_hi:[1,0]
	v_cvt_pk_bf16_f32 v112, v116, v117
	v_cvt_pk_bf16_f32 v113, v118, v119
	v_pk_add_f32 v[108:109], v[108:109], 0 op_sel_hi:[1,0]
	v_cvt_pk_bf16_f32 v114, v114, v115
	v_cvt_pk_bf16_f32 v115, v120, v121
	global_store_dwordx4 v[144:145], v[112:115], off offset:256
	v_pk_add_f32 v[100:101], v[100:101], 0 op_sel_hi:[1,0]
	v_pk_add_f32 v[102:103], v[102:103], 0 op_sel_hi:[1,0]
	v_or_b32_e32 v112, 16, v154
	v_ashrrev_i32_e32 v113, 31, v112
	v_lshlrev_b64 v[112:113], 11, v[112:113]
	v_lshl_add_u64 v[112:113], s[10:11], 0, v[112:113]
	v_lshl_add_u64 v[112:113], v[112:113], 0, v[158:159]
	v_pk_add_f32 v[114:115], v[106:107], 0 op_sel_hi:[1,0]
	v_pk_add_f32 v[106:107], v[104:105], 0 op_sel_hi:[1,0]
	v_cvt_pk_bf16_f32 v104, v108, v109
	v_cvt_pk_bf16_f32 v105, v110, v111
	v_pk_add_f32 v[94:95], v[94:95], 0 op_sel_hi:[1,0]
	v_cvt_pk_bf16_f32 v106, v106, v107
	v_cvt_pk_bf16_f32 v107, v114, v115
	global_store_dwordx4 v[112:113], v[104:107], off
	v_pk_add_f32 v[92:93], v[92:93], 0 op_sel_hi:[1,0]
	v_pk_add_f32 v[84:85], v[84:85], 0 op_sel_hi:[1,0]
; __device__ __forceinline__ unsigned cvt_pk_bf16(float lo, float hi) { unsigned r; asm volatile("v_cvt_pk_bf16_f32 %0, %1, %2" : "=v"(r) : "v"(lo), "v"(hi)); return r; }
;     __device__ __forceinline__ void operator()(const f32x4 (&acc)[2][2][4][2], const Unit& u, int wr, int wc, int fr, int fq) const {
;     ...
;         const int row0 = u.pm * BM + wr * 64 + fr, col0 = u.pn * BM + wc * 32 + 8 * fq, bcol0 = wc * 32 + 8 * fq;
;         f32x4 bv[2][2];
; #pragma unroll
;         for (int bj = 0; bj < 2; ++bj)
; #pragma unroll
;             for (int n = 0; n < 2; ++n) bv[bj][n] = bias ? *(const f32x4*)(bias + bcol0 + bj * HALF + 4 * n) : (f32x4){0.f, 0.f, 0.f, 0.f};
; #pragma unroll
;         for (int ai = 0; ai < 2; ++ai)
; #pragma unroll
;             for (int m = 0; m < 4; ++m) { bf16_t* rowp = O + (size_t)(row0 + ai * HALF + m * 16) * ldc + col0;
; #pragma unroll
;                 for (int bj = 0; bj < 2; ++bj) { f32x4 v0 = acc[ai][bj][m][0] + bv[bj][0], v1 = acc[ai][bj][m][1] + bv[bj][1];
;                     if (act == 1) {
; #pragma unroll
;                         for (int j = 0; j < 1; ++j) { v0 = v0 * sigmoid4(v0); v1 = v1 * sigmoid4(v1); } }
;                     else if (act == 2) {
; #pragma unroll
;                         for (int j = 0; j < 1; ++j) { v0 = sigmoid4(v0); v1 = sigmoid4(v1); } }
;                     else if (act == 3) {
; #pragma unroll
;                         for (int j = 0; j < 4; ++j) { v0[j] = flogsig16(v0[j]); v1[j] = flogsig16(v1[j]); } }
;                     u32x4 w; w.x = cvt_pk_bf16(v0[0], v0[1]); w.y = cvt_pk_bf16(v0[2], v0[3]); w.z = cvt_pk_bf16(v1[0], v1[1]); w.w = cvt_pk_bf16(v1[2], v1[3]);
;                     *(u32x4*)(rowp + bj * HALF) = w; } }
; template <class Epi, class Sched>
; __device__ __forceinline__ void gemm_phase(PG8_LAS unsigned char* lds, const Gemm g, const Sched& S, const Epi& E) {
;     ...
;         if constexpr (!Epi::AFTER_DRAIN) { E(acc, cur, wr, wc, fr, fq); S.done(cur); }
;         if (!has_next) break;
; #pragma unroll
;         for (int a = 0; a < 2; ++a)
; #pragma unroll
;             for (int b = 0; b < 2; ++b)
; #pragma unroll
;                 for (int m = 0; m < 4; ++m)
; #pragma unroll
;                     for (int n = 0; n < 2; ++n) acc[a][b][m][n] = (f32x4){0.f, 0.f, 0.f, 0.f};
;         cur = nxt; cA = nA; cB = nB; ++ui;
;     }
;     PG8_WAIT_V(0);
;     if (wr == 0) PG8_BAR;
;     PG8_BAR;
	v_pk_add_f32 v[104:105], v[98:99], 0 op_sel_hi:[1,0]
	v_pk_add_f32 v[98:99], v[96:97], 0 op_sel_hi:[1,0]
	v_cvt_pk_bf16_f32 v96, v100, v101
	v_cvt_pk_bf16_f32 v97, v102, v103
	v_pk_add_f32 v[86:87], v[86:87], 0 op_sel_hi:[1,0]
	v_cvt_pk_bf16_f32 v98, v98, v99
	v_cvt_pk_bf16_f32 v99, v104, v105
	global_store_dwordx4 v[112:113], v[96:99], off offset:256
	v_pk_add_f32 v[78:79], v[78:79], 0 op_sel_hi:[1,0]
	v_pk_add_f32 v[76:77], v[76:77], 0 op_sel_hi:[1,0]
	v_or_b32_e32 v96, 32, v154
	v_ashrrev_i32_e32 v97, 31, v96
	v_lshlrev_b64 v[96:97], 11, v[96:97]
	v_lshl_add_u64 v[96:97], s[10:11], 0, v[96:97]
	v_lshl_add_u64 v[96:97], v[96:97], 0, v[158:159]
	v_pk_add_f32 v[98:99], v[90:91], 0 op_sel_hi:[1,0]
	v_pk_add_f32 v[90:91], v[88:89], 0 op_sel_hi:[1,0]
	v_cvt_pk_bf16_f32 v88, v92, v93
	v_cvt_pk_bf16_f32 v89, v94, v95
	v_pk_add_f32 v[70:71], v[70:71], 0 op_sel_hi:[1,0]
	v_cvt_pk_bf16_f32 v90, v90, v91
	v_cvt_pk_bf16_f32 v91, v98, v99
	global_store_dwordx4 v[96:97], v[88:91], off
	v_pk_add_f32 v[68:69], v[68:69], 0 op_sel_hi:[1,0]
	s_mov_b64 s[22:23], 0x40000
	v_pk_add_f32 v[88:89], v[82:83], 0 op_sel_hi:[1,0]
	v_pk_add_f32 v[82:83], v[80:81], 0 op_sel_hi:[1,0]
	v_cvt_pk_bf16_f32 v80, v84, v85
	v_cvt_pk_bf16_f32 v81, v86, v87
	v_pk_add_f32 v[60:61], v[60:61], 0 op_sel_hi:[1,0]
	v_cvt_pk_bf16_f32 v82, v82, v83
	v_cvt_pk_bf16_f32 v83, v88, v89
	global_store_dwordx4 v[96:97], v[80:83], off offset:256
	v_pk_add_f32 v[62:63], v[62:63], 0 op_sel_hi:[1,0]
	v_pk_add_f32 v[54:55], v[54:55], 0 op_sel_hi:[1,0]
	v_or_b32_e32 v80, 48, v154
	v_ashrrev_i32_e32 v81, 31, v80
	v_lshlrev_b64 v[80:81], 11, v[80:81]
	v_lshl_add_u64 v[80:81], s[10:11], 0, v[80:81]
	v_lshl_add_u64 v[80:81], v[80:81], 0, v[158:159]
	v_pk_add_f32 v[82:83], v[74:75], 0 op_sel_hi:[1,0]
	v_pk_add_f32 v[74:75], v[72:73], 0 op_sel_hi:[1,0]
	v_cvt_pk_bf16_f32 v72, v76, v77
	v_cvt_pk_bf16_f32 v73, v78, v79
	v_pk_add_f32 v[52:53], v[52:53], 0 op_sel_hi:[1,0]
	v_cvt_pk_bf16_f32 v74, v74, v75
	v_cvt_pk_bf16_f32 v75, v82, v83
	global_store_dwordx4 v[80:81], v[72:75], off
	v_pk_add_f32 v[48:49], v[48:49], 0 op_sel_hi:[1,0]
	v_pk_add_f32 v[38:39], v[38:39], 0 op_sel_hi:[1,0]
	v_pk_add_f32 v[72:73], v[66:67], 0 op_sel_hi:[1,0]
	v_pk_add_f32 v[66:67], v[64:65], 0 op_sel_hi:[1,0]
	v_cvt_pk_bf16_f32 v64, v68, v69
	v_cvt_pk_bf16_f32 v65, v70, v71
	v_pk_add_f32 v[36:37], v[36:37], 0 op_sel_hi:[1,0]
	v_cvt_pk_bf16_f32 v66, v66, v67
	v_cvt_pk_bf16_f32 v67, v72, v73
	global_store_dwordx4 v[80:81], v[64:67], off offset:256
	v_pk_add_f32 v[32:33], v[32:33], 0 op_sel_hi:[1,0]
	v_pk_add_f32 v[22:23], v[22:23], 0 op_sel_hi:[1,0]
	v_lshl_add_u64 v[64:65], v[144:145], 0, s[22:23]
	s_mov_b32 s22, 0x40000
	v_pk_add_f32 v[66:67], v[58:59], 0 op_sel_hi:[1,0]
	v_pk_add_f32 v[58:59], v[56:57], 0 op_sel_hi:[1,0]
	v_cvt_pk_bf16_f32 v56, v60, v61
	v_add_co_u32_e32 v60, vcc, s22, v144
	v_cvt_pk_bf16_f32 v57, v62, v63
	v_cvt_pk_bf16_f32 v58, v58, v59
	v_cvt_pk_bf16_f32 v59, v66, v67
	s_mov_b64 s[22:23], 0x48000
	s_nop 0
	v_addc_co_u32_e32 v61, vcc, 0, v145, vcc
	global_store_dwordx4 v[60:61], v[56:59], off
	v_pk_add_f32 v[20:21], v[20:21], 0 op_sel_hi:[1,0]
	v_pk_add_f32 v[16:17], v[16:17], 0 op_sel_hi:[1,0]
	v_pk_add_f32 v[56:57], v[46:47], 0 op_sel_hi:[1,0]
	v_pk_add_f32 v[46:47], v[44:45], 0 op_sel_hi:[1,0]
	v_cvt_pk_bf16_f32 v44, v52, v53
	v_cvt_pk_bf16_f32 v45, v54, v55
	s_mov_b32 s54, s51
	v_cvt_pk_bf16_f32 v46, v46, v47
	v_cvt_pk_bf16_f32 v47, v56, v57
	global_store_dwordx4 v[64:65], v[44:47], off offset:256
	s_mov_b32 s53, s52
	s_mov_b64 s[24:25], s[4:5]
	v_pk_add_f32 v[46:47], v[50:51], 0 op_sel_hi:[1,0]
	v_pk_add_f32 v[50:51], v[42:43], 0 op_sel_hi:[1,0]
	v_pk_add_f32 v[42:43], v[40:41], 0 op_sel_hi:[1,0]
	v_cvt_pk_bf16_f32 v40, v48, v49
	v_cvt_pk_bf16_f32 v41, v46, v47
	v_add_co_u32_e32 v46, vcc, s48, v144
	v_cvt_pk_bf16_f32 v42, v42, v43
	v_cvt_pk_bf16_f32 v43, v50, v51
	v_lshl_add_u64 v[44:45], v[144:145], 0, s[22:23]
	s_nop 0
	v_addc_co_u32_e32 v47, vcc, 0, v145, vcc
	global_store_dwordx4 v[46:47], v[40:43], off
	s_mov_b64 s[22:23], s[0:1]
	v_pk_add_f32 v[6:7], v[6:7], 0 op_sel_hi:[1,0]
	v_pk_add_f32 v[40:41], v[30:31], 0 op_sel_hi:[1,0]
	v_pk_add_f32 v[30:31], v[28:29], 0 op_sel_hi:[1,0]
	v_cvt_pk_bf16_f32 v28, v36, v37
	v_cvt_pk_bf16_f32 v29, v38, v39
	v_pk_add_f32 v[4:5], v[4:5], 0 op_sel_hi:[1,0]
	v_cvt_pk_bf16_f32 v30, v30, v31
	v_cvt_pk_bf16_f32 v31, v40, v41
	global_store_dwordx4 v[44:45], v[28:31], off offset:256
	s_nop 1
	v_pk_add_f32 v[30:31], v[34:35], 0 op_sel_hi:[1,0]
	v_pk_add_f32 v[34:35], v[26:27], 0 op_sel_hi:[1,0]
	v_pk_add_f32 v[26:27], v[24:25], 0 op_sel_hi:[1,0]
	v_cvt_pk_bf16_f32 v24, v32, v33
	v_cvt_pk_bf16_f32 v25, v30, v31
	v_add_co_u32_e32 v30, vcc, s49, v144
	v_cvt_pk_bf16_f32 v26, v26, v27
	v_cvt_pk_bf16_f32 v27, v34, v35
	v_lshl_add_u64 v[28:29], v[144:145], 0, s[16:17]
	s_nop 0
	v_addc_co_u32_e32 v31, vcc, 0, v145, vcc
	global_store_dwordx4 v[30:31], v[24:27], off
	s_nop 1
	v_pk_add_f32 v[24:25], v[14:15], 0 op_sel_hi:[1,0]
	v_pk_add_f32 v[14:15], v[12:13], 0 op_sel_hi:[1,0]
	v_cvt_pk_bf16_f32 v12, v20, v21
	v_cvt_pk_bf16_f32 v13, v22, v23
	s_nop 0
	v_cvt_pk_bf16_f32 v14, v14, v15
	v_cvt_pk_bf16_f32 v15, v24, v25
	global_store_dwordx4 v[28:29], v[12:15], off offset:256
	s_nop 1
	v_pk_add_f32 v[14:15], v[18:19], 0 op_sel_hi:[1,0]
	v_pk_add_f32 v[18:19], v[10:11], 0 op_sel_hi:[1,0]
	v_pk_add_f32 v[10:11], v[8:9], 0 op_sel_hi:[1,0]
	v_cvt_pk_bf16_f32 v8, v16, v17
	v_cvt_pk_bf16_f32 v9, v14, v15
	v_add_co_u32_e32 v14, vcc, s50, v144
	v_lshl_add_u64 v[12:13], v[144:145], 0, s[18:19]
	s_nop 0
	v_addc_co_u32_e32 v15, vcc, 0, v145, vcc
	v_cvt_pk_bf16_f32 v10, v10, v11
	v_cvt_pk_bf16_f32 v11, v18, v19
	global_store_dwordx4 v[14:15], v[8:11], off
	s_and_b64 vcc, exec, s[2:3]
	s_nop 0
	v_pk_add_f32 v[8:9], v[2:3], 0 op_sel_hi:[1,0]
	v_pk_add_f32 v[2:3], v[0:1], 0 op_sel_hi:[1,0]
	v_cvt_pk_bf16_f32 v0, v4, v5
	v_cvt_pk_bf16_f32 v1, v6, v7
	s_nop 0
	v_cvt_pk_bf16_f32 v2, v2, v3
	v_cvt_pk_bf16_f32 v3, v8, v9
	global_store_dwordx4 v[12:13], v[0:3], off offset:256
	s_cbranch_vccz .LBB0_275
	s_waitcnt vmcnt(0)
	s_cmpk_gt_u32 s31, 0xff
	s_cbranch_scc1 .LBB0_290
	s_barrier

; #define PG8_STAGE(bufoff, gbase, voff) do { _Pragma("unroll") for (int _i = 0; _i < 2; ++_i) \
;         __builtin_amdgcn_global_load_lds((const unsigned*)((const char*)(gbase) + (voff)[_i]), (PG8_LAS unsigned*)(lds + (bufoff) + ldsw + _i * 8192), 16, 0, 0); } while (0)
; #define PG8_LDA(dst, b, h) do { _Pragma("unroll") for (int m = 0; m < 4; ++m) _Pragma("unroll") for (int k = 0; k < 2; ++k) dst[m][k] = *(const PG8_LAS bf16x8*)(lds + PG8_SA(b, h) + aoff + m * 2048 + k * 1024); } while (0)
; #define PG8_LDB(dst, b, h) do { _Pragma("unroll") for (int n = 0; n < 2; ++n) _Pragma("unroll") for (int k = 0; k < 2; ++k) dst[n][k] = *(const PG8_LAS bf16x8*)(lds + PG8_SB(b, h) + boff + n * 2048 + k * 1024); } while (0)
; #define PG8_MMA(ai, bj, At, Bt) do { __builtin_amdgcn_s_setprio(1); _Pragma("unroll") for (int m = 0; m < 4; ++m) _Pragma("unroll") for (int n = 0; n < 2; ++n) _Pragma("unroll") for (int k = 0; k < 2; ++k) \
;         acc[ai][bj][m][n] = __builtin_amdgcn_mfma_f32_16x16x32_bf16(Bt[n][k], At[m][k], acc[ai][bj][m][n], 0, 0, 0); __builtin_amdgcn_s_setprio(0); } while (0)
; #define PG8_WAIT_V(n) asm volatile("s_waitcnt vmcnt(" #n ")" ::: "memory")
; #define PG8_WAIT_L(n) asm volatile("s_waitcnt lgkmcnt(" #n ")" ::: "memory")
; template <class Epi, class Sched>
; __device__ __forceinline__ void gemm_phase(PG8_LAS unsigned char* lds, const Gemm g, const Sched& S, const Epi& E) {
;     ...
;             const bool last = (t == nt - 2);
;             const char* a1 = cA + (size_t)(t + 1) * kstep;
;             const char* a2 = last ? nA : cA + (size_t)(t + 2) * kstep; const char* b2 = last ? nB : cB + (size_t)(t + 2) * kstep;
;             const char* a3 = a2 + kstep; const char* b3 = b2 + kstep;
;             if (last && has_next) S.a_ready(nxt);
;             PG8_LDB(B0, 0, 0); PG8_SCHED; PG8_LDA(At, 0, 0); PG8_STAGE(PG8_SA(1, 1), a1 + hstep, voffA);
;             PG8_WAIT_L(8); PG8_BAR; PG8_WAIT_L(0); PG8_MMA(0, 0, At, B0); PG8_BAR; PG8_SCHED;
;             PG8_LDB(B1, 0, 1); PG8_STAGE(PG8_SB(0, 0), b2, voffB);
;             PG8_BAR; PG8_WAIT_L(0); PG8_MMA(0, 1, At, B1); PG8_BAR;
;             PG8_LDA(At, 0, 1); PG8_STAGE(PG8_SA(0, 0), a2, voffA);
;             PG8_BAR; PG8_WAIT_L(0); PG8_MMA(1, 0, At, B0); PG8_BAR; PG8_SCHED;
;             PG8_STAGE(PG8_SB(0, 1), b2 + hstep, voffB);
;             PG8_WAIT_V(6); PG8_BAR; PG8_MMA(1, 1, At, B1); PG8_BAR;
.LBB0_416:
	ds_read_b128 v[24:27], v186
	ds_read_b128 v[28:31], v186 offset:1024
	ds_read_b128 v[40:43], v186 offset:2048
	ds_read_b128 v[44:47], v186 offset:3072
	s_add_u32 s4, s0, 0xfffc0080
	s_addc_u32 s5, s1, -1
	s_cmp_eq_u32 s53, 12
	s_cselect_b32 s29, s7, s5
	s_cselect_b32 s28, s10, s4
	s_cselect_b32 s5, s19, s52
	s_cselect_b32 s4, s21, s51
	v_lshl_add_u64 v[174:175], s[0:1], 0, v[166:167]
	s_add_i32 m0, s27, 0xc000
	ds_read_b128 v[144:147], v187
	ds_read_b128 v[148:151], v187 offset:1024
	ds_read_b128 v[182:185], v187 offset:2048
	ds_read_b128 v[192:195], v187 offset:3072
	ds_read_b128 v[196:199], v187 offset:4096
	ds_read_b128 v[200:203], v187 offset:5120
	ds_read_b128 v[204:207], v187 offset:6144
	ds_read_b128 v[208:211], v187 offset:7168
	global_load_lds_dwordx4 v[174:175], off
	v_lshl_add_u64 v[174:175], s[0:1], 0, v[168:169]
	s_add_i32 m0, s27, 0xe000
	s_nop 0
	global_load_lds_dwordx4 v[174:175], off
	ds_read_b128 v[212:215], v189
	ds_read_b128 v[216:219], v189 offset:1024
	ds_read_b128 v[220:223], v189 offset:2048
	ds_read_b128 v[224:227], v189 offset:3072
	s_waitcnt vmcnt(8) lgkmcnt(0)
	s_barrier
	v_mfma_f32_16x16x32_bf16 v[140:143], v[24:27], v[144:147], v[140:143]
	v_mfma_f32_16x16x32_bf16 v[136:139], v[40:43], v[144:147], v[136:139]
	v_mfma_f32_16x16x32_bf16 v[124:127], v[24:27], v[182:185], v[124:127]
	v_mfma_f32_16x16x32_bf16 v[120:123], v[40:43], v[182:185], v[120:123]
	v_mfma_f32_16x16x32_bf16 v[108:111], v[24:27], v[196:199], v[108:111]
	v_mfma_f32_16x16x32_bf16 v[104:107], v[40:43], v[196:199], v[104:107]
	v_mfma_f32_16x16x32_bf16 v[92:95], v[24:27], v[204:207], v[92:95]
	v_mfma_f32_16x16x32_bf16 v[88:91], v[40:43], v[204:207], v[88:91]
	v_mfma_f32_16x16x32_bf16 v[140:143], v[28:31], v[148:151], v[140:143]
	v_mfma_f32_16x16x32_bf16 v[136:139], v[44:47], v[148:151], v[136:139]
	v_mfma_f32_16x16x32_bf16 v[124:127], v[28:31], v[192:195], v[124:127]
	v_mfma_f32_16x16x32_bf16 v[120:123], v[44:47], v[192:195], v[120:123]
	v_mfma_f32_16x16x32_bf16 v[108:111], v[28:31], v[200:203], v[108:111]
	v_mfma_f32_16x16x32_bf16 v[104:107], v[44:47], v[200:203], v[104:107]
	v_mfma_f32_16x16x32_bf16 v[92:95], v[28:31], v[208:211], v[92:95]
	v_mfma_f32_16x16x32_bf16 v[88:91], v[44:47], v[208:211], v[88:91]
	v_mfma_f32_16x16x32_bf16 v[132:135], v[212:215], v[144:147], v[132:135]
	v_mfma_f32_16x16x32_bf16 v[128:131], v[220:223], v[144:147], v[128:131]
	v_mfma_f32_16x16x32_bf16 v[116:119], v[212:215], v[182:185], v[116:119]
	v_mfma_f32_16x16x32_bf16 v[112:115], v[220:223], v[182:185], v[112:115]
	v_mfma_f32_16x16x32_bf16 v[100:103], v[212:215], v[196:199], v[100:103]
	v_mfma_f32_16x16x32_bf16 v[96:99], v[220:223], v[196:199], v[96:99]
	v_mfma_f32_16x16x32_bf16 v[84:87], v[212:215], v[204:207], v[84:87]
	v_mfma_f32_16x16x32_bf16 v[80:83], v[220:223], v[204:207], v[80:83]
	v_mfma_f32_16x16x32_bf16 v[132:135], v[216:219], v[148:151], v[132:135]
	v_mfma_f32_16x16x32_bf16 v[128:131], v[224:227], v[148:151], v[128:131]
	v_mfma_f32_16x16x32_bf16 v[116:119], v[216:219], v[192:195], v[116:119]
	v_mfma_f32_16x16x32_bf16 v[112:115], v[224:227], v[192:195], v[112:115]
	v_mfma_f32_16x16x32_bf16 v[100:103], v[216:219], v[200:203], v[100:103]
	v_mfma_f32_16x16x32_bf16 v[96:99], v[224:227], v[200:203], v[96:99]
	v_mfma_f32_16x16x32_bf16 v[84:87], v[216:219], v[208:211], v[84:87]
	v_mfma_f32_16x16x32_bf16 v[80:83], v[224:227], v[208:211], v[80:83]
	s_barrier
	ds_read_b128 v[144:147], v187 offset:16384
	ds_read_b128 v[148:151], v187 offset:17408
	ds_read_b128 v[182:185], v187 offset:18432
	ds_read_b128 v[192:195], v187 offset:19456
	ds_read_b128 v[196:199], v187 offset:20480
	ds_read_b128 v[200:203], v187 offset:21504
	ds_read_b128 v[204:207], v187 offset:22528
	ds_read_b128 v[208:211], v187 offset:23552
	s_add_i32 s54, s43, s35
	v_lshl_add_u64 v[174:175], s[4:5], 0, v[156:157]
	s_mov_b32 m0, s54
	s_nop 0
	global_load_lds_dwordx4 v[174:175], off
	v_lshl_add_u64 v[228:229], s[4:5], 0, v[160:161]
	s_add_i32 m0, s54, 0x2000
	s_nop 0
	global_load_lds_dwordx4 v[228:229], off
	s_mov_b32 m0, s27
	v_lshl_add_u64 v[230:231], s[28:29], 0, v[154:155]
	global_load_lds_dwordx4 v[230:231], off
	v_lshl_add_u64 v[232:233], s[28:29], 0, v[158:159]
	s_mov_b32 m0, s36
	s_nop 0
	global_load_lds_dwordx4 v[232:233], off
	s_add_u32 s54, s4, 0x40000
	s_addc_u32 s55, s5, 0
	s_add_i32 s56, s44, s35
	v_lshl_add_u64 v[246:247], s[54:55], 0, v[156:157]
	s_mov_b32 m0, s56
	s_nop 0
	global_load_lds_dwordx4 v[246:247], off
	v_lshl_add_u64 v[246:247], s[54:55], 0, v[160:161]
	s_add_i32 m0, s56, 0x2000
	s_nop 0
	global_load_lds_dwordx4 v[246:247], off
	s_waitcnt vmcnt(8) lgkmcnt(0)
	s_barrier
; #define PG8_STAGE(bufoff, gbase, voff) do { _Pragma("unroll") for (int _i = 0; _i < 2; ++_i) \
;         __builtin_amdgcn_global_load_lds((const unsigned*)((const char*)(gbase) + (voff)[_i]), (PG8_LAS unsigned*)(lds + (bufoff) + ldsw + _i * 8192), 16, 0, 0); } while (0)
; #define PG8_LDA(dst, b, h) do { _Pragma("unroll") for (int m = 0; m < 4; ++m) _Pragma("unroll") for (int k = 0; k < 2; ++k) dst[m][k] = *(const PG8_LAS bf16x8*)(lds + PG8_SA(b, h) + aoff + m * 2048 + k * 1024); } while (0)
; #define PG8_LDB(dst, b, h) do { _Pragma("unroll") for (int n = 0; n < 2; ++n) _Pragma("unroll") for (int k = 0; k < 2; ++k) dst[n][k] = *(const PG8_LAS bf16x8*)(lds + PG8_SB(b, h) + boff + n * 2048 + k * 1024); } while (0)
; #define PG8_MMA(ai, bj, At, Bt) do { __builtin_amdgcn_s_setprio(1); _Pragma("unroll") for (int m = 0; m < 4; ++m) _Pragma("unroll") for (int n = 0; n < 2; ++n) _Pragma("unroll") for (int k = 0; k < 2; ++k) \
;         acc[ai][bj][m][n] = __builtin_amdgcn_mfma_f32_16x16x32_bf16(Bt[n][k], At[m][k], acc[ai][bj][m][n], 0, 0, 0); __builtin_amdgcn_s_setprio(0); } while (0)
; #define PG8_WAIT_V(n) asm volatile("s_waitcnt vmcnt(" #n ")" ::: "memory")
; #define PG8_WAIT_L(n) asm volatile("s_waitcnt lgkmcnt(" #n ")" ::: "memory")
; #define PG8_BAR __builtin_amdgcn_s_barrier()
; #define PG8_SCHED __builtin_amdgcn_sched_barrier(0)
; template <class Epi, class Sched>
; __device__ __forceinline__ void gemm_phase(PG8_LAS unsigned char* lds, const Gemm g, const Sched& S, const Epi& E) {
;     ...
;             PG8_BAR; PG8_WAIT_L(0); PG8_MMA(1, 0, At, B0); PG8_BAR; PG8_SCHED;
;             PG8_STAGE(PG8_SB(0, 1), b2 + hstep, voffB);
;             PG8_WAIT_V(6); PG8_BAR; PG8_MMA(1, 1, At, B1); PG8_BAR;
;             PG8_LDB(B0, 1, 0); PG8_SCHED; PG8_LDA(At, 1, 0); PG8_STAGE(PG8_SA(0, 1), a2 + hstep, voffA);
;             PG8_WAIT_L(8); PG8_BAR; PG8_WAIT_L(0); PG8_MMA(0, 0, At, B0); PG8_BAR; PG8_SCHED;
;             PG8_LDB(B1, 1, 1); PG8_STAGE(PG8_SB(1, 0), b3, voffB);
;             PG8_BAR; PG8_WAIT_L(0); PG8_MMA(0, 1, At, B1); PG8_BAR;
	v_mfma_f32_16x16x32_bf16 v[76:79], v[24:27], v[144:147], v[76:79]
	v_mfma_f32_16x16x32_bf16 v[72:75], v[40:43], v[144:147], v[72:75]
	v_mfma_f32_16x16x32_bf16 v[60:63], v[24:27], v[182:185], v[60:63]
	v_mfma_f32_16x16x32_bf16 v[56:59], v[40:43], v[182:185], v[56:59]
	v_mfma_f32_16x16x32_bf16 v[36:39], v[24:27], v[196:199], v[36:39]
	v_mfma_f32_16x16x32_bf16 v[32:35], v[40:43], v[196:199], v[32:35]
	v_mfma_f32_16x16x32_bf16 v[12:15], v[24:27], v[204:207], v[12:15]
	v_mfma_f32_16x16x32_bf16 v[8:11], v[40:43], v[204:207], v[8:11]
	v_mfma_f32_16x16x32_bf16 v[76:79], v[28:31], v[148:151], v[76:79]
	v_mfma_f32_16x16x32_bf16 v[72:75], v[44:47], v[148:151], v[72:75]
	v_mfma_f32_16x16x32_bf16 v[60:63], v[28:31], v[192:195], v[60:63]
	v_mfma_f32_16x16x32_bf16 v[56:59], v[44:47], v[192:195], v[56:59]
	v_mfma_f32_16x16x32_bf16 v[36:39], v[28:31], v[200:203], v[36:39]
	v_mfma_f32_16x16x32_bf16 v[32:35], v[44:47], v[200:203], v[32:35]
	v_mfma_f32_16x16x32_bf16 v[12:15], v[28:31], v[208:211], v[12:15]
	v_mfma_f32_16x16x32_bf16 v[8:11], v[44:47], v[208:211], v[8:11]
	v_mfma_f32_16x16x32_bf16 v[20:23], v[212:215], v[196:199], v[20:23]
	v_mfma_f32_16x16x32_bf16 v[16:19], v[220:223], v[196:199], v[16:19]
	v_mfma_f32_16x16x32_bf16 v[4:7], v[212:215], v[204:207], v[4:7]
	v_mfma_f32_16x16x32_bf16 v[0:3], v[220:223], v[204:207], v[0:3]
	v_mfma_f32_16x16x32_bf16 v[24:27], v[212:215], v[144:147], v[68:71]
	v_mfma_f32_16x16x32_bf16 v[28:31], v[220:223], v[144:147], v[64:67]
	v_mfma_f32_16x16x32_bf16 v[40:43], v[212:215], v[182:185], v[52:55]
	v_mfma_f32_16x16x32_bf16 v[44:47], v[220:223], v[182:185], v[48:51]
	v_mfma_f32_16x16x32_bf16 v[20:23], v[216:219], v[200:203], v[20:23]
	v_mfma_f32_16x16x32_bf16 v[16:19], v[224:227], v[200:203], v[16:19]
	v_mfma_f32_16x16x32_bf16 v[4:7], v[216:219], v[208:211], v[4:7]
	v_mfma_f32_16x16x32_bf16 v[0:3], v[224:227], v[208:211], v[0:3]
	v_mfma_f32_16x16x32_bf16 v[24:27], v[216:219], v[148:151], v[24:27]
	v_mfma_f32_16x16x32_bf16 v[28:31], v[224:227], v[148:151], v[28:31]
	v_mfma_f32_16x16x32_bf16 v[40:43], v[216:219], v[192:195], v[40:43]
	v_mfma_f32_16x16x32_bf16 v[44:47], v[224:227], v[192:195], v[44:47]
	s_barrier
	s_add_i32 s54, 0, 0x18000
	v_add_u32_e32 v68, s54, v179
	ds_read_b128 v[48:51], v68
	ds_read_b128 v[52:55], v68 offset:1024
	ds_read_b128 v[64:67], v68 offset:2048
	ds_read_b128 v[68:71], v68 offset:3072
	s_add_u32 s28, s28, 0x40000
	s_addc_u32 s29, s29, 0
	s_mov_b32 m0, s37
	v_lshl_add_u64 v[212:213], s[28:29], 0, v[154:155]
	ds_read_b128 v[144:147], v187 offset:32768
	ds_read_b128 v[148:151], v187 offset:33792
	ds_read_b128 v[182:185], v187 offset:34816
	ds_read_b128 v[192:195], v187 offset:35840
	ds_read_b128 v[196:199], v187 offset:36864
	ds_read_b128 v[200:203], v187 offset:37888
	ds_read_b128 v[204:207], v187 offset:38912
	ds_read_b128 v[208:211], v187 offset:39936
	global_load_lds_dwordx4 v[212:213], off
	v_lshl_add_u64 v[212:213], s[28:29], 0, v[158:159]
	s_mov_b32 m0, s38
	s_nop 0
	global_load_lds_dwordx4 v[212:213], off
	s_add_i32 s28, 0, 0x1c000
	v_add_u32_e32 v162, s28, v179
	ds_read_b128 v[212:215], v162
	ds_read_b128 v[216:219], v162 offset:1024
	ds_read_b128 v[220:223], v162 offset:2048
	ds_read_b128 v[224:227], v162 offset:3072
	s_waitcnt vmcnt(8) lgkmcnt(0)
	s_barrier
	v_mfma_f32_16x16x32_bf16 v[140:143], v[48:51], v[144:147], v[140:143]
	v_mfma_f32_16x16x32_bf16 v[136:139], v[64:67], v[144:147], v[136:139]
	v_mfma_f32_16x16x32_bf16 v[124:127], v[48:51], v[182:185], v[124:127]
	v_mfma_f32_16x16x32_bf16 v[120:123], v[64:67], v[182:185], v[120:123]
	v_mfma_f32_16x16x32_bf16 v[108:111], v[48:51], v[196:199], v[108:111]
	v_mfma_f32_16x16x32_bf16 v[104:107], v[64:67], v[196:199], v[104:107]
	v_mfma_f32_16x16x32_bf16 v[92:95], v[48:51], v[204:207], v[92:95]
	v_mfma_f32_16x16x32_bf16 v[88:91], v[64:67], v[204:207], v[88:91]
	v_mfma_f32_16x16x32_bf16 v[140:143], v[52:55], v[148:151], v[140:143]
	v_mfma_f32_16x16x32_bf16 v[136:139], v[68:71], v[148:151], v[136:139]
	v_mfma_f32_16x16x32_bf16 v[124:127], v[52:55], v[192:195], v[124:127]
	v_mfma_f32_16x16x32_bf16 v[120:123], v[68:71], v[192:195], v[120:123]
	v_mfma_f32_16x16x32_bf16 v[108:111], v[52:55], v[200:203], v[108:111]
	v_mfma_f32_16x16x32_bf16 v[104:107], v[68:71], v[200:203], v[104:107]
	v_mfma_f32_16x16x32_bf16 v[92:95], v[52:55], v[208:211], v[92:95]
	v_mfma_f32_16x16x32_bf16 v[88:91], v[68:71], v[208:211], v[88:91]
	v_mfma_f32_16x16x32_bf16 v[132:135], v[212:215], v[144:147], v[132:135]
	v_mfma_f32_16x16x32_bf16 v[128:131], v[220:223], v[144:147], v[128:131]
	v_mfma_f32_16x16x32_bf16 v[116:119], v[212:215], v[182:185], v[116:119]
	v_mfma_f32_16x16x32_bf16 v[112:115], v[220:223], v[182:185], v[112:115]
	v_mfma_f32_16x16x32_bf16 v[100:103], v[212:215], v[196:199], v[100:103]
	v_mfma_f32_16x16x32_bf16 v[96:99], v[220:223], v[196:199], v[96:99]
	v_mfma_f32_16x16x32_bf16 v[84:87], v[212:215], v[204:207], v[84:87]
	v_mfma_f32_16x16x32_bf16 v[80:83], v[220:223], v[204:207], v[80:83]
	v_mfma_f32_16x16x32_bf16 v[132:135], v[216:219], v[148:151], v[132:135]
	v_mfma_f32_16x16x32_bf16 v[128:131], v[224:227], v[148:151], v[128:131]
	v_mfma_f32_16x16x32_bf16 v[116:119], v[216:219], v[192:195], v[116:119]
	v_mfma_f32_16x16x32_bf16 v[112:115], v[224:227], v[192:195], v[112:115]
	v_mfma_f32_16x16x32_bf16 v[100:103], v[216:219], v[200:203], v[100:103]
	v_mfma_f32_16x16x32_bf16 v[96:99], v[224:227], v[200:203], v[96:99]
	v_mfma_f32_16x16x32_bf16 v[84:87], v[216:219], v[208:211], v[84:87]
	v_mfma_f32_16x16x32_bf16 v[80:83], v[224:227], v[208:211], v[80:83]
	s_barrier
; #define PG8_STAGE(bufoff, gbase, voff) do { _Pragma("unroll") for (int _i = 0; _i < 2; ++_i) \
;         __builtin_amdgcn_global_load_lds((const unsigned*)((const char*)(gbase) + (voff)[_i]), (PG8_LAS unsigned*)(lds + (bufoff) + ldsw + _i * 8192), 16, 0, 0); } while (0)
; #define PG8_LDA(dst, b, h) do { _Pragma("unroll") for (int m = 0; m < 4; ++m) _Pragma("unroll") for (int k = 0; k < 2; ++k) dst[m][k] = *(const PG8_LAS bf16x8*)(lds + PG8_SA(b, h) + aoff + m * 2048 + k * 1024); } while (0)
; #define PG8_MMA(ai, bj, At, Bt) do { __builtin_amdgcn_s_setprio(1); _Pragma("unroll") for (int m = 0; m < 4; ++m) _Pragma("unroll") for (int n = 0; n < 2; ++n) _Pragma("unroll") for (int k = 0; k < 2; ++k) \
;         acc[ai][bj][m][n] = __builtin_amdgcn_mfma_f32_16x16x32_bf16(Bt[n][k], At[m][k], acc[ai][bj][m][n], 0, 0, 0); __builtin_amdgcn_s_setprio(0); } while (0)
; #define PG8_WAIT_V(n) asm volatile("s_waitcnt vmcnt(" #n ")" ::: "memory")
; #define PG8_WAIT_L(n) asm volatile("s_waitcnt lgkmcnt(" #n ")" ::: "memory")
; #define PG8_BAR __builtin_amdgcn_s_barrier()
; #define PG8_SCHED __builtin_amdgcn_sched_barrier(0)
;     __device__ __forceinline__ void operator()(const f32x4 (&acc)[2][2][4][2], const Unit& u, int wr, int wc, int fr, int fq) const {
;         int act = 0; const float* bias = nullptr;
;         if (mode == 1) { if (u.pn >= 8 && u.pn < 12) act = 1; else if (u.pn >= 12) { act = 3; bias = (u.pn >= 14) ? bias_b + (u.pn - 14) * 256 : bias_f + (u.pn - 12) * 256; } }
;         else if (mode == 2) { if (u.pn >= 6) act = 2; }
;         const int row0 = u.pm * BM + wr * 64 + fr, col0 = u.pn * BM + wc * 32 + 8 * fq, bcol0 = wc * 32 + 8 * fq;
;         f32x4 bv[2][2];
; #pragma unroll
;         for (int bj = 0; bj < 2; ++bj)
; #pragma unroll
;             for (int n = 0; n < 2; ++n) bv[bj][n] = bias ? *(const f32x4*)(bias + bcol0 + bj * HALF + 4 * n) : (f32x4){0.f, 0.f, 0.f, 0.f};
; template <class Epi, class Sched>
; __device__ __forceinline__ void gemm_phase(PG8_LAS unsigned char* lds, const Gemm g, const Sched& S, const Epi& E) {
;     ...
;             PG8_LDA(At, 1, 1); PG8_STAGE(PG8_SA(1, 0), a3, voffA);
;             PG8_BAR; PG8_WAIT_L(0); PG8_MMA(1, 0, At, B0); PG8_BAR; PG8_SCHED;
;             PG8_STAGE(PG8_SB(1, 1), b3 + hstep, voffB);
;             PG8_WAIT_V(6); PG8_BAR; PG8_MMA(1, 1, At, B1); PG8_BAR;
;         }
	ds_read_b128 v[144:147], v187 offset:49152
	ds_read_b128 v[148:151], v187 offset:50176
	ds_read_b128 v[182:185], v187 offset:51200
	ds_read_b128 v[192:195], v187 offset:52224
	ds_read_b128 v[196:199], v187 offset:53248
	ds_read_b128 v[200:203], v187 offset:54272
	ds_read_b128 v[204:207], v187 offset:55296
	ds_read_b128 v[208:211], v187 offset:56320
	s_add_i32 s29, s54, s35
	v_lshl_add_u64 v[174:175], v[174:175], 0, s[14:15]
	s_mov_b32 m0, s29
	s_nop 0
	global_load_lds_dwordx4 v[174:175], off
	v_lshl_add_u64 v[174:175], v[228:229], 0, s[14:15]
	s_add_i32 m0, s29, 0x2000
	s_nop 0
	global_load_lds_dwordx4 v[174:175], off
	s_mov_b32 m0, s39
	v_lshl_add_u64 v[174:175], v[230:231], 0, s[14:15]
	global_load_lds_dwordx4 v[174:175], off
	v_lshl_add_u64 v[174:175], v[232:233], 0, s[14:15]
	s_mov_b32 m0, s40
	s_nop 0
	global_load_lds_dwordx4 v[174:175], off
	s_add_u32 s4, s4, 0x40080
	s_addc_u32 s5, s5, 0
	s_add_i32 s28, s28, s35
	v_lshl_add_u64 v[246:247], s[4:5], 0, v[156:157]
	s_mov_b32 m0, s28
	s_nop 0
	global_load_lds_dwordx4 v[246:247], off
	v_lshl_add_u64 v[246:247], s[4:5], 0, v[160:161]
	s_add_i32 m0, s28, 0x2000
	s_nop 0
	global_load_lds_dwordx4 v[246:247], off
	s_waitcnt vmcnt(8) lgkmcnt(0)
	s_barrier
	v_mfma_f32_16x16x32_bf16 v[76:79], v[48:51], v[144:147], v[76:79]
	v_mfma_f32_16x16x32_bf16 v[72:75], v[64:67], v[144:147], v[72:75]
	v_mfma_f32_16x16x32_bf16 v[60:63], v[48:51], v[182:185], v[60:63]
	v_mfma_f32_16x16x32_bf16 v[56:59], v[64:67], v[182:185], v[56:59]
	v_mfma_f32_16x16x32_bf16 v[36:39], v[48:51], v[196:199], v[36:39]
	v_mfma_f32_16x16x32_bf16 v[32:35], v[64:67], v[196:199], v[32:35]
	v_mfma_f32_16x16x32_bf16 v[12:15], v[48:51], v[204:207], v[12:15]
	v_mfma_f32_16x16x32_bf16 v[8:11], v[64:67], v[204:207], v[8:11]
	v_mfma_f32_16x16x32_bf16 v[76:79], v[52:55], v[148:151], v[76:79]
	v_mfma_f32_16x16x32_bf16 v[72:75], v[68:71], v[148:151], v[72:75]
	v_mfma_f32_16x16x32_bf16 v[60:63], v[52:55], v[192:195], v[60:63]
	v_mfma_f32_16x16x32_bf16 v[56:59], v[68:71], v[192:195], v[56:59]
	v_mfma_f32_16x16x32_bf16 v[36:39], v[52:55], v[200:203], v[36:39]
	v_mfma_f32_16x16x32_bf16 v[32:35], v[68:71], v[200:203], v[32:35]
	v_mfma_f32_16x16x32_bf16 v[12:15], v[52:55], v[208:211], v[12:15]
	v_mfma_f32_16x16x32_bf16 v[8:11], v[68:71], v[208:211], v[8:11]
	v_mfma_f32_16x16x32_bf16 v[24:27], v[212:215], v[144:147], v[24:27]
	v_mfma_f32_16x16x32_bf16 v[68:71], v[216:219], v[148:151], v[24:27]
	v_mfma_f32_16x16x32_bf16 v[24:27], v[220:223], v[144:147], v[28:31]
	v_mfma_f32_16x16x32_bf16 v[64:67], v[224:227], v[148:151], v[24:27]
	v_mfma_f32_16x16x32_bf16 v[24:27], v[212:215], v[182:185], v[40:43]
	v_mfma_f32_16x16x32_bf16 v[52:55], v[216:219], v[192:195], v[24:27]
	v_mfma_f32_16x16x32_bf16 v[24:27], v[220:223], v[182:185], v[44:47]
	v_mfma_f32_16x16x32_bf16 v[20:23], v[212:215], v[196:199], v[20:23]
	v_mfma_f32_16x16x32_bf16 v[16:19], v[220:223], v[196:199], v[16:19]
	v_mfma_f32_16x16x32_bf16 v[4:7], v[212:215], v[204:207], v[4:7]
	v_mfma_f32_16x16x32_bf16 v[0:3], v[220:223], v[204:207], v[0:3]
	v_mfma_f32_16x16x32_bf16 v[48:51], v[224:227], v[192:195], v[24:27]
	v_mfma_f32_16x16x32_bf16 v[20:23], v[216:219], v[200:203], v[20:23]
	v_mfma_f32_16x16x32_bf16 v[16:19], v[224:227], v[200:203], v[16:19]
	v_mfma_f32_16x16x32_bf16 v[4:7], v[216:219], v[208:211], v[4:7]
	v_mfma_f32_16x16x32_bf16 v[0:3], v[224:227], v[208:211], v[0:3]
	s_barrier
	s_add_i32 s53, s53, 2
	s_add_u32 s0, s0, 0x100
	s_addc_u32 s1, s1, 0
	s_add_u32 s51, s51, 0x100
	s_addc_u32 s52, s52, 0
	s_cmp_gt_u32 s53, 13
	s_cbranch_scc0 .LBB0_416
	s_cmp_gt_i32 s26, 11
	s_cselect_b64 s[4:5], -1, 0
	s_cmp_lt_i32 s26, 12
	s_mov_b64 s[0:1], 0
	s_cbranch_scc1 .LBB0_422
	s_lshl_b32 s10, s26, 8
	s_cmp_lt_u32 s26, 14
	s_mov_b64 s[28:29], -1
	s_cbranch_scc0 .LBB0_420
	s_lshl_b64 s[0:1], s[10:11], 2
	v_readlane_b32 s52, v245, 0
	v_readlane_b32 s53, v245, 1
	s_add_u32 s0, s52, s0
	s_addc_u32 s1, s53, s1
	s_add_u32 s0, s0, 0xffffd000
	v_readlane_b32 s54, v245, 2
	v_readlane_b32 s55, v245, 3
	v_readlane_b32 s56, v245, 4
	v_readlane_b32 s57, v245, 5
	v_readlane_b32 s58, v245, 6
	v_readlane_b32 s59, v245, 7
	v_readlane_b32 s60, v245, 8
	v_readlane_b32 s61, v245, 9
	v_readlane_b32 s62, v245, 10
	v_readlane_b32 s63, v245, 11
	v_readlane_b32 s64, v245, 12
	v_readlane_b32 s65, v245, 13
	v_readlane_b32 s66, v245, 14
	v_readlane_b32 s67, v245, 15
	s_addc_u32 s1, s1, -1
	s_mov_b64 s[28:29], 0

; #define PG8_STAGE(bufoff, gbase, voff) do { _Pragma("unroll") for (int _i = 0; _i < 2; ++_i) \
;         __builtin_amdgcn_global_load_lds((const unsigned*)((const char*)(gbase) + (voff)[_i]), (PG8_LAS unsigned*)(lds + (bufoff) + ldsw + _i * 8192), 16, 0, 0); } while (0)
; #define PG8_LDA(dst, b, h) do { _Pragma("unroll") for (int m = 0; m < 4; ++m) _Pragma("unroll") for (int k = 0; k < 2; ++k) dst[m][k] = *(const PG8_LAS bf16x8*)(lds + PG8_SA(b, h) + aoff + m * 2048 + k * 1024); } while (0)
; #define PG8_LDB(dst, b, h) do { _Pragma("unroll") for (int n = 0; n < 2; ++n) _Pragma("unroll") for (int k = 0; k < 2; ++k) dst[n][k] = *(const PG8_LAS bf16x8*)(lds + PG8_SB(b, h) + boff + n * 2048 + k * 1024); } while (0)
; #define PG8_MMA(ai, bj, At, Bt) do { __builtin_amdgcn_s_setprio(1); _Pragma("unroll") for (int m = 0; m < 4; ++m) _Pragma("unroll") for (int n = 0; n < 2; ++n) _Pragma("unroll") for (int k = 0; k < 2; ++k) \
;         acc[ai][bj][m][n] = __builtin_amdgcn_mfma_f32_16x16x32_bf16(Bt[n][k], At[m][k], acc[ai][bj][m][n], 0, 0, 0); __builtin_amdgcn_s_setprio(0); } while (0)
; #define PG8_WAIT_V(n) asm volatile("s_waitcnt vmcnt(" #n ")" ::: "memory")
; #define PG8_WAIT_L(n) asm volatile("s_waitcnt lgkmcnt(" #n ")" ::: "memory")
; template <class Epi, class Sched>
; __device__ __forceinline__ void gemm_phase(PG8_LAS unsigned char* lds, const Gemm g, const Sched& S, const Epi& E) {
;     ...
;             const bool last = (t == nt - 2);
;             const char* a1 = cA + (size_t)(t + 1) * kstep;
;             const char* a2 = last ? nA : cA + (size_t)(t + 2) * kstep; const char* b2 = last ? nB : cB + (size_t)(t + 2) * kstep;
;             const char* a3 = a2 + kstep; const char* b3 = b2 + kstep;
;             if (last && has_next) S.a_ready(nxt);
;             PG8_LDB(B0, 0, 0); PG8_SCHED; PG8_LDA(At, 0, 0); PG8_STAGE(PG8_SA(1, 1), a1 + hstep, voffA);
;             PG8_WAIT_L(8); PG8_BAR; PG8_WAIT_L(0); PG8_MMA(0, 0, At, B0); PG8_BAR; PG8_SCHED;
;             PG8_LDB(B1, 0, 1); PG8_STAGE(PG8_SB(0, 0), b2, voffB);
;             PG8_BAR; PG8_WAIT_L(0); PG8_MMA(0, 1, At, B1); PG8_BAR;
;             PG8_LDA(At, 0, 1); PG8_STAGE(PG8_SA(0, 0), a2, voffA);
;             PG8_BAR; PG8_WAIT_L(0); PG8_MMA(1, 0, At, B0); PG8_BAR; PG8_SCHED;
;             PG8_STAGE(PG8_SB(0, 1), b2 + hstep, voffB);
;             PG8_WAIT_V(6); PG8_BAR; PG8_MMA(1, 1, At, B1); PG8_BAR;
.LBB0_724:
	ds_read_b128 v[144:147], v151
	ds_read_b128 v[156:159], v151 offset:1024
	ds_read_b128 v[160:163], v151 offset:2048
	ds_read_b128 v[166:169], v151 offset:3072
	s_add_u32 s20, s18, 0xfffc0080
	s_addc_u32 s21, s19, -1
	s_cmp_eq_u32 s48, 12
	s_cselect_b32 s23, s5, s21
	s_cselect_b32 s22, s11, s20
	s_cselect_b32 s21, s9, s47
	s_cselect_b32 s20, s45, s46
	v_lshl_add_u64 v[174:175], s[18:19], 0, v[136:137]
	s_add_i32 m0, s17, 0xc000
	ds_read_b128 v[170:173], v153
	ds_read_b128 v[182:185], v153 offset:1024
	ds_read_b128 v[190:193], v153 offset:2048
	ds_read_b128 v[194:197], v153 offset:3072
	ds_read_b128 v[198:201], v153 offset:4096
	ds_read_b128 v[202:205], v153 offset:5120
	ds_read_b128 v[206:209], v153 offset:6144
	ds_read_b128 v[210:213], v153 offset:7168
	global_load_lds_dwordx4 v[174:175], off
	v_lshl_add_u64 v[174:175], s[18:19], 0, v[138:139]
	s_add_i32 m0, s17, 0xe000
	s_nop 0
	global_load_lds_dwordx4 v[174:175], off
	ds_read_b128 v[214:217], v154
	ds_read_b128 v[218:221], v154 offset:1024
	ds_read_b128 v[222:225], v154 offset:2048
	ds_read_b128 v[226:229], v154 offset:3072
	s_waitcnt vmcnt(8) lgkmcnt(0)
	s_barrier
	v_mfma_f32_16x16x32_bf16 v[124:127], v[144:147], v[170:173], v[124:127]
	v_mfma_f32_16x16x32_bf16 v[120:123], v[160:163], v[170:173], v[120:123]
	v_mfma_f32_16x16x32_bf16 v[108:111], v[144:147], v[190:193], v[108:111]
	v_mfma_f32_16x16x32_bf16 v[104:107], v[160:163], v[190:193], v[104:107]
	v_mfma_f32_16x16x32_bf16 v[92:95], v[144:147], v[198:201], v[92:95]
	v_mfma_f32_16x16x32_bf16 v[88:91], v[160:163], v[198:201], v[88:91]
	v_mfma_f32_16x16x32_bf16 v[76:79], v[144:147], v[206:209], v[76:79]
	v_mfma_f32_16x16x32_bf16 v[72:75], v[160:163], v[206:209], v[72:75]
	v_mfma_f32_16x16x32_bf16 v[124:127], v[156:159], v[182:185], v[124:127]
	v_mfma_f32_16x16x32_bf16 v[120:123], v[166:169], v[182:185], v[120:123]
	v_mfma_f32_16x16x32_bf16 v[108:111], v[156:159], v[194:197], v[108:111]
	v_mfma_f32_16x16x32_bf16 v[104:107], v[166:169], v[194:197], v[104:107]
	v_mfma_f32_16x16x32_bf16 v[92:95], v[156:159], v[202:205], v[92:95]
	v_mfma_f32_16x16x32_bf16 v[88:91], v[166:169], v[202:205], v[88:91]
	v_mfma_f32_16x16x32_bf16 v[76:79], v[156:159], v[210:213], v[76:79]
	v_mfma_f32_16x16x32_bf16 v[72:75], v[166:169], v[210:213], v[72:75]
	v_mfma_f32_16x16x32_bf16 v[116:119], v[214:217], v[170:173], v[116:119]
	v_mfma_f32_16x16x32_bf16 v[112:115], v[222:225], v[170:173], v[112:115]
	v_mfma_f32_16x16x32_bf16 v[100:103], v[214:217], v[190:193], v[100:103]
	v_mfma_f32_16x16x32_bf16 v[96:99], v[222:225], v[190:193], v[96:99]
	v_mfma_f32_16x16x32_bf16 v[84:87], v[214:217], v[198:201], v[84:87]
	v_mfma_f32_16x16x32_bf16 v[80:83], v[222:225], v[198:201], v[80:83]
	v_mfma_f32_16x16x32_bf16 v[68:71], v[214:217], v[206:209], v[68:71]
	v_mfma_f32_16x16x32_bf16 v[64:67], v[222:225], v[206:209], v[64:67]
	v_mfma_f32_16x16x32_bf16 v[116:119], v[218:221], v[182:185], v[116:119]
	v_mfma_f32_16x16x32_bf16 v[112:115], v[226:229], v[182:185], v[112:115]
	v_mfma_f32_16x16x32_bf16 v[100:103], v[218:221], v[194:197], v[100:103]
	v_mfma_f32_16x16x32_bf16 v[96:99], v[226:229], v[194:197], v[96:99]
	v_mfma_f32_16x16x32_bf16 v[84:87], v[218:221], v[202:205], v[84:87]
	v_mfma_f32_16x16x32_bf16 v[80:83], v[226:229], v[202:205], v[80:83]
	v_mfma_f32_16x16x32_bf16 v[68:71], v[218:221], v[210:213], v[68:71]
	v_mfma_f32_16x16x32_bf16 v[64:67], v[226:229], v[210:213], v[64:67]
	s_barrier
	ds_read_b128 v[170:173], v153 offset:16384
	ds_read_b128 v[182:185], v153 offset:17408
	ds_read_b128 v[190:193], v153 offset:18432
	ds_read_b128 v[194:197], v153 offset:19456
	ds_read_b128 v[198:201], v153 offset:20480
	ds_read_b128 v[202:205], v153 offset:21504
	ds_read_b128 v[206:209], v153 offset:22528
	ds_read_b128 v[210:213], v153 offset:23552
	s_add_i32 s49, s42, s30
	v_lshl_add_u64 v[174:175], s[20:21], 0, v[130:131]
	s_mov_b32 m0, s49
	s_nop 0
	global_load_lds_dwordx4 v[174:175], off
	v_lshl_add_u64 v[186:187], s[20:21], 0, v[134:135]
	s_add_i32 m0, s49, 0x2000
	s_nop 0
	global_load_lds_dwordx4 v[186:187], off
	s_mov_b32 m0, s17
	v_lshl_add_u64 v[230:231], s[22:23], 0, v[128:129]
	global_load_lds_dwordx4 v[230:231], off
	v_lshl_add_u64 v[232:233], s[22:23], 0, v[132:133]
	s_mov_b32 m0, s31
	s_nop 0
	global_load_lds_dwordx4 v[232:233], off
	s_add_u32 s50, s20, 0x40000
	s_addc_u32 s51, s21, 0
	s_add_i32 s49, s43, s30
	v_lshl_add_u64 v[246:247], s[50:51], 0, v[130:131]
	s_mov_b32 m0, s49
	s_nop 0
	global_load_lds_dwordx4 v[246:247], off
	v_lshl_add_u64 v[246:247], s[50:51], 0, v[134:135]
	s_add_i32 m0, s49, 0x2000
	s_nop 0
	global_load_lds_dwordx4 v[246:247], off
	s_waitcnt vmcnt(8) lgkmcnt(0)
	s_barrier
; #define PG8_STAGE(bufoff, gbase, voff) do { _Pragma("unroll") for (int _i = 0; _i < 2; ++_i) \
;         __builtin_amdgcn_global_load_lds((const unsigned*)((const char*)(gbase) + (voff)[_i]), (PG8_LAS unsigned*)(lds + (bufoff) + ldsw + _i * 8192), 16, 0, 0); } while (0)
; #define PG8_LDA(dst, b, h) do { _Pragma("unroll") for (int m = 0; m < 4; ++m) _Pragma("unroll") for (int k = 0; k < 2; ++k) dst[m][k] = *(const PG8_LAS bf16x8*)(lds + PG8_SA(b, h) + aoff + m * 2048 + k * 1024); } while (0)
; #define PG8_LDB(dst, b, h) do { _Pragma("unroll") for (int n = 0; n < 2; ++n) _Pragma("unroll") for (int k = 0; k < 2; ++k) dst[n][k] = *(const PG8_LAS bf16x8*)(lds + PG8_SB(b, h) + boff + n * 2048 + k * 1024); } while (0)
; #define PG8_MMA(ai, bj, At, Bt) do { __builtin_amdgcn_s_setprio(1); _Pragma("unroll") for (int m = 0; m < 4; ++m) _Pragma("unroll") for (int n = 0; n < 2; ++n) _Pragma("unroll") for (int k = 0; k < 2; ++k) \
;         acc[ai][bj][m][n] = __builtin_amdgcn_mfma_f32_16x16x32_bf16(Bt[n][k], At[m][k], acc[ai][bj][m][n], 0, 0, 0); __builtin_amdgcn_s_setprio(0); } while (0)
; #define PG8_WAIT_V(n) asm volatile("s_waitcnt vmcnt(" #n ")" ::: "memory")
; #define PG8_WAIT_L(n) asm volatile("s_waitcnt lgkmcnt(" #n ")" ::: "memory")
; #define PG8_BAR __builtin_amdgcn_s_barrier()
; #define PG8_SCHED __builtin_amdgcn_sched_barrier(0)
; template <class Epi, class Sched>
; __device__ __forceinline__ void gemm_phase(PG8_LAS unsigned char* lds, const Gemm g, const Sched& S, const Epi& E) {
;     ...
;             PG8_BAR; PG8_WAIT_L(0); PG8_MMA(1, 0, At, B0); PG8_BAR; PG8_SCHED;
;             PG8_STAGE(PG8_SB(0, 1), b2 + hstep, voffB);
;             PG8_WAIT_V(6); PG8_BAR; PG8_MMA(1, 1, At, B1); PG8_BAR;
;             PG8_LDB(B0, 1, 0); PG8_SCHED; PG8_LDA(At, 1, 0); PG8_STAGE(PG8_SA(0, 1), a2 + hstep, voffA);
;             PG8_WAIT_L(8); PG8_BAR; PG8_WAIT_L(0); PG8_MMA(0, 0, At, B0); PG8_BAR; PG8_SCHED;
;             PG8_LDB(B1, 1, 1); PG8_STAGE(PG8_SB(1, 0), b3, voffB);
;             PG8_BAR; PG8_WAIT_L(0); PG8_MMA(0, 1, At, B1); PG8_BAR;
	v_mfma_f32_16x16x32_bf16 v[60:63], v[144:147], v[170:173], v[60:63]
	v_mfma_f32_16x16x32_bf16 v[56:59], v[160:163], v[170:173], v[56:59]
	v_mfma_f32_16x16x32_bf16 v[44:47], v[144:147], v[190:193], v[44:47]
	v_mfma_f32_16x16x32_bf16 v[40:43], v[160:163], v[190:193], v[40:43]
	v_mfma_f32_16x16x32_bf16 v[28:31], v[144:147], v[198:201], v[28:31]
	v_mfma_f32_16x16x32_bf16 v[24:27], v[160:163], v[198:201], v[24:27]
	v_mfma_f32_16x16x32_bf16 v[12:15], v[144:147], v[206:209], v[12:15]
	v_mfma_f32_16x16x32_bf16 v[8:11], v[160:163], v[206:209], v[8:11]
	v_mfma_f32_16x16x32_bf16 v[60:63], v[156:159], v[182:185], v[60:63]
	v_mfma_f32_16x16x32_bf16 v[56:59], v[166:169], v[182:185], v[56:59]
	v_mfma_f32_16x16x32_bf16 v[44:47], v[156:159], v[194:197], v[44:47]
	v_mfma_f32_16x16x32_bf16 v[40:43], v[166:169], v[194:197], v[40:43]
	v_mfma_f32_16x16x32_bf16 v[28:31], v[156:159], v[202:205], v[28:31]
	v_mfma_f32_16x16x32_bf16 v[24:27], v[166:169], v[202:205], v[24:27]
	v_mfma_f32_16x16x32_bf16 v[12:15], v[156:159], v[210:213], v[12:15]
	v_mfma_f32_16x16x32_bf16 v[8:11], v[166:169], v[210:213], v[8:11]
	v_mfma_f32_16x16x32_bf16 v[52:55], v[214:217], v[170:173], v[52:55]
	v_mfma_f32_16x16x32_bf16 v[48:51], v[222:225], v[170:173], v[48:51]
	v_mfma_f32_16x16x32_bf16 v[36:39], v[214:217], v[190:193], v[36:39]
	v_mfma_f32_16x16x32_bf16 v[32:35], v[222:225], v[190:193], v[32:35]
	v_mfma_f32_16x16x32_bf16 v[20:23], v[214:217], v[198:201], v[20:23]
	v_mfma_f32_16x16x32_bf16 v[16:19], v[222:225], v[198:201], v[16:19]
	v_mfma_f32_16x16x32_bf16 v[4:7], v[214:217], v[206:209], v[4:7]
	v_mfma_f32_16x16x32_bf16 v[0:3], v[222:225], v[206:209], v[0:3]
	v_mfma_f32_16x16x32_bf16 v[52:55], v[218:221], v[182:185], v[52:55]
	v_mfma_f32_16x16x32_bf16 v[48:51], v[226:229], v[182:185], v[48:51]
	v_mfma_f32_16x16x32_bf16 v[36:39], v[218:221], v[194:197], v[36:39]
	v_mfma_f32_16x16x32_bf16 v[32:35], v[226:229], v[194:197], v[32:35]
	v_mfma_f32_16x16x32_bf16 v[20:23], v[218:221], v[202:205], v[20:23]
	v_mfma_f32_16x16x32_bf16 v[16:19], v[226:229], v[202:205], v[16:19]
	v_mfma_f32_16x16x32_bf16 v[4:7], v[218:221], v[210:213], v[4:7]
	v_mfma_f32_16x16x32_bf16 v[0:3], v[226:229], v[210:213], v[0:3]
	s_barrier
	s_add_i32 s49, 0, 0x18000
	v_add_u32_e32 v155, s49, v149
	ds_read_b128 v[144:147], v155
	ds_read_b128 v[156:159], v155 offset:1024
	ds_read_b128 v[160:163], v155 offset:2048
	ds_read_b128 v[166:169], v155 offset:3072
	s_add_u32 s22, s22, 0x40000
	s_addc_u32 s23, s23, 0
	s_mov_b32 m0, s34
	v_lshl_add_u64 v[214:215], s[22:23], 0, v[128:129]
	ds_read_b128 v[170:173], v153 offset:32768
	ds_read_b128 v[182:185], v153 offset:33792
	ds_read_b128 v[190:193], v153 offset:34816
	ds_read_b128 v[194:197], v153 offset:35840
	ds_read_b128 v[198:201], v153 offset:36864
	ds_read_b128 v[202:205], v153 offset:37888
	ds_read_b128 v[206:209], v153 offset:38912
	ds_read_b128 v[210:213], v153 offset:39936
	global_load_lds_dwordx4 v[214:215], off
	v_lshl_add_u64 v[214:215], s[22:23], 0, v[132:133]
	s_mov_b32 m0, s35
	s_nop 0
	global_load_lds_dwordx4 v[214:215], off
	s_add_i32 s22, 0, 0x1c000
	v_add_u32_e32 v155, s22, v149
	ds_read_b128 v[214:217], v155
	ds_read_b128 v[218:221], v155 offset:1024
	ds_read_b128 v[222:225], v155 offset:2048
	ds_read_b128 v[226:229], v155 offset:3072
	s_waitcnt vmcnt(8) lgkmcnt(0)
	s_barrier
	v_mfma_f32_16x16x32_bf16 v[124:127], v[144:147], v[170:173], v[124:127]
	v_mfma_f32_16x16x32_bf16 v[120:123], v[160:163], v[170:173], v[120:123]
	v_mfma_f32_16x16x32_bf16 v[108:111], v[144:147], v[190:193], v[108:111]
	v_mfma_f32_16x16x32_bf16 v[104:107], v[160:163], v[190:193], v[104:107]
	v_mfma_f32_16x16x32_bf16 v[92:95], v[144:147], v[198:201], v[92:95]
	v_mfma_f32_16x16x32_bf16 v[88:91], v[160:163], v[198:201], v[88:91]
	v_mfma_f32_16x16x32_bf16 v[76:79], v[144:147], v[206:209], v[76:79]
	v_mfma_f32_16x16x32_bf16 v[72:75], v[160:163], v[206:209], v[72:75]
	v_mfma_f32_16x16x32_bf16 v[124:127], v[156:159], v[182:185], v[124:127]
	v_mfma_f32_16x16x32_bf16 v[120:123], v[166:169], v[182:185], v[120:123]
	v_mfma_f32_16x16x32_bf16 v[108:111], v[156:159], v[194:197], v[108:111]
	v_mfma_f32_16x16x32_bf16 v[104:107], v[166:169], v[194:197], v[104:107]
	v_mfma_f32_16x16x32_bf16 v[92:95], v[156:159], v[202:205], v[92:95]
	v_mfma_f32_16x16x32_bf16 v[88:91], v[166:169], v[202:205], v[88:91]
	v_mfma_f32_16x16x32_bf16 v[76:79], v[156:159], v[210:213], v[76:79]
	v_mfma_f32_16x16x32_bf16 v[72:75], v[166:169], v[210:213], v[72:75]
	v_mfma_f32_16x16x32_bf16 v[116:119], v[214:217], v[170:173], v[116:119]
	v_mfma_f32_16x16x32_bf16 v[112:115], v[222:225], v[170:173], v[112:115]
	v_mfma_f32_16x16x32_bf16 v[100:103], v[214:217], v[190:193], v[100:103]
	v_mfma_f32_16x16x32_bf16 v[96:99], v[222:225], v[190:193], v[96:99]
	v_mfma_f32_16x16x32_bf16 v[84:87], v[214:217], v[198:201], v[84:87]
	v_mfma_f32_16x16x32_bf16 v[80:83], v[222:225], v[198:201], v[80:83]
	v_mfma_f32_16x16x32_bf16 v[68:71], v[214:217], v[206:209], v[68:71]
	v_mfma_f32_16x16x32_bf16 v[64:67], v[222:225], v[206:209], v[64:67]
	v_mfma_f32_16x16x32_bf16 v[116:119], v[218:221], v[182:185], v[116:119]
	v_mfma_f32_16x16x32_bf16 v[112:115], v[226:229], v[182:185], v[112:115]
	v_mfma_f32_16x16x32_bf16 v[100:103], v[218:221], v[194:197], v[100:103]
	v_mfma_f32_16x16x32_bf16 v[96:99], v[226:229], v[194:197], v[96:99]
	v_mfma_f32_16x16x32_bf16 v[84:87], v[218:221], v[202:205], v[84:87]
	v_mfma_f32_16x16x32_bf16 v[80:83], v[226:229], v[202:205], v[80:83]
	v_mfma_f32_16x16x32_bf16 v[68:71], v[218:221], v[210:213], v[68:71]
	v_mfma_f32_16x16x32_bf16 v[64:67], v[226:229], v[210:213], v[64:67]
	s_barrier
; #define PG8_STAGE(bufoff, gbase, voff) do { _Pragma("unroll") for (int _i = 0; _i < 2; ++_i) \
;         __builtin_amdgcn_global_load_lds((const unsigned*)((const char*)(gbase) + (voff)[_i]), (PG8_LAS unsigned*)(lds + (bufoff) + ldsw + _i * 8192), 16, 0, 0); } while (0)
; #define PG8_LDA(dst, b, h) do { _Pragma("unroll") for (int m = 0; m < 4; ++m) _Pragma("unroll") for (int k = 0; k < 2; ++k) dst[m][k] = *(const PG8_LAS bf16x8*)(lds + PG8_SA(b, h) + aoff + m * 2048 + k * 1024); } while (0)
; #define PG8_BAR __builtin_amdgcn_s_barrier()
;     __device__ __forceinline__ void operator()(const f32x4 (&acc)[2][2][4][2], const Unit& u, int wr, int wc, int fr, int fq) const {
;     ...
;         if (mode == 1) { if (u.pn >= 8 && u.pn < 12) act = 1; else if (u.pn >= 12) { act = 3; bias = (u.pn >= 14) ? bias_b + (u.pn - 14) * 256 : bias_f + (u.pn - 12) * 256; } }
;         else if (mode == 2) { if (u.pn >= 6) act = 2; }
;         const int row0 = u.pm * BM + wr * 64 + fr, col0 = u.pn * BM + wc * 32 + 8 * fq, bcol0 = wc * 32 + 8 * fq;
;         f32x4 bv[2][2];
; #pragma unroll
;         for (int bj = 0; bj < 2; ++bj)
; #pragma unroll
;             for (int n = 0; n < 2; ++n) bv[bj][n] = bias ? *(const f32x4*)(bias + bcol0 + bj * HALF + 4 * n) : (f32x4){0.f, 0.f, 0.f, 0.f};
; #pragma unroll
;         for (int ai = 0; ai < 2; ++ai)
; #pragma unroll
;             for (int m = 0; m < 4; ++m) { bf16_t* rowp = O + (size_t)(row0 + ai * HALF + m * 16) * ldc + col0;
; #pragma unroll
;                 for (int bj = 0; bj < 2; ++bj) { f32x4 v0 = acc[ai][bj][m][0] + bv[bj][0], v1 = acc[ai][bj][m][1] + bv[bj][1];
;                     if (act == 1) {
; #pragma unroll
;                         for (int j = 0; j < 1; ++j) { v0 = v0 * sigmoid4(v0); v1 = v1 * sigmoid4(v1); } }
;                     else if (act == 2) {
; #pragma unroll
;                         for (int j = 0; j < 1; ++j) { v0 = sigmoid4(v0); v1 = sigmoid4(v1); } }
; template <class Epi, class Sched>
; __device__ __forceinline__ void gemm_phase(PG8_LAS unsigned char* lds, const Gemm g, const Sched& S, const Epi& E) {
;     ...
;             PG8_LDA(At, 1, 1); PG8_STAGE(PG8_SA(1, 0), a3, voffA);
;             PG8_BAR; PG8_WAIT_L(0); PG8_MMA(1, 0, At, B0); PG8_BAR; PG8_SCHED;
;             PG8_STAGE(PG8_SB(1, 1), b3 + hstep, voffB);
;             PG8_WAIT_V(6); PG8_BAR; PG8_MMA(1, 1, At, B1); PG8_BAR;
;         }
	ds_read_b128 v[170:173], v153 offset:49152
	ds_read_b128 v[182:185], v153 offset:50176
	ds_read_b128 v[190:193], v153 offset:51200
	ds_read_b128 v[194:197], v153 offset:52224
	ds_read_b128 v[198:201], v153 offset:53248
	ds_read_b128 v[202:205], v153 offset:54272
	ds_read_b128 v[206:209], v153 offset:55296
	ds_read_b128 v[210:213], v153 offset:56320
	s_add_i32 s23, s49, s30
	v_lshl_add_u64 v[174:175], v[174:175], 0, s[6:7]
	s_mov_b32 m0, s23
	s_nop 0
	global_load_lds_dwordx4 v[174:175], off
	v_lshl_add_u64 v[174:175], v[186:187], 0, s[6:7]
	s_add_i32 m0, s23, 0x2000
	s_nop 0
	global_load_lds_dwordx4 v[174:175], off
	s_mov_b32 m0, s37
	v_lshl_add_u64 v[174:175], v[230:231], 0, s[6:7]
	global_load_lds_dwordx4 v[174:175], off
	v_lshl_add_u64 v[174:175], v[232:233], 0, s[6:7]
	s_mov_b32 m0, s38
	s_nop 0
	global_load_lds_dwordx4 v[174:175], off
	s_add_u32 s20, s20, 0x40080
	s_addc_u32 s21, s21, 0
	s_add_i32 s22, s22, s30
	v_lshl_add_u64 v[246:247], s[20:21], 0, v[130:131]
	s_mov_b32 m0, s22
	s_nop 0
	global_load_lds_dwordx4 v[246:247], off
	v_lshl_add_u64 v[246:247], s[20:21], 0, v[134:135]
	s_add_i32 m0, s22, 0x2000
	s_nop 0
	global_load_lds_dwordx4 v[246:247], off
	s_waitcnt vmcnt(8) lgkmcnt(0)
	s_barrier
	v_mfma_f32_16x16x32_bf16 v[60:63], v[144:147], v[170:173], v[60:63]
	v_mfma_f32_16x16x32_bf16 v[56:59], v[160:163], v[170:173], v[56:59]
	v_mfma_f32_16x16x32_bf16 v[44:47], v[144:147], v[190:193], v[44:47]
	v_mfma_f32_16x16x32_bf16 v[40:43], v[160:163], v[190:193], v[40:43]
	v_mfma_f32_16x16x32_bf16 v[28:31], v[144:147], v[198:201], v[28:31]
	v_mfma_f32_16x16x32_bf16 v[24:27], v[160:163], v[198:201], v[24:27]
	v_mfma_f32_16x16x32_bf16 v[12:15], v[144:147], v[206:209], v[12:15]
	v_mfma_f32_16x16x32_bf16 v[8:11], v[160:163], v[206:209], v[8:11]
	v_mfma_f32_16x16x32_bf16 v[60:63], v[156:159], v[182:185], v[60:63]
	v_mfma_f32_16x16x32_bf16 v[56:59], v[166:169], v[182:185], v[56:59]
	v_mfma_f32_16x16x32_bf16 v[44:47], v[156:159], v[194:197], v[44:47]
	v_mfma_f32_16x16x32_bf16 v[40:43], v[166:169], v[194:197], v[40:43]
	v_mfma_f32_16x16x32_bf16 v[28:31], v[156:159], v[202:205], v[28:31]
	v_mfma_f32_16x16x32_bf16 v[24:27], v[166:169], v[202:205], v[24:27]
	v_mfma_f32_16x16x32_bf16 v[12:15], v[156:159], v[210:213], v[12:15]
	v_mfma_f32_16x16x32_bf16 v[8:11], v[166:169], v[210:213], v[8:11]
	v_mfma_f32_16x16x32_bf16 v[52:55], v[214:217], v[170:173], v[52:55]
	v_mfma_f32_16x16x32_bf16 v[48:51], v[222:225], v[170:173], v[48:51]
	v_mfma_f32_16x16x32_bf16 v[36:39], v[214:217], v[190:193], v[36:39]
	v_mfma_f32_16x16x32_bf16 v[32:35], v[222:225], v[190:193], v[32:35]
	v_mfma_f32_16x16x32_bf16 v[20:23], v[214:217], v[198:201], v[20:23]
	v_mfma_f32_16x16x32_bf16 v[16:19], v[222:225], v[198:201], v[16:19]
	v_mfma_f32_16x16x32_bf16 v[4:7], v[214:217], v[206:209], v[4:7]
	v_mfma_f32_16x16x32_bf16 v[0:3], v[222:225], v[206:209], v[0:3]
	v_mfma_f32_16x16x32_bf16 v[52:55], v[218:221], v[182:185], v[52:55]
	v_mfma_f32_16x16x32_bf16 v[48:51], v[226:229], v[182:185], v[48:51]
	v_mfma_f32_16x16x32_bf16 v[36:39], v[218:221], v[194:197], v[36:39]
	v_mfma_f32_16x16x32_bf16 v[32:35], v[226:229], v[194:197], v[32:35]
	v_mfma_f32_16x16x32_bf16 v[20:23], v[218:221], v[202:205], v[20:23]
	v_mfma_f32_16x16x32_bf16 v[16:19], v[226:229], v[202:205], v[16:19]
	v_mfma_f32_16x16x32_bf16 v[4:7], v[218:221], v[210:213], v[4:7]
	v_mfma_f32_16x16x32_bf16 v[0:3], v[226:229], v[210:213], v[0:3]
	s_barrier
	s_add_i32 s48, s48, 2
	s_add_u32 s18, s18, 0x100
	s_addc_u32 s19, s19, 0
	s_add_u32 s46, s46, 0x100
	s_addc_u32 s47, s47, 0
	s_cmp_gt_u32 s48, 13
	s_cbranch_scc0 .LBB0_724
	s_cmp_gt_i32 s4, 5
	s_cselect_b64 s[18:19], -1, 0
	s_cmp_lt_i32 s4, 6
	v_pk_add_f32 v[144:145], v[126:127], 0 op_sel_hi:[1,0]
	v_pk_add_f32 v[146:147], v[124:125], 0 op_sel_hi:[1,0]
	v_pk_add_f32 v[124:125], v[122:123], 0 op_sel_hi:[1,0]
	v_pk_add_f32 v[126:127], v[120:121], 0 op_sel_hi:[1,0]
	s_cbranch_scc1 .LBB0_727
	v_max_f32_e32 v122, v144, v144
	v_max_f32_e32 v122, 0xc1a00000, v122
	v_mul_f32_e32 v122, 0xbfb8aa3b, v122
	v_max_f32_e32 v120, v146, v146
	v_max_f32_e32 v121, v147, v147
	v_exp_f32_e32 v123, v122
	v_max_f32_e32 v122, v145, v145
	v_max_f32_e32 v120, 0xc1a00000, v120
	v_max_f32_e32 v121, 0xc1a00000, v121
	v_max_f32_e32 v122, 0xc1a00000, v122
	v_mul_f32_e32 v120, 0xbfb8aa3b, v120
	v_mul_f32_e32 v121, 0xbfb8aa3b, v121
	v_mul_f32_e32 v122, 0xbfb8aa3b, v122
	v_exp_f32_e32 v120, v120
	v_exp_f32_e32 v121, v121
	v_exp_f32_e32 v122, v122
	v_max_f32_e32 v124, v124, v124
	v_max_f32_e32 v124, 0xc1a00000, v124
	v_pk_add_f32 v[120:121], v[120:121], 1.0 op_sel_hi:[1,0]
	v_pk_add_f32 v[122:123], v[122:123], 1.0 op_sel_hi:[1,0]
	v_mov_b32_e32 v144, v120
	v_mov_b32_e32 v145, v123
	v_pk_mov_b32 v[146:147], v[120:121], v[122:123] op_sel:[1,0]
	v_mul_f32_e32 v124, 0xbfb8aa3b, v124
	v_pk_mul_f32 v[144:145], v[144:145], v[146:147]
	v_max_f32_e32 v126, v126, v126
	v_max_f32_e32 v127, v127, v127
	v_exp_f32_e32 v147, v124
	v_max_f32_e32 v124, v125, v125
	v_max_f32_e32 v126, 0xc1a00000, v126
	v_max_f32_e32 v127, 0xc1a00000, v127
	v_max_f32_e32 v124, 0xc1a00000, v124
	v_mul_f32_e32 v146, v144, v145
	v_mul_f32_e32 v126, 0xbfb8aa3b, v126
	v_mul_f32_e32 v127, 0xbfb8aa3b, v127
	v_mul_f32_e32 v124, 0xbfb8aa3b, v124
	v_rcp_f32_e32 v155, v146
	v_exp_f32_e32 v126, v126
	v_exp_f32_e32 v127, v127
	v_exp_f32_e32 v146, v124
	v_mul_f32_e32 v124, v145, v155
	v_mul_f32_e32 v144, v144, v155
	v_pk_add_f32 v[126:127], v[126:127], 1.0 op_sel_hi:[1,0]
	v_pk_add_f32 v[156:157], v[146:147], 1.0 op_sel_hi:[1,0]
	v_mov_b32_e32 v146, v126
	v_mov_b32_e32 v147, v157
	v_pk_mov_b32 v[158:159], v[126:127], v[156:157] op_sel:[1,0]
	v_pk_mul_f32 v[144:145], v[122:123], v[144:145] op_sel_hi:[1,0]
	v_pk_mul_f32 v[158:159], v[146:147], v[158:159]
	s_nop 0
	v_mul_f32_e32 v125, v158, v159
	v_rcp_f32_e32 v125, v125
	s_nop 0
	v_pk_mul_f32 v[146:147], v[120:121], v[124:125] op_sel:[1,0] op_sel_hi:[0,0]
	v_mul_f32_e32 v120, v159, v125
	v_mul_f32_e32 v122, v158, v125
	v_pk_mul_f32 v[124:125], v[156:157], v[122:123] op_sel_hi:[1,0]
	v_pk_mul_f32 v[126:127], v[126:127], v[120:121] op_sel:[1,0] op_sel_hi:[0,0]

; #define PG8_STAGE(bufoff, gbase, voff) do { _Pragma("unroll") for (int _i = 0; _i < 2; ++_i) \
;         __builtin_amdgcn_global_load_lds((const unsigned*)((const char*)(gbase) + (voff)[_i]), (PG8_LAS unsigned*)(lds + (bufoff) + ldsw + _i * 8192), 16, 0, 0); } while (0)
; #define PG8_LDA(dst, b, h) do { _Pragma("unroll") for (int m = 0; m < 4; ++m) _Pragma("unroll") for (int k = 0; k < 2; ++k) dst[m][k] = *(const PG8_LAS bf16x8*)(lds + PG8_SA(b, h) + aoff + m * 2048 + k * 1024); } while (0)
; #define PG8_LDB(dst, b, h) do { _Pragma("unroll") for (int n = 0; n < 2; ++n) _Pragma("unroll") for (int k = 0; k < 2; ++k) dst[n][k] = *(const PG8_LAS bf16x8*)(lds + PG8_SB(b, h) + boff + n * 2048 + k * 1024); } while (0)
; #define PG8_MMA(ai, bj, At, Bt) do { __builtin_amdgcn_s_setprio(1); _Pragma("unroll") for (int m = 0; m < 4; ++m) _Pragma("unroll") for (int n = 0; n < 2; ++n) _Pragma("unroll") for (int k = 0; k < 2; ++k) \
;         acc[ai][bj][m][n] = __builtin_amdgcn_mfma_f32_16x16x32_bf16(Bt[n][k], At[m][k], acc[ai][bj][m][n], 0, 0, 0); __builtin_amdgcn_s_setprio(0); } while (0)
; #define PG8_WAIT_V(n) asm volatile("s_waitcnt vmcnt(" #n ")" ::: "memory")
; #define PG8_WAIT_L(n) asm volatile("s_waitcnt lgkmcnt(" #n ")" ::: "memory")
; template <class Epi, class Sched>
; __device__ __forceinline__ void gemm_phase(PG8_LAS unsigned char* lds, const Gemm g, const Sched& S, const Epi& E) {
;     ...
;             const bool last = (t == nt - 2);
;             const char* a1 = cA + (size_t)(t + 1) * kstep;
;             const char* a2 = last ? nA : cA + (size_t)(t + 2) * kstep; const char* b2 = last ? nB : cB + (size_t)(t + 2) * kstep;
;             const char* a3 = a2 + kstep; const char* b3 = b2 + kstep;
;             if (last && has_next) S.a_ready(nxt);
;             PG8_LDB(B0, 0, 0); PG8_SCHED; PG8_LDA(At, 0, 0); PG8_STAGE(PG8_SA(1, 1), a1 + hstep, voffA);
;             PG8_WAIT_L(8); PG8_BAR; PG8_WAIT_L(0); PG8_MMA(0, 0, At, B0); PG8_BAR; PG8_SCHED;
;             PG8_LDB(B1, 0, 1); PG8_STAGE(PG8_SB(0, 0), b2, voffB);
;             PG8_BAR; PG8_WAIT_L(0); PG8_MMA(0, 1, At, B1); PG8_BAR;
;             PG8_LDA(At, 0, 1); PG8_STAGE(PG8_SA(0, 0), a2, voffA);
;             PG8_BAR; PG8_WAIT_L(0); PG8_MMA(1, 0, At, B0); PG8_BAR; PG8_SCHED;
;             PG8_STAGE(PG8_SB(0, 1), b2 + hstep, voffB);
;             PG8_WAIT_V(6); PG8_BAR; PG8_MMA(1, 1, At, B1); PG8_BAR;
.LBB0_991:
	ds_read_b128 v[144:147], v153
	ds_read_b128 v[156:159], v153 offset:1024
	ds_read_b128 v[160:163], v153 offset:2048
	ds_read_b128 v[164:167], v153 offset:3072
	s_add_u32 s20, s18, 0xfffc0080
	s_addc_u32 s21, s19, -1
	s_cmp_eq_u32 s47, 12
	s_cselect_b32 s23, s11, s21
	s_cselect_b32 s22, s43, s20
	s_cselect_b32 s21, s9, s46
	s_cselect_b32 s20, s44, s45
	v_lshl_add_u64 v[148:149], s[18:19], 0, v[136:137]
	s_add_i32 m0, s17, 0xc000
	ds_read_b128 v[168:171], v154
	ds_read_b128 v[172:175], v154 offset:1024
	ds_read_b128 v[182:185], v154 offset:2048
	ds_read_b128 v[190:193], v154 offset:3072
	ds_read_b128 v[194:197], v154 offset:4096
	ds_read_b128 v[198:201], v154 offset:5120
	ds_read_b128 v[202:205], v154 offset:6144
	ds_read_b128 v[206:209], v154 offset:7168
	global_load_lds_dwordx4 v[148:149], off
	v_lshl_add_u64 v[148:149], s[18:19], 0, v[138:139]
	s_add_i32 m0, s17, 0xe000
	s_nop 0
	global_load_lds_dwordx4 v[148:149], off
	ds_read_b128 v[210:213], v155
	ds_read_b128 v[214:217], v155 offset:1024
	ds_read_b128 v[218:221], v155 offset:2048
	ds_read_b128 v[222:225], v155 offset:3072
	s_waitcnt vmcnt(8) lgkmcnt(0)
	s_barrier
	v_mfma_f32_16x16x32_bf16 v[124:127], v[144:147], v[168:171], v[124:127]
	v_mfma_f32_16x16x32_bf16 v[120:123], v[160:163], v[168:171], v[120:123]
	v_mfma_f32_16x16x32_bf16 v[112:115], v[144:147], v[182:185], v[112:115]
	v_mfma_f32_16x16x32_bf16 v[104:107], v[160:163], v[182:185], v[104:107]
	v_mfma_f32_16x16x32_bf16 v[96:99], v[144:147], v[194:197], v[96:99]
	v_mfma_f32_16x16x32_bf16 v[88:91], v[160:163], v[194:197], v[88:91]
	v_mfma_f32_16x16x32_bf16 v[80:83], v[144:147], v[202:205], v[80:83]
	v_mfma_f32_16x16x32_bf16 v[72:75], v[160:163], v[202:205], v[72:75]
	v_mfma_f32_16x16x32_bf16 v[124:127], v[156:159], v[172:175], v[124:127]
	v_mfma_f32_16x16x32_bf16 v[120:123], v[164:167], v[172:175], v[120:123]
	v_mfma_f32_16x16x32_bf16 v[112:115], v[156:159], v[190:193], v[112:115]
	v_mfma_f32_16x16x32_bf16 v[104:107], v[164:167], v[190:193], v[104:107]
	v_mfma_f32_16x16x32_bf16 v[96:99], v[156:159], v[198:201], v[96:99]
	v_mfma_f32_16x16x32_bf16 v[88:91], v[164:167], v[198:201], v[88:91]
	v_mfma_f32_16x16x32_bf16 v[80:83], v[156:159], v[206:209], v[80:83]
	v_mfma_f32_16x16x32_bf16 v[72:75], v[164:167], v[206:209], v[72:75]
	v_mfma_f32_16x16x32_bf16 v[116:119], v[210:213], v[168:171], v[116:119]
	v_mfma_f32_16x16x32_bf16 v[108:111], v[218:221], v[168:171], v[108:111]
	v_mfma_f32_16x16x32_bf16 v[100:103], v[210:213], v[182:185], v[100:103]
	v_mfma_f32_16x16x32_bf16 v[92:95], v[218:221], v[182:185], v[92:95]
	v_mfma_f32_16x16x32_bf16 v[84:87], v[210:213], v[194:197], v[84:87]
	v_mfma_f32_16x16x32_bf16 v[76:79], v[218:221], v[194:197], v[76:79]
	v_mfma_f32_16x16x32_bf16 v[68:71], v[210:213], v[202:205], v[68:71]
	v_mfma_f32_16x16x32_bf16 v[64:67], v[218:221], v[202:205], v[64:67]
	v_mfma_f32_16x16x32_bf16 v[116:119], v[214:217], v[172:175], v[116:119]
	v_mfma_f32_16x16x32_bf16 v[108:111], v[222:225], v[172:175], v[108:111]
	v_mfma_f32_16x16x32_bf16 v[100:103], v[214:217], v[190:193], v[100:103]
	v_mfma_f32_16x16x32_bf16 v[92:95], v[222:225], v[190:193], v[92:95]
	v_mfma_f32_16x16x32_bf16 v[84:87], v[214:217], v[198:201], v[84:87]
	v_mfma_f32_16x16x32_bf16 v[76:79], v[222:225], v[198:201], v[76:79]
	v_mfma_f32_16x16x32_bf16 v[68:71], v[214:217], v[206:209], v[68:71]
	v_mfma_f32_16x16x32_bf16 v[64:67], v[222:225], v[206:209], v[64:67]
	s_barrier
	ds_read_b128 v[168:171], v154 offset:16384
	ds_read_b128 v[172:175], v154 offset:17408
	ds_read_b128 v[182:185], v154 offset:18432
	ds_read_b128 v[190:193], v154 offset:19456
	ds_read_b128 v[194:197], v154 offset:20480
	ds_read_b128 v[198:201], v154 offset:21504
	ds_read_b128 v[202:205], v154 offset:22528
	ds_read_b128 v[206:209], v154 offset:23552
	s_add_i32 s48, s39, s29
	v_lshl_add_u64 v[148:149], s[20:21], 0, v[130:131]
	s_mov_b32 m0, s48
	s_nop 0
	global_load_lds_dwordx4 v[148:149], off
	v_lshl_add_u64 v[186:187], s[20:21], 0, v[134:135]
	s_add_i32 m0, s48, 0x2000
	s_nop 0
	global_load_lds_dwordx4 v[186:187], off
	s_mov_b32 m0, s17
	v_lshl_add_u64 v[226:227], s[22:23], 0, v[128:129]
	global_load_lds_dwordx4 v[226:227], off
	v_lshl_add_u64 v[228:229], s[22:23], 0, v[132:133]
	s_mov_b32 m0, s30
	s_nop 0
	global_load_lds_dwordx4 v[228:229], off
	s_add_u32 s48, s20, 0x40000
	s_addc_u32 s49, s21, 0
	s_add_i32 s50, s40, s29
	v_lshl_add_u64 v[246:247], s[48:49], 0, v[130:131]
	s_mov_b32 m0, s50
	s_nop 0
	global_load_lds_dwordx4 v[246:247], off
	v_lshl_add_u64 v[246:247], s[48:49], 0, v[134:135]
	s_add_i32 m0, s50, 0x2000
	s_nop 0
	global_load_lds_dwordx4 v[246:247], off
	s_waitcnt vmcnt(8) lgkmcnt(0)
	s_barrier
; #define PG8_STAGE(bufoff, gbase, voff) do { _Pragma("unroll") for (int _i = 0; _i < 2; ++_i) \
;         __builtin_amdgcn_global_load_lds((const unsigned*)((const char*)(gbase) + (voff)[_i]), (PG8_LAS unsigned*)(lds + (bufoff) + ldsw + _i * 8192), 16, 0, 0); } while (0)
; #define PG8_LDA(dst, b, h) do { _Pragma("unroll") for (int m = 0; m < 4; ++m) _Pragma("unroll") for (int k = 0; k < 2; ++k) dst[m][k] = *(const PG8_LAS bf16x8*)(lds + PG8_SA(b, h) + aoff + m * 2048 + k * 1024); } while (0)
; #define PG8_LDB(dst, b, h) do { _Pragma("unroll") for (int n = 0; n < 2; ++n) _Pragma("unroll") for (int k = 0; k < 2; ++k) dst[n][k] = *(const PG8_LAS bf16x8*)(lds + PG8_SB(b, h) + boff + n * 2048 + k * 1024); } while (0)
; #define PG8_MMA(ai, bj, At, Bt) do { __builtin_amdgcn_s_setprio(1); _Pragma("unroll") for (int m = 0; m < 4; ++m) _Pragma("unroll") for (int n = 0; n < 2; ++n) _Pragma("unroll") for (int k = 0; k < 2; ++k) \
;         acc[ai][bj][m][n] = __builtin_amdgcn_mfma_f32_16x16x32_bf16(Bt[n][k], At[m][k], acc[ai][bj][m][n], 0, 0, 0); __builtin_amdgcn_s_setprio(0); } while (0)
; #define PG8_WAIT_V(n) asm volatile("s_waitcnt vmcnt(" #n ")" ::: "memory")
; #define PG8_WAIT_L(n) asm volatile("s_waitcnt lgkmcnt(" #n ")" ::: "memory")
; #define PG8_BAR __builtin_amdgcn_s_barrier()
; #define PG8_SCHED __builtin_amdgcn_sched_barrier(0)
; template <class Epi, class Sched>
; __device__ __forceinline__ void gemm_phase(PG8_LAS unsigned char* lds, const Gemm g, const Sched& S, const Epi& E) {
;     ...
;             PG8_BAR; PG8_WAIT_L(0); PG8_MMA(1, 0, At, B0); PG8_BAR; PG8_SCHED;
;             PG8_STAGE(PG8_SB(0, 1), b2 + hstep, voffB);
;             PG8_WAIT_V(6); PG8_BAR; PG8_MMA(1, 1, At, B1); PG8_BAR;
;             PG8_LDB(B0, 1, 0); PG8_SCHED; PG8_LDA(At, 1, 0); PG8_STAGE(PG8_SA(0, 1), a2 + hstep, voffA);
;             PG8_WAIT_L(8); PG8_BAR; PG8_WAIT_L(0); PG8_MMA(0, 0, At, B0); PG8_BAR; PG8_SCHED;
;             PG8_LDB(B1, 1, 1); PG8_STAGE(PG8_SB(1, 0), b3, voffB);
;             PG8_BAR; PG8_WAIT_L(0); PG8_MMA(0, 1, At, B1); PG8_BAR;
	v_mfma_f32_16x16x32_bf16 v[60:63], v[144:147], v[168:171], v[60:63]
	v_mfma_f32_16x16x32_bf16 v[56:59], v[160:163], v[168:171], v[56:59]
	v_mfma_f32_16x16x32_bf16 v[48:51], v[144:147], v[182:185], v[48:51]
	v_mfma_f32_16x16x32_bf16 v[40:43], v[160:163], v[182:185], v[40:43]
	v_mfma_f32_16x16x32_bf16 v[32:35], v[144:147], v[194:197], v[32:35]
	v_mfma_f32_16x16x32_bf16 v[24:27], v[160:163], v[194:197], v[24:27]
	v_mfma_f32_16x16x32_bf16 v[16:19], v[144:147], v[202:205], v[16:19]
	v_mfma_f32_16x16x32_bf16 v[8:11], v[160:163], v[202:205], v[8:11]
	v_mfma_f32_16x16x32_bf16 v[60:63], v[156:159], v[172:175], v[60:63]
	v_mfma_f32_16x16x32_bf16 v[56:59], v[164:167], v[172:175], v[56:59]
	v_mfma_f32_16x16x32_bf16 v[48:51], v[156:159], v[190:193], v[48:51]
	v_mfma_f32_16x16x32_bf16 v[40:43], v[164:167], v[190:193], v[40:43]
	v_mfma_f32_16x16x32_bf16 v[32:35], v[156:159], v[198:201], v[32:35]
	v_mfma_f32_16x16x32_bf16 v[24:27], v[164:167], v[198:201], v[24:27]
	v_mfma_f32_16x16x32_bf16 v[16:19], v[156:159], v[206:209], v[16:19]
	v_mfma_f32_16x16x32_bf16 v[8:11], v[164:167], v[206:209], v[8:11]
	v_mfma_f32_16x16x32_bf16 v[52:55], v[210:213], v[168:171], v[52:55]
	v_mfma_f32_16x16x32_bf16 v[44:47], v[218:221], v[168:171], v[44:47]
	v_mfma_f32_16x16x32_bf16 v[36:39], v[210:213], v[182:185], v[36:39]
	v_mfma_f32_16x16x32_bf16 v[28:31], v[218:221], v[182:185], v[28:31]
	v_mfma_f32_16x16x32_bf16 v[20:23], v[210:213], v[194:197], v[20:23]
	v_mfma_f32_16x16x32_bf16 v[12:15], v[218:221], v[194:197], v[12:15]
	v_mfma_f32_16x16x32_bf16 v[4:7], v[210:213], v[202:205], v[4:7]
	v_mfma_f32_16x16x32_bf16 v[0:3], v[218:221], v[202:205], v[0:3]
	v_mfma_f32_16x16x32_bf16 v[52:55], v[214:217], v[172:175], v[52:55]
	v_mfma_f32_16x16x32_bf16 v[44:47], v[222:225], v[172:175], v[44:47]
	v_mfma_f32_16x16x32_bf16 v[36:39], v[214:217], v[190:193], v[36:39]
	v_mfma_f32_16x16x32_bf16 v[28:31], v[222:225], v[190:193], v[28:31]
	v_mfma_f32_16x16x32_bf16 v[20:23], v[214:217], v[198:201], v[20:23]
	v_mfma_f32_16x16x32_bf16 v[12:15], v[222:225], v[198:201], v[12:15]
	v_mfma_f32_16x16x32_bf16 v[4:7], v[214:217], v[206:209], v[4:7]
	v_mfma_f32_16x16x32_bf16 v[0:3], v[222:225], v[206:209], v[0:3]
	s_barrier
	s_add_i32 s48, 0, 0x18000
	v_add_u32_e32 v164, s48, v151
	ds_read_b128 v[144:147], v164
	ds_read_b128 v[156:159], v164 offset:1024
	ds_read_b128 v[160:163], v164 offset:2048
	ds_read_b128 v[164:167], v164 offset:3072
	s_add_u32 s22, s22, 0x40000
	s_addc_u32 s23, s23, 0
	s_mov_b32 m0, s31
	v_lshl_add_u64 v[210:211], s[22:23], 0, v[128:129]
	ds_read_b128 v[168:171], v154 offset:32768
	ds_read_b128 v[172:175], v154 offset:33792
	ds_read_b128 v[182:185], v154 offset:34816
	ds_read_b128 v[190:193], v154 offset:35840
	ds_read_b128 v[194:197], v154 offset:36864
	ds_read_b128 v[198:201], v154 offset:37888
	ds_read_b128 v[202:205], v154 offset:38912
	ds_read_b128 v[206:209], v154 offset:39936
	global_load_lds_dwordx4 v[210:211], off
	v_lshl_add_u64 v[210:211], s[22:23], 0, v[132:133]
	s_mov_b32 m0, s34
	s_nop 0
	global_load_lds_dwordx4 v[210:211], off
	s_add_i32 s22, 0, 0x1c000
	v_add_u32_e32 v179, s22, v151
	ds_read_b128 v[210:213], v179
	ds_read_b128 v[214:217], v179 offset:1024
	ds_read_b128 v[218:221], v179 offset:2048
	ds_read_b128 v[222:225], v179 offset:3072
	s_waitcnt vmcnt(8) lgkmcnt(0)
	s_barrier
	v_mfma_f32_16x16x32_bf16 v[124:127], v[144:147], v[168:171], v[124:127]
	v_mfma_f32_16x16x32_bf16 v[120:123], v[160:163], v[168:171], v[120:123]
	v_mfma_f32_16x16x32_bf16 v[112:115], v[144:147], v[182:185], v[112:115]
	v_mfma_f32_16x16x32_bf16 v[104:107], v[160:163], v[182:185], v[104:107]
	v_mfma_f32_16x16x32_bf16 v[96:99], v[144:147], v[194:197], v[96:99]
	v_mfma_f32_16x16x32_bf16 v[88:91], v[160:163], v[194:197], v[88:91]
	v_mfma_f32_16x16x32_bf16 v[80:83], v[144:147], v[202:205], v[80:83]
	v_mfma_f32_16x16x32_bf16 v[72:75], v[160:163], v[202:205], v[72:75]
	v_mfma_f32_16x16x32_bf16 v[124:127], v[156:159], v[172:175], v[124:127]
	v_mfma_f32_16x16x32_bf16 v[120:123], v[164:167], v[172:175], v[120:123]
	v_mfma_f32_16x16x32_bf16 v[112:115], v[156:159], v[190:193], v[112:115]
	v_mfma_f32_16x16x32_bf16 v[104:107], v[164:167], v[190:193], v[104:107]
	v_mfma_f32_16x16x32_bf16 v[96:99], v[156:159], v[198:201], v[96:99]
	v_mfma_f32_16x16x32_bf16 v[88:91], v[164:167], v[198:201], v[88:91]
	v_mfma_f32_16x16x32_bf16 v[80:83], v[156:159], v[206:209], v[80:83]
	v_mfma_f32_16x16x32_bf16 v[72:75], v[164:167], v[206:209], v[72:75]
	v_mfma_f32_16x16x32_bf16 v[116:119], v[210:213], v[168:171], v[116:119]
	v_mfma_f32_16x16x32_bf16 v[108:111], v[218:221], v[168:171], v[108:111]
	v_mfma_f32_16x16x32_bf16 v[100:103], v[210:213], v[182:185], v[100:103]
	v_mfma_f32_16x16x32_bf16 v[92:95], v[218:221], v[182:185], v[92:95]
	v_mfma_f32_16x16x32_bf16 v[84:87], v[210:213], v[194:197], v[84:87]
	v_mfma_f32_16x16x32_bf16 v[76:79], v[218:221], v[194:197], v[76:79]
	v_mfma_f32_16x16x32_bf16 v[68:71], v[210:213], v[202:205], v[68:71]
	v_mfma_f32_16x16x32_bf16 v[64:67], v[218:221], v[202:205], v[64:67]
	v_mfma_f32_16x16x32_bf16 v[116:119], v[214:217], v[172:175], v[116:119]
	v_mfma_f32_16x16x32_bf16 v[108:111], v[222:225], v[172:175], v[108:111]
	v_mfma_f32_16x16x32_bf16 v[100:103], v[214:217], v[190:193], v[100:103]
	v_mfma_f32_16x16x32_bf16 v[92:95], v[222:225], v[190:193], v[92:95]
	v_mfma_f32_16x16x32_bf16 v[84:87], v[214:217], v[198:201], v[84:87]
	v_mfma_f32_16x16x32_bf16 v[76:79], v[222:225], v[198:201], v[76:79]
	v_mfma_f32_16x16x32_bf16 v[68:71], v[214:217], v[206:209], v[68:71]
	v_mfma_f32_16x16x32_bf16 v[64:67], v[222:225], v[206:209], v[64:67]
	s_barrier
; __device__ __forceinline__ unsigned cvt_pk_bf16(float lo, float hi) { unsigned r; asm volatile("v_cvt_pk_bf16_f32 %0, %1, %2" : "=v"(r) : "v"(lo), "v"(hi)); return r; }
; __device__ __forceinline__ float bf_lo(unsigned u) { return __uint_as_float(u << 16); }
; __device__ __forceinline__ float bf_hi(unsigned u) { return __uint_as_float(u & 0xffff0000u); }
; #define PG8_WAIT_V(n) asm volatile("s_waitcnt vmcnt(" #n ")" ::: "memory")
; #define PG8_WAIT_L(n) asm volatile("s_waitcnt lgkmcnt(" #n ")" ::: "memory")
;     __device__ __forceinline__ void operator()(const f32x4 (&acc)[2][2][4][2], const Unit& u, int wr, int wc, int fr, int fq) const {
;         const int row0 = u.pm * BM + wr * 64 + fr, col0 = u.pn * BM + wc * 32 + 8 * fq;
; #pragma unroll
;         for (int ai = 0; ai < 2; ++ai)
; #pragma unroll
;             for (int m = 0; m < 4; ++m) { const size_t r = (size_t)(row0 + ai * HALF + m * 16); bf16_t* rowp = O + r * ldc + col0; const bf16_t* gp = G + r * ldg + col0;
; #pragma unroll
;                 for (int bj = 0; bj < 2; ++bj) { const u32x4 gw = *(const u32x4*)(gp + bj * HALF);
;                     f32x4 v0 = acc[ai][bj][m][0], v1 = acc[ai][bj][m][1];
;                     v0[0] *= bf_lo(gw.x); v0[1] *= bf_hi(gw.x); v0[2] *= bf_lo(gw.y); v0[3] *= bf_hi(gw.y);
;                     v1[0] *= bf_lo(gw.z); v1[1] *= bf_hi(gw.z); v1[2] *= bf_lo(gw.w); v1[3] *= bf_hi(gw.w);
;                     if (ACCUM) { const u32x4 pw = *(const u32x4*)(rowp + bj * HALF);
;                         v0[0] += bf_lo(pw.x); v0[1] += bf_hi(pw.x); v0[2] += bf_lo(pw.y); v0[3] += bf_hi(pw.y);
;                         v1[0] += bf_lo(pw.z); v1[1] += bf_hi(pw.z); v1[2] += bf_lo(pw.w); v1[3] += bf_hi(pw.w); }
;                     u32x4 w; w.x = cvt_pk_bf16(v0[0], v0[1]); w.y = cvt_pk_bf16(v0[2], v0[3]); w.z = cvt_pk_bf16(v1[0], v1[1]); w.w = cvt_pk_bf16(v1[2], v1[3]);
;                     *(u32x4*)(rowp + bj * HALF) = w; } }
; template <class Epi, class Sched>
; __device__ __forceinline__ void gemm_phase(PG8_LAS unsigned char* lds, const Gemm g, const Sched& S, const Epi& E) {
;     ...
;             PG8_LDA(At, 1, 1); PG8_STAGE(PG8_SA(1, 0), a3, voffA);
;             PG8_BAR; PG8_WAIT_L(0); PG8_MMA(1, 0, At, B0); PG8_BAR; PG8_SCHED;
;             PG8_STAGE(PG8_SB(1, 1), b3 + hstep, voffB);
;             PG8_WAIT_V(6); PG8_BAR; PG8_MMA(1, 1, At, B1); PG8_BAR;
	ds_read_b128 v[168:171], v154 offset:49152
	ds_read_b128 v[172:175], v154 offset:50176
	ds_read_b128 v[182:185], v154 offset:51200
	ds_read_b128 v[190:193], v154 offset:52224
	ds_read_b128 v[194:197], v154 offset:53248
	ds_read_b128 v[198:201], v154 offset:54272
	ds_read_b128 v[202:205], v154 offset:55296
	ds_read_b128 v[206:209], v154 offset:56320
	s_add_i32 s23, s48, s29
	v_lshl_add_u64 v[148:149], v[148:149], 0, s[6:7]
	s_mov_b32 m0, s23
	s_nop 0
	global_load_lds_dwordx4 v[148:149], off
	v_lshl_add_u64 v[148:149], v[186:187], 0, s[6:7]
	s_add_i32 m0, s23, 0x2000
	s_nop 0
	global_load_lds_dwordx4 v[148:149], off
	s_mov_b32 m0, s36
	v_lshl_add_u64 v[148:149], v[226:227], 0, s[6:7]
	global_load_lds_dwordx4 v[148:149], off
	v_lshl_add_u64 v[148:149], v[228:229], 0, s[6:7]
	s_mov_b32 m0, s37
	s_nop 0
	global_load_lds_dwordx4 v[148:149], off
	s_add_u32 s20, s20, 0x40080
	s_addc_u32 s21, s21, 0
	s_add_i32 s22, s22, s29
	v_lshl_add_u64 v[246:247], s[20:21], 0, v[130:131]
	s_mov_b32 m0, s22
	s_nop 0
	global_load_lds_dwordx4 v[246:247], off
	v_lshl_add_u64 v[246:247], s[20:21], 0, v[134:135]
	s_add_i32 m0, s22, 0x2000
	s_nop 0
	global_load_lds_dwordx4 v[246:247], off
	s_waitcnt vmcnt(8) lgkmcnt(0)
	s_barrier
	v_mfma_f32_16x16x32_bf16 v[60:63], v[144:147], v[168:171], v[60:63]
	v_mfma_f32_16x16x32_bf16 v[56:59], v[160:163], v[168:171], v[56:59]
	v_mfma_f32_16x16x32_bf16 v[48:51], v[144:147], v[182:185], v[48:51]
	v_mfma_f32_16x16x32_bf16 v[40:43], v[160:163], v[182:185], v[40:43]
	v_mfma_f32_16x16x32_bf16 v[32:35], v[144:147], v[194:197], v[32:35]
	v_mfma_f32_16x16x32_bf16 v[24:27], v[160:163], v[194:197], v[24:27]
	v_mfma_f32_16x16x32_bf16 v[16:19], v[144:147], v[202:205], v[16:19]
	v_mfma_f32_16x16x32_bf16 v[8:11], v[160:163], v[202:205], v[8:11]
	v_mfma_f32_16x16x32_bf16 v[60:63], v[156:159], v[172:175], v[60:63]
	v_mfma_f32_16x16x32_bf16 v[56:59], v[164:167], v[172:175], v[56:59]
	v_mfma_f32_16x16x32_bf16 v[48:51], v[156:159], v[190:193], v[48:51]
	v_mfma_f32_16x16x32_bf16 v[40:43], v[164:167], v[190:193], v[40:43]
	v_mfma_f32_16x16x32_bf16 v[32:35], v[156:159], v[198:201], v[32:35]
	v_mfma_f32_16x16x32_bf16 v[24:27], v[164:167], v[198:201], v[24:27]
	v_mfma_f32_16x16x32_bf16 v[16:19], v[156:159], v[206:209], v[16:19]
	v_mfma_f32_16x16x32_bf16 v[8:11], v[164:167], v[206:209], v[8:11]
	v_mfma_f32_16x16x32_bf16 v[52:55], v[210:213], v[168:171], v[52:55]
	v_mfma_f32_16x16x32_bf16 v[44:47], v[218:221], v[168:171], v[44:47]
	v_mfma_f32_16x16x32_bf16 v[36:39], v[210:213], v[182:185], v[36:39]
	v_mfma_f32_16x16x32_bf16 v[28:31], v[218:221], v[182:185], v[28:31]
	v_mfma_f32_16x16x32_bf16 v[20:23], v[210:213], v[194:197], v[20:23]
	v_mfma_f32_16x16x32_bf16 v[12:15], v[218:221], v[194:197], v[12:15]
	v_mfma_f32_16x16x32_bf16 v[4:7], v[210:213], v[202:205], v[4:7]
	v_mfma_f32_16x16x32_bf16 v[0:3], v[218:221], v[202:205], v[0:3]
	v_mfma_f32_16x16x32_bf16 v[52:55], v[214:217], v[172:175], v[52:55]
	v_mfma_f32_16x16x32_bf16 v[44:47], v[222:225], v[172:175], v[44:47]
	v_mfma_f32_16x16x32_bf16 v[36:39], v[214:217], v[190:193], v[36:39]
	v_mfma_f32_16x16x32_bf16 v[28:31], v[222:225], v[190:193], v[28:31]
	v_mfma_f32_16x16x32_bf16 v[20:23], v[214:217], v[198:201], v[20:23]
	v_mfma_f32_16x16x32_bf16 v[12:15], v[222:225], v[198:201], v[12:15]
	v_mfma_f32_16x16x32_bf16 v[4:7], v[214:217], v[206:209], v[4:7]
	v_mfma_f32_16x16x32_bf16 v[0:3], v[222:225], v[206:209], v[0:3]
	s_barrier
	s_add_i32 s47, s47, 2
	s_add_u32 s18, s18, 0x100
	s_addc_u32 s19, s19, 0
	s_add_u32 s45, s45, 0x100
	s_addc_u32 s46, s46, 0
	s_cmp_gt_u32 s47, 13
	s_cbranch_scc0 .LBB0_991
	v_lshl_or_b32 v144, s42, 8, v152
	v_lshl_add_u32 v146, s16, 8, v150
	v_ashrrev_i32_e32 v145, 31, v144
	v_mov_b64_e32 v[148:149], s[4:5]
	v_lshlrev_b64 v[144:145], 1, v[144:145]
	v_mad_i64_i32 v[156:157], s[18:19], v146, s41, v[148:149]
	v_lshl_add_u64 v[160:161], v[156:157], 0, v[144:145]
	global_load_dwordx4 v[156:159], v[160:161], off offset:3072
	s_and_b64 vcc, exec, s[2:3]
	s_mov_b32 s42, s8
	s_mov_b32 s16, s10
	s_mov_b64 s[20:21], s[14:15]
	s_waitcnt vmcnt(0)
	v_lshlrev_b32_e32 v147, 16, v156
	v_and_b32_e32 v156, 0xffff0000, v156
	v_lshlrev_b32_e32 v162, 16, v157
	v_and_b32_e32 v157, 0xffff0000, v157
	v_lshlrev_b32_e32 v164, 16, v159
	v_and_b32_e32 v159, 0xffff0000, v159
	v_lshlrev_b32_e32 v163, 16, v158
	v_and_b32_e32 v158, 0xffff0000, v158
	v_mul_f32_e32 v124, v124, v147
	v_mul_f32_e32 v125, v125, v156
	v_mul_f32_e32 v126, v126, v162
	v_mul_f32_e32 v127, v127, v157
	v_mul_f32_e32 v123, v123, v159
	v_mul_f32_e32 v147, v120, v163
	v_mul_f32_e32 v156, v121, v158
	v_mul_f32_e32 v157, v122, v164
	v_cvt_pk_bf16_f32 v120, v124, v125
	v_cvt_pk_bf16_f32 v121, v126, v127
	v_cvt_pk_bf16_f32 v122, v147, v156
	v_cvt_pk_bf16_f32 v123, v157, v123
	global_load_dwordx4 v[124:127], v[160:161], off offset:3328
	v_ashrrev_i32_e32 v147, 31, v146
	v_lshlrev_b64 v[158:159], 11, v[146:147]
	v_lshl_add_u64 v[158:159], s[0:1], 0, v[158:159]
	v_or_b32_e32 v156, 16, v146
	v_lshl_add_u64 v[158:159], v[158:159], 0, v[144:145]
	v_mad_i64_i32 v[160:161], s[18:19], v156, s41, v[148:149]
	global_store_dwordx4 v[158:159], v[120:123], off
	v_lshl_add_u64 v[160:161], v[160:161], 0, v[144:145]
	v_ashrrev_i32_e32 v157, 31, v156
	s_waitcnt vmcnt(0)
; __device__ __forceinline__ unsigned cvt_pk_bf16(float lo, float hi) { unsigned r; asm volatile("v_cvt_pk_bf16_f32 %0, %1, %2" : "=v"(r) : "v"(lo), "v"(hi)); return r; }
; __device__ __forceinline__ float bf_lo(unsigned u) { return __uint_as_float(u << 16); }
; __device__ __forceinline__ float bf_hi(unsigned u) { return __uint_as_float(u & 0xffff0000u); }
;     __device__ __forceinline__ void operator()(const f32x4 (&acc)[2][2][4][2], const Unit& u, int wr, int wc, int fr, int fq) const {
;         const int row0 = u.pm * BM + wr * 64 + fr, col0 = u.pn * BM + wc * 32 + 8 * fq;
; #pragma unroll
;         for (int ai = 0; ai < 2; ++ai)
; #pragma unroll
;             for (int m = 0; m < 4; ++m) { const size_t r = (size_t)(row0 + ai * HALF + m * 16); bf16_t* rowp = O + r * ldc + col0; const bf16_t* gp = G + r * ldg + col0;
; #pragma unroll
;                 for (int bj = 0; bj < 2; ++bj) { const u32x4 gw = *(const u32x4*)(gp + bj * HALF);
;                     f32x4 v0 = acc[ai][bj][m][0], v1 = acc[ai][bj][m][1];
;                     v0[0] *= bf_lo(gw.x); v0[1] *= bf_hi(gw.x); v0[2] *= bf_lo(gw.y); v0[3] *= bf_hi(gw.y);
;                     v1[0] *= bf_lo(gw.z); v1[1] *= bf_hi(gw.z); v1[2] *= bf_lo(gw.w); v1[3] *= bf_hi(gw.w);
;                     if (ACCUM) { const u32x4 pw = *(const u32x4*)(rowp + bj * HALF);
;                         v0[0] += bf_lo(pw.x); v0[1] += bf_hi(pw.x); v0[2] += bf_lo(pw.y); v0[3] += bf_hi(pw.y);
;                         v1[0] += bf_lo(pw.z); v1[1] += bf_hi(pw.z); v1[2] += bf_lo(pw.w); v1[3] += bf_hi(pw.w); }
;                     u32x4 w; w.x = cvt_pk_bf16(v0[0], v0[1]); w.y = cvt_pk_bf16(v0[2], v0[3]); w.z = cvt_pk_bf16(v1[0], v1[1]); w.w = cvt_pk_bf16(v1[2], v1[3]);
;                     *(u32x4*)(rowp + bj * HALF) = w; } }
	v_lshlrev_b32_e32 v120, 16, v124
	v_and_b32_e32 v121, 0xffff0000, v124
	v_lshlrev_b32_e32 v122, 16, v125
	v_and_b32_e32 v123, 0xffff0000, v125
	v_lshlrev_b32_e32 v124, 16, v126
	v_and_b32_e32 v125, 0xffff0000, v126
	v_lshlrev_b32_e32 v126, 16, v127
	v_and_b32_e32 v127, 0xffff0000, v127
	v_mul_f32_e32 v116, v116, v120
	v_mul_f32_e32 v117, v117, v121
	v_mul_f32_e32 v118, v118, v122
	v_mul_f32_e32 v119, v119, v123
	v_mul_f32_e32 v111, v111, v127
	v_mul_f32_e32 v120, v108, v124
	v_mul_f32_e32 v121, v109, v125
	v_mul_f32_e32 v122, v110, v126
	v_cvt_pk_bf16_f32 v108, v116, v117
	v_cvt_pk_bf16_f32 v109, v118, v119
	v_cvt_pk_bf16_f32 v110, v120, v121
	v_cvt_pk_bf16_f32 v111, v122, v111
	global_load_dwordx4 v[116:119], v[160:161], off offset:3072
	s_nop 0
	global_store_dwordx4 v[158:159], v[108:111], off offset:256
	s_waitcnt vmcnt(0)
	s_nop 0
	v_lshlrev_b32_e32 v108, 16, v116
	v_and_b32_e32 v109, 0xffff0000, v116
	v_lshlrev_b32_e32 v110, 16, v117
	v_and_b32_e32 v111, 0xffff0000, v117
	v_lshlrev_b32_e32 v116, 16, v118
	v_and_b32_e32 v117, 0xffff0000, v118
	v_lshlrev_b32_e32 v118, 16, v119
	v_and_b32_e32 v119, 0xffff0000, v119
	v_mul_f32_e32 v108, v112, v108
	v_mul_f32_e32 v109, v113, v109
	v_mul_f32_e32 v110, v114, v110
	v_mul_f32_e32 v111, v115, v111
	v_mul_f32_e32 v107, v107, v119
	v_mul_f32_e32 v112, v104, v116
	v_mul_f32_e32 v113, v105, v117
	v_mul_f32_e32 v114, v106, v118
	v_cvt_pk_bf16_f32 v104, v108, v109
	v_cvt_pk_bf16_f32 v105, v110, v111
	v_cvt_pk_bf16_f32 v106, v112, v113
	v_cvt_pk_bf16_f32 v107, v114, v107
	global_load_dwordx4 v[108:111], v[160:161], off offset:3328
	v_lshlrev_b64 v[116:117], 11, v[156:157]
	v_lshl_add_u64 v[116:117], s[0:1], 0, v[116:117]
	v_or_b32_e32 v112, 32, v146
	v_lshl_add_u64 v[116:117], v[116:117], 0, v[144:145]
	v_mad_i64_i32 v[114:115], s[18:19], v112, s41, v[148:149]
	global_store_dwordx4 v[116:117], v[104:107], off
	v_lshl_add_u64 v[114:115], v[114:115], 0, v[144:145]
	v_ashrrev_i32_e32 v113, 31, v112
	s_waitcnt vmcnt(0)
	v_lshlrev_b32_e32 v104, 16, v108
	v_and_b32_e32 v105, 0xffff0000, v108
	v_lshlrev_b32_e32 v106, 16, v109
	v_and_b32_e32 v107, 0xffff0000, v109
	v_lshlrev_b32_e32 v108, 16, v110
	v_and_b32_e32 v109, 0xffff0000, v110
	v_lshlrev_b32_e32 v110, 16, v111
	v_and_b32_e32 v111, 0xffff0000, v111
	v_mul_f32_e32 v100, v100, v104
	v_mul_f32_e32 v101, v101, v105
	v_mul_f32_e32 v102, v102, v106
	v_mul_f32_e32 v103, v103, v107
	v_mul_f32_e32 v95, v95, v111
	v_mul_f32_e32 v104, v92, v108
	v_mul_f32_e32 v105, v93, v109
	v_mul_f32_e32 v106, v94, v110
	v_cvt_pk_bf16_f32 v92, v100, v101
	v_cvt_pk_bf16_f32 v93, v102, v103
	v_cvt_pk_bf16_f32 v94, v104, v105
	v_cvt_pk_bf16_f32 v95, v106, v95
	global_load_dwordx4 v[100:103], v[114:115], off offset:3072
	s_nop 0
	global_store_dwordx4 v[116:117], v[92:95], off offset:256
	s_waitcnt vmcnt(0)
	s_nop 0
	v_lshlrev_b32_e32 v92, 16, v100
	v_and_b32_e32 v93, 0xffff0000, v100
	v_lshlrev_b32_e32 v94, 16, v101
	v_and_b32_e32 v95, 0xffff0000, v101
	v_lshlrev_b32_e32 v100, 16, v102
	v_and_b32_e32 v101, 0xffff0000, v102
	v_lshlrev_b32_e32 v102, 16, v103
	v_and_b32_e32 v103, 0xffff0000, v103
	v_mul_f32_e32 v92, v96, v92
	v_mul_f32_e32 v93, v97, v93
	v_mul_f32_e32 v94, v98, v94
	v_mul_f32_e32 v95, v99, v95
	v_mul_f32_e32 v91, v91, v103
	v_mul_f32_e32 v96, v88, v100
	v_mul_f32_e32 v97, v89, v101
	v_mul_f32_e32 v98, v90, v102
	v_cvt_pk_bf16_f32 v88, v92, v93
	v_cvt_pk_bf16_f32 v89, v94, v95
	v_cvt_pk_bf16_f32 v90, v96, v97
	v_cvt_pk_bf16_f32 v91, v98, v91
	global_load_dwordx4 v[92:95], v[114:115], off offset:3328
	v_lshlrev_b64 v[100:101], 11, v[112:113]
	v_lshl_add_u64 v[100:101], s[0:1], 0, v[100:101]
	v_or_b32_e32 v96, 48, v146
	v_lshl_add_u64 v[100:101], v[100:101], 0, v[144:145]
	v_mad_i64_i32 v[98:99], s[18:19], v96, s41, v[148:149]
	global_store_dwordx4 v[100:101], v[88:91], off
	v_lshl_add_u64 v[98:99], v[98:99], 0, v[144:145]
	v_ashrrev_i32_e32 v97, 31, v96
	s_waitcnt vmcnt(0)
	v_lshlrev_b32_e32 v88, 16, v92
	v_and_b32_e32 v89, 0xffff0000, v92
	v_lshlrev_b32_e32 v90, 16, v93
	v_and_b32_e32 v91, 0xffff0000, v93
	v_lshlrev_b32_e32 v92, 16, v94
	v_and_b32_e32 v93, 0xffff0000, v94
	v_lshlrev_b32_e32 v94, 16, v95
	v_and_b32_e32 v95, 0xffff0000, v95
	v_mul_f32_e32 v84, v84, v88
	v_mul_f32_e32 v85, v85, v89
	v_mul_f32_e32 v86, v86, v90
	v_mul_f32_e32 v87, v87, v91
	v_mul_f32_e32 v79, v79, v95
	v_mul_f32_e32 v88, v76, v92
	v_mul_f32_e32 v89, v77, v93
	v_mul_f32_e32 v90, v78, v94
	v_cvt_pk_bf16_f32 v76, v84, v85
	v_cvt_pk_bf16_f32 v77, v86, v87
	v_cvt_pk_bf16_f32 v78, v88, v89
	v_cvt_pk_bf16_f32 v79, v90, v79
	global_load_dwordx4 v[84:87], v[98:99], off offset:3072
	s_nop 0
	global_store_dwordx4 v[100:101], v[76:79], off offset:256
	s_waitcnt vmcnt(0)
	s_nop 0
	v_lshlrev_b32_e32 v76, 16, v84
	v_and_b32_e32 v77, 0xffff0000, v84
	v_lshlrev_b32_e32 v78, 16, v85
	v_and_b32_e32 v79, 0xffff0000, v85
	v_lshlrev_b32_e32 v84, 16, v86
	v_and_b32_e32 v85, 0xffff0000, v86
	v_lshlrev_b32_e32 v86, 16, v87
	v_and_b32_e32 v87, 0xffff0000, v87
	v_mul_f32_e32 v76, v80, v76
	v_mul_f32_e32 v77, v81, v77
	v_mul_f32_e32 v78, v82, v78
	v_mul_f32_e32 v79, v83, v79
	v_mul_f32_e32 v75, v75, v87
	v_mul_f32_e32 v80, v72, v84
	v_mul_f32_e32 v81, v73, v85
	v_mul_f32_e32 v82, v74, v86
	v_cvt_pk_bf16_f32 v72, v76, v77
	v_cvt_pk_bf16_f32 v73, v78, v79
	v_cvt_pk_bf16_f32 v74, v80, v81
	v_cvt_pk_bf16_f32 v75, v82, v75
	global_load_dwordx4 v[76:79], v[98:99], off offset:3328
	v_lshlrev_b64 v[84:85], 11, v[96:97]
	v_lshl_add_u64 v[84:85], s[0:1], 0, v[84:85]
	v_add_u32_e32 v80, 0x80, v146
	v_lshl_add_u64 v[84:85], v[84:85], 0, v[144:145]
	v_mad_i64_i32 v[82:83], s[18:19], v80, s41, v[148:149]
	global_store_dwordx4 v[84:85], v[72:75], off
	v_lshl_add_u64 v[82:83], v[82:83], 0, v[144:145]
	v_ashrrev_i32_e32 v81, 31, v80
	s_waitcnt vmcnt(0)
; __device__ __forceinline__ unsigned cvt_pk_bf16(float lo, float hi) { unsigned r; asm volatile("v_cvt_pk_bf16_f32 %0, %1, %2" : "=v"(r) : "v"(lo), "v"(hi)); return r; }
; __device__ __forceinline__ float bf_lo(unsigned u) { return __uint_as_float(u << 16); }
; __device__ __forceinline__ float bf_hi(unsigned u) { return __uint_as_float(u & 0xffff0000u); }
;     __device__ __forceinline__ void operator()(const f32x4 (&acc)[2][2][4][2], const Unit& u, int wr, int wc, int fr, int fq) const {
;         const int row0 = u.pm * BM + wr * 64 + fr, col0 = u.pn * BM + wc * 32 + 8 * fq;
; #pragma unroll
;         for (int ai = 0; ai < 2; ++ai)
; #pragma unroll
;             for (int m = 0; m < 4; ++m) { const size_t r = (size_t)(row0 + ai * HALF + m * 16); bf16_t* rowp = O + r * ldc + col0; const bf16_t* gp = G + r * ldg + col0;
; #pragma unroll
;                 for (int bj = 0; bj < 2; ++bj) { const u32x4 gw = *(const u32x4*)(gp + bj * HALF);
;                     f32x4 v0 = acc[ai][bj][m][0], v1 = acc[ai][bj][m][1];
;                     v0[0] *= bf_lo(gw.x); v0[1] *= bf_hi(gw.x); v0[2] *= bf_lo(gw.y); v0[3] *= bf_hi(gw.y);
;                     v1[0] *= bf_lo(gw.z); v1[1] *= bf_hi(gw.z); v1[2] *= bf_lo(gw.w); v1[3] *= bf_hi(gw.w);
;                     if (ACCUM) { const u32x4 pw = *(const u32x4*)(rowp + bj * HALF);
;                         v0[0] += bf_lo(pw.x); v0[1] += bf_hi(pw.x); v0[2] += bf_lo(pw.y); v0[3] += bf_hi(pw.y);
;                         v1[0] += bf_lo(pw.z); v1[1] += bf_hi(pw.z); v1[2] += bf_lo(pw.w); v1[3] += bf_hi(pw.w); }
;                     u32x4 w; w.x = cvt_pk_bf16(v0[0], v0[1]); w.y = cvt_pk_bf16(v0[2], v0[3]); w.z = cvt_pk_bf16(v1[0], v1[1]); w.w = cvt_pk_bf16(v1[2], v1[3]);
;                     *(u32x4*)(rowp + bj * HALF) = w; } }
	v_lshlrev_b32_e32 v72, 16, v76
	v_and_b32_e32 v73, 0xffff0000, v76
	v_lshlrev_b32_e32 v74, 16, v77
	v_and_b32_e32 v75, 0xffff0000, v77
	v_lshlrev_b32_e32 v76, 16, v78
	v_and_b32_e32 v77, 0xffff0000, v78
	v_lshlrev_b32_e32 v78, 16, v79
	v_and_b32_e32 v79, 0xffff0000, v79
	v_mul_f32_e32 v68, v68, v72
	v_mul_f32_e32 v69, v69, v73
	v_mul_f32_e32 v70, v70, v74
	v_mul_f32_e32 v71, v71, v75
	v_mul_f32_e32 v67, v67, v79
	v_mul_f32_e32 v72, v64, v76
	v_mul_f32_e32 v73, v65, v77
	v_mul_f32_e32 v74, v66, v78
	v_cvt_pk_bf16_f32 v64, v68, v69
	v_cvt_pk_bf16_f32 v65, v70, v71
	v_cvt_pk_bf16_f32 v66, v72, v73
	v_cvt_pk_bf16_f32 v67, v74, v67
	global_load_dwordx4 v[68:71], v[82:83], off offset:3072
	s_nop 0
	global_store_dwordx4 v[84:85], v[64:67], off offset:256
	s_waitcnt vmcnt(0)
	s_nop 0
	v_lshlrev_b32_e32 v64, 16, v68
	v_and_b32_e32 v65, 0xffff0000, v68
	v_lshlrev_b32_e32 v66, 16, v69
	v_and_b32_e32 v67, 0xffff0000, v69
	v_lshlrev_b32_e32 v68, 16, v70
	v_and_b32_e32 v69, 0xffff0000, v70
	v_lshlrev_b32_e32 v70, 16, v71
	v_and_b32_e32 v71, 0xffff0000, v71
	v_mul_f32_e32 v60, v60, v64
	v_mul_f32_e32 v61, v61, v65
	v_mul_f32_e32 v62, v62, v66
	v_mul_f32_e32 v63, v63, v67
	v_mul_f32_e32 v59, v59, v71
	v_mul_f32_e32 v64, v56, v68
	v_mul_f32_e32 v65, v57, v69
	v_mul_f32_e32 v66, v58, v70
	v_cvt_pk_bf16_f32 v56, v60, v61
	v_cvt_pk_bf16_f32 v57, v62, v63
	v_cvt_pk_bf16_f32 v58, v64, v65
	v_cvt_pk_bf16_f32 v59, v66, v59
	global_load_dwordx4 v[60:63], v[82:83], off offset:3328
	v_lshlrev_b64 v[68:69], 11, v[80:81]
	v_lshl_add_u64 v[68:69], s[0:1], 0, v[68:69]
	v_add_u32_e32 v64, 0x90, v146
	v_lshl_add_u64 v[68:69], v[68:69], 0, v[144:145]
	v_mad_i64_i32 v[66:67], s[18:19], v64, s41, v[148:149]
	global_store_dwordx4 v[68:69], v[56:59], off
	v_lshl_add_u64 v[66:67], v[66:67], 0, v[144:145]
	v_ashrrev_i32_e32 v65, 31, v64
	s_waitcnt vmcnt(0)
	v_lshlrev_b32_e32 v56, 16, v60
	v_and_b32_e32 v57, 0xffff0000, v60
	v_lshlrev_b32_e32 v58, 16, v61
	v_and_b32_e32 v59, 0xffff0000, v61
	v_lshlrev_b32_e32 v60, 16, v62
	v_and_b32_e32 v61, 0xffff0000, v62
	v_lshlrev_b32_e32 v62, 16, v63
	v_and_b32_e32 v63, 0xffff0000, v63
	v_mul_f32_e32 v52, v52, v56
	v_mul_f32_e32 v53, v53, v57
	v_mul_f32_e32 v54, v54, v58
	v_mul_f32_e32 v55, v55, v59
	v_mul_f32_e32 v47, v47, v63
	v_mul_f32_e32 v56, v44, v60
	v_mul_f32_e32 v57, v45, v61
	v_mul_f32_e32 v58, v46, v62
	v_cvt_pk_bf16_f32 v44, v52, v53
	v_cvt_pk_bf16_f32 v45, v54, v55
	v_cvt_pk_bf16_f32 v46, v56, v57
	v_cvt_pk_bf16_f32 v47, v58, v47
	global_load_dwordx4 v[52:55], v[66:67], off offset:3072
	s_nop 0
	global_store_dwordx4 v[68:69], v[44:47], off offset:256
	s_waitcnt vmcnt(0)
	s_nop 0
	v_lshlrev_b32_e32 v44, 16, v52
	v_and_b32_e32 v45, 0xffff0000, v52
	v_lshlrev_b32_e32 v46, 16, v53
	v_and_b32_e32 v47, 0xffff0000, v53
	v_lshlrev_b32_e32 v52, 16, v54
	v_and_b32_e32 v53, 0xffff0000, v54
	v_lshlrev_b32_e32 v54, 16, v55
	v_and_b32_e32 v55, 0xffff0000, v55
	v_mul_f32_e32 v44, v48, v44
	v_mul_f32_e32 v45, v49, v45
	v_mul_f32_e32 v46, v50, v46
	v_mul_f32_e32 v47, v51, v47
	v_mul_f32_e32 v43, v43, v55
	v_mul_f32_e32 v48, v40, v52
	v_mul_f32_e32 v49, v41, v53
	v_mul_f32_e32 v50, v42, v54
	v_cvt_pk_bf16_f32 v40, v44, v45
	v_cvt_pk_bf16_f32 v41, v46, v47
	v_cvt_pk_bf16_f32 v42, v48, v49
	v_cvt_pk_bf16_f32 v43, v50, v43
	global_load_dwordx4 v[44:47], v[66:67], off offset:3328
	v_lshlrev_b64 v[52:53], 11, v[64:65]
	v_lshl_add_u64 v[52:53], s[0:1], 0, v[52:53]
	v_add_u32_e32 v48, 0xa0, v146
	v_lshl_add_u64 v[52:53], v[52:53], 0, v[144:145]
	v_mad_i64_i32 v[50:51], s[18:19], v48, s41, v[148:149]
	global_store_dwordx4 v[52:53], v[40:43], off
	v_lshl_add_u64 v[50:51], v[50:51], 0, v[144:145]
	v_ashrrev_i32_e32 v49, 31, v48
	s_waitcnt vmcnt(0)
; __device__ __forceinline__ unsigned cvt_pk_bf16(float lo, float hi) { unsigned r; asm volatile("v_cvt_pk_bf16_f32 %0, %1, %2" : "=v"(r) : "v"(lo), "v"(hi)); return r; }
; __device__ __forceinline__ float bf_lo(unsigned u) { return __uint_as_float(u << 16); }
; __device__ __forceinline__ float bf_hi(unsigned u) { return __uint_as_float(u & 0xffff0000u); }
;     __device__ __forceinline__ void operator()(const f32x4 (&acc)[2][2][4][2], const Unit& u, int wr, int wc, int fr, int fq) const {
;         const int row0 = u.pm * BM + wr * 64 + fr, col0 = u.pn * BM + wc * 32 + 8 * fq;
; #pragma unroll
;         for (int ai = 0; ai < 2; ++ai)
; #pragma unroll
;             for (int m = 0; m < 4; ++m) { const size_t r = (size_t)(row0 + ai * HALF + m * 16); bf16_t* rowp = O + r * ldc + col0; const bf16_t* gp = G + r * ldg + col0;
; #pragma unroll
;                 for (int bj = 0; bj < 2; ++bj) { const u32x4 gw = *(const u32x4*)(gp + bj * HALF);
;                     f32x4 v0 = acc[ai][bj][m][0], v1 = acc[ai][bj][m][1];
;                     v0[0] *= bf_lo(gw.x); v0[1] *= bf_hi(gw.x); v0[2] *= bf_lo(gw.y); v0[3] *= bf_hi(gw.y);
;                     v1[0] *= bf_lo(gw.z); v1[1] *= bf_hi(gw.z); v1[2] *= bf_lo(gw.w); v1[3] *= bf_hi(gw.w);
;                     if (ACCUM) { const u32x4 pw = *(const u32x4*)(rowp + bj * HALF);
;                         v0[0] += bf_lo(pw.x); v0[1] += bf_hi(pw.x); v0[2] += bf_lo(pw.y); v0[3] += bf_hi(pw.y);
;                         v1[0] += bf_lo(pw.z); v1[1] += bf_hi(pw.z); v1[2] += bf_lo(pw.w); v1[3] += bf_hi(pw.w); }
;                     u32x4 w; w.x = cvt_pk_bf16(v0[0], v0[1]); w.y = cvt_pk_bf16(v0[2], v0[3]); w.z = cvt_pk_bf16(v1[0], v1[1]); w.w = cvt_pk_bf16(v1[2], v1[3]);
;                     *(u32x4*)(rowp + bj * HALF) = w; } }
	v_lshlrev_b32_e32 v40, 16, v44
	v_and_b32_e32 v41, 0xffff0000, v44
	v_lshlrev_b32_e32 v42, 16, v45
	v_and_b32_e32 v43, 0xffff0000, v45
	v_lshlrev_b32_e32 v44, 16, v46
	v_and_b32_e32 v45, 0xffff0000, v46
	v_lshlrev_b32_e32 v46, 16, v47
	v_and_b32_e32 v47, 0xffff0000, v47
	v_mul_f32_e32 v36, v36, v40
	v_mul_f32_e32 v37, v37, v41
	v_mul_f32_e32 v38, v38, v42
	v_mul_f32_e32 v39, v39, v43
	v_mul_f32_e32 v31, v31, v47
	v_mul_f32_e32 v40, v28, v44
	v_mul_f32_e32 v41, v29, v45
	v_mul_f32_e32 v42, v30, v46
	v_cvt_pk_bf16_f32 v28, v36, v37
	v_cvt_pk_bf16_f32 v29, v38, v39
	v_cvt_pk_bf16_f32 v30, v40, v41
	v_cvt_pk_bf16_f32 v31, v42, v31
	global_load_dwordx4 v[36:39], v[50:51], off offset:3072
	s_nop 0
	global_store_dwordx4 v[52:53], v[28:31], off offset:256
	s_waitcnt vmcnt(0)
	s_nop 0
	v_lshlrev_b32_e32 v28, 16, v36
	v_and_b32_e32 v29, 0xffff0000, v36
	v_lshlrev_b32_e32 v30, 16, v37
	v_and_b32_e32 v31, 0xffff0000, v37
	v_lshlrev_b32_e32 v36, 16, v38
	v_and_b32_e32 v37, 0xffff0000, v38
	v_lshlrev_b32_e32 v38, 16, v39
	v_and_b32_e32 v39, 0xffff0000, v39
	v_mul_f32_e32 v28, v32, v28
	v_mul_f32_e32 v29, v33, v29
	v_mul_f32_e32 v30, v34, v30
	v_mul_f32_e32 v31, v35, v31
	v_mul_f32_e32 v27, v27, v39
	v_mul_f32_e32 v32, v24, v36
	v_mul_f32_e32 v33, v25, v37
	v_mul_f32_e32 v34, v26, v38
	v_cvt_pk_bf16_f32 v24, v28, v29
	v_cvt_pk_bf16_f32 v25, v30, v31
	v_cvt_pk_bf16_f32 v26, v32, v33
	v_cvt_pk_bf16_f32 v27, v34, v27
	global_load_dwordx4 v[28:31], v[50:51], off offset:3328
	v_lshlrev_b64 v[36:37], 11, v[48:49]
	v_lshl_add_u64 v[36:37], s[0:1], 0, v[36:37]
	v_add_u32_e32 v32, 0xb0, v146
	v_lshl_add_u64 v[36:37], v[36:37], 0, v[144:145]
	v_mad_i64_i32 v[34:35], s[18:19], v32, s41, v[148:149]
	global_store_dwordx4 v[36:37], v[24:27], off
	v_lshl_add_u64 v[34:35], v[34:35], 0, v[144:145]
	v_ashrrev_i32_e32 v33, 31, v32
	s_mov_b64 s[18:19], s[12:13]
	s_waitcnt vmcnt(0)
	v_lshlrev_b32_e32 v24, 16, v28
	v_and_b32_e32 v25, 0xffff0000, v28
	v_lshlrev_b32_e32 v26, 16, v29
	v_and_b32_e32 v27, 0xffff0000, v29
	v_lshlrev_b32_e32 v28, 16, v30
	v_and_b32_e32 v29, 0xffff0000, v30
	v_lshlrev_b32_e32 v30, 16, v31
	v_and_b32_e32 v31, 0xffff0000, v31
	v_mul_f32_e32 v20, v20, v24
	v_mul_f32_e32 v21, v21, v25
	v_mul_f32_e32 v22, v22, v26
	v_mul_f32_e32 v23, v23, v27
	v_mul_f32_e32 v15, v15, v31
	v_mul_f32_e32 v24, v12, v28
	v_mul_f32_e32 v25, v13, v29
	v_mul_f32_e32 v26, v14, v30
	v_cvt_pk_bf16_f32 v12, v20, v21
	v_cvt_pk_bf16_f32 v13, v22, v23
	v_cvt_pk_bf16_f32 v14, v24, v25
	v_cvt_pk_bf16_f32 v15, v26, v15
	global_load_dwordx4 v[20:23], v[34:35], off offset:3072
	s_nop 0
	global_store_dwordx4 v[36:37], v[12:15], off offset:256
	s_waitcnt vmcnt(0)
	s_nop 0
	v_lshlrev_b32_e32 v12, 16, v20
	v_and_b32_e32 v13, 0xffff0000, v20
	v_lshlrev_b32_e32 v14, 16, v21
	v_and_b32_e32 v15, 0xffff0000, v21
	v_lshlrev_b32_e32 v20, 16, v22
	v_and_b32_e32 v21, 0xffff0000, v22
	v_lshlrev_b32_e32 v22, 16, v23
	v_and_b32_e32 v23, 0xffff0000, v23
	v_mul_f32_e32 v12, v16, v12
	v_mul_f32_e32 v13, v17, v13
	v_mul_f32_e32 v14, v18, v14
	v_mul_f32_e32 v15, v19, v15
	v_mul_f32_e32 v11, v11, v23
	v_mul_f32_e32 v16, v8, v20
	v_mul_f32_e32 v17, v9, v21
	v_mul_f32_e32 v18, v10, v22
	v_cvt_pk_bf16_f32 v8, v12, v13
	v_cvt_pk_bf16_f32 v9, v14, v15
	v_cvt_pk_bf16_f32 v10, v16, v17
	v_cvt_pk_bf16_f32 v11, v18, v11
	global_load_dwordx4 v[12:15], v[34:35], off offset:3328
	v_lshlrev_b64 v[16:17], 11, v[32:33]
	v_lshl_add_u64 v[16:17], s[0:1], 0, v[16:17]
	v_lshl_add_u64 v[16:17], v[16:17], 0, v[144:145]
	global_store_dwordx4 v[16:17], v[8:11], off
	s_waitcnt vmcnt(0)
	s_nop 0
	v_lshlrev_b32_e32 v8, 16, v12
	v_and_b32_e32 v9, 0xffff0000, v12
	v_lshlrev_b32_e32 v10, 16, v13
	v_and_b32_e32 v11, 0xffff0000, v13
	v_lshlrev_b32_e32 v12, 16, v14
	v_and_b32_e32 v13, 0xffff0000, v14
	v_lshlrev_b32_e32 v14, 16, v15
	v_and_b32_e32 v15, 0xffff0000, v15
	v_mul_f32_e32 v3, v3, v15
	v_mul_f32_e32 v4, v4, v8
	v_mul_f32_e32 v5, v5, v9
	v_mul_f32_e32 v6, v6, v10
	v_mul_f32_e32 v7, v7, v11
	v_mul_f32_e32 v8, v0, v12
	v_mul_f32_e32 v9, v1, v13
	v_mul_f32_e32 v10, v2, v14
	v_cvt_pk_bf16_f32 v0, v4, v5
	v_cvt_pk_bf16_f32 v1, v6, v7
	v_cvt_pk_bf16_f32 v2, v8, v9
	v_cvt_pk_bf16_f32 v3, v10, v3
	global_store_dwordx4 v[16:17], v[0:3], off offset:256
	s_cbranch_vccz .LBB0_984
	s_waitcnt vmcnt(0)
	s_cmpk_gt_u32 s25, 0xff
	s_cbranch_scc1 .LBB0_995
	s_barrier

; #define PG8_STAGE(bufoff, gbase, voff) do { _Pragma("unroll") for (int _i = 0; _i < 2; ++_i) \
;         __builtin_amdgcn_global_load_lds((const unsigned*)((const char*)(gbase) + (voff)[_i]), (PG8_LAS unsigned*)(lds + (bufoff) + ldsw + _i * 8192), 16, 0, 0); } while (0)
; #define PG8_LDA(dst, b, h) do { _Pragma("unroll") for (int m = 0; m < 4; ++m) _Pragma("unroll") for (int k = 0; k < 2; ++k) dst[m][k] = *(const PG8_LAS bf16x8*)(lds + PG8_SA(b, h) + aoff + m * 2048 + k * 1024); } while (0)
; #define PG8_LDB(dst, b, h) do { _Pragma("unroll") for (int n = 0; n < 2; ++n) _Pragma("unroll") for (int k = 0; k < 2; ++k) dst[n][k] = *(const PG8_LAS bf16x8*)(lds + PG8_SB(b, h) + boff + n * 2048 + k * 1024); } while (0)
; #define PG8_MMA(ai, bj, At, Bt) do { __builtin_amdgcn_s_setprio(1); _Pragma("unroll") for (int m = 0; m < 4; ++m) _Pragma("unroll") for (int n = 0; n < 2; ++n) _Pragma("unroll") for (int k = 0; k < 2; ++k) \
;         acc[ai][bj][m][n] = __builtin_amdgcn_mfma_f32_16x16x32_bf16(Bt[n][k], At[m][k], acc[ai][bj][m][n], 0, 0, 0); __builtin_amdgcn_s_setprio(0); } while (0)
; #define PG8_WAIT_V(n) asm volatile("s_waitcnt vmcnt(" #n ")" ::: "memory")
; #define PG8_WAIT_L(n) asm volatile("s_waitcnt lgkmcnt(" #n ")" ::: "memory")
; template <class Epi, class Sched>
; __device__ __forceinline__ void gemm_phase(PG8_LAS unsigned char* lds, const Gemm g, const Sched& S, const Epi& E) {
;     ...
;             const bool last = (t == nt - 2);
;             const char* a1 = cA + (size_t)(t + 1) * kstep;
;             const char* a2 = last ? nA : cA + (size_t)(t + 2) * kstep; const char* b2 = last ? nB : cB + (size_t)(t + 2) * kstep;
;             const char* a3 = a2 + kstep; const char* b3 = b2 + kstep;
;             if (last && has_next) S.a_ready(nxt);
;             PG8_LDB(B0, 0, 0); PG8_SCHED; PG8_LDA(At, 0, 0); PG8_STAGE(PG8_SA(1, 1), a1 + hstep, voffA);
;             PG8_WAIT_L(8); PG8_BAR; PG8_WAIT_L(0); PG8_MMA(0, 0, At, B0); PG8_BAR; PG8_SCHED;
;             PG8_LDB(B1, 0, 1); PG8_STAGE(PG8_SB(0, 0), b2, voffB);
;             PG8_BAR; PG8_WAIT_L(0); PG8_MMA(0, 1, At, B1); PG8_BAR;
;             PG8_LDA(At, 0, 1); PG8_STAGE(PG8_SA(0, 0), a2, voffA);
;             PG8_BAR; PG8_WAIT_L(0); PG8_MMA(1, 0, At, B0); PG8_BAR; PG8_SCHED;
;             PG8_STAGE(PG8_SB(0, 1), b2 + hstep, voffB);
;             PG8_WAIT_V(6); PG8_BAR; PG8_MMA(1, 1, At, B1); PG8_BAR;
.LBB0_1011:
	ds_read_b128 v[144:147], v153
	ds_read_b128 v[156:159], v153 offset:1024
	ds_read_b128 v[160:163], v153 offset:2048
	ds_read_b128 v[164:167], v153 offset:3072
	s_add_u32 s20, s18, 0xfffc0080
	s_addc_u32 s21, s19, -1
	s_cmp_eq_u32 s47, 12
	s_cselect_b32 s23, s11, s21
	s_cselect_b32 s22, s43, s20
	s_cselect_b32 s21, s9, s46
	s_cselect_b32 s20, s44, s45
	v_lshl_add_u64 v[148:149], s[18:19], 0, v[136:137]
	s_add_i32 m0, s17, 0xc000
	ds_read_b128 v[168:171], v154
	ds_read_b128 v[172:175], v154 offset:1024
	ds_read_b128 v[182:185], v154 offset:2048
	ds_read_b128 v[190:193], v154 offset:3072
	ds_read_b128 v[194:197], v154 offset:4096
	ds_read_b128 v[198:201], v154 offset:5120
	ds_read_b128 v[202:205], v154 offset:6144
	ds_read_b128 v[206:209], v154 offset:7168
	global_load_lds_dwordx4 v[148:149], off
	v_lshl_add_u64 v[148:149], s[18:19], 0, v[138:139]
	s_add_i32 m0, s17, 0xe000
	s_nop 0
	global_load_lds_dwordx4 v[148:149], off
	ds_read_b128 v[210:213], v155
	ds_read_b128 v[214:217], v155 offset:1024
	ds_read_b128 v[218:221], v155 offset:2048
	ds_read_b128 v[222:225], v155 offset:3072
	s_waitcnt vmcnt(8) lgkmcnt(0)
	s_barrier
	v_mfma_f32_16x16x32_bf16 v[124:127], v[144:147], v[168:171], v[124:127]
	v_mfma_f32_16x16x32_bf16 v[120:123], v[160:163], v[168:171], v[120:123]
	v_mfma_f32_16x16x32_bf16 v[108:111], v[144:147], v[182:185], v[108:111]
	v_mfma_f32_16x16x32_bf16 v[104:107], v[160:163], v[182:185], v[104:107]
	v_mfma_f32_16x16x32_bf16 v[92:95], v[144:147], v[194:197], v[92:95]
	v_mfma_f32_16x16x32_bf16 v[88:91], v[160:163], v[194:197], v[88:91]
	v_mfma_f32_16x16x32_bf16 v[76:79], v[144:147], v[202:205], v[76:79]
	v_mfma_f32_16x16x32_bf16 v[72:75], v[160:163], v[202:205], v[72:75]
	v_mfma_f32_16x16x32_bf16 v[124:127], v[156:159], v[172:175], v[124:127]
	v_mfma_f32_16x16x32_bf16 v[120:123], v[164:167], v[172:175], v[120:123]
	v_mfma_f32_16x16x32_bf16 v[108:111], v[156:159], v[190:193], v[108:111]
	v_mfma_f32_16x16x32_bf16 v[104:107], v[164:167], v[190:193], v[104:107]
	v_mfma_f32_16x16x32_bf16 v[92:95], v[156:159], v[198:201], v[92:95]
	v_mfma_f32_16x16x32_bf16 v[88:91], v[164:167], v[198:201], v[88:91]
	v_mfma_f32_16x16x32_bf16 v[76:79], v[156:159], v[206:209], v[76:79]
	v_mfma_f32_16x16x32_bf16 v[72:75], v[164:167], v[206:209], v[72:75]
	v_mfma_f32_16x16x32_bf16 v[116:119], v[210:213], v[168:171], v[116:119]
	v_mfma_f32_16x16x32_bf16 v[112:115], v[218:221], v[168:171], v[112:115]
	v_mfma_f32_16x16x32_bf16 v[100:103], v[210:213], v[182:185], v[100:103]
	v_mfma_f32_16x16x32_bf16 v[96:99], v[218:221], v[182:185], v[96:99]
	v_mfma_f32_16x16x32_bf16 v[84:87], v[210:213], v[194:197], v[84:87]
	v_mfma_f32_16x16x32_bf16 v[80:83], v[218:221], v[194:197], v[80:83]
	v_mfma_f32_16x16x32_bf16 v[68:71], v[210:213], v[202:205], v[68:71]
	v_mfma_f32_16x16x32_bf16 v[64:67], v[218:221], v[202:205], v[64:67]
	v_mfma_f32_16x16x32_bf16 v[116:119], v[214:217], v[172:175], v[116:119]
	v_mfma_f32_16x16x32_bf16 v[112:115], v[222:225], v[172:175], v[112:115]
	v_mfma_f32_16x16x32_bf16 v[100:103], v[214:217], v[190:193], v[100:103]
	v_mfma_f32_16x16x32_bf16 v[96:99], v[222:225], v[190:193], v[96:99]
	v_mfma_f32_16x16x32_bf16 v[84:87], v[214:217], v[198:201], v[84:87]
	v_mfma_f32_16x16x32_bf16 v[80:83], v[222:225], v[198:201], v[80:83]
	v_mfma_f32_16x16x32_bf16 v[68:71], v[214:217], v[206:209], v[68:71]
	v_mfma_f32_16x16x32_bf16 v[64:67], v[222:225], v[206:209], v[64:67]
	s_barrier
	ds_read_b128 v[168:171], v154 offset:16384
	ds_read_b128 v[172:175], v154 offset:17408
	ds_read_b128 v[182:185], v154 offset:18432
	ds_read_b128 v[190:193], v154 offset:19456
	ds_read_b128 v[194:197], v154 offset:20480
	ds_read_b128 v[198:201], v154 offset:21504
	ds_read_b128 v[202:205], v154 offset:22528
	ds_read_b128 v[206:209], v154 offset:23552
	s_add_i32 s48, s39, s29
	v_lshl_add_u64 v[148:149], s[20:21], 0, v[130:131]
	s_mov_b32 m0, s48
	s_nop 0
	global_load_lds_dwordx4 v[148:149], off
	v_lshl_add_u64 v[186:187], s[20:21], 0, v[134:135]
	s_add_i32 m0, s48, 0x2000
	s_nop 0
	global_load_lds_dwordx4 v[186:187], off
	s_mov_b32 m0, s17
	v_lshl_add_u64 v[226:227], s[22:23], 0, v[128:129]
	global_load_lds_dwordx4 v[226:227], off
	v_lshl_add_u64 v[228:229], s[22:23], 0, v[132:133]
	s_mov_b32 m0, s30
	s_nop 0
	global_load_lds_dwordx4 v[228:229], off
	s_add_u32 s48, s20, 0x40000
	s_addc_u32 s49, s21, 0
	s_add_i32 s50, s40, s29
	v_lshl_add_u64 v[246:247], s[48:49], 0, v[130:131]
	s_mov_b32 m0, s50
	s_nop 0
	global_load_lds_dwordx4 v[246:247], off
	v_lshl_add_u64 v[246:247], s[48:49], 0, v[134:135]
	s_add_i32 m0, s50, 0x2000
	s_nop 0
	global_load_lds_dwordx4 v[246:247], off
	s_waitcnt vmcnt(8) lgkmcnt(0)
	s_barrier
; #define PG8_STAGE(bufoff, gbase, voff) do { _Pragma("unroll") for (int _i = 0; _i < 2; ++_i) \
;         __builtin_amdgcn_global_load_lds((const unsigned*)((const char*)(gbase) + (voff)[_i]), (PG8_LAS unsigned*)(lds + (bufoff) + ldsw + _i * 8192), 16, 0, 0); } while (0)
; #define PG8_LDA(dst, b, h) do { _Pragma("unroll") for (int m = 0; m < 4; ++m) _Pragma("unroll") for (int k = 0; k < 2; ++k) dst[m][k] = *(const PG8_LAS bf16x8*)(lds + PG8_SA(b, h) + aoff + m * 2048 + k * 1024); } while (0)
; #define PG8_LDB(dst, b, h) do { _Pragma("unroll") for (int n = 0; n < 2; ++n) _Pragma("unroll") for (int k = 0; k < 2; ++k) dst[n][k] = *(const PG8_LAS bf16x8*)(lds + PG8_SB(b, h) + boff + n * 2048 + k * 1024); } while (0)
; #define PG8_MMA(ai, bj, At, Bt) do { __builtin_amdgcn_s_setprio(1); _Pragma("unroll") for (int m = 0; m < 4; ++m) _Pragma("unroll") for (int n = 0; n < 2; ++n) _Pragma("unroll") for (int k = 0; k < 2; ++k) \
;         acc[ai][bj][m][n] = __builtin_amdgcn_mfma_f32_16x16x32_bf16(Bt[n][k], At[m][k], acc[ai][bj][m][n], 0, 0, 0); __builtin_amdgcn_s_setprio(0); } while (0)
; #define PG8_WAIT_V(n) asm volatile("s_waitcnt vmcnt(" #n ")" ::: "memory")
; #define PG8_WAIT_L(n) asm volatile("s_waitcnt lgkmcnt(" #n ")" ::: "memory")
; #define PG8_BAR __builtin_amdgcn_s_barrier()
; #define PG8_SCHED __builtin_amdgcn_sched_barrier(0)
; template <class Epi, class Sched>
; __device__ __forceinline__ void gemm_phase(PG8_LAS unsigned char* lds, const Gemm g, const Sched& S, const Epi& E) {
;     ...
;             PG8_BAR; PG8_WAIT_L(0); PG8_MMA(1, 0, At, B0); PG8_BAR; PG8_SCHED;
;             PG8_STAGE(PG8_SB(0, 1), b2 + hstep, voffB);
;             PG8_WAIT_V(6); PG8_BAR; PG8_MMA(1, 1, At, B1); PG8_BAR;
;             PG8_LDB(B0, 1, 0); PG8_SCHED; PG8_LDA(At, 1, 0); PG8_STAGE(PG8_SA(0, 1), a2 + hstep, voffA);
;             PG8_WAIT_L(8); PG8_BAR; PG8_WAIT_L(0); PG8_MMA(0, 0, At, B0); PG8_BAR; PG8_SCHED;
;             PG8_LDB(B1, 1, 1); PG8_STAGE(PG8_SB(1, 0), b3, voffB);
;             PG8_BAR; PG8_WAIT_L(0); PG8_MMA(0, 1, At, B1); PG8_BAR;
	v_mfma_f32_16x16x32_bf16 v[60:63], v[144:147], v[168:171], v[60:63]
	v_mfma_f32_16x16x32_bf16 v[56:59], v[160:163], v[168:171], v[56:59]
	v_mfma_f32_16x16x32_bf16 v[44:47], v[144:147], v[182:185], v[44:47]
	v_mfma_f32_16x16x32_bf16 v[40:43], v[160:163], v[182:185], v[40:43]
	v_mfma_f32_16x16x32_bf16 v[28:31], v[144:147], v[194:197], v[28:31]
	v_mfma_f32_16x16x32_bf16 v[24:27], v[160:163], v[194:197], v[24:27]
	v_mfma_f32_16x16x32_bf16 v[12:15], v[144:147], v[202:205], v[12:15]
	v_mfma_f32_16x16x32_bf16 v[8:11], v[160:163], v[202:205], v[8:11]
	v_mfma_f32_16x16x32_bf16 v[60:63], v[156:159], v[172:175], v[60:63]
	v_mfma_f32_16x16x32_bf16 v[56:59], v[164:167], v[172:175], v[56:59]
	v_mfma_f32_16x16x32_bf16 v[44:47], v[156:159], v[190:193], v[44:47]
	v_mfma_f32_16x16x32_bf16 v[40:43], v[164:167], v[190:193], v[40:43]
	v_mfma_f32_16x16x32_bf16 v[28:31], v[156:159], v[198:201], v[28:31]
	v_mfma_f32_16x16x32_bf16 v[24:27], v[164:167], v[198:201], v[24:27]
	v_mfma_f32_16x16x32_bf16 v[12:15], v[156:159], v[206:209], v[12:15]
	v_mfma_f32_16x16x32_bf16 v[8:11], v[164:167], v[206:209], v[8:11]
	v_mfma_f32_16x16x32_bf16 v[52:55], v[210:213], v[168:171], v[52:55]
	v_mfma_f32_16x16x32_bf16 v[48:51], v[218:221], v[168:171], v[48:51]
	v_mfma_f32_16x16x32_bf16 v[36:39], v[210:213], v[182:185], v[36:39]
	v_mfma_f32_16x16x32_bf16 v[32:35], v[218:221], v[182:185], v[32:35]
	v_mfma_f32_16x16x32_bf16 v[20:23], v[210:213], v[194:197], v[20:23]
	v_mfma_f32_16x16x32_bf16 v[16:19], v[218:221], v[194:197], v[16:19]
	v_mfma_f32_16x16x32_bf16 v[4:7], v[210:213], v[202:205], v[4:7]
	v_mfma_f32_16x16x32_bf16 v[0:3], v[218:221], v[202:205], v[0:3]
	v_mfma_f32_16x16x32_bf16 v[52:55], v[214:217], v[172:175], v[52:55]
	v_mfma_f32_16x16x32_bf16 v[48:51], v[222:225], v[172:175], v[48:51]
	v_mfma_f32_16x16x32_bf16 v[36:39], v[214:217], v[190:193], v[36:39]
	v_mfma_f32_16x16x32_bf16 v[32:35], v[222:225], v[190:193], v[32:35]
	v_mfma_f32_16x16x32_bf16 v[20:23], v[214:217], v[198:201], v[20:23]
	v_mfma_f32_16x16x32_bf16 v[16:19], v[222:225], v[198:201], v[16:19]
	v_mfma_f32_16x16x32_bf16 v[4:7], v[214:217], v[206:209], v[4:7]
	v_mfma_f32_16x16x32_bf16 v[0:3], v[222:225], v[206:209], v[0:3]
	s_barrier
	s_add_i32 s48, 0, 0x18000
	v_add_u32_e32 v164, s48, v151
	ds_read_b128 v[144:147], v164
	ds_read_b128 v[156:159], v164 offset:1024
	ds_read_b128 v[160:163], v164 offset:2048
	ds_read_b128 v[164:167], v164 offset:3072
	s_add_u32 s22, s22, 0x40000
	s_addc_u32 s23, s23, 0
	s_mov_b32 m0, s31
	v_lshl_add_u64 v[210:211], s[22:23], 0, v[128:129]
	ds_read_b128 v[168:171], v154 offset:32768
	ds_read_b128 v[172:175], v154 offset:33792
	ds_read_b128 v[182:185], v154 offset:34816
	ds_read_b128 v[190:193], v154 offset:35840
	ds_read_b128 v[194:197], v154 offset:36864
	ds_read_b128 v[198:201], v154 offset:37888
	ds_read_b128 v[202:205], v154 offset:38912
	ds_read_b128 v[206:209], v154 offset:39936
	global_load_lds_dwordx4 v[210:211], off
	v_lshl_add_u64 v[210:211], s[22:23], 0, v[132:133]
	s_mov_b32 m0, s34
	s_nop 0
	global_load_lds_dwordx4 v[210:211], off
	s_add_i32 s22, 0, 0x1c000
	v_add_u32_e32 v179, s22, v151
	ds_read_b128 v[210:213], v179
	ds_read_b128 v[214:217], v179 offset:1024
	ds_read_b128 v[218:221], v179 offset:2048
	ds_read_b128 v[222:225], v179 offset:3072
	s_waitcnt vmcnt(8) lgkmcnt(0)
	s_barrier
	v_mfma_f32_16x16x32_bf16 v[124:127], v[144:147], v[168:171], v[124:127]
	v_mfma_f32_16x16x32_bf16 v[120:123], v[160:163], v[168:171], v[120:123]
	v_mfma_f32_16x16x32_bf16 v[108:111], v[144:147], v[182:185], v[108:111]
	v_mfma_f32_16x16x32_bf16 v[104:107], v[160:163], v[182:185], v[104:107]
	v_mfma_f32_16x16x32_bf16 v[92:95], v[144:147], v[194:197], v[92:95]
	v_mfma_f32_16x16x32_bf16 v[88:91], v[160:163], v[194:197], v[88:91]
	v_mfma_f32_16x16x32_bf16 v[76:79], v[144:147], v[202:205], v[76:79]
	v_mfma_f32_16x16x32_bf16 v[72:75], v[160:163], v[202:205], v[72:75]
	v_mfma_f32_16x16x32_bf16 v[124:127], v[156:159], v[172:175], v[124:127]
	v_mfma_f32_16x16x32_bf16 v[120:123], v[164:167], v[172:175], v[120:123]
	v_mfma_f32_16x16x32_bf16 v[108:111], v[156:159], v[190:193], v[108:111]
	v_mfma_f32_16x16x32_bf16 v[104:107], v[164:167], v[190:193], v[104:107]
	v_mfma_f32_16x16x32_bf16 v[92:95], v[156:159], v[198:201], v[92:95]
	v_mfma_f32_16x16x32_bf16 v[88:91], v[164:167], v[198:201], v[88:91]
	v_mfma_f32_16x16x32_bf16 v[76:79], v[156:159], v[206:209], v[76:79]
	v_mfma_f32_16x16x32_bf16 v[72:75], v[164:167], v[206:209], v[72:75]
	v_mfma_f32_16x16x32_bf16 v[116:119], v[210:213], v[168:171], v[116:119]
	v_mfma_f32_16x16x32_bf16 v[112:115], v[218:221], v[168:171], v[112:115]
	v_mfma_f32_16x16x32_bf16 v[100:103], v[210:213], v[182:185], v[100:103]
	v_mfma_f32_16x16x32_bf16 v[96:99], v[218:221], v[182:185], v[96:99]
	v_mfma_f32_16x16x32_bf16 v[84:87], v[210:213], v[194:197], v[84:87]
	v_mfma_f32_16x16x32_bf16 v[80:83], v[218:221], v[194:197], v[80:83]
	v_mfma_f32_16x16x32_bf16 v[68:71], v[210:213], v[202:205], v[68:71]
	v_mfma_f32_16x16x32_bf16 v[64:67], v[218:221], v[202:205], v[64:67]
	v_mfma_f32_16x16x32_bf16 v[116:119], v[214:217], v[172:175], v[116:119]
	v_mfma_f32_16x16x32_bf16 v[112:115], v[222:225], v[172:175], v[112:115]
	v_mfma_f32_16x16x32_bf16 v[100:103], v[214:217], v[190:193], v[100:103]
	v_mfma_f32_16x16x32_bf16 v[96:99], v[222:225], v[190:193], v[96:99]
	v_mfma_f32_16x16x32_bf16 v[84:87], v[214:217], v[198:201], v[84:87]
	v_mfma_f32_16x16x32_bf16 v[80:83], v[222:225], v[198:201], v[80:83]
	v_mfma_f32_16x16x32_bf16 v[68:71], v[214:217], v[206:209], v[68:71]
	v_mfma_f32_16x16x32_bf16 v[64:67], v[222:225], v[206:209], v[64:67]
	s_barrier
; __device__ __forceinline__ unsigned cvt_pk_bf16(float lo, float hi) { unsigned r; asm volatile("v_cvt_pk_bf16_f32 %0, %1, %2" : "=v"(r) : "v"(lo), "v"(hi)); return r; }
; __device__ __forceinline__ float bf_lo(unsigned u) { return __uint_as_float(u << 16); }
; __device__ __forceinline__ float bf_hi(unsigned u) { return __uint_as_float(u & 0xffff0000u); }
; #define PG8_STAGE(bufoff, gbase, voff) do { _Pragma("unroll") for (int _i = 0; _i < 2; ++_i) \
;         __builtin_amdgcn_global_load_lds((const unsigned*)((const char*)(gbase) + (voff)[_i]), (PG8_LAS unsigned*)(lds + (bufoff) + ldsw + _i * 8192), 16, 0, 0); } while (0)
; #define PG8_BAR __builtin_amdgcn_s_barrier()
;     __device__ __forceinline__ void operator()(const f32x4 (&acc)[2][2][4][2], const Unit& u, int wr, int wc, int fr, int fq) const {
;     ...
;             for (int m = 0; m < 4; ++m) { const size_t r = (size_t)(row0 + ai * HALF + m * 16); bf16_t* rowp = O + r * ldc + col0; const bf16_t* gp = G + r * ldg + col0;
; #pragma unroll
;                 for (int bj = 0; bj < 2; ++bj) { const u32x4 gw = *(const u32x4*)(gp + bj * HALF);
;                     f32x4 v0 = acc[ai][bj][m][0], v1 = acc[ai][bj][m][1];
;                     v0[0] *= bf_lo(gw.x); v0[1] *= bf_hi(gw.x); v0[2] *= bf_lo(gw.y); v0[3] *= bf_hi(gw.y);
;                     v1[0] *= bf_lo(gw.z); v1[1] *= bf_hi(gw.z); v1[2] *= bf_lo(gw.w); v1[3] *= bf_hi(gw.w);
;                     if (ACCUM) { const u32x4 pw = *(const u32x4*)(rowp + bj * HALF);
;                         v0[0] += bf_lo(pw.x); v0[1] += bf_hi(pw.x); v0[2] += bf_lo(pw.y); v0[3] += bf_hi(pw.y);
;                         v1[0] += bf_lo(pw.z); v1[1] += bf_hi(pw.z); v1[2] += bf_lo(pw.w); v1[3] += bf_hi(pw.w); }
;                     u32x4 w; w.x = cvt_pk_bf16(v0[0], v0[1]); w.y = cvt_pk_bf16(v0[2], v0[3]); w.z = cvt_pk_bf16(v1[0], v1[1]); w.w = cvt_pk_bf16(v1[2], v1[3]);
;                     *(u32x4*)(rowp + bj * HALF) = w; } }
; template <class Epi, class Sched>
; __device__ __forceinline__ void gemm_phase(PG8_LAS unsigned char* lds, const Gemm g, const Sched& S, const Epi& E) {
;     ...
;             PG8_LDA(At, 1, 1); PG8_STAGE(PG8_SA(1, 0), a3, voffA);
;             PG8_BAR; PG8_WAIT_L(0); PG8_MMA(1, 0, At, B0); PG8_BAR; PG8_SCHED;
;             PG8_STAGE(PG8_SB(1, 1), b3 + hstep, voffB);
;             PG8_WAIT_V(6); PG8_BAR; PG8_MMA(1, 1, At, B1); PG8_BAR;
	ds_read_b128 v[168:171], v154 offset:49152
	ds_read_b128 v[172:175], v154 offset:50176
	ds_read_b128 v[182:185], v154 offset:51200
	ds_read_b128 v[190:193], v154 offset:52224
	ds_read_b128 v[194:197], v154 offset:53248
	ds_read_b128 v[198:201], v154 offset:54272
	ds_read_b128 v[202:205], v154 offset:55296
	ds_read_b128 v[206:209], v154 offset:56320
	s_add_i32 s23, s48, s29
	v_lshl_add_u64 v[148:149], v[148:149], 0, s[6:7]
	s_mov_b32 m0, s23
	s_nop 0
	global_load_lds_dwordx4 v[148:149], off
	v_lshl_add_u64 v[148:149], v[186:187], 0, s[6:7]
	s_add_i32 m0, s23, 0x2000
	s_nop 0
	global_load_lds_dwordx4 v[148:149], off
	s_mov_b32 m0, s36
	v_lshl_add_u64 v[148:149], v[226:227], 0, s[6:7]
	global_load_lds_dwordx4 v[148:149], off
	v_lshl_add_u64 v[148:149], v[228:229], 0, s[6:7]
	s_mov_b32 m0, s37
	s_nop 0
	global_load_lds_dwordx4 v[148:149], off
	s_add_u32 s20, s20, 0x40080
	s_addc_u32 s21, s21, 0
	s_add_i32 s22, s22, s29
	v_lshl_add_u64 v[246:247], s[20:21], 0, v[130:131]
	s_mov_b32 m0, s22
	s_nop 0
	global_load_lds_dwordx4 v[246:247], off
	v_lshl_add_u64 v[246:247], s[20:21], 0, v[134:135]
	s_add_i32 m0, s22, 0x2000
	s_nop 0
	global_load_lds_dwordx4 v[246:247], off
	s_waitcnt vmcnt(8) lgkmcnt(0)
	s_barrier
	v_mfma_f32_16x16x32_bf16 v[60:63], v[144:147], v[168:171], v[60:63]
	v_mfma_f32_16x16x32_bf16 v[56:59], v[160:163], v[168:171], v[56:59]
	v_mfma_f32_16x16x32_bf16 v[44:47], v[144:147], v[182:185], v[44:47]
	v_mfma_f32_16x16x32_bf16 v[40:43], v[160:163], v[182:185], v[40:43]
	v_mfma_f32_16x16x32_bf16 v[28:31], v[144:147], v[194:197], v[28:31]
	v_mfma_f32_16x16x32_bf16 v[24:27], v[160:163], v[194:197], v[24:27]
	v_mfma_f32_16x16x32_bf16 v[12:15], v[144:147], v[202:205], v[12:15]
	v_mfma_f32_16x16x32_bf16 v[8:11], v[160:163], v[202:205], v[8:11]
	v_mfma_f32_16x16x32_bf16 v[60:63], v[156:159], v[172:175], v[60:63]
	v_mfma_f32_16x16x32_bf16 v[56:59], v[164:167], v[172:175], v[56:59]
	v_mfma_f32_16x16x32_bf16 v[44:47], v[156:159], v[190:193], v[44:47]
	v_mfma_f32_16x16x32_bf16 v[40:43], v[164:167], v[190:193], v[40:43]
	v_mfma_f32_16x16x32_bf16 v[28:31], v[156:159], v[198:201], v[28:31]
	v_mfma_f32_16x16x32_bf16 v[24:27], v[164:167], v[198:201], v[24:27]
	v_mfma_f32_16x16x32_bf16 v[12:15], v[156:159], v[206:209], v[12:15]
	v_mfma_f32_16x16x32_bf16 v[8:11], v[164:167], v[206:209], v[8:11]
	v_mfma_f32_16x16x32_bf16 v[52:55], v[210:213], v[168:171], v[52:55]
	v_mfma_f32_16x16x32_bf16 v[48:51], v[218:221], v[168:171], v[48:51]
	v_mfma_f32_16x16x32_bf16 v[36:39], v[210:213], v[182:185], v[36:39]
	v_mfma_f32_16x16x32_bf16 v[32:35], v[218:221], v[182:185], v[32:35]
	v_mfma_f32_16x16x32_bf16 v[20:23], v[210:213], v[194:197], v[20:23]
	v_mfma_f32_16x16x32_bf16 v[16:19], v[218:221], v[194:197], v[16:19]
	v_mfma_f32_16x16x32_bf16 v[4:7], v[210:213], v[202:205], v[4:7]
	v_mfma_f32_16x16x32_bf16 v[0:3], v[218:221], v[202:205], v[0:3]
	v_mfma_f32_16x16x32_bf16 v[52:55], v[214:217], v[172:175], v[52:55]
	v_mfma_f32_16x16x32_bf16 v[48:51], v[222:225], v[172:175], v[48:51]
	v_mfma_f32_16x16x32_bf16 v[36:39], v[214:217], v[190:193], v[36:39]
	v_mfma_f32_16x16x32_bf16 v[32:35], v[222:225], v[190:193], v[32:35]
	v_mfma_f32_16x16x32_bf16 v[20:23], v[214:217], v[198:201], v[20:23]
	v_mfma_f32_16x16x32_bf16 v[16:19], v[222:225], v[198:201], v[16:19]
	v_mfma_f32_16x16x32_bf16 v[4:7], v[214:217], v[206:209], v[4:7]
	v_mfma_f32_16x16x32_bf16 v[0:3], v[222:225], v[206:209], v[0:3]
	s_barrier
	s_add_i32 s47, s47, 2
	s_add_u32 s18, s18, 0x100
	s_addc_u32 s19, s19, 0
	s_add_u32 s45, s45, 0x100
	s_addc_u32 s46, s46, 0
	s_cmp_gt_u32 s47, 13
	s_cbranch_scc0 .LBB0_1011
	v_lshl_add_u32 v146, s16, 8, v150
	v_lshl_or_b32 v144, s42, 8, v152
	v_ashrrev_i32_e32 v147, 31, v146
	v_ashrrev_i32_e32 v145, 31, v144
	v_mov_b64_e32 v[148:149], s[4:5]
	v_lshlrev_b64 v[160:161], 11, v[146:147]
	v_lshlrev_b64 v[144:145], 1, v[144:145]
	v_mad_i64_i32 v[156:157], s[18:19], v146, s41, v[148:149]
	v_lshl_add_u64 v[160:161], s[0:1], 0, v[160:161]
	v_lshl_add_u64 v[164:165], v[156:157], 0, v[144:145]
	v_lshl_add_u64 v[166:167], v[160:161], 0, v[144:145]
	global_load_dwordx4 v[156:159], v[164:165], off
	global_load_dwordx4 v[160:163], v[166:167], off
	s_and_b64 vcc, exec, s[2:3]
	s_mov_b32 s42, s8
	s_mov_b32 s16, s10
	s_mov_b64 s[20:21], s[14:15]
	s_waitcnt vmcnt(0)
	v_lshlrev_b32_e32 v147, 16, v156
	v_and_b32_e32 v156, 0xffff0000, v156
	v_lshlrev_b32_e32 v168, 16, v157
	v_and_b32_e32 v157, 0xffff0000, v157
	v_lshlrev_b32_e32 v169, 16, v158
	v_and_b32_e32 v158, 0xffff0000, v158
	v_lshlrev_b32_e32 v170, 16, v159
	v_and_b32_e32 v159, 0xffff0000, v159
	v_lshlrev_b32_e32 v171, 16, v160
	v_and_b32_e32 v160, 0xffff0000, v160
	v_lshlrev_b32_e32 v172, 16, v161
	v_and_b32_e32 v161, 0xffff0000, v161
	v_lshlrev_b32_e32 v173, 16, v162
	v_and_b32_e32 v162, 0xffff0000, v162
	v_lshlrev_b32_e32 v174, 16, v163
	v_and_b32_e32 v163, 0xffff0000, v163
	v_fmac_f32_e32 v171, v124, v147
	v_fmac_f32_e32 v160, v125, v156
	v_fmac_f32_e32 v172, v126, v168
	v_fmac_f32_e32 v161, v127, v157
	v_fmac_f32_e32 v173, v120, v169
	v_fmac_f32_e32 v162, v121, v158
	v_fmac_f32_e32 v174, v122, v170
	v_fmac_f32_e32 v163, v123, v159
	v_cvt_pk_bf16_f32 v120, v171, v160
	v_cvt_pk_bf16_f32 v121, v172, v161
	v_cvt_pk_bf16_f32 v122, v173, v162
	v_cvt_pk_bf16_f32 v123, v174, v163
	global_load_dwordx4 v[124:127], v[164:165], off offset:256
	global_load_dwordx4 v[156:159], v[166:167], off offset:256
	v_or_b32_e32 v160, 16, v146
	global_store_dwordx4 v[166:167], v[120:123], off
	v_mad_i64_i32 v[162:163], s[18:19], v160, s41, v[148:149]
	v_lshl_add_u64 v[162:163], v[162:163], 0, v[144:145]
	s_waitcnt vmcnt(0)
; __device__ __forceinline__ unsigned cvt_pk_bf16(float lo, float hi) { unsigned r; asm volatile("v_cvt_pk_bf16_f32 %0, %1, %2" : "=v"(r) : "v"(lo), "v"(hi)); return r; }
; __device__ __forceinline__ float bf_lo(unsigned u) { return __uint_as_float(u << 16); }
; __device__ __forceinline__ float bf_hi(unsigned u) { return __uint_as_float(u & 0xffff0000u); }
;     __device__ __forceinline__ void operator()(const f32x4 (&acc)[2][2][4][2], const Unit& u, int wr, int wc, int fr, int fq) const {
;     ...
;             for (int m = 0; m < 4; ++m) { const size_t r = (size_t)(row0 + ai * HALF + m * 16); bf16_t* rowp = O + r * ldc + col0; const bf16_t* gp = G + r * ldg + col0;
; #pragma unroll
;                 for (int bj = 0; bj < 2; ++bj) { const u32x4 gw = *(const u32x4*)(gp + bj * HALF);
;                     f32x4 v0 = acc[ai][bj][m][0], v1 = acc[ai][bj][m][1];
;                     v0[0] *= bf_lo(gw.x); v0[1] *= bf_hi(gw.x); v0[2] *= bf_lo(gw.y); v0[3] *= bf_hi(gw.y);
;                     v1[0] *= bf_lo(gw.z); v1[1] *= bf_hi(gw.z); v1[2] *= bf_lo(gw.w); v1[3] *= bf_hi(gw.w);
;                     if (ACCUM) { const u32x4 pw = *(const u32x4*)(rowp + bj * HALF);
;                         v0[0] += bf_lo(pw.x); v0[1] += bf_hi(pw.x); v0[2] += bf_lo(pw.y); v0[3] += bf_hi(pw.y);
;                         v1[0] += bf_lo(pw.z); v1[1] += bf_hi(pw.z); v1[2] += bf_lo(pw.w); v1[3] += bf_hi(pw.w); }
;                     u32x4 w; w.x = cvt_pk_bf16(v0[0], v0[1]); w.y = cvt_pk_bf16(v0[2], v0[3]); w.z = cvt_pk_bf16(v1[0], v1[1]); w.w = cvt_pk_bf16(v1[2], v1[3]);
;                     *(u32x4*)(rowp + bj * HALF) = w; } }
	v_lshlrev_b32_e32 v122, 16, v125
	v_lshlrev_b32_e32 v161, 16, v157
	v_lshlrev_b32_e32 v120, 16, v124
	v_and_b32_e32 v121, 0xffff0000, v124
	v_and_b32_e32 v123, 0xffff0000, v125
	v_lshlrev_b32_e32 v124, 16, v126
	v_and_b32_e32 v125, 0xffff0000, v126
	v_lshlrev_b32_e32 v147, 16, v156
	v_and_b32_e32 v156, 0xffff0000, v156
	v_and_b32_e32 v157, 0xffff0000, v157
	v_lshlrev_b32_e32 v164, 16, v158
	v_and_b32_e32 v158, 0xffff0000, v158
	v_fmac_f32_e32 v161, v118, v122
	v_fmac_f32_e32 v147, v116, v120
	v_fmac_f32_e32 v156, v117, v121
	v_fmac_f32_e32 v157, v119, v123
	v_fmac_f32_e32 v164, v112, v124
	v_fmac_f32_e32 v158, v113, v125
	v_cvt_pk_bf16_f32 v112, v147, v156
	v_cvt_pk_bf16_f32 v113, v161, v157
	v_ashrrev_i32_e32 v161, 31, v160
	v_lshlrev_b64 v[120:121], 11, v[160:161]
	v_lshl_add_u64 v[120:121], s[0:1], 0, v[120:121]
	v_lshlrev_b32_e32 v126, 16, v127
	v_and_b32_e32 v127, 0xffff0000, v127
	v_lshlrev_b32_e32 v165, 16, v159
	v_and_b32_e32 v159, 0xffff0000, v159
	v_lshl_add_u64 v[124:125], v[120:121], 0, v[144:145]
	v_fmac_f32_e32 v165, v114, v126
	v_fmac_f32_e32 v159, v115, v127
	v_cvt_pk_bf16_f32 v114, v164, v158
	v_cvt_pk_bf16_f32 v115, v165, v159
	global_load_dwordx4 v[116:119], v[162:163], off
	global_load_dwordx4 v[120:123], v[124:125], off
	s_waitcnt vmcnt(0)
	v_lshlrev_b32_e32 v126, 16, v120
	global_store_dwordx4 v[166:167], v[112:115], off offset:256
	v_and_b32_e32 v120, 0xffff0000, v120
	v_lshlrev_b32_e32 v127, 16, v121
	v_lshlrev_b32_e32 v112, 16, v116
	v_and_b32_e32 v113, 0xffff0000, v116
	v_lshlrev_b32_e32 v114, 16, v117
	v_and_b32_e32 v115, 0xffff0000, v117
	v_lshlrev_b32_e32 v116, 16, v118
	v_and_b32_e32 v117, 0xffff0000, v118
	v_lshlrev_b32_e32 v118, 16, v119
	v_and_b32_e32 v119, 0xffff0000, v119
	v_and_b32_e32 v121, 0xffff0000, v121
	v_lshlrev_b32_e32 v147, 16, v122
	v_and_b32_e32 v122, 0xffff0000, v122
	v_lshlrev_b32_e32 v156, 16, v123
	v_and_b32_e32 v123, 0xffff0000, v123
	v_fmac_f32_e32 v126, v108, v112
	v_fmac_f32_e32 v120, v109, v113
	v_fmac_f32_e32 v127, v110, v114
	v_fmac_f32_e32 v121, v111, v115
	v_fmac_f32_e32 v147, v104, v116
	v_fmac_f32_e32 v122, v105, v117
	v_fmac_f32_e32 v156, v106, v118
	v_fmac_f32_e32 v123, v107, v119
	v_cvt_pk_bf16_f32 v104, v126, v120
	v_cvt_pk_bf16_f32 v105, v127, v121
	v_cvt_pk_bf16_f32 v106, v147, v122
	v_cvt_pk_bf16_f32 v107, v156, v123
	global_load_dwordx4 v[108:111], v[162:163], off offset:256
	global_load_dwordx4 v[112:115], v[124:125], off offset:256
	v_or_b32_e32 v116, 32, v146
	global_store_dwordx4 v[124:125], v[104:107], off
	v_mad_i64_i32 v[118:119], s[18:19], v116, s41, v[148:149]
	v_lshl_add_u64 v[118:119], v[118:119], 0, v[144:145]
	s_waitcnt vmcnt(0)
	v_lshlrev_b32_e32 v104, 16, v108
	v_lshlrev_b32_e32 v117, 16, v112
	v_and_b32_e32 v105, 0xffff0000, v108
	v_lshlrev_b32_e32 v108, 16, v110
	v_and_b32_e32 v112, 0xffff0000, v112
	v_lshlrev_b32_e32 v121, 16, v114
	v_fmac_f32_e32 v117, v100, v104
	v_fmac_f32_e32 v112, v101, v105
	v_fmac_f32_e32 v121, v96, v108
	v_cvt_pk_bf16_f32 v96, v117, v112
	v_ashrrev_i32_e32 v117, 31, v116
	v_lshlrev_b64 v[104:105], 11, v[116:117]
	v_lshlrev_b32_e32 v106, 16, v109
	v_and_b32_e32 v107, 0xffff0000, v109
	v_and_b32_e32 v109, 0xffff0000, v110
	v_and_b32_e32 v114, 0xffff0000, v114
	v_lshl_add_u64 v[104:105], s[0:1], 0, v[104:105]
	v_lshlrev_b32_e32 v110, 16, v111
	v_and_b32_e32 v111, 0xffff0000, v111
	v_lshlrev_b32_e32 v120, 16, v113
	v_and_b32_e32 v113, 0xffff0000, v113
	v_lshlrev_b32_e32 v122, 16, v115
	v_and_b32_e32 v115, 0xffff0000, v115
	v_fmac_f32_e32 v114, v97, v109
	v_lshl_add_u64 v[108:109], v[104:105], 0, v[144:145]
	v_fmac_f32_e32 v120, v102, v106
	v_fmac_f32_e32 v113, v103, v107
	v_fmac_f32_e32 v122, v98, v110
	v_fmac_f32_e32 v115, v99, v111
	v_cvt_pk_bf16_f32 v97, v120, v113
	v_cvt_pk_bf16_f32 v98, v121, v114
	v_cvt_pk_bf16_f32 v99, v122, v115
	global_load_dwordx4 v[100:103], v[118:119], off
	global_load_dwordx4 v[104:107], v[108:109], off
	s_waitcnt vmcnt(0)
	v_lshlrev_b32_e32 v110, 16, v104
	global_store_dwordx4 v[124:125], v[96:99], off offset:256
	v_and_b32_e32 v104, 0xffff0000, v104
	v_lshlrev_b32_e32 v111, 16, v105
	v_lshlrev_b32_e32 v96, 16, v100
	v_and_b32_e32 v97, 0xffff0000, v100
	v_lshlrev_b32_e32 v98, 16, v101
	v_and_b32_e32 v99, 0xffff0000, v101
	v_lshlrev_b32_e32 v100, 16, v102
	v_and_b32_e32 v101, 0xffff0000, v102
	v_lshlrev_b32_e32 v102, 16, v103
	v_and_b32_e32 v103, 0xffff0000, v103
	v_and_b32_e32 v105, 0xffff0000, v105
	v_lshlrev_b32_e32 v112, 16, v106
	v_and_b32_e32 v106, 0xffff0000, v106
	v_lshlrev_b32_e32 v113, 16, v107
	v_and_b32_e32 v107, 0xffff0000, v107
	v_fmac_f32_e32 v110, v92, v96
	v_fmac_f32_e32 v104, v93, v97
	v_fmac_f32_e32 v111, v94, v98
	v_fmac_f32_e32 v105, v95, v99
	v_fmac_f32_e32 v112, v88, v100
	v_fmac_f32_e32 v106, v89, v101
	v_fmac_f32_e32 v113, v90, v102
	v_fmac_f32_e32 v107, v91, v103
	v_cvt_pk_bf16_f32 v88, v110, v104
	v_cvt_pk_bf16_f32 v89, v111, v105
	v_cvt_pk_bf16_f32 v90, v112, v106
	v_cvt_pk_bf16_f32 v91, v113, v107
	global_load_dwordx4 v[92:95], v[118:119], off offset:256
	global_load_dwordx4 v[96:99], v[108:109], off offset:256
	v_or_b32_e32 v100, 48, v146
	global_store_dwordx4 v[108:109], v[88:91], off
	v_mad_i64_i32 v[102:103], s[18:19], v100, s41, v[148:149]
	v_lshl_add_u64 v[102:103], v[102:103], 0, v[144:145]
	s_waitcnt vmcnt(0)
; __device__ __forceinline__ unsigned cvt_pk_bf16(float lo, float hi) { unsigned r; asm volatile("v_cvt_pk_bf16_f32 %0, %1, %2" : "=v"(r) : "v"(lo), "v"(hi)); return r; }
; __device__ __forceinline__ float bf_lo(unsigned u) { return __uint_as_float(u << 16); }
; __device__ __forceinline__ float bf_hi(unsigned u) { return __uint_as_float(u & 0xffff0000u); }
;     __device__ __forceinline__ void operator()(const f32x4 (&acc)[2][2][4][2], const Unit& u, int wr, int wc, int fr, int fq) const {
;     ...
;             for (int m = 0; m < 4; ++m) { const size_t r = (size_t)(row0 + ai * HALF + m * 16); bf16_t* rowp = O + r * ldc + col0; const bf16_t* gp = G + r * ldg + col0;
; #pragma unroll
;                 for (int bj = 0; bj < 2; ++bj) { const u32x4 gw = *(const u32x4*)(gp + bj * HALF);
;                     f32x4 v0 = acc[ai][bj][m][0], v1 = acc[ai][bj][m][1];
;                     v0[0] *= bf_lo(gw.x); v0[1] *= bf_hi(gw.x); v0[2] *= bf_lo(gw.y); v0[3] *= bf_hi(gw.y);
;                     v1[0] *= bf_lo(gw.z); v1[1] *= bf_hi(gw.z); v1[2] *= bf_lo(gw.w); v1[3] *= bf_hi(gw.w);
;                     if (ACCUM) { const u32x4 pw = *(const u32x4*)(rowp + bj * HALF);
;                         v0[0] += bf_lo(pw.x); v0[1] += bf_hi(pw.x); v0[2] += bf_lo(pw.y); v0[3] += bf_hi(pw.y);
;                         v1[0] += bf_lo(pw.z); v1[1] += bf_hi(pw.z); v1[2] += bf_lo(pw.w); v1[3] += bf_hi(pw.w); }
;                     u32x4 w; w.x = cvt_pk_bf16(v0[0], v0[1]); w.y = cvt_pk_bf16(v0[2], v0[3]); w.z = cvt_pk_bf16(v1[0], v1[1]); w.w = cvt_pk_bf16(v1[2], v1[3]);
;                     *(u32x4*)(rowp + bj * HALF) = w; } }
	v_lshlrev_b32_e32 v88, 16, v92
	v_lshlrev_b32_e32 v101, 16, v96
	v_and_b32_e32 v89, 0xffff0000, v92
	v_lshlrev_b32_e32 v92, 16, v94
	v_and_b32_e32 v96, 0xffff0000, v96
	v_lshlrev_b32_e32 v105, 16, v98
	v_fmac_f32_e32 v101, v84, v88
	v_fmac_f32_e32 v96, v85, v89
	v_fmac_f32_e32 v105, v80, v92
	v_cvt_pk_bf16_f32 v80, v101, v96
	v_ashrrev_i32_e32 v101, 31, v100
	v_lshlrev_b64 v[88:89], 11, v[100:101]
	v_lshlrev_b32_e32 v90, 16, v93
	v_and_b32_e32 v91, 0xffff0000, v93
	v_and_b32_e32 v93, 0xffff0000, v94
	v_and_b32_e32 v98, 0xffff0000, v98
	v_lshl_add_u64 v[88:89], s[0:1], 0, v[88:89]
	v_lshlrev_b32_e32 v94, 16, v95
	v_and_b32_e32 v95, 0xffff0000, v95
	v_lshlrev_b32_e32 v104, 16, v97
	v_and_b32_e32 v97, 0xffff0000, v97
	v_lshlrev_b32_e32 v106, 16, v99
	v_and_b32_e32 v99, 0xffff0000, v99
	v_fmac_f32_e32 v98, v81, v93
	v_lshl_add_u64 v[92:93], v[88:89], 0, v[144:145]
	v_fmac_f32_e32 v104, v86, v90
	v_fmac_f32_e32 v97, v87, v91
	v_fmac_f32_e32 v106, v82, v94
	v_fmac_f32_e32 v99, v83, v95
	v_cvt_pk_bf16_f32 v81, v104, v97
	v_cvt_pk_bf16_f32 v82, v105, v98
	v_cvt_pk_bf16_f32 v83, v106, v99
	global_load_dwordx4 v[84:87], v[102:103], off
	global_load_dwordx4 v[88:91], v[92:93], off
	s_waitcnt vmcnt(0)
	v_lshlrev_b32_e32 v94, 16, v88
	global_store_dwordx4 v[108:109], v[80:83], off offset:256
	v_and_b32_e32 v88, 0xffff0000, v88
	v_lshlrev_b32_e32 v95, 16, v89
	v_lshlrev_b32_e32 v80, 16, v84
	v_and_b32_e32 v81, 0xffff0000, v84
	v_lshlrev_b32_e32 v82, 16, v85
	v_and_b32_e32 v83, 0xffff0000, v85
	v_lshlrev_b32_e32 v84, 16, v86
	v_and_b32_e32 v85, 0xffff0000, v86
	v_lshlrev_b32_e32 v86, 16, v87
	v_and_b32_e32 v87, 0xffff0000, v87
	v_and_b32_e32 v89, 0xffff0000, v89
	v_lshlrev_b32_e32 v96, 16, v90
	v_and_b32_e32 v90, 0xffff0000, v90
	v_lshlrev_b32_e32 v97, 16, v91
	v_and_b32_e32 v91, 0xffff0000, v91
	v_fmac_f32_e32 v94, v76, v80
	v_fmac_f32_e32 v88, v77, v81
	v_fmac_f32_e32 v95, v78, v82
	v_fmac_f32_e32 v89, v79, v83
	v_fmac_f32_e32 v96, v72, v84
	v_fmac_f32_e32 v90, v73, v85
	v_fmac_f32_e32 v97, v74, v86
	v_fmac_f32_e32 v91, v75, v87
	v_cvt_pk_bf16_f32 v72, v94, v88
	v_cvt_pk_bf16_f32 v73, v95, v89
	v_cvt_pk_bf16_f32 v74, v96, v90
	v_cvt_pk_bf16_f32 v75, v97, v91
	global_load_dwordx4 v[76:79], v[102:103], off offset:256
	global_load_dwordx4 v[80:83], v[92:93], off offset:256
	v_add_u32_e32 v84, 0x80, v146
	global_store_dwordx4 v[92:93], v[72:75], off
	v_mad_i64_i32 v[86:87], s[18:19], v84, s41, v[148:149]
	v_lshl_add_u64 v[86:87], v[86:87], 0, v[144:145]
	s_waitcnt vmcnt(0)
	v_lshlrev_b32_e32 v72, 16, v76
	v_lshlrev_b32_e32 v85, 16, v80
	v_and_b32_e32 v73, 0xffff0000, v76
	v_lshlrev_b32_e32 v76, 16, v78
	v_and_b32_e32 v80, 0xffff0000, v80
	v_lshlrev_b32_e32 v89, 16, v82
	v_fmac_f32_e32 v85, v68, v72
	v_fmac_f32_e32 v80, v69, v73
	v_fmac_f32_e32 v89, v64, v76
	v_cvt_pk_bf16_f32 v64, v85, v80
	v_ashrrev_i32_e32 v85, 31, v84
	v_lshlrev_b64 v[72:73], 11, v[84:85]
	v_lshlrev_b32_e32 v74, 16, v77
	v_and_b32_e32 v75, 0xffff0000, v77
	v_and_b32_e32 v77, 0xffff0000, v78
	v_and_b32_e32 v82, 0xffff0000, v82
	v_lshl_add_u64 v[72:73], s[0:1], 0, v[72:73]
	v_lshlrev_b32_e32 v78, 16, v79
	v_and_b32_e32 v79, 0xffff0000, v79
	v_lshlrev_b32_e32 v88, 16, v81
	v_and_b32_e32 v81, 0xffff0000, v81
	v_lshlrev_b32_e32 v90, 16, v83
	v_and_b32_e32 v83, 0xffff0000, v83
	v_fmac_f32_e32 v82, v65, v77
	v_lshl_add_u64 v[76:77], v[72:73], 0, v[144:145]
	v_fmac_f32_e32 v88, v70, v74
	v_fmac_f32_e32 v81, v71, v75
	v_fmac_f32_e32 v90, v66, v78
	v_fmac_f32_e32 v83, v67, v79
	v_cvt_pk_bf16_f32 v65, v88, v81
	v_cvt_pk_bf16_f32 v66, v89, v82
	v_cvt_pk_bf16_f32 v67, v90, v83
	global_load_dwordx4 v[68:71], v[86:87], off
	global_load_dwordx4 v[72:75], v[76:77], off
	s_waitcnt vmcnt(0)
	v_lshlrev_b32_e32 v78, 16, v72
	global_store_dwordx4 v[92:93], v[64:67], off offset:256
	v_and_b32_e32 v72, 0xffff0000, v72
	v_lshlrev_b32_e32 v79, 16, v73
	v_lshlrev_b32_e32 v64, 16, v68
	v_and_b32_e32 v65, 0xffff0000, v68
	v_lshlrev_b32_e32 v66, 16, v69
	v_and_b32_e32 v67, 0xffff0000, v69
	v_lshlrev_b32_e32 v68, 16, v70
	v_and_b32_e32 v69, 0xffff0000, v70
	v_lshlrev_b32_e32 v70, 16, v71
	v_and_b32_e32 v71, 0xffff0000, v71
	v_and_b32_e32 v73, 0xffff0000, v73
	v_lshlrev_b32_e32 v80, 16, v74
	v_and_b32_e32 v74, 0xffff0000, v74
	v_lshlrev_b32_e32 v81, 16, v75
	v_and_b32_e32 v75, 0xffff0000, v75
	v_fmac_f32_e32 v78, v60, v64
	v_fmac_f32_e32 v72, v61, v65
	v_fmac_f32_e32 v79, v62, v66
	v_fmac_f32_e32 v73, v63, v67
	v_fmac_f32_e32 v80, v56, v68
	v_fmac_f32_e32 v74, v57, v69
	v_fmac_f32_e32 v81, v58, v70
	v_fmac_f32_e32 v75, v59, v71
	v_cvt_pk_bf16_f32 v56, v78, v72
	v_cvt_pk_bf16_f32 v57, v79, v73
	v_cvt_pk_bf16_f32 v58, v80, v74
	v_cvt_pk_bf16_f32 v59, v81, v75
	global_load_dwordx4 v[60:63], v[86:87], off offset:256
	global_load_dwordx4 v[64:67], v[76:77], off offset:256
	v_add_u32_e32 v68, 0x90, v146
	global_store_dwordx4 v[76:77], v[56:59], off
	v_mad_i64_i32 v[70:71], s[18:19], v68, s41, v[148:149]
	v_lshl_add_u64 v[70:71], v[70:71], 0, v[144:145]
	s_waitcnt vmcnt(0)
	v_lshlrev_b32_e32 v56, 16, v60
	v_lshlrev_b32_e32 v69, 16, v64
	v_and_b32_e32 v57, 0xffff0000, v60
	v_lshlrev_b32_e32 v60, 16, v62
	v_and_b32_e32 v64, 0xffff0000, v64
	v_lshlrev_b32_e32 v73, 16, v66
	v_fmac_f32_e32 v69, v52, v56
	v_fmac_f32_e32 v64, v53, v57
	v_fmac_f32_e32 v73, v48, v60
	v_cvt_pk_bf16_f32 v48, v69, v64
	v_ashrrev_i32_e32 v69, 31, v68
	v_lshlrev_b64 v[56:57], 11, v[68:69]
	v_lshlrev_b32_e32 v58, 16, v61
	v_and_b32_e32 v59, 0xffff0000, v61
	v_and_b32_e32 v61, 0xffff0000, v62
	v_and_b32_e32 v66, 0xffff0000, v66
	v_lshl_add_u64 v[56:57], s[0:1], 0, v[56:57]
	v_lshlrev_b32_e32 v62, 16, v63
	v_and_b32_e32 v63, 0xffff0000, v63
	v_lshlrev_b32_e32 v72, 16, v65
	v_and_b32_e32 v65, 0xffff0000, v65
	v_lshlrev_b32_e32 v74, 16, v67
	v_and_b32_e32 v67, 0xffff0000, v67
	v_fmac_f32_e32 v66, v49, v61
	v_lshl_add_u64 v[60:61], v[56:57], 0, v[144:145]
	v_fmac_f32_e32 v72, v54, v58
	v_fmac_f32_e32 v65, v55, v59
	v_fmac_f32_e32 v74, v50, v62
	v_fmac_f32_e32 v67, v51, v63
	v_cvt_pk_bf16_f32 v49, v72, v65
	v_cvt_pk_bf16_f32 v50, v73, v66
	v_cvt_pk_bf16_f32 v51, v74, v67
	global_load_dwordx4 v[52:55], v[70:71], off
	global_load_dwordx4 v[56:59], v[60:61], off
	s_waitcnt vmcnt(0)
; __device__ __forceinline__ unsigned cvt_pk_bf16(float lo, float hi) { unsigned r; asm volatile("v_cvt_pk_bf16_f32 %0, %1, %2" : "=v"(r) : "v"(lo), "v"(hi)); return r; }
; __device__ __forceinline__ float bf_lo(unsigned u) { return __uint_as_float(u << 16); }
; __device__ __forceinline__ float bf_hi(unsigned u) { return __uint_as_float(u & 0xffff0000u); }
;     __device__ __forceinline__ void operator()(const f32x4 (&acc)[2][2][4][2], const Unit& u, int wr, int wc, int fr, int fq) const {
;     ...
;             for (int m = 0; m < 4; ++m) { const size_t r = (size_t)(row0 + ai * HALF + m * 16); bf16_t* rowp = O + r * ldc + col0; const bf16_t* gp = G + r * ldg + col0;
; #pragma unroll
;                 for (int bj = 0; bj < 2; ++bj) { const u32x4 gw = *(const u32x4*)(gp + bj * HALF);
;                     f32x4 v0 = acc[ai][bj][m][0], v1 = acc[ai][bj][m][1];
;                     v0[0] *= bf_lo(gw.x); v0[1] *= bf_hi(gw.x); v0[2] *= bf_lo(gw.y); v0[3] *= bf_hi(gw.y);
;                     v1[0] *= bf_lo(gw.z); v1[1] *= bf_hi(gw.z); v1[2] *= bf_lo(gw.w); v1[3] *= bf_hi(gw.w);
;                     if (ACCUM) { const u32x4 pw = *(const u32x4*)(rowp + bj * HALF);
;                         v0[0] += bf_lo(pw.x); v0[1] += bf_hi(pw.x); v0[2] += bf_lo(pw.y); v0[3] += bf_hi(pw.y);
;                         v1[0] += bf_lo(pw.z); v1[1] += bf_hi(pw.z); v1[2] += bf_lo(pw.w); v1[3] += bf_hi(pw.w); }
;                     u32x4 w; w.x = cvt_pk_bf16(v0[0], v0[1]); w.y = cvt_pk_bf16(v0[2], v0[3]); w.z = cvt_pk_bf16(v1[0], v1[1]); w.w = cvt_pk_bf16(v1[2], v1[3]);
;                     *(u32x4*)(rowp + bj * HALF) = w; } }
	v_lshlrev_b32_e32 v62, 16, v56
	global_store_dwordx4 v[76:77], v[48:51], off offset:256
	v_and_b32_e32 v56, 0xffff0000, v56
	v_lshlrev_b32_e32 v63, 16, v57
	v_lshlrev_b32_e32 v48, 16, v52
	v_and_b32_e32 v49, 0xffff0000, v52
	v_lshlrev_b32_e32 v50, 16, v53
	v_and_b32_e32 v51, 0xffff0000, v53
	v_lshlrev_b32_e32 v52, 16, v54
	v_and_b32_e32 v53, 0xffff0000, v54
	v_lshlrev_b32_e32 v54, 16, v55
	v_and_b32_e32 v55, 0xffff0000, v55
	v_and_b32_e32 v57, 0xffff0000, v57
	v_lshlrev_b32_e32 v64, 16, v58
	v_and_b32_e32 v58, 0xffff0000, v58
	v_lshlrev_b32_e32 v65, 16, v59
	v_and_b32_e32 v59, 0xffff0000, v59
	v_fmac_f32_e32 v62, v44, v48
	v_fmac_f32_e32 v56, v45, v49
	v_fmac_f32_e32 v63, v46, v50
	v_fmac_f32_e32 v57, v47, v51
	v_fmac_f32_e32 v64, v40, v52
	v_fmac_f32_e32 v58, v41, v53
	v_fmac_f32_e32 v65, v42, v54
	v_fmac_f32_e32 v59, v43, v55
	v_cvt_pk_bf16_f32 v40, v62, v56
	v_cvt_pk_bf16_f32 v41, v63, v57
	v_cvt_pk_bf16_f32 v42, v64, v58
	v_cvt_pk_bf16_f32 v43, v65, v59
	global_load_dwordx4 v[44:47], v[70:71], off offset:256
	global_load_dwordx4 v[48:51], v[60:61], off offset:256
	v_add_u32_e32 v52, 0xa0, v146
	global_store_dwordx4 v[60:61], v[40:43], off
	v_mad_i64_i32 v[54:55], s[18:19], v52, s41, v[148:149]
	v_lshl_add_u64 v[54:55], v[54:55], 0, v[144:145]
	s_waitcnt vmcnt(0)
	v_lshlrev_b32_e32 v40, 16, v44
	v_lshlrev_b32_e32 v53, 16, v48
	v_and_b32_e32 v41, 0xffff0000, v44
	v_lshlrev_b32_e32 v44, 16, v46
	v_and_b32_e32 v48, 0xffff0000, v48
	v_lshlrev_b32_e32 v57, 16, v50
	v_fmac_f32_e32 v53, v36, v40
	v_fmac_f32_e32 v48, v37, v41
	v_fmac_f32_e32 v57, v32, v44
	v_cvt_pk_bf16_f32 v32, v53, v48
	v_ashrrev_i32_e32 v53, 31, v52
	v_lshlrev_b64 v[40:41], 11, v[52:53]
	v_lshlrev_b32_e32 v42, 16, v45
	v_and_b32_e32 v43, 0xffff0000, v45
	v_and_b32_e32 v45, 0xffff0000, v46
	v_and_b32_e32 v50, 0xffff0000, v50
	v_lshl_add_u64 v[40:41], s[0:1], 0, v[40:41]
	v_lshlrev_b32_e32 v46, 16, v47
	v_and_b32_e32 v47, 0xffff0000, v47
	v_lshlrev_b32_e32 v56, 16, v49
	v_and_b32_e32 v49, 0xffff0000, v49
	v_lshlrev_b32_e32 v58, 16, v51
	v_and_b32_e32 v51, 0xffff0000, v51
	v_fmac_f32_e32 v50, v33, v45
	v_lshl_add_u64 v[44:45], v[40:41], 0, v[144:145]
	v_fmac_f32_e32 v56, v38, v42
	v_fmac_f32_e32 v49, v39, v43
	v_fmac_f32_e32 v58, v34, v46
	v_fmac_f32_e32 v51, v35, v47
	v_cvt_pk_bf16_f32 v33, v56, v49
	v_cvt_pk_bf16_f32 v34, v57, v50
	v_cvt_pk_bf16_f32 v35, v58, v51
	global_load_dwordx4 v[36:39], v[54:55], off
	global_load_dwordx4 v[40:43], v[44:45], off
	s_waitcnt vmcnt(0)
	v_lshlrev_b32_e32 v46, 16, v40
	global_store_dwordx4 v[60:61], v[32:35], off offset:256
	v_and_b32_e32 v40, 0xffff0000, v40
	v_lshlrev_b32_e32 v47, 16, v41
	v_lshlrev_b32_e32 v32, 16, v36
	v_and_b32_e32 v33, 0xffff0000, v36
	v_lshlrev_b32_e32 v34, 16, v37
	v_and_b32_e32 v35, 0xffff0000, v37
	v_lshlrev_b32_e32 v36, 16, v38
	v_and_b32_e32 v37, 0xffff0000, v38
	v_lshlrev_b32_e32 v38, 16, v39
	v_and_b32_e32 v39, 0xffff0000, v39
	v_and_b32_e32 v41, 0xffff0000, v41
	v_lshlrev_b32_e32 v48, 16, v42
	v_and_b32_e32 v42, 0xffff0000, v42
	v_lshlrev_b32_e32 v49, 16, v43
	v_and_b32_e32 v43, 0xffff0000, v43
	v_fmac_f32_e32 v46, v28, v32
	v_fmac_f32_e32 v40, v29, v33
	v_fmac_f32_e32 v47, v30, v34
	v_fmac_f32_e32 v41, v31, v35
	v_fmac_f32_e32 v48, v24, v36
	v_fmac_f32_e32 v42, v25, v37
	v_fmac_f32_e32 v49, v26, v38
	v_fmac_f32_e32 v43, v27, v39
	v_cvt_pk_bf16_f32 v24, v46, v40
	v_cvt_pk_bf16_f32 v25, v47, v41
	v_cvt_pk_bf16_f32 v26, v48, v42
	v_cvt_pk_bf16_f32 v27, v49, v43
	global_load_dwordx4 v[28:31], v[54:55], off offset:256
	global_load_dwordx4 v[32:35], v[44:45], off offset:256
	v_add_u32_e32 v36, 0xb0, v146
	global_store_dwordx4 v[44:45], v[24:27], off
	v_mad_i64_i32 v[38:39], s[18:19], v36, s41, v[148:149]
	v_lshl_add_u64 v[38:39], v[38:39], 0, v[144:145]
	s_mov_b64 s[18:19], s[12:13]
	s_waitcnt vmcnt(0)
; __device__ __forceinline__ unsigned cvt_pk_bf16(float lo, float hi) { unsigned r; asm volatile("v_cvt_pk_bf16_f32 %0, %1, %2" : "=v"(r) : "v"(lo), "v"(hi)); return r; }
; __device__ __forceinline__ float bf_lo(unsigned u) { return __uint_as_float(u << 16); }
; __device__ __forceinline__ float bf_hi(unsigned u) { return __uint_as_float(u & 0xffff0000u); }
; #define PG8_WAIT_V(n) asm volatile("s_waitcnt vmcnt(" #n ")" ::: "memory")
; #define PG8_BAR __builtin_amdgcn_s_barrier()
;     __device__ __forceinline__ void operator()(const f32x4 (&acc)[2][2][4][2], const Unit& u, int wr, int wc, int fr, int fq) const {
;     ...
;             for (int m = 0; m < 4; ++m) { const size_t r = (size_t)(row0 + ai * HALF + m * 16); bf16_t* rowp = O + r * ldc + col0; const bf16_t* gp = G + r * ldg + col0;
; #pragma unroll
;                 for (int bj = 0; bj < 2; ++bj) { const u32x4 gw = *(const u32x4*)(gp + bj * HALF);
;                     f32x4 v0 = acc[ai][bj][m][0], v1 = acc[ai][bj][m][1];
;                     v0[0] *= bf_lo(gw.x); v0[1] *= bf_hi(gw.x); v0[2] *= bf_lo(gw.y); v0[3] *= bf_hi(gw.y);
;                     v1[0] *= bf_lo(gw.z); v1[1] *= bf_hi(gw.z); v1[2] *= bf_lo(gw.w); v1[3] *= bf_hi(gw.w);
;                     if (ACCUM) { const u32x4 pw = *(const u32x4*)(rowp + bj * HALF);
;                         v0[0] += bf_lo(pw.x); v0[1] += bf_hi(pw.x); v0[2] += bf_lo(pw.y); v0[3] += bf_hi(pw.y);
;                         v1[0] += bf_lo(pw.z); v1[1] += bf_hi(pw.z); v1[2] += bf_lo(pw.w); v1[3] += bf_hi(pw.w); }
;                     u32x4 w; w.x = cvt_pk_bf16(v0[0], v0[1]); w.y = cvt_pk_bf16(v0[2], v0[3]); w.z = cvt_pk_bf16(v1[0], v1[1]); w.w = cvt_pk_bf16(v1[2], v1[3]);
;                     *(u32x4*)(rowp + bj * HALF) = w; } }
; template <class Epi, class Sched>
; __device__ __forceinline__ void gemm_phase(PG8_LAS unsigned char* lds, const Gemm g, const Sched& S, const Epi& E) {
;     ...
;         if (!has_next) break;
; #pragma unroll
;         for (int a = 0; a < 2; ++a)
; #pragma unroll
;             for (int b = 0; b < 2; ++b)
; #pragma unroll
;                 for (int m = 0; m < 4; ++m)
; #pragma unroll
;                     for (int n = 0; n < 2; ++n) acc[a][b][m][n] = (f32x4){0.f, 0.f, 0.f, 0.f};
;         cur = nxt; cA = nA; cB = nB; ++ui;
;     }
;     PG8_WAIT_V(0);
;     if (wr == 0) PG8_BAR;
;     PG8_BAR;
	v_lshlrev_b32_e32 v24, 16, v28
	v_lshlrev_b32_e32 v37, 16, v32
	v_and_b32_e32 v25, 0xffff0000, v28
	v_lshlrev_b32_e32 v28, 16, v30
	v_and_b32_e32 v32, 0xffff0000, v32
	v_lshlrev_b32_e32 v41, 16, v34
	v_fmac_f32_e32 v37, v20, v24
	v_fmac_f32_e32 v32, v21, v25
	v_fmac_f32_e32 v41, v16, v28
	v_cvt_pk_bf16_f32 v16, v37, v32
	v_ashrrev_i32_e32 v37, 31, v36
	v_lshlrev_b64 v[24:25], 11, v[36:37]
	v_lshlrev_b32_e32 v26, 16, v29
	v_and_b32_e32 v27, 0xffff0000, v29
	v_and_b32_e32 v29, 0xffff0000, v30
	v_and_b32_e32 v34, 0xffff0000, v34
	v_lshl_add_u64 v[24:25], s[0:1], 0, v[24:25]
	v_lshlrev_b32_e32 v30, 16, v31
	v_and_b32_e32 v31, 0xffff0000, v31
	v_lshlrev_b32_e32 v40, 16, v33
	v_and_b32_e32 v33, 0xffff0000, v33
	v_lshlrev_b32_e32 v42, 16, v35
	v_and_b32_e32 v35, 0xffff0000, v35
	v_fmac_f32_e32 v34, v17, v29
	v_lshl_add_u64 v[28:29], v[24:25], 0, v[144:145]
	v_fmac_f32_e32 v40, v22, v26
	v_fmac_f32_e32 v33, v23, v27
	v_fmac_f32_e32 v42, v18, v30
	v_fmac_f32_e32 v35, v19, v31
	v_cvt_pk_bf16_f32 v17, v40, v33
	v_cvt_pk_bf16_f32 v18, v41, v34
	v_cvt_pk_bf16_f32 v19, v42, v35
	global_load_dwordx4 v[20:23], v[38:39], off
	global_load_dwordx4 v[24:27], v[28:29], off
	s_waitcnt vmcnt(0)
	v_lshlrev_b32_e32 v30, 16, v24
	global_store_dwordx4 v[44:45], v[16:19], off offset:256
	v_and_b32_e32 v24, 0xffff0000, v24
	v_lshlrev_b32_e32 v31, 16, v25
	v_lshlrev_b32_e32 v16, 16, v20
	v_and_b32_e32 v17, 0xffff0000, v20
	v_lshlrev_b32_e32 v18, 16, v21
	v_and_b32_e32 v19, 0xffff0000, v21
	v_lshlrev_b32_e32 v20, 16, v22
	v_and_b32_e32 v21, 0xffff0000, v22
	v_lshlrev_b32_e32 v22, 16, v23
	v_and_b32_e32 v23, 0xffff0000, v23
	v_and_b32_e32 v25, 0xffff0000, v25
	v_lshlrev_b32_e32 v32, 16, v26
	v_and_b32_e32 v26, 0xffff0000, v26
	v_lshlrev_b32_e32 v33, 16, v27
	v_and_b32_e32 v27, 0xffff0000, v27
	v_fmac_f32_e32 v30, v12, v16
	v_fmac_f32_e32 v24, v13, v17
	v_fmac_f32_e32 v31, v14, v18
	v_fmac_f32_e32 v25, v15, v19
	v_fmac_f32_e32 v32, v8, v20
	v_fmac_f32_e32 v26, v9, v21
	v_fmac_f32_e32 v33, v10, v22
	v_fmac_f32_e32 v27, v11, v23
	v_cvt_pk_bf16_f32 v8, v30, v24
	v_cvt_pk_bf16_f32 v9, v31, v25
	v_cvt_pk_bf16_f32 v10, v32, v26
	v_cvt_pk_bf16_f32 v11, v33, v27
	global_load_dwordx4 v[12:15], v[38:39], off offset:256
	global_load_dwordx4 v[16:19], v[28:29], off offset:256
	s_waitcnt vmcnt(0)
	v_lshlrev_b32_e32 v20, 16, v16
	global_store_dwordx4 v[28:29], v[8:11], off
	v_and_b32_e32 v16, 0xffff0000, v16
	v_lshlrev_b32_e32 v21, 16, v17
	v_lshlrev_b32_e32 v8, 16, v12
	v_and_b32_e32 v9, 0xffff0000, v12
	v_lshlrev_b32_e32 v10, 16, v13
	v_and_b32_e32 v11, 0xffff0000, v13
	v_lshlrev_b32_e32 v12, 16, v14
	v_and_b32_e32 v13, 0xffff0000, v14
	v_lshlrev_b32_e32 v14, 16, v15
	v_and_b32_e32 v15, 0xffff0000, v15
	v_and_b32_e32 v17, 0xffff0000, v17
	v_lshlrev_b32_e32 v22, 16, v18
	v_and_b32_e32 v18, 0xffff0000, v18
	v_lshlrev_b32_e32 v23, 16, v19
	v_and_b32_e32 v19, 0xffff0000, v19
	v_fmac_f32_e32 v20, v4, v8
	v_fmac_f32_e32 v16, v5, v9
	v_fmac_f32_e32 v21, v6, v10
	v_fmac_f32_e32 v17, v7, v11
	v_fmac_f32_e32 v22, v0, v12
	v_fmac_f32_e32 v18, v1, v13
	v_fmac_f32_e32 v23, v2, v14
	v_fmac_f32_e32 v19, v3, v15
	v_cvt_pk_bf16_f32 v0, v20, v16
	v_cvt_pk_bf16_f32 v1, v21, v17
	v_cvt_pk_bf16_f32 v2, v22, v18
	v_cvt_pk_bf16_f32 v3, v23, v19
	global_store_dwordx4 v[28:29], v[0:3], off offset:256
	s_cbranch_vccz .LBB0_1004
	s_waitcnt vmcnt(0)
	s_cmpk_gt_u32 s25, 0xff
	s_cbranch_scc1 .LBB0_1015
	s_barrier

; #define PG8_STAGE(bufoff, gbase, voff) do { _Pragma("unroll") for (int _i = 0; _i < 2; ++_i) \
;         __builtin_amdgcn_global_load_lds((const unsigned*)((const char*)(gbase) + (voff)[_i]), (PG8_LAS unsigned*)(lds + (bufoff) + ldsw + _i * 8192), 16, 0, 0); } while (0)
; #define PG8_LDA(dst, b, h) do { _Pragma("unroll") for (int m = 0; m < 4; ++m) _Pragma("unroll") for (int k = 0; k < 2; ++k) dst[m][k] = *(const PG8_LAS bf16x8*)(lds + PG8_SA(b, h) + aoff + m * 2048 + k * 1024); } while (0)
; #define PG8_LDB(dst, b, h) do { _Pragma("unroll") for (int n = 0; n < 2; ++n) _Pragma("unroll") for (int k = 0; k < 2; ++k) dst[n][k] = *(const PG8_LAS bf16x8*)(lds + PG8_SB(b, h) + boff + n * 2048 + k * 1024); } while (0)
; #define PG8_MMA(ai, bj, At, Bt) do { __builtin_amdgcn_s_setprio(1); _Pragma("unroll") for (int m = 0; m < 4; ++m) _Pragma("unroll") for (int n = 0; n < 2; ++n) _Pragma("unroll") for (int k = 0; k < 2; ++k) \
;         acc[ai][bj][m][n] = __builtin_amdgcn_mfma_f32_16x16x32_bf16(Bt[n][k], At[m][k], acc[ai][bj][m][n], 0, 0, 0); __builtin_amdgcn_s_setprio(0); } while (0)
; #define PG8_WAIT_L(n) asm volatile("s_waitcnt lgkmcnt(" #n ")" ::: "memory")
; #define PG8_BAR __builtin_amdgcn_s_barrier()
; #define PG8_SCHED __builtin_amdgcn_sched_barrier(0)
; template <class Epi, class Sched>
; __device__ __forceinline__ void gemm_phase(PG8_LAS unsigned char* lds, const Gemm g, const Sched& S, const Epi& E) {
;     ...
;             const bool last = (t == nt - 2);
;             const char* a1 = cA + (size_t)(t + 1) * kstep;
;             const char* a2 = last ? nA : cA + (size_t)(t + 2) * kstep; const char* b2 = last ? nB : cB + (size_t)(t + 2) * kstep;
;             const char* a3 = a2 + kstep; const char* b3 = b2 + kstep;
;             if (last && has_next) S.a_ready(nxt);
;             PG8_LDB(B0, 0, 0); PG8_SCHED; PG8_LDA(At, 0, 0); PG8_STAGE(PG8_SA(1, 1), a1 + hstep, voffA);
;             PG8_WAIT_L(8); PG8_BAR; PG8_WAIT_L(0); PG8_MMA(0, 0, At, B0); PG8_BAR; PG8_SCHED;
;             PG8_LDB(B1, 0, 1); PG8_STAGE(PG8_SB(0, 0), b2, voffB);
;             PG8_BAR; PG8_WAIT_L(0); PG8_MMA(0, 1, At, B1); PG8_BAR;
;             PG8_LDA(At, 0, 1); PG8_STAGE(PG8_SA(0, 0), a2, voffA);
;             PG8_BAR; PG8_WAIT_L(0); PG8_MMA(1, 0, At, B0); PG8_BAR; PG8_SCHED;
.LBB0_1083:
	ds_read_b128 v[152:155], v149
	ds_read_b128 v[156:159], v149 offset:1024
	ds_read_b128 v[160:163], v149 offset:2048
	ds_read_b128 v[164:167], v149 offset:3072
	s_add_u32 s26, s24, 0xfffc0080
	s_addc_u32 s27, s25, -1
	s_cmp_eq_u32 s56, 12
	s_cselect_b32 s29, s17, s27
	s_cselect_b32 s28, s52, s26
	s_cselect_b32 s27, s15, s55
	s_cselect_b32 s26, s53, s54
	v_lshl_add_u64 v[144:145], s[24:25], 0, v[136:137]
	s_add_i32 m0, s23, 0xc000
	ds_read_b128 v[168:171], v150
	ds_read_b128 v[172:175], v150 offset:1024
	ds_read_b128 v[182:185], v150 offset:2048
	ds_read_b128 v[190:193], v150 offset:3072
	ds_read_b128 v[194:197], v150 offset:4096
	ds_read_b128 v[198:201], v150 offset:5120
	ds_read_b128 v[202:205], v150 offset:6144
	ds_read_b128 v[206:209], v150 offset:7168
	global_load_lds_dwordx4 v[144:145], off
	v_lshl_add_u64 v[144:145], s[24:25], 0, v[138:139]
	s_add_i32 m0, s23, 0xe000
	s_nop 0
	global_load_lds_dwordx4 v[144:145], off
	ds_read_b128 v[210:213], v151
	ds_read_b128 v[214:217], v151 offset:1024
	ds_read_b128 v[218:221], v151 offset:2048
	ds_read_b128 v[222:225], v151 offset:3072
	s_waitcnt vmcnt(8) lgkmcnt(0)
	s_barrier
	v_mfma_f32_16x16x32_bf16 v[124:127], v[152:155], v[168:171], v[124:127]
	v_mfma_f32_16x16x32_bf16 v[120:123], v[160:163], v[168:171], v[120:123]
	v_mfma_f32_16x16x32_bf16 v[108:111], v[152:155], v[182:185], v[108:111]
	v_mfma_f32_16x16x32_bf16 v[104:107], v[160:163], v[182:185], v[104:107]
	v_mfma_f32_16x16x32_bf16 v[92:95], v[152:155], v[194:197], v[92:95]
	v_mfma_f32_16x16x32_bf16 v[88:91], v[160:163], v[194:197], v[88:91]
	v_mfma_f32_16x16x32_bf16 v[76:79], v[152:155], v[202:205], v[76:79]
	v_mfma_f32_16x16x32_bf16 v[72:75], v[160:163], v[202:205], v[72:75]
	v_mfma_f32_16x16x32_bf16 v[124:127], v[156:159], v[172:175], v[124:127]
	v_mfma_f32_16x16x32_bf16 v[120:123], v[164:167], v[172:175], v[120:123]
	v_mfma_f32_16x16x32_bf16 v[108:111], v[156:159], v[190:193], v[108:111]
	v_mfma_f32_16x16x32_bf16 v[104:107], v[164:167], v[190:193], v[104:107]
	v_mfma_f32_16x16x32_bf16 v[92:95], v[156:159], v[198:201], v[92:95]
	v_mfma_f32_16x16x32_bf16 v[88:91], v[164:167], v[198:201], v[88:91]
	v_mfma_f32_16x16x32_bf16 v[76:79], v[156:159], v[206:209], v[76:79]
	v_mfma_f32_16x16x32_bf16 v[72:75], v[164:167], v[206:209], v[72:75]
	v_mfma_f32_16x16x32_bf16 v[116:119], v[210:213], v[168:171], v[116:119]
	v_mfma_f32_16x16x32_bf16 v[112:115], v[218:221], v[168:171], v[112:115]
	v_mfma_f32_16x16x32_bf16 v[100:103], v[210:213], v[182:185], v[100:103]
	v_mfma_f32_16x16x32_bf16 v[96:99], v[218:221], v[182:185], v[96:99]
	v_mfma_f32_16x16x32_bf16 v[84:87], v[210:213], v[194:197], v[84:87]
	v_mfma_f32_16x16x32_bf16 v[80:83], v[218:221], v[194:197], v[80:83]
	v_mfma_f32_16x16x32_bf16 v[68:71], v[210:213], v[202:205], v[68:71]
	v_mfma_f32_16x16x32_bf16 v[64:67], v[218:221], v[202:205], v[64:67]
	v_mfma_f32_16x16x32_bf16 v[116:119], v[214:217], v[172:175], v[116:119]
	v_mfma_f32_16x16x32_bf16 v[112:115], v[222:225], v[172:175], v[112:115]
	v_mfma_f32_16x16x32_bf16 v[100:103], v[214:217], v[190:193], v[100:103]
	v_mfma_f32_16x16x32_bf16 v[96:99], v[222:225], v[190:193], v[96:99]
	v_mfma_f32_16x16x32_bf16 v[84:87], v[214:217], v[198:201], v[84:87]
	v_mfma_f32_16x16x32_bf16 v[80:83], v[222:225], v[198:201], v[80:83]
	v_mfma_f32_16x16x32_bf16 v[68:71], v[214:217], v[206:209], v[68:71]
	v_mfma_f32_16x16x32_bf16 v[64:67], v[222:225], v[206:209], v[64:67]
	s_barrier
	ds_read_b128 v[168:171], v150 offset:16384
	ds_read_b128 v[172:175], v150 offset:17408
	ds_read_b128 v[182:185], v150 offset:18432
	ds_read_b128 v[190:193], v150 offset:19456
	ds_read_b128 v[194:197], v150 offset:20480
	ds_read_b128 v[198:201], v150 offset:21504
	ds_read_b128 v[202:205], v150 offset:22528
	ds_read_b128 v[206:209], v150 offset:23552
	s_add_i32 s57, s45, s37
	v_lshl_add_u64 v[144:145], s[26:27], 0, v[130:131]
	s_mov_b32 m0, s57
	s_nop 0
	global_load_lds_dwordx4 v[144:145], off
	v_lshl_add_u64 v[186:187], s[26:27], 0, v[134:135]
	s_add_i32 m0, s57, 0x2000
	s_nop 0
	global_load_lds_dwordx4 v[186:187], off
	s_mov_b32 m0, s23
	v_lshl_add_u64 v[226:227], s[28:29], 0, v[128:129]
	global_load_lds_dwordx4 v[226:227], off
	v_lshl_add_u64 v[228:229], s[28:29], 0, v[132:133]
	s_mov_b32 m0, s38
	s_nop 0
	global_load_lds_dwordx4 v[228:229], off
	s_add_u32 s58, s26, 0x40000
	s_addc_u32 s59, s27, 0
	s_add_i32 s57, s46, s37
	v_lshl_add_u64 v[246:247], s[58:59], 0, v[130:131]
	s_mov_b32 m0, s57
	s_nop 0
	global_load_lds_dwordx4 v[246:247], off
	v_lshl_add_u64 v[246:247], s[58:59], 0, v[134:135]
	s_add_i32 m0, s57, 0x2000
	s_nop 0
	global_load_lds_dwordx4 v[246:247], off
	s_waitcnt vmcnt(8) lgkmcnt(0)
	s_barrier
; #define PG8_STAGE(bufoff, gbase, voff) do { _Pragma("unroll") for (int _i = 0; _i < 2; ++_i) \
;         __builtin_amdgcn_global_load_lds((const unsigned*)((const char*)(gbase) + (voff)[_i]), (PG8_LAS unsigned*)(lds + (bufoff) + ldsw + _i * 8192), 16, 0, 0); } while (0)
; #define PG8_LDA(dst, b, h) do { _Pragma("unroll") for (int m = 0; m < 4; ++m) _Pragma("unroll") for (int k = 0; k < 2; ++k) dst[m][k] = *(const PG8_LAS bf16x8*)(lds + PG8_SA(b, h) + aoff + m * 2048 + k * 1024); } while (0)
; #define PG8_LDB(dst, b, h) do { _Pragma("unroll") for (int n = 0; n < 2; ++n) _Pragma("unroll") for (int k = 0; k < 2; ++k) dst[n][k] = *(const PG8_LAS bf16x8*)(lds + PG8_SB(b, h) + boff + n * 2048 + k * 1024); } while (0)
; #define PG8_MMA(ai, bj, At, Bt) do { __builtin_amdgcn_s_setprio(1); _Pragma("unroll") for (int m = 0; m < 4; ++m) _Pragma("unroll") for (int n = 0; n < 2; ++n) _Pragma("unroll") for (int k = 0; k < 2; ++k) \
;         acc[ai][bj][m][n] = __builtin_amdgcn_mfma_f32_16x16x32_bf16(Bt[n][k], At[m][k], acc[ai][bj][m][n], 0, 0, 0); __builtin_amdgcn_s_setprio(0); } while (0)
; #define PG8_WAIT_V(n) asm volatile("s_waitcnt vmcnt(" #n ")" ::: "memory")
; #define PG8_WAIT_L(n) asm volatile("s_waitcnt lgkmcnt(" #n ")" ::: "memory")
; #define PG8_BAR __builtin_amdgcn_s_barrier()
; #define PG8_SCHED __builtin_amdgcn_sched_barrier(0)
; template <class Epi, class Sched>
; __device__ __forceinline__ void gemm_phase(PG8_LAS unsigned char* lds, const Gemm g, const Sched& S, const Epi& E) {
;     ...
;             PG8_BAR; PG8_WAIT_L(0); PG8_MMA(1, 0, At, B0); PG8_BAR; PG8_SCHED;
;             PG8_STAGE(PG8_SB(0, 1), b2 + hstep, voffB);
;             PG8_WAIT_V(6); PG8_BAR; PG8_MMA(1, 1, At, B1); PG8_BAR;
;             PG8_LDB(B0, 1, 0); PG8_SCHED; PG8_LDA(At, 1, 0); PG8_STAGE(PG8_SA(0, 1), a2 + hstep, voffA);
;             PG8_WAIT_L(8); PG8_BAR; PG8_WAIT_L(0); PG8_MMA(0, 0, At, B0); PG8_BAR; PG8_SCHED;
;             PG8_LDB(B1, 1, 1); PG8_STAGE(PG8_SB(1, 0), b3, voffB);
;             PG8_BAR; PG8_WAIT_L(0); PG8_MMA(0, 1, At, B1); PG8_BAR;
;             PG8_LDA(At, 1, 1); PG8_STAGE(PG8_SA(1, 0), a3, voffA);
;             PG8_BAR; PG8_WAIT_L(0); PG8_MMA(1, 0, At, B0); PG8_BAR; PG8_SCHED;
	v_mfma_f32_16x16x32_bf16 v[60:63], v[152:155], v[168:171], v[60:63]
	v_mfma_f32_16x16x32_bf16 v[56:59], v[160:163], v[168:171], v[56:59]
	v_mfma_f32_16x16x32_bf16 v[48:51], v[152:155], v[182:185], v[48:51]
	v_mfma_f32_16x16x32_bf16 v[40:43], v[160:163], v[182:185], v[40:43]
	v_mfma_f32_16x16x32_bf16 v[32:35], v[152:155], v[194:197], v[32:35]
	v_mfma_f32_16x16x32_bf16 v[24:27], v[160:163], v[194:197], v[24:27]
	v_mfma_f32_16x16x32_bf16 v[16:19], v[152:155], v[202:205], v[16:19]
	v_mfma_f32_16x16x32_bf16 v[8:11], v[160:163], v[202:205], v[8:11]
	v_mfma_f32_16x16x32_bf16 v[60:63], v[156:159], v[172:175], v[60:63]
	v_mfma_f32_16x16x32_bf16 v[56:59], v[164:167], v[172:175], v[56:59]
	v_mfma_f32_16x16x32_bf16 v[48:51], v[156:159], v[190:193], v[48:51]
	v_mfma_f32_16x16x32_bf16 v[40:43], v[164:167], v[190:193], v[40:43]
	v_mfma_f32_16x16x32_bf16 v[32:35], v[156:159], v[198:201], v[32:35]
	v_mfma_f32_16x16x32_bf16 v[24:27], v[164:167], v[198:201], v[24:27]
	v_mfma_f32_16x16x32_bf16 v[16:19], v[156:159], v[206:209], v[16:19]
	v_mfma_f32_16x16x32_bf16 v[8:11], v[164:167], v[206:209], v[8:11]
	v_mfma_f32_16x16x32_bf16 v[52:55], v[210:213], v[168:171], v[52:55]
	v_mfma_f32_16x16x32_bf16 v[44:47], v[218:221], v[168:171], v[44:47]
	v_mfma_f32_16x16x32_bf16 v[36:39], v[210:213], v[182:185], v[36:39]
	v_mfma_f32_16x16x32_bf16 v[28:31], v[218:221], v[182:185], v[28:31]
	v_mfma_f32_16x16x32_bf16 v[20:23], v[210:213], v[194:197], v[20:23]
	v_mfma_f32_16x16x32_bf16 v[12:15], v[218:221], v[194:197], v[12:15]
	v_mfma_f32_16x16x32_bf16 v[4:7], v[210:213], v[202:205], v[4:7]
	v_mfma_f32_16x16x32_bf16 v[0:3], v[218:221], v[202:205], v[0:3]
	v_mfma_f32_16x16x32_bf16 v[52:55], v[214:217], v[172:175], v[52:55]
	v_mfma_f32_16x16x32_bf16 v[44:47], v[222:225], v[172:175], v[44:47]
	v_mfma_f32_16x16x32_bf16 v[36:39], v[214:217], v[190:193], v[36:39]
	v_mfma_f32_16x16x32_bf16 v[28:31], v[222:225], v[190:193], v[28:31]
	v_mfma_f32_16x16x32_bf16 v[20:23], v[214:217], v[198:201], v[20:23]
	v_mfma_f32_16x16x32_bf16 v[12:15], v[222:225], v[198:201], v[12:15]
	v_mfma_f32_16x16x32_bf16 v[4:7], v[214:217], v[206:209], v[4:7]
	v_mfma_f32_16x16x32_bf16 v[0:3], v[222:225], v[206:209], v[0:3]
	s_barrier
	s_add_i32 s57, 0, 0x18000
	v_add_u32_e32 v164, s57, v147
	ds_read_b128 v[152:155], v164
	ds_read_b128 v[156:159], v164 offset:1024
	ds_read_b128 v[160:163], v164 offset:2048
	ds_read_b128 v[164:167], v164 offset:3072
	s_add_u32 s28, s28, 0x40000
	s_addc_u32 s29, s29, 0
	s_mov_b32 m0, s39
	v_lshl_add_u64 v[210:211], s[28:29], 0, v[128:129]
	ds_read_b128 v[168:171], v150 offset:32768
	ds_read_b128 v[172:175], v150 offset:33792
	ds_read_b128 v[182:185], v150 offset:34816
	ds_read_b128 v[190:193], v150 offset:35840
	ds_read_b128 v[194:197], v150 offset:36864
	ds_read_b128 v[198:201], v150 offset:37888
	ds_read_b128 v[202:205], v150 offset:38912
	ds_read_b128 v[206:209], v150 offset:39936
	global_load_lds_dwordx4 v[210:211], off
	v_lshl_add_u64 v[210:211], s[28:29], 0, v[132:133]
	s_mov_b32 m0, s40
	s_nop 0
	global_load_lds_dwordx4 v[210:211], off
	s_add_i32 s28, 0, 0x1c000
	v_add_u32_e32 v179, s28, v147
	ds_read_b128 v[210:213], v179
	ds_read_b128 v[214:217], v179 offset:1024
	ds_read_b128 v[218:221], v179 offset:2048
	ds_read_b128 v[222:225], v179 offset:3072
	s_waitcnt vmcnt(8) lgkmcnt(0)
	s_barrier
	v_mfma_f32_16x16x32_bf16 v[124:127], v[152:155], v[168:171], v[124:127]
	v_mfma_f32_16x16x32_bf16 v[120:123], v[160:163], v[168:171], v[120:123]
	v_mfma_f32_16x16x32_bf16 v[108:111], v[152:155], v[182:185], v[108:111]
	v_mfma_f32_16x16x32_bf16 v[104:107], v[160:163], v[182:185], v[104:107]
	v_mfma_f32_16x16x32_bf16 v[92:95], v[152:155], v[194:197], v[92:95]
	v_mfma_f32_16x16x32_bf16 v[88:91], v[160:163], v[194:197], v[88:91]
	v_mfma_f32_16x16x32_bf16 v[76:79], v[152:155], v[202:205], v[76:79]
	v_mfma_f32_16x16x32_bf16 v[72:75], v[160:163], v[202:205], v[72:75]
	v_mfma_f32_16x16x32_bf16 v[124:127], v[156:159], v[172:175], v[124:127]
	v_mfma_f32_16x16x32_bf16 v[120:123], v[164:167], v[172:175], v[120:123]
	v_mfma_f32_16x16x32_bf16 v[108:111], v[156:159], v[190:193], v[108:111]
	v_mfma_f32_16x16x32_bf16 v[104:107], v[164:167], v[190:193], v[104:107]
	v_mfma_f32_16x16x32_bf16 v[92:95], v[156:159], v[198:201], v[92:95]
	v_mfma_f32_16x16x32_bf16 v[88:91], v[164:167], v[198:201], v[88:91]
	v_mfma_f32_16x16x32_bf16 v[76:79], v[156:159], v[206:209], v[76:79]
	v_mfma_f32_16x16x32_bf16 v[72:75], v[164:167], v[206:209], v[72:75]
	v_mfma_f32_16x16x32_bf16 v[116:119], v[210:213], v[168:171], v[116:119]
	v_mfma_f32_16x16x32_bf16 v[112:115], v[218:221], v[168:171], v[112:115]
	v_mfma_f32_16x16x32_bf16 v[100:103], v[210:213], v[182:185], v[100:103]
	v_mfma_f32_16x16x32_bf16 v[96:99], v[218:221], v[182:185], v[96:99]
	v_mfma_f32_16x16x32_bf16 v[84:87], v[210:213], v[194:197], v[84:87]
	v_mfma_f32_16x16x32_bf16 v[80:83], v[218:221], v[194:197], v[80:83]
	v_mfma_f32_16x16x32_bf16 v[68:71], v[210:213], v[202:205], v[68:71]
	v_mfma_f32_16x16x32_bf16 v[64:67], v[218:221], v[202:205], v[64:67]
	v_mfma_f32_16x16x32_bf16 v[116:119], v[214:217], v[172:175], v[116:119]
	v_mfma_f32_16x16x32_bf16 v[112:115], v[222:225], v[172:175], v[112:115]
	v_mfma_f32_16x16x32_bf16 v[100:103], v[214:217], v[190:193], v[100:103]
	v_mfma_f32_16x16x32_bf16 v[96:99], v[222:225], v[190:193], v[96:99]
	v_mfma_f32_16x16x32_bf16 v[84:87], v[214:217], v[198:201], v[84:87]
	v_mfma_f32_16x16x32_bf16 v[80:83], v[222:225], v[198:201], v[80:83]
	v_mfma_f32_16x16x32_bf16 v[68:71], v[214:217], v[206:209], v[68:71]
	v_mfma_f32_16x16x32_bf16 v[64:67], v[222:225], v[206:209], v[64:67]
	s_barrier
; __device__ __forceinline__ unsigned cvt_pk_bf16(float lo, float hi) { unsigned r; asm volatile("v_cvt_pk_bf16_f32 %0, %1, %2" : "=v"(r) : "v"(lo), "v"(hi)); return r; }
; __device__ __forceinline__ float flogsig16(float x) { return (fminf(x, 0.f) - __logf(1.0f + __expf(-fabsf(x)))) * 0.0625f; }
; #define PG8_STAGE(bufoff, gbase, voff) do { _Pragma("unroll") for (int _i = 0; _i < 2; ++_i) \
;         __builtin_amdgcn_global_load_lds((const unsigned*)((const char*)(gbase) + (voff)[_i]), (PG8_LAS unsigned*)(lds + (bufoff) + ldsw + _i * 8192), 16, 0, 0); } while (0)
; #define PG8_LDA(dst, b, h) do { _Pragma("unroll") for (int m = 0; m < 4; ++m) _Pragma("unroll") for (int k = 0; k < 2; ++k) dst[m][k] = *(const PG8_LAS bf16x8*)(lds + PG8_SA(b, h) + aoff + m * 2048 + k * 1024); } while (0)
; #define PG8_BAR __builtin_amdgcn_s_barrier()
;     __device__ __forceinline__ void operator()(const f32x4 (&acc)[2][2][4][2], const Unit& u, int wr, int wc, int fr, int fq) const {
;     ...
;             for (int m = 0; m < 4; ++m) { bf16_t* rowp = O + (size_t)(row0 + ai * HALF + m * 16) * ldc + col0;
; #pragma unroll
;                 for (int bj = 0; bj < 2; ++bj) { f32x4 v0 = acc[ai][bj][m][0] + bv[bj][0], v1 = acc[ai][bj][m][1] + bv[bj][1];
;                     if (act == 1) {
; #pragma unroll
;                         for (int j = 0; j < 1; ++j) { v0 = v0 * sigmoid4(v0); v1 = v1 * sigmoid4(v1); } }
;                     else if (act == 2) {
; #pragma unroll
;                         for (int j = 0; j < 1; ++j) { v0 = sigmoid4(v0); v1 = sigmoid4(v1); } }
;                     else if (act == 3) {
; #pragma unroll
;                         for (int j = 0; j < 4; ++j) { v0[j] = flogsig16(v0[j]); v1[j] = flogsig16(v1[j]); } }
;                     u32x4 w; w.x = cvt_pk_bf16(v0[0], v0[1]); w.y = cvt_pk_bf16(v0[2], v0[3]); w.z = cvt_pk_bf16(v1[0], v1[1]); w.w = cvt_pk_bf16(v1[2], v1[3]);
;                     *(u32x4*)(rowp + bj * HALF) = w; } }
; template <class Epi, class Sched>
; __device__ __forceinline__ void gemm_phase(PG8_LAS unsigned char* lds, const Gemm g, const Sched& S, const Epi& E) {
;     ...
;             PG8_LDA(At, 1, 1); PG8_STAGE(PG8_SA(1, 0), a3, voffA);
;             PG8_BAR; PG8_WAIT_L(0); PG8_MMA(1, 0, At, B0); PG8_BAR; PG8_SCHED;
;             PG8_STAGE(PG8_SB(1, 1), b3 + hstep, voffB);
;             PG8_WAIT_V(6); PG8_BAR; PG8_MMA(1, 1, At, B1); PG8_BAR;
;         }
	ds_read_b128 v[168:171], v150 offset:49152
	ds_read_b128 v[172:175], v150 offset:50176
	ds_read_b128 v[182:185], v150 offset:51200
	ds_read_b128 v[190:193], v150 offset:52224
	ds_read_b128 v[194:197], v150 offset:53248
	ds_read_b128 v[198:201], v150 offset:54272
	ds_read_b128 v[202:205], v150 offset:55296
	ds_read_b128 v[206:209], v150 offset:56320
	s_add_i32 s29, s57, s37
	v_lshl_add_u64 v[144:145], v[144:145], 0, s[6:7]
	s_mov_b32 m0, s29
	s_nop 0
	global_load_lds_dwordx4 v[144:145], off
	v_lshl_add_u64 v[144:145], v[186:187], 0, s[6:7]
	s_add_i32 m0, s29, 0x2000
	s_nop 0
	global_load_lds_dwordx4 v[144:145], off
	s_mov_b32 m0, s42
	v_lshl_add_u64 v[144:145], v[226:227], 0, s[6:7]
	global_load_lds_dwordx4 v[144:145], off
	v_lshl_add_u64 v[144:145], v[228:229], 0, s[6:7]
	s_mov_b32 m0, s43
	s_nop 0
	global_load_lds_dwordx4 v[144:145], off
	s_add_u32 s26, s26, 0x40080
	s_addc_u32 s27, s27, 0
	s_add_i32 s28, s28, s37
	v_lshl_add_u64 v[144:145], s[26:27], 0, v[130:131]
	s_mov_b32 m0, s28
	s_nop 0
	global_load_lds_dwordx4 v[144:145], off
	v_lshl_add_u64 v[144:145], s[26:27], 0, v[134:135]
	s_add_i32 m0, s28, 0x2000
	s_nop 0
	global_load_lds_dwordx4 v[144:145], off
	s_waitcnt vmcnt(8) lgkmcnt(0)
	s_barrier
	v_mfma_f32_16x16x32_bf16 v[60:63], v[152:155], v[168:171], v[60:63]
	v_mfma_f32_16x16x32_bf16 v[56:59], v[160:163], v[168:171], v[56:59]
	v_mfma_f32_16x16x32_bf16 v[48:51], v[152:155], v[182:185], v[48:51]
	v_mfma_f32_16x16x32_bf16 v[40:43], v[160:163], v[182:185], v[40:43]
	v_mfma_f32_16x16x32_bf16 v[32:35], v[152:155], v[194:197], v[32:35]
	v_mfma_f32_16x16x32_bf16 v[24:27], v[160:163], v[194:197], v[24:27]
	v_mfma_f32_16x16x32_bf16 v[16:19], v[152:155], v[202:205], v[16:19]
	v_mfma_f32_16x16x32_bf16 v[8:11], v[160:163], v[202:205], v[8:11]
	v_mfma_f32_16x16x32_bf16 v[60:63], v[156:159], v[172:175], v[60:63]
	v_mfma_f32_16x16x32_bf16 v[56:59], v[164:167], v[172:175], v[56:59]
	v_mfma_f32_16x16x32_bf16 v[48:51], v[156:159], v[190:193], v[48:51]
	v_mfma_f32_16x16x32_bf16 v[40:43], v[164:167], v[190:193], v[40:43]
	v_mfma_f32_16x16x32_bf16 v[32:35], v[156:159], v[198:201], v[32:35]
	v_mfma_f32_16x16x32_bf16 v[24:27], v[164:167], v[198:201], v[24:27]
	v_mfma_f32_16x16x32_bf16 v[16:19], v[156:159], v[206:209], v[16:19]
	v_mfma_f32_16x16x32_bf16 v[8:11], v[164:167], v[206:209], v[8:11]
	v_mfma_f32_16x16x32_bf16 v[52:55], v[210:213], v[168:171], v[52:55]
	v_mfma_f32_16x16x32_bf16 v[44:47], v[218:221], v[168:171], v[44:47]
	v_mfma_f32_16x16x32_bf16 v[36:39], v[210:213], v[182:185], v[36:39]
	v_mfma_f32_16x16x32_bf16 v[28:31], v[218:221], v[182:185], v[28:31]
	v_mfma_f32_16x16x32_bf16 v[20:23], v[210:213], v[194:197], v[20:23]
	v_mfma_f32_16x16x32_bf16 v[12:15], v[218:221], v[194:197], v[12:15]
	v_mfma_f32_16x16x32_bf16 v[4:7], v[210:213], v[202:205], v[4:7]
	v_mfma_f32_16x16x32_bf16 v[0:3], v[218:221], v[202:205], v[0:3]
	v_mfma_f32_16x16x32_bf16 v[52:55], v[214:217], v[172:175], v[52:55]
	v_mfma_f32_16x16x32_bf16 v[44:47], v[222:225], v[172:175], v[44:47]
	v_mfma_f32_16x16x32_bf16 v[36:39], v[214:217], v[190:193], v[36:39]
	v_mfma_f32_16x16x32_bf16 v[28:31], v[222:225], v[190:193], v[28:31]
	v_mfma_f32_16x16x32_bf16 v[20:23], v[214:217], v[198:201], v[20:23]
	v_mfma_f32_16x16x32_bf16 v[12:15], v[222:225], v[198:201], v[12:15]
	v_mfma_f32_16x16x32_bf16 v[4:7], v[214:217], v[206:209], v[4:7]
	v_mfma_f32_16x16x32_bf16 v[0:3], v[222:225], v[206:209], v[0:3]
	s_barrier
	s_add_i32 s56, s56, 2
	s_add_u32 s24, s24, 0x100
	s_addc_u32 s25, s25, 0
	s_add_u32 s54, s54, 0x100
	s_addc_u32 s55, s55, 0
	s_cmp_gt_u32 s56, 13
	s_cbranch_scc0 .LBB0_1083
	v_lshl_add_u32 v152, s22, 8, v146
	v_lshl_or_b32 v144, s51, 8, v148
	v_ashrrev_i32_e32 v153, 31, v152
	v_ashrrev_i32_e32 v145, 31, v144
	v_lshlrev_b64 v[154:155], 11, v[152:153]
	v_lshl_add_u64 v[154:155], s[4:5], 0, v[154:155]
	v_lshlrev_b64 v[156:157], 1, v[144:145]
	v_lshl_add_u64 v[144:145], v[154:155], 0, v[156:157]
	v_pk_add_f32 v[126:127], v[126:127], 0 op_sel_hi:[1,0]
	v_pk_add_f32 v[124:125], v[124:125], 0 op_sel_hi:[1,0]
	v_pk_add_f32 v[154:155], v[122:123], 0 op_sel_hi:[1,0]
	v_pk_add_f32 v[122:123], v[120:121], 0 op_sel_hi:[1,0]
	v_cvt_pk_bf16_f32 v120, v124, v125
	v_cvt_pk_bf16_f32 v121, v126, v127
	v_pk_add_f32 v[116:117], v[116:117], 0 op_sel_hi:[1,0]
	v_cvt_pk_bf16_f32 v122, v122, v123
	v_cvt_pk_bf16_f32 v123, v154, v155
	global_store_dwordx4 v[144:145], v[120:123], off
	v_pk_add_f32 v[118:119], v[118:119], 0 op_sel_hi:[1,0]
	v_pk_add_f32 v[110:111], v[110:111], 0 op_sel_hi:[1,0]
	v_pk_add_f32 v[120:121], v[114:115], 0 op_sel_hi:[1,0]
	v_pk_add_f32 v[114:115], v[112:113], 0 op_sel_hi:[1,0]
	v_cvt_pk_bf16_f32 v112, v116, v117
	v_cvt_pk_bf16_f32 v113, v118, v119
	v_pk_add_f32 v[108:109], v[108:109], 0 op_sel_hi:[1,0]
	v_cvt_pk_bf16_f32 v114, v114, v115
	v_cvt_pk_bf16_f32 v115, v120, v121
	global_store_dwordx4 v[144:145], v[112:115], off offset:256
	v_pk_add_f32 v[100:101], v[100:101], 0 op_sel_hi:[1,0]
	v_pk_add_f32 v[102:103], v[102:103], 0 op_sel_hi:[1,0]
	v_or_b32_e32 v112, 16, v152
	v_ashrrev_i32_e32 v113, 31, v112
	v_lshlrev_b64 v[112:113], 11, v[112:113]
	v_lshl_add_u64 v[112:113], s[4:5], 0, v[112:113]
	v_lshl_add_u64 v[112:113], v[112:113], 0, v[156:157]
	v_pk_add_f32 v[114:115], v[106:107], 0 op_sel_hi:[1,0]
	v_pk_add_f32 v[106:107], v[104:105], 0 op_sel_hi:[1,0]
	v_cvt_pk_bf16_f32 v104, v108, v109
	v_cvt_pk_bf16_f32 v105, v110, v111
	v_pk_add_f32 v[94:95], v[94:95], 0 op_sel_hi:[1,0]
	v_cvt_pk_bf16_f32 v106, v106, v107
	v_cvt_pk_bf16_f32 v107, v114, v115
	global_store_dwordx4 v[112:113], v[104:107], off
	v_pk_add_f32 v[92:93], v[92:93], 0 op_sel_hi:[1,0]
	v_pk_add_f32 v[84:85], v[84:85], 0 op_sel_hi:[1,0]
; __device__ __forceinline__ unsigned cvt_pk_bf16(float lo, float hi) { unsigned r; asm volatile("v_cvt_pk_bf16_f32 %0, %1, %2" : "=v"(r) : "v"(lo), "v"(hi)); return r; }
; __device__ __forceinline__ float flogsig16(float x) { return (fminf(x, 0.f) - __logf(1.0f + __expf(-fabsf(x)))) * 0.0625f; }
;     __device__ __forceinline__ void operator()(const f32x4 (&acc)[2][2][4][2], const Unit& u, int wr, int wc, int fr, int fq) const {
;     ...
;             for (int m = 0; m < 4; ++m) { bf16_t* rowp = O + (size_t)(row0 + ai * HALF + m * 16) * ldc + col0;
; #pragma unroll
;                 for (int bj = 0; bj < 2; ++bj) { f32x4 v0 = acc[ai][bj][m][0] + bv[bj][0], v1 = acc[ai][bj][m][1] + bv[bj][1];
;                     if (act == 1) {
; #pragma unroll
;                         for (int j = 0; j < 1; ++j) { v0 = v0 * sigmoid4(v0); v1 = v1 * sigmoid4(v1); } }
;                     else if (act == 2) {
; #pragma unroll
;                         for (int j = 0; j < 1; ++j) { v0 = sigmoid4(v0); v1 = sigmoid4(v1); } }
;                     else if (act == 3) {
; #pragma unroll
;                         for (int j = 0; j < 4; ++j) { v0[j] = flogsig16(v0[j]); v1[j] = flogsig16(v1[j]); } }
;                     u32x4 w; w.x = cvt_pk_bf16(v0[0], v0[1]); w.y = cvt_pk_bf16(v0[2], v0[3]); w.z = cvt_pk_bf16(v1[0], v1[1]); w.w = cvt_pk_bf16(v1[2], v1[3]);
;                     *(u32x4*)(rowp + bj * HALF) = w; } }
	v_pk_add_f32 v[104:105], v[98:99], 0 op_sel_hi:[1,0]
	v_pk_add_f32 v[98:99], v[96:97], 0 op_sel_hi:[1,0]
	v_cvt_pk_bf16_f32 v96, v100, v101
	v_cvt_pk_bf16_f32 v97, v102, v103
	v_pk_add_f32 v[86:87], v[86:87], 0 op_sel_hi:[1,0]
	v_cvt_pk_bf16_f32 v98, v98, v99
	v_cvt_pk_bf16_f32 v99, v104, v105
	global_store_dwordx4 v[112:113], v[96:99], off offset:256
	v_pk_add_f32 v[78:79], v[78:79], 0 op_sel_hi:[1,0]
	v_pk_add_f32 v[76:77], v[76:77], 0 op_sel_hi:[1,0]
	v_or_b32_e32 v96, 32, v152
	v_ashrrev_i32_e32 v97, 31, v96
	v_lshlrev_b64 v[96:97], 11, v[96:97]
	v_lshl_add_u64 v[96:97], s[4:5], 0, v[96:97]
	v_lshl_add_u64 v[96:97], v[96:97], 0, v[156:157]
	v_pk_add_f32 v[98:99], v[90:91], 0 op_sel_hi:[1,0]
	v_pk_add_f32 v[90:91], v[88:89], 0 op_sel_hi:[1,0]
	v_cvt_pk_bf16_f32 v88, v92, v93
	v_cvt_pk_bf16_f32 v89, v94, v95
	v_pk_add_f32 v[70:71], v[70:71], 0 op_sel_hi:[1,0]
	v_cvt_pk_bf16_f32 v90, v90, v91
	v_cvt_pk_bf16_f32 v91, v98, v99
	global_store_dwordx4 v[96:97], v[88:91], off
	v_pk_add_f32 v[68:69], v[68:69], 0 op_sel_hi:[1,0]
	v_pk_add_f32 v[60:61], v[60:61], 0 op_sel_hi:[1,0]
	v_pk_add_f32 v[88:89], v[82:83], 0 op_sel_hi:[1,0]
	v_pk_add_f32 v[82:83], v[80:81], 0 op_sel_hi:[1,0]
	v_cvt_pk_bf16_f32 v80, v84, v85
	v_cvt_pk_bf16_f32 v81, v86, v87
	v_pk_add_f32 v[62:63], v[62:63], 0 op_sel_hi:[1,0]
	v_cvt_pk_bf16_f32 v82, v82, v83
	v_cvt_pk_bf16_f32 v83, v88, v89
	global_store_dwordx4 v[96:97], v[80:83], off offset:256
	v_pk_add_f32 v[54:55], v[54:55], 0 op_sel_hi:[1,0]
	v_pk_add_f32 v[52:53], v[52:53], 0 op_sel_hi:[1,0]
	v_or_b32_e32 v80, 48, v152
	v_ashrrev_i32_e32 v81, 31, v80
	v_lshlrev_b64 v[80:81], 11, v[80:81]
	v_lshl_add_u64 v[80:81], s[4:5], 0, v[80:81]
	v_lshl_add_u64 v[80:81], v[80:81], 0, v[156:157]
	v_pk_add_f32 v[82:83], v[74:75], 0 op_sel_hi:[1,0]
	v_pk_add_f32 v[74:75], v[72:73], 0 op_sel_hi:[1,0]
	v_cvt_pk_bf16_f32 v72, v76, v77
	v_cvt_pk_bf16_f32 v73, v78, v79
	v_pk_add_f32 v[48:49], v[48:49], 0 op_sel_hi:[1,0]
	v_cvt_pk_bf16_f32 v74, v74, v75
	v_cvt_pk_bf16_f32 v75, v82, v83
	global_store_dwordx4 v[80:81], v[72:75], off
	v_pk_add_f32 v[38:39], v[38:39], 0 op_sel_hi:[1,0]
	v_pk_add_f32 v[36:37], v[36:37], 0 op_sel_hi:[1,0]
	v_pk_add_f32 v[72:73], v[66:67], 0 op_sel_hi:[1,0]
	v_pk_add_f32 v[66:67], v[64:65], 0 op_sel_hi:[1,0]
	v_cvt_pk_bf16_f32 v64, v68, v69
	v_cvt_pk_bf16_f32 v65, v70, v71
	v_pk_add_f32 v[32:33], v[32:33], 0 op_sel_hi:[1,0]
	v_cvt_pk_bf16_f32 v66, v66, v67
	v_cvt_pk_bf16_f32 v67, v72, v73
	global_store_dwordx4 v[80:81], v[64:67], off offset:256
	v_pk_add_f32 v[22:23], v[22:23], 0 op_sel_hi:[1,0]
	v_pk_add_f32 v[20:21], v[20:21], 0 op_sel_hi:[1,0]
	v_pk_add_f32 v[66:67], v[58:59], 0 op_sel_hi:[1,0]
	v_pk_add_f32 v[58:59], v[56:57], 0 op_sel_hi:[1,0]
	v_cvt_pk_bf16_f32 v56, v60, v61
	v_add_co_u32_e32 v60, vcc, s47, v144
	v_cvt_pk_bf16_f32 v57, v62, v63
	v_cvt_pk_bf16_f32 v58, v58, v59
	v_cvt_pk_bf16_f32 v59, v66, v67
	v_lshl_add_u64 v[64:65], v[144:145], 0, s[0:1]
	s_nop 0
	v_addc_co_u32_e32 v61, vcc, 0, v145, vcc
	global_store_dwordx4 v[60:61], v[56:59], off
	v_pk_add_f32 v[16:17], v[16:17], 0 op_sel_hi:[1,0]
	s_mov_b32 s51, s14
	v_pk_add_f32 v[56:57], v[46:47], 0 op_sel_hi:[1,0]
	v_pk_add_f32 v[46:47], v[44:45], 0 op_sel_hi:[1,0]
	v_cvt_pk_bf16_f32 v44, v52, v53
	v_cvt_pk_bf16_f32 v45, v54, v55
	s_mov_b32 s22, s16
	v_cvt_pk_bf16_f32 v46, v46, v47
	v_cvt_pk_bf16_f32 v47, v56, v57
	global_store_dwordx4 v[64:65], v[44:47], off offset:256
	s_mov_b64 s[26:27], s[20:21]
	s_mov_b64 s[24:25], s[18:19]
	v_pk_add_f32 v[46:47], v[50:51], 0 op_sel_hi:[1,0]
	v_pk_add_f32 v[50:51], v[42:43], 0 op_sel_hi:[1,0]
	v_pk_add_f32 v[42:43], v[40:41], 0 op_sel_hi:[1,0]
	v_cvt_pk_bf16_f32 v40, v48, v49
	v_cvt_pk_bf16_f32 v41, v46, v47
	v_add_co_u32_e32 v46, vcc, s48, v144
	v_cvt_pk_bf16_f32 v42, v42, v43
	v_cvt_pk_bf16_f32 v43, v50, v51
	v_lshl_add_u64 v[44:45], v[144:145], 0, s[8:9]
	s_nop 0
	v_addc_co_u32_e32 v47, vcc, 0, v145, vcc
	global_store_dwordx4 v[46:47], v[40:43], off
	v_pk_add_f32 v[6:7], v[6:7], 0 op_sel_hi:[1,0]
	v_pk_add_f32 v[4:5], v[4:5], 0 op_sel_hi:[1,0]
	v_pk_add_f32 v[40:41], v[30:31], 0 op_sel_hi:[1,0]
	v_pk_add_f32 v[30:31], v[28:29], 0 op_sel_hi:[1,0]
	v_cvt_pk_bf16_f32 v28, v36, v37
	v_cvt_pk_bf16_f32 v29, v38, v39
	s_nop 0
	v_cvt_pk_bf16_f32 v30, v30, v31
	v_cvt_pk_bf16_f32 v31, v40, v41
	global_store_dwordx4 v[44:45], v[28:31], off offset:256
	s_nop 1
	v_pk_add_f32 v[30:31], v[34:35], 0 op_sel_hi:[1,0]
	v_pk_add_f32 v[34:35], v[26:27], 0 op_sel_hi:[1,0]
	v_pk_add_f32 v[26:27], v[24:25], 0 op_sel_hi:[1,0]
	v_cvt_pk_bf16_f32 v24, v32, v33
	v_cvt_pk_bf16_f32 v25, v30, v31
	v_add_co_u32_e32 v30, vcc, s49, v144
	v_cvt_pk_bf16_f32 v26, v26, v27
	v_cvt_pk_bf16_f32 v27, v34, v35
	v_lshl_add_u64 v[28:29], v[144:145], 0, s[10:11]
	s_nop 0
	v_addc_co_u32_e32 v31, vcc, 0, v145, vcc
	global_store_dwordx4 v[30:31], v[24:27], off
	s_nop 1
	v_pk_add_f32 v[24:25], v[14:15], 0 op_sel_hi:[1,0]
	v_pk_add_f32 v[14:15], v[12:13], 0 op_sel_hi:[1,0]
	v_cvt_pk_bf16_f32 v12, v20, v21
	v_cvt_pk_bf16_f32 v13, v22, v23
	s_nop 0
	v_cvt_pk_bf16_f32 v14, v14, v15
	v_cvt_pk_bf16_f32 v15, v24, v25
	global_store_dwordx4 v[28:29], v[12:15], off offset:256
	s_nop 1
	v_pk_add_f32 v[14:15], v[18:19], 0 op_sel_hi:[1,0]
	v_pk_add_f32 v[18:19], v[10:11], 0 op_sel_hi:[1,0]
	v_pk_add_f32 v[10:11], v[8:9], 0 op_sel_hi:[1,0]
	v_cvt_pk_bf16_f32 v8, v16, v17
	v_cvt_pk_bf16_f32 v9, v14, v15
	v_add_co_u32_e32 v14, vcc, s50, v144
	v_lshl_add_u64 v[12:13], v[144:145], 0, s[12:13]
	s_nop 0
	v_addc_co_u32_e32 v15, vcc, 0, v145, vcc
	v_cvt_pk_bf16_f32 v10, v10, v11
	v_cvt_pk_bf16_f32 v11, v18, v19
	global_store_dwordx4 v[14:15], v[8:11], off
	s_and_b64 vcc, exec, s[2:3]
	s_nop 0
	v_pk_add_f32 v[8:9], v[2:3], 0 op_sel_hi:[1,0]
	v_pk_add_f32 v[2:3], v[0:1], 0 op_sel_hi:[1,0]
	v_cvt_pk_bf16_f32 v0, v4, v5
	v_cvt_pk_bf16_f32 v1, v6, v7
	s_nop 0
	v_cvt_pk_bf16_f32 v2, v2, v3
	v_cvt_pk_bf16_f32 v3, v8, v9
	global_store_dwordx4 v[12:13], v[0:3], off offset:256
	s_cbranch_vccz .LBB0_1076
	s_waitcnt vmcnt(0)
	s_cmpk_gt_u32 s31, 0xff
	s_cbranch_scc1 .LBB0_1087
	s_barrier

; #define PG8_STAGE(bufoff, gbase, voff) do { _Pragma("unroll") for (int _i = 0; _i < 2; ++_i) \
;         __builtin_amdgcn_global_load_lds((const unsigned*)((const char*)(gbase) + (voff)[_i]), (PG8_LAS unsigned*)(lds + (bufoff) + ldsw + _i * 8192), 16, 0, 0); } while (0)
; #define PG8_LDA(dst, b, h) do { _Pragma("unroll") for (int m = 0; m < 4; ++m) _Pragma("unroll") for (int k = 0; k < 2; ++k) dst[m][k] = *(const PG8_LAS bf16x8*)(lds + PG8_SA(b, h) + aoff + m * 2048 + k * 1024); } while (0)
; #define PG8_LDB(dst, b, h) do { _Pragma("unroll") for (int n = 0; n < 2; ++n) _Pragma("unroll") for (int k = 0; k < 2; ++k) dst[n][k] = *(const PG8_LAS bf16x8*)(lds + PG8_SB(b, h) + boff + n * 2048 + k * 1024); } while (0)
; #define PG8_MMA(ai, bj, At, Bt) do { __builtin_amdgcn_s_setprio(1); _Pragma("unroll") for (int m = 0; m < 4; ++m) _Pragma("unroll") for (int n = 0; n < 2; ++n) _Pragma("unroll") for (int k = 0; k < 2; ++k) \
;         acc[ai][bj][m][n] = __builtin_amdgcn_mfma_f32_16x16x32_bf16(Bt[n][k], At[m][k], acc[ai][bj][m][n], 0, 0, 0); __builtin_amdgcn_s_setprio(0); } while (0)
; #define PG8_WAIT_L(n) asm volatile("s_waitcnt lgkmcnt(" #n ")" ::: "memory")
; #define PG8_BAR __builtin_amdgcn_s_barrier()
; #define PG8_SCHED __builtin_amdgcn_sched_barrier(0)
; template <class Epi, class Sched>
; __device__ __forceinline__ void gemm_phase(PG8_LAS unsigned char* lds, const Gemm g, const Sched& S, const Epi& E) {
;     ...
;             const bool last = (t == nt - 2);
;             const char* a1 = cA + (size_t)(t + 1) * kstep;
;             const char* a2 = last ? nA : cA + (size_t)(t + 2) * kstep; const char* b2 = last ? nB : cB + (size_t)(t + 2) * kstep;
;             const char* a3 = a2 + kstep; const char* b3 = b2 + kstep;
;             if (last && has_next) S.a_ready(nxt);
;             PG8_LDB(B0, 0, 0); PG8_SCHED; PG8_LDA(At, 0, 0); PG8_STAGE(PG8_SA(1, 1), a1 + hstep, voffA);
;             PG8_WAIT_L(8); PG8_BAR; PG8_WAIT_L(0); PG8_MMA(0, 0, At, B0); PG8_BAR; PG8_SCHED;
;             PG8_LDB(B1, 0, 1); PG8_STAGE(PG8_SB(0, 0), b2, voffB);
;             PG8_BAR; PG8_WAIT_L(0); PG8_MMA(0, 1, At, B1); PG8_BAR;
;             PG8_LDA(At, 0, 1); PG8_STAGE(PG8_SA(0, 0), a2, voffA);
;             PG8_BAR; PG8_WAIT_L(0); PG8_MMA(1, 0, At, B0); PG8_BAR; PG8_SCHED;
.LBB0_1202:
	ds_read_b128 v[144:147], v151
	ds_read_b128 v[154:157], v151 offset:1024
	ds_read_b128 v[158:161], v151 offset:2048
	ds_read_b128 v[162:165], v151 offset:3072
	s_add_u32 s18, s16, 0xfffc0080
	s_addc_u32 s19, s17, -1
	s_cmp_eq_u32 s46, 12
	s_cselect_b32 s21, s9, s19
	s_cselect_b32 s20, s42, s18
	s_cselect_b32 s19, s7, s45
	s_cselect_b32 s18, s43, s44
	v_lshl_add_u64 v[174:175], s[16:17], 0, v[136:137]
	s_add_i32 m0, s15, 0xc000
	ds_read_b128 v[166:169], v152
	ds_read_b128 v[170:173], v152 offset:1024
	ds_read_b128 v[182:185], v152 offset:2048
	ds_read_b128 v[190:193], v152 offset:3072
	ds_read_b128 v[194:197], v152 offset:4096
	ds_read_b128 v[198:201], v152 offset:5120
	ds_read_b128 v[202:205], v152 offset:6144
	ds_read_b128 v[206:209], v152 offset:7168
	global_load_lds_dwordx4 v[174:175], off
	v_lshl_add_u64 v[174:175], s[16:17], 0, v[138:139]
	s_add_i32 m0, s15, 0xe000
	s_nop 0
	global_load_lds_dwordx4 v[174:175], off
	ds_read_b128 v[210:213], v153
	ds_read_b128 v[214:217], v153 offset:1024
	ds_read_b128 v[218:221], v153 offset:2048
	ds_read_b128 v[222:225], v153 offset:3072
	s_waitcnt vmcnt(8) lgkmcnt(0)
	s_barrier
	v_mfma_f32_16x16x32_bf16 v[124:127], v[144:147], v[166:169], v[124:127]
	v_mfma_f32_16x16x32_bf16 v[120:123], v[158:161], v[166:169], v[120:123]
	v_mfma_f32_16x16x32_bf16 v[108:111], v[144:147], v[182:185], v[108:111]
	v_mfma_f32_16x16x32_bf16 v[104:107], v[158:161], v[182:185], v[104:107]
	v_mfma_f32_16x16x32_bf16 v[92:95], v[144:147], v[194:197], v[92:95]
	v_mfma_f32_16x16x32_bf16 v[88:91], v[158:161], v[194:197], v[88:91]
	v_mfma_f32_16x16x32_bf16 v[76:79], v[144:147], v[202:205], v[76:79]
	v_mfma_f32_16x16x32_bf16 v[72:75], v[158:161], v[202:205], v[72:75]
	v_mfma_f32_16x16x32_bf16 v[124:127], v[154:157], v[170:173], v[124:127]
	v_mfma_f32_16x16x32_bf16 v[120:123], v[162:165], v[170:173], v[120:123]
	v_mfma_f32_16x16x32_bf16 v[108:111], v[154:157], v[190:193], v[108:111]
	v_mfma_f32_16x16x32_bf16 v[104:107], v[162:165], v[190:193], v[104:107]
	v_mfma_f32_16x16x32_bf16 v[92:95], v[154:157], v[198:201], v[92:95]
	v_mfma_f32_16x16x32_bf16 v[88:91], v[162:165], v[198:201], v[88:91]
	v_mfma_f32_16x16x32_bf16 v[76:79], v[154:157], v[206:209], v[76:79]
	v_mfma_f32_16x16x32_bf16 v[72:75], v[162:165], v[206:209], v[72:75]
	v_mfma_f32_16x16x32_bf16 v[116:119], v[210:213], v[166:169], v[116:119]
	v_mfma_f32_16x16x32_bf16 v[112:115], v[218:221], v[166:169], v[112:115]
	v_mfma_f32_16x16x32_bf16 v[100:103], v[210:213], v[182:185], v[100:103]
	v_mfma_f32_16x16x32_bf16 v[96:99], v[218:221], v[182:185], v[96:99]
	v_mfma_f32_16x16x32_bf16 v[84:87], v[210:213], v[194:197], v[84:87]
	v_mfma_f32_16x16x32_bf16 v[80:83], v[218:221], v[194:197], v[80:83]
	v_mfma_f32_16x16x32_bf16 v[68:71], v[210:213], v[202:205], v[68:71]
	v_mfma_f32_16x16x32_bf16 v[64:67], v[218:221], v[202:205], v[64:67]
	v_mfma_f32_16x16x32_bf16 v[116:119], v[214:217], v[170:173], v[116:119]
	v_mfma_f32_16x16x32_bf16 v[112:115], v[222:225], v[170:173], v[112:115]
	v_mfma_f32_16x16x32_bf16 v[100:103], v[214:217], v[190:193], v[100:103]
	v_mfma_f32_16x16x32_bf16 v[96:99], v[222:225], v[190:193], v[96:99]
	v_mfma_f32_16x16x32_bf16 v[84:87], v[214:217], v[198:201], v[84:87]
	v_mfma_f32_16x16x32_bf16 v[80:83], v[222:225], v[198:201], v[80:83]
	v_mfma_f32_16x16x32_bf16 v[68:71], v[214:217], v[206:209], v[68:71]
	v_mfma_f32_16x16x32_bf16 v[64:67], v[222:225], v[206:209], v[64:67]
	s_barrier
	ds_read_b128 v[166:169], v152 offset:16384
	ds_read_b128 v[170:173], v152 offset:17408
	ds_read_b128 v[182:185], v152 offset:18432
	ds_read_b128 v[190:193], v152 offset:19456
	ds_read_b128 v[194:197], v152 offset:20480
	ds_read_b128 v[198:201], v152 offset:21504
	ds_read_b128 v[202:205], v152 offset:22528
	ds_read_b128 v[206:209], v152 offset:23552
	s_add_i32 s47, s38, s26
	v_lshl_add_u64 v[174:175], s[18:19], 0, v[132:133]
	s_mov_b32 m0, s47
	s_nop 0
	global_load_lds_dwordx4 v[174:175], off
	v_lshl_add_u64 v[186:187], s[18:19], 0, v[128:129]
	s_add_i32 m0, s47, 0x2000
	s_nop 0
	global_load_lds_dwordx4 v[186:187], off
	s_mov_b32 m0, s15
	v_lshl_add_u64 v[226:227], s[20:21], 0, v[134:135]
	global_load_lds_dwordx4 v[226:227], off
	v_lshl_add_u64 v[228:229], s[20:21], 0, v[130:131]
	s_mov_b32 m0, s29
	s_nop 0
	global_load_lds_dwordx4 v[228:229], off
	s_add_u32 s48, s18, 0x40000
	s_addc_u32 s49, s19, 0
	s_add_i32 s47, s39, s26
	v_lshl_add_u64 v[246:247], s[48:49], 0, v[132:133]
	s_mov_b32 m0, s47
	s_nop 0
	global_load_lds_dwordx4 v[246:247], off
	v_lshl_add_u64 v[246:247], s[48:49], 0, v[128:129]
	s_add_i32 m0, s47, 0x2000
	s_nop 0
	global_load_lds_dwordx4 v[246:247], off
	s_waitcnt vmcnt(8) lgkmcnt(0)
	s_barrier
; #define PG8_STAGE(bufoff, gbase, voff) do { _Pragma("unroll") for (int _i = 0; _i < 2; ++_i) \
;         __builtin_amdgcn_global_load_lds((const unsigned*)((const char*)(gbase) + (voff)[_i]), (PG8_LAS unsigned*)(lds + (bufoff) + ldsw + _i * 8192), 16, 0, 0); } while (0)
; #define PG8_LDA(dst, b, h) do { _Pragma("unroll") for (int m = 0; m < 4; ++m) _Pragma("unroll") for (int k = 0; k < 2; ++k) dst[m][k] = *(const PG8_LAS bf16x8*)(lds + PG8_SA(b, h) + aoff + m * 2048 + k * 1024); } while (0)
; #define PG8_LDB(dst, b, h) do { _Pragma("unroll") for (int n = 0; n < 2; ++n) _Pragma("unroll") for (int k = 0; k < 2; ++k) dst[n][k] = *(const PG8_LAS bf16x8*)(lds + PG8_SB(b, h) + boff + n * 2048 + k * 1024); } while (0)
; #define PG8_MMA(ai, bj, At, Bt) do { __builtin_amdgcn_s_setprio(1); _Pragma("unroll") for (int m = 0; m < 4; ++m) _Pragma("unroll") for (int n = 0; n < 2; ++n) _Pragma("unroll") for (int k = 0; k < 2; ++k) \
;         acc[ai][bj][m][n] = __builtin_amdgcn_mfma_f32_16x16x32_bf16(Bt[n][k], At[m][k], acc[ai][bj][m][n], 0, 0, 0); __builtin_amdgcn_s_setprio(0); } while (0)
; #define PG8_WAIT_V(n) asm volatile("s_waitcnt vmcnt(" #n ")" ::: "memory")
; #define PG8_WAIT_L(n) asm volatile("s_waitcnt lgkmcnt(" #n ")" ::: "memory")
; #define PG8_BAR __builtin_amdgcn_s_barrier()
; #define PG8_SCHED __builtin_amdgcn_sched_barrier(0)
; template <class Epi, class Sched>
; __device__ __forceinline__ void gemm_phase(PG8_LAS unsigned char* lds, const Gemm g, const Sched& S, const Epi& E) {
;     ...
;             PG8_BAR; PG8_WAIT_L(0); PG8_MMA(1, 0, At, B0); PG8_BAR; PG8_SCHED;
;             PG8_STAGE(PG8_SB(0, 1), b2 + hstep, voffB);
;             PG8_WAIT_V(6); PG8_BAR; PG8_MMA(1, 1, At, B1); PG8_BAR;
;             PG8_LDB(B0, 1, 0); PG8_SCHED; PG8_LDA(At, 1, 0); PG8_STAGE(PG8_SA(0, 1), a2 + hstep, voffA);
;             PG8_WAIT_L(8); PG8_BAR; PG8_WAIT_L(0); PG8_MMA(0, 0, At, B0); PG8_BAR; PG8_SCHED;
;             PG8_LDB(B1, 1, 1); PG8_STAGE(PG8_SB(1, 0), b3, voffB);
;             PG8_BAR; PG8_WAIT_L(0); PG8_MMA(0, 1, At, B1); PG8_BAR;
;             PG8_LDA(At, 1, 1); PG8_STAGE(PG8_SA(1, 0), a3, voffA);
;             PG8_BAR; PG8_WAIT_L(0); PG8_MMA(1, 0, At, B0); PG8_BAR; PG8_SCHED;
	v_mfma_f32_16x16x32_bf16 v[60:63], v[144:147], v[166:169], v[60:63]
	v_mfma_f32_16x16x32_bf16 v[56:59], v[158:161], v[166:169], v[56:59]
	v_mfma_f32_16x16x32_bf16 v[44:47], v[144:147], v[182:185], v[44:47]
	v_mfma_f32_16x16x32_bf16 v[40:43], v[158:161], v[182:185], v[40:43]
	v_mfma_f32_16x16x32_bf16 v[28:31], v[144:147], v[194:197], v[28:31]
	v_mfma_f32_16x16x32_bf16 v[24:27], v[158:161], v[194:197], v[24:27]
	v_mfma_f32_16x16x32_bf16 v[12:15], v[144:147], v[202:205], v[12:15]
	v_mfma_f32_16x16x32_bf16 v[8:11], v[158:161], v[202:205], v[8:11]
	v_mfma_f32_16x16x32_bf16 v[60:63], v[154:157], v[170:173], v[60:63]
	v_mfma_f32_16x16x32_bf16 v[56:59], v[162:165], v[170:173], v[56:59]
	v_mfma_f32_16x16x32_bf16 v[44:47], v[154:157], v[190:193], v[44:47]
	v_mfma_f32_16x16x32_bf16 v[40:43], v[162:165], v[190:193], v[40:43]
	v_mfma_f32_16x16x32_bf16 v[28:31], v[154:157], v[198:201], v[28:31]
	v_mfma_f32_16x16x32_bf16 v[24:27], v[162:165], v[198:201], v[24:27]
	v_mfma_f32_16x16x32_bf16 v[12:15], v[154:157], v[206:209], v[12:15]
	v_mfma_f32_16x16x32_bf16 v[8:11], v[162:165], v[206:209], v[8:11]
	v_mfma_f32_16x16x32_bf16 v[52:55], v[210:213], v[166:169], v[52:55]
	v_mfma_f32_16x16x32_bf16 v[48:51], v[218:221], v[166:169], v[48:51]
	v_mfma_f32_16x16x32_bf16 v[36:39], v[210:213], v[182:185], v[36:39]
	v_mfma_f32_16x16x32_bf16 v[32:35], v[218:221], v[182:185], v[32:35]
	v_mfma_f32_16x16x32_bf16 v[20:23], v[210:213], v[194:197], v[20:23]
	v_mfma_f32_16x16x32_bf16 v[16:19], v[218:221], v[194:197], v[16:19]
	v_mfma_f32_16x16x32_bf16 v[4:7], v[210:213], v[202:205], v[4:7]
	v_mfma_f32_16x16x32_bf16 v[0:3], v[218:221], v[202:205], v[0:3]
	v_mfma_f32_16x16x32_bf16 v[52:55], v[214:217], v[170:173], v[52:55]
	v_mfma_f32_16x16x32_bf16 v[48:51], v[222:225], v[170:173], v[48:51]
	v_mfma_f32_16x16x32_bf16 v[36:39], v[214:217], v[190:193], v[36:39]
	v_mfma_f32_16x16x32_bf16 v[32:35], v[222:225], v[190:193], v[32:35]
	v_mfma_f32_16x16x32_bf16 v[20:23], v[214:217], v[198:201], v[20:23]
	v_mfma_f32_16x16x32_bf16 v[16:19], v[222:225], v[198:201], v[16:19]
	v_mfma_f32_16x16x32_bf16 v[4:7], v[214:217], v[206:209], v[4:7]
	v_mfma_f32_16x16x32_bf16 v[0:3], v[222:225], v[206:209], v[0:3]
	s_barrier
	s_add_i32 s47, 0, 0x18000
	v_add_u32_e32 v162, s47, v149
	ds_read_b128 v[144:147], v162
	ds_read_b128 v[154:157], v162 offset:1024
	ds_read_b128 v[158:161], v162 offset:2048
	ds_read_b128 v[162:165], v162 offset:3072
	s_add_u32 s20, s20, 0x40000
	s_addc_u32 s21, s21, 0
	s_mov_b32 m0, s30
	v_lshl_add_u64 v[210:211], s[20:21], 0, v[134:135]
	ds_read_b128 v[166:169], v152 offset:32768
	ds_read_b128 v[170:173], v152 offset:33792
	ds_read_b128 v[182:185], v152 offset:34816
	ds_read_b128 v[190:193], v152 offset:35840
	ds_read_b128 v[194:197], v152 offset:36864
	ds_read_b128 v[198:201], v152 offset:37888
	ds_read_b128 v[202:205], v152 offset:38912
	ds_read_b128 v[206:209], v152 offset:39936
	global_load_lds_dwordx4 v[210:211], off
	v_lshl_add_u64 v[210:211], s[20:21], 0, v[130:131]
	s_mov_b32 m0, s31
	s_nop 0
	global_load_lds_dwordx4 v[210:211], off
	s_add_i32 s20, 0, 0x1c000
	v_add_u32_e32 v179, s20, v149
	ds_read_b128 v[210:213], v179
	ds_read_b128 v[214:217], v179 offset:1024
	ds_read_b128 v[218:221], v179 offset:2048
	ds_read_b128 v[222:225], v179 offset:3072
	s_waitcnt vmcnt(8) lgkmcnt(0)
	s_barrier
	v_mfma_f32_16x16x32_bf16 v[124:127], v[144:147], v[166:169], v[124:127]
	v_mfma_f32_16x16x32_bf16 v[120:123], v[158:161], v[166:169], v[120:123]
	v_mfma_f32_16x16x32_bf16 v[108:111], v[144:147], v[182:185], v[108:111]
	v_mfma_f32_16x16x32_bf16 v[104:107], v[158:161], v[182:185], v[104:107]
	v_mfma_f32_16x16x32_bf16 v[92:95], v[144:147], v[194:197], v[92:95]
	v_mfma_f32_16x16x32_bf16 v[88:91], v[158:161], v[194:197], v[88:91]
	v_mfma_f32_16x16x32_bf16 v[76:79], v[144:147], v[202:205], v[76:79]
	v_mfma_f32_16x16x32_bf16 v[72:75], v[158:161], v[202:205], v[72:75]
	v_mfma_f32_16x16x32_bf16 v[124:127], v[154:157], v[170:173], v[124:127]
	v_mfma_f32_16x16x32_bf16 v[120:123], v[162:165], v[170:173], v[120:123]
	v_mfma_f32_16x16x32_bf16 v[108:111], v[154:157], v[190:193], v[108:111]
	v_mfma_f32_16x16x32_bf16 v[104:107], v[162:165], v[190:193], v[104:107]
	v_mfma_f32_16x16x32_bf16 v[92:95], v[154:157], v[198:201], v[92:95]
	v_mfma_f32_16x16x32_bf16 v[88:91], v[162:165], v[198:201], v[88:91]
	v_mfma_f32_16x16x32_bf16 v[76:79], v[154:157], v[206:209], v[76:79]
	v_mfma_f32_16x16x32_bf16 v[72:75], v[162:165], v[206:209], v[72:75]
	v_mfma_f32_16x16x32_bf16 v[116:119], v[210:213], v[166:169], v[116:119]
	v_mfma_f32_16x16x32_bf16 v[112:115], v[218:221], v[166:169], v[112:115]
	v_mfma_f32_16x16x32_bf16 v[100:103], v[210:213], v[182:185], v[100:103]
	v_mfma_f32_16x16x32_bf16 v[96:99], v[218:221], v[182:185], v[96:99]
	v_mfma_f32_16x16x32_bf16 v[84:87], v[210:213], v[194:197], v[84:87]
	v_mfma_f32_16x16x32_bf16 v[80:83], v[218:221], v[194:197], v[80:83]
	v_mfma_f32_16x16x32_bf16 v[68:71], v[210:213], v[202:205], v[68:71]
	v_mfma_f32_16x16x32_bf16 v[64:67], v[218:221], v[202:205], v[64:67]
	v_mfma_f32_16x16x32_bf16 v[116:119], v[214:217], v[170:173], v[116:119]
	v_mfma_f32_16x16x32_bf16 v[112:115], v[222:225], v[170:173], v[112:115]
	v_mfma_f32_16x16x32_bf16 v[100:103], v[214:217], v[190:193], v[100:103]
	v_mfma_f32_16x16x32_bf16 v[96:99], v[222:225], v[190:193], v[96:99]
	v_mfma_f32_16x16x32_bf16 v[84:87], v[214:217], v[198:201], v[84:87]
	v_mfma_f32_16x16x32_bf16 v[80:83], v[222:225], v[198:201], v[80:83]
	v_mfma_f32_16x16x32_bf16 v[68:71], v[214:217], v[206:209], v[68:71]
	v_mfma_f32_16x16x32_bf16 v[64:67], v[222:225], v[206:209], v[64:67]
	s_barrier
; __device__ __forceinline__ unsigned cvt_pk_bf16(float lo, float hi) { unsigned r; asm volatile("v_cvt_pk_bf16_f32 %0, %1, %2" : "=v"(r) : "v"(lo), "v"(hi)); return r; }
; #define PG8_STAGE(bufoff, gbase, voff) do { _Pragma("unroll") for (int _i = 0; _i < 2; ++_i) \
;         __builtin_amdgcn_global_load_lds((const unsigned*)((const char*)(gbase) + (voff)[_i]), (PG8_LAS unsigned*)(lds + (bufoff) + ldsw + _i * 8192), 16, 0, 0); } while (0)
; #define PG8_LDA(dst, b, h) do { _Pragma("unroll") for (int m = 0; m < 4; ++m) _Pragma("unroll") for (int k = 0; k < 2; ++k) dst[m][k] = *(const PG8_LAS bf16x8*)(lds + PG8_SA(b, h) + aoff + m * 2048 + k * 1024); } while (0)
; #define PG8_MMA(ai, bj, At, Bt) do { __builtin_amdgcn_s_setprio(1); _Pragma("unroll") for (int m = 0; m < 4; ++m) _Pragma("unroll") for (int n = 0; n < 2; ++n) _Pragma("unroll") for (int k = 0; k < 2; ++k) \
;         acc[ai][bj][m][n] = __builtin_amdgcn_mfma_f32_16x16x32_bf16(Bt[n][k], At[m][k], acc[ai][bj][m][n], 0, 0, 0); __builtin_amdgcn_s_setprio(0); } while (0)
; #define PG8_WAIT_V(n) asm volatile("s_waitcnt vmcnt(" #n ")" ::: "memory")
; #define PG8_WAIT_L(n) asm volatile("s_waitcnt lgkmcnt(" #n ")" ::: "memory")
;     __device__ __forceinline__ void operator()(const f32x4 (&acc)[2][2][4][2], const Unit& u, int wr, int wc, int fr, int fq) const {
;     ...
;         for (int ai = 0; ai < 2; ++ai)
; #pragma unroll
;             for (int m = 0; m < 4; ++m) { bf16_t* rowp = O + (size_t)(row0 + ai * HALF + m * 16) * ldc + col0;
;                 f32x4 v0, v1;
; #pragma unroll
;                 for (int j = 0; j < 1; ++j) { v0 = acc[ai][0][m][0] * sigmoid4(acc[ai][0][m][0]) * acc[ai][1][m][0]; v1 = acc[ai][0][m][1] * sigmoid4(acc[ai][0][m][1]) * acc[ai][1][m][1]; }
;                 u32x4 w; w.x = cvt_pk_bf16(v0[0], v0[1]); w.y = cvt_pk_bf16(v0[2], v0[3]); w.z = cvt_pk_bf16(v1[0], v1[1]); w.w = cvt_pk_bf16(v1[2], v1[3]);
;                 *(u32x4*)rowp = w; }
; template <class Epi, class Sched>
; __device__ __forceinline__ void gemm_phase(PG8_LAS unsigned char* lds, const Gemm g, const Sched& S, const Epi& E) {
;     ...
;             PG8_LDA(At, 1, 1); PG8_STAGE(PG8_SA(1, 0), a3, voffA);
;             PG8_BAR; PG8_WAIT_L(0); PG8_MMA(1, 0, At, B0); PG8_BAR; PG8_SCHED;
;             PG8_STAGE(PG8_SB(1, 1), b3 + hstep, voffB);
;             PG8_WAIT_V(6); PG8_BAR; PG8_MMA(1, 1, At, B1); PG8_BAR;
;         }
	ds_read_b128 v[166:169], v152 offset:49152
	ds_read_b128 v[170:173], v152 offset:50176
	ds_read_b128 v[182:185], v152 offset:51200
	ds_read_b128 v[190:193], v152 offset:52224
	ds_read_b128 v[194:197], v152 offset:53248
	ds_read_b128 v[198:201], v152 offset:54272
	ds_read_b128 v[202:205], v152 offset:55296
	ds_read_b128 v[206:209], v152 offset:56320
	s_add_i32 s21, s47, s26
	v_lshl_add_u64 v[174:175], v[174:175], 0, s[4:5]
	s_mov_b32 m0, s21
	s_nop 0
	global_load_lds_dwordx4 v[174:175], off
	v_lshl_add_u64 v[174:175], v[186:187], 0, s[4:5]
	s_add_i32 m0, s21, 0x2000
	s_nop 0
	global_load_lds_dwordx4 v[174:175], off
	s_mov_b32 m0, s35
	v_lshl_add_u64 v[174:175], v[226:227], 0, s[4:5]
	global_load_lds_dwordx4 v[174:175], off
	v_lshl_add_u64 v[174:175], v[228:229], 0, s[4:5]
	s_mov_b32 m0, s36
	s_nop 0
	global_load_lds_dwordx4 v[174:175], off
	s_add_u32 s18, s18, 0x40080
	s_addc_u32 s19, s19, 0
	s_add_i32 s20, s20, s26
	v_lshl_add_u64 v[246:247], s[18:19], 0, v[132:133]
	s_mov_b32 m0, s20
	s_nop 0
	global_load_lds_dwordx4 v[246:247], off
	v_lshl_add_u64 v[246:247], s[18:19], 0, v[128:129]
	s_add_i32 m0, s20, 0x2000
	s_nop 0
	global_load_lds_dwordx4 v[246:247], off
	s_waitcnt vmcnt(8) lgkmcnt(0)
	s_barrier
	v_mfma_f32_16x16x32_bf16 v[60:63], v[144:147], v[166:169], v[60:63]
	v_mfma_f32_16x16x32_bf16 v[56:59], v[158:161], v[166:169], v[56:59]
	v_mfma_f32_16x16x32_bf16 v[44:47], v[144:147], v[182:185], v[44:47]
	v_mfma_f32_16x16x32_bf16 v[40:43], v[158:161], v[182:185], v[40:43]
	v_mfma_f32_16x16x32_bf16 v[28:31], v[144:147], v[194:197], v[28:31]
	v_mfma_f32_16x16x32_bf16 v[24:27], v[158:161], v[194:197], v[24:27]
	v_mfma_f32_16x16x32_bf16 v[12:15], v[144:147], v[202:205], v[12:15]
	v_mfma_f32_16x16x32_bf16 v[8:11], v[158:161], v[202:205], v[8:11]
	v_mfma_f32_16x16x32_bf16 v[60:63], v[154:157], v[170:173], v[60:63]
	v_mfma_f32_16x16x32_bf16 v[56:59], v[162:165], v[170:173], v[56:59]
	v_mfma_f32_16x16x32_bf16 v[44:47], v[154:157], v[190:193], v[44:47]
	v_mfma_f32_16x16x32_bf16 v[40:43], v[162:165], v[190:193], v[40:43]
	v_mfma_f32_16x16x32_bf16 v[28:31], v[154:157], v[198:201], v[28:31]
	v_mfma_f32_16x16x32_bf16 v[24:27], v[162:165], v[198:201], v[24:27]
	v_mfma_f32_16x16x32_bf16 v[12:15], v[154:157], v[206:209], v[12:15]
	v_mfma_f32_16x16x32_bf16 v[8:11], v[162:165], v[206:209], v[8:11]
	v_mfma_f32_16x16x32_bf16 v[52:55], v[210:213], v[166:169], v[52:55]
	v_mfma_f32_16x16x32_bf16 v[48:51], v[218:221], v[166:169], v[48:51]
	v_mfma_f32_16x16x32_bf16 v[36:39], v[210:213], v[182:185], v[36:39]
	v_mfma_f32_16x16x32_bf16 v[32:35], v[218:221], v[182:185], v[32:35]
	v_mfma_f32_16x16x32_bf16 v[20:23], v[210:213], v[194:197], v[20:23]
	v_mfma_f32_16x16x32_bf16 v[16:19], v[218:221], v[194:197], v[16:19]
	v_mfma_f32_16x16x32_bf16 v[4:7], v[210:213], v[202:205], v[4:7]
	v_mfma_f32_16x16x32_bf16 v[0:3], v[218:221], v[202:205], v[0:3]
	v_mfma_f32_16x16x32_bf16 v[52:55], v[214:217], v[170:173], v[52:55]
	v_mfma_f32_16x16x32_bf16 v[48:51], v[222:225], v[170:173], v[48:51]
	v_mfma_f32_16x16x32_bf16 v[36:39], v[214:217], v[190:193], v[36:39]
	v_mfma_f32_16x16x32_bf16 v[32:35], v[222:225], v[190:193], v[32:35]
	v_mfma_f32_16x16x32_bf16 v[20:23], v[214:217], v[198:201], v[20:23]
	v_mfma_f32_16x16x32_bf16 v[16:19], v[222:225], v[198:201], v[16:19]
	v_mfma_f32_16x16x32_bf16 v[4:7], v[214:217], v[206:209], v[4:7]
	v_mfma_f32_16x16x32_bf16 v[0:3], v[222:225], v[206:209], v[0:3]
	s_barrier
	s_add_i32 s46, s46, 2
	s_add_u32 s16, s16, 0x100
	s_addc_u32 s17, s17, 0
	s_add_u32 s44, s44, 0x100
	s_addc_u32 s45, s45, 0
	s_cmp_gt_u32 s46, 13
	s_cbranch_scc0 .LBB0_1202
	v_max_f32_e32 v144, v124, v124
	v_max_f32_e32 v144, 0xc1a00000, v144
	v_mul_f32_e32 v144, 0xbfb8aa3b, v144
	v_exp_f32_e32 v157, v144
	v_max_f32_e32 v144, v125, v125
	v_max_f32_e32 v144, 0xc1a00000, v144
	v_mul_f32_e32 v144, 0xbfb8aa3b, v144
	v_exp_f32_e32 v156, v144
	v_max_f32_e32 v144, v126, v126
	v_max_f32_e32 v144, 0xc1a00000, v144
	v_mul_f32_e32 v144, 0xbfb8aa3b, v144
	v_exp_f32_e32 v159, v144
	v_max_f32_e32 v144, v127, v127
	v_max_f32_e32 v144, 0xc1a00000, v144
	v_mul_f32_e32 v144, 0xbfb8aa3b, v144
	v_exp_f32_e32 v158, v144
	v_pk_add_f32 v[156:157], v[156:157], 1.0 op_sel_hi:[1,0]
	v_lshl_or_b32 v146, s41, 7, v150
	v_mov_b32_e32 v160, v157
	v_pk_add_f32 v[158:159], v[158:159], 1.0 op_sel_hi:[1,0]
	v_mov_b32_e32 v162, v156
	v_mov_b32_e32 v161, v159
	v_mov_b32_e32 v163, v158
	v_pk_mul_f32 v[160:161], v[160:161], v[162:163]
	v_lshl_add_u32 v154, s14, 8, v148
	v_mul_f32_e32 v155, v160, v161
	v_rcp_f32_e32 v155, v155
	v_ashrrev_i32_e32 v147, 31, v146
	v_mov_b64_e32 v[144:145], s[0:1]
	v_mad_i64_i32 v[162:163], s[16:17], v154, s40, v[144:145]
	v_mul_f32_e32 v164, v161, v155
	v_mul_f32_e32 v160, v160, v155
	v_max_f32_e32 v155, v120, v120
	v_max_f32_e32 v155, 0xc1a00000, v155
	v_mul_f32_e32 v155, 0xbfb8aa3b, v155
	v_pk_mul_f32 v[158:159], v[158:159], v[160:161] op_sel_hi:[1,0]
	v_exp_f32_e32 v161, v155
	v_max_f32_e32 v155, v121, v121
	v_max_f32_e32 v155, 0xc1a00000, v155
	v_mul_f32_e32 v155, 0xbfb8aa3b, v155
	v_exp_f32_e32 v160, v155
	v_max_f32_e32 v155, v122, v122
	v_max_f32_e32 v155, 0xc1a00000, v155
	v_mul_f32_e32 v155, 0xbfb8aa3b, v155
	v_exp_f32_e32 v167, v155
	v_max_f32_e32 v155, v123, v123
	v_max_f32_e32 v155, 0xc1a00000, v155
	v_mul_f32_e32 v155, 0xbfb8aa3b, v155
	v_exp_f32_e32 v166, v155
	v_pk_mul_f32 v[156:157], v[156:157], v[164:165] op_sel_hi:[1,0]
	v_pk_mul_f32 v[126:127], v[126:127], v[158:159]
	v_pk_mul_f32 v[124:125], v[124:125], v[156:157]
	v_pk_add_f32 v[156:157], v[160:161], 1.0 op_sel_hi:[1,0]
	v_pk_add_f32 v[160:161], v[166:167], 1.0 op_sel_hi:[1,0]
	v_mov_b32_e32 v164, v157
	v_mov_b32_e32 v165, v161
; __device__ __forceinline__ unsigned cvt_pk_bf16(float lo, float hi) { unsigned r; asm volatile("v_cvt_pk_bf16_f32 %0, %1, %2" : "=v"(r) : "v"(lo), "v"(hi)); return r; }
; __device__ __forceinline__ f32x4 sigmoid4(f32x4 x) {
;     f32x4 d;
; #pragma unroll
;     for (int j = 0; j < 4; ++j) d[j] = 1.0f + __expf(-fmaxf(x[j], -20.0f));
;     const float p01 = d[0] * d[1], p23 = d[2] * d[3], r = __builtin_amdgcn_rcpf(p01 * p23), r01 = r * p23, r23 = r * p01;
;     return (f32x4){r01 * d[1], r01 * d[0], r23 * d[3], r23 * d[2]};
; }
;     __device__ __forceinline__ void operator()(const f32x4 (&acc)[2][2][4][2], const Unit& u, int wr, int wc, int fr, int fq) const {
;     ...
;         for (int ai = 0; ai < 2; ++ai)
; #pragma unroll
;             for (int m = 0; m < 4; ++m) { bf16_t* rowp = O + (size_t)(row0 + ai * HALF + m * 16) * ldc + col0;
;                 f32x4 v0, v1;
; #pragma unroll
;                 for (int j = 0; j < 1; ++j) { v0 = acc[ai][0][m][0] * sigmoid4(acc[ai][0][m][0]) * acc[ai][1][m][0]; v1 = acc[ai][0][m][1] * sigmoid4(acc[ai][0][m][1]) * acc[ai][1][m][1]; }
;                 u32x4 w; w.x = cvt_pk_bf16(v0[0], v0[1]); w.y = cvt_pk_bf16(v0[2], v0[3]); w.z = cvt_pk_bf16(v1[0], v1[1]); w.w = cvt_pk_bf16(v1[2], v1[3]);
;                 *(u32x4*)rowp = w; }
	v_mov_b32_e32 v166, v156
	v_mov_b32_e32 v167, v160
	v_pk_mul_f32 v[164:165], v[164:165], v[166:167]
	v_pk_mul_f32 v[118:119], v[126:127], v[118:119]
	v_mul_f32_e32 v155, v164, v165
	v_rcp_f32_e32 v155, v155
	v_pk_mul_f32 v[116:117], v[124:125], v[116:117]
	v_lshlrev_b64 v[146:147], 1, v[146:147]
	v_lshl_add_u64 v[162:163], v[162:163], 0, v[146:147]
	v_mul_f32_e32 v124, v165, v155
	v_mul_f32_e32 v126, v164, v155
	v_pk_mul_f32 v[126:127], v[160:161], v[126:127] op_sel_hi:[1,0]
	v_pk_mul_f32 v[124:125], v[156:157], v[124:125] op_sel_hi:[1,0]
	v_pk_mul_f32 v[122:123], v[122:123], v[126:127]
	v_pk_mul_f32 v[120:121], v[120:121], v[124:125]
	v_pk_mul_f32 v[122:123], v[122:123], v[114:115]
	v_pk_mul_f32 v[114:115], v[120:121], v[112:113]
	v_cvt_pk_bf16_f32 v112, v116, v117
	v_cvt_pk_bf16_f32 v113, v118, v119
	v_max_f32_e32 v116, v108, v108
	v_max_f32_e32 v118, v110, v110
	v_max_f32_e32 v116, 0xc1a00000, v116
	v_max_f32_e32 v118, 0xc1a00000, v118
	v_mul_f32_e32 v116, 0xbfb8aa3b, v116
	v_mul_f32_e32 v118, 0xbfb8aa3b, v118
	v_exp_f32_e32 v117, v116
	v_max_f32_e32 v116, v109, v109
	v_exp_f32_e32 v119, v118
	v_max_f32_e32 v118, v111, v111
	v_max_f32_e32 v116, 0xc1a00000, v116
	v_max_f32_e32 v118, 0xc1a00000, v118
	v_mul_f32_e32 v116, 0xbfb8aa3b, v116
	v_mul_f32_e32 v118, 0xbfb8aa3b, v118
	v_exp_f32_e32 v116, v116
	v_exp_f32_e32 v118, v118
	v_cvt_pk_bf16_f32 v114, v114, v115
	v_cvt_pk_bf16_f32 v115, v122, v123
	global_store_dwordx4 v[162:163], v[112:115], off
	v_or_b32_e32 v120, 16, v154
	s_and_b64 vcc, exec, s[2:3]
	v_pk_add_f32 v[112:113], v[116:117], 1.0 op_sel_hi:[1,0]
	v_pk_add_f32 v[114:115], v[118:119], 1.0 op_sel_hi:[1,0]
	v_mov_b32_e32 v116, v113
	v_mov_b32_e32 v117, v115
	v_mov_b32_e32 v118, v112
	v_mov_b32_e32 v119, v114
	v_pk_mul_f32 v[116:117], v[116:117], v[118:119]
	s_mov_b32 s41, s6
	v_mul_f32_e32 v118, v116, v117
	v_rcp_f32_e32 v121, v118
	v_mad_i64_i32 v[118:119], s[16:17], v120, s40, v[144:145]
	v_lshl_add_u64 v[118:119], v[118:119], 0, v[146:147]
	v_mul_f32_e32 v116, v116, v121
	v_mul_f32_e32 v120, v117, v121
	v_pk_mul_f32 v[114:115], v[114:115], v[116:117] op_sel_hi:[1,0]
	v_max_f32_e32 v116, v104, v104
	v_max_f32_e32 v121, v106, v106
	v_max_f32_e32 v116, 0xc1a00000, v116
	v_max_f32_e32 v121, 0xc1a00000, v121
	v_mul_f32_e32 v116, 0xbfb8aa3b, v116
	v_mul_f32_e32 v121, 0xbfb8aa3b, v121
	v_exp_f32_e32 v117, v116
	v_max_f32_e32 v116, v105, v105
	v_exp_f32_e32 v123, v121
	v_max_f32_e32 v121, v107, v107
	v_max_f32_e32 v116, 0xc1a00000, v116
	v_max_f32_e32 v121, 0xc1a00000, v121
	v_mul_f32_e32 v116, 0xbfb8aa3b, v116
	v_mul_f32_e32 v121, 0xbfb8aa3b, v121
	v_exp_f32_e32 v116, v116
	v_exp_f32_e32 v122, v121
	v_pk_mul_f32 v[112:113], v[112:113], v[120:121] op_sel_hi:[1,0]
	v_pk_mul_f32 v[110:111], v[110:111], v[114:115]
	v_pk_mul_f32 v[108:109], v[108:109], v[112:113]
	v_pk_add_f32 v[112:113], v[116:117], 1.0 op_sel_hi:[1,0]
	v_pk_add_f32 v[116:117], v[122:123], 1.0 op_sel_hi:[1,0]
	v_mov_b32_e32 v120, v113
	v_mov_b32_e32 v121, v117
	v_mov_b32_e32 v122, v112
	v_mov_b32_e32 v123, v116
	v_pk_mul_f32 v[120:121], v[120:121], v[122:123]
	v_pk_mul_f32 v[102:103], v[110:111], v[102:103]
	v_mul_f32_e32 v122, v120, v121
	v_rcp_f32_e32 v122, v122
	v_pk_mul_f32 v[100:101], v[108:109], v[100:101]
	s_mov_b32 s14, s8
	s_mov_b64 s[18:19], s[12:13]
	v_mul_f32_e32 v108, v121, v122
	v_mul_f32_e32 v110, v120, v122
	v_pk_mul_f32 v[110:111], v[116:117], v[110:111] op_sel_hi:[1,0]
	v_pk_mul_f32 v[108:109], v[112:113], v[108:109] op_sel_hi:[1,0]
	v_pk_mul_f32 v[106:107], v[106:107], v[110:111]
	v_pk_mul_f32 v[104:105], v[104:105], v[108:109]
	v_pk_mul_f32 v[106:107], v[106:107], v[98:99]
	v_pk_mul_f32 v[98:99], v[104:105], v[96:97]
	v_cvt_pk_bf16_f32 v96, v100, v101
	v_cvt_pk_bf16_f32 v97, v102, v103
	v_max_f32_e32 v100, v92, v92
	v_max_f32_e32 v102, v94, v94
	v_max_f32_e32 v100, 0xc1a00000, v100
	v_max_f32_e32 v102, 0xc1a00000, v102
	v_mul_f32_e32 v100, 0xbfb8aa3b, v100
	v_mul_f32_e32 v102, 0xbfb8aa3b, v102
	v_exp_f32_e32 v101, v100
	v_max_f32_e32 v100, v93, v93
	v_exp_f32_e32 v103, v102
	v_max_f32_e32 v102, v95, v95
	v_max_f32_e32 v100, 0xc1a00000, v100
	v_max_f32_e32 v102, 0xc1a00000, v102
	v_mul_f32_e32 v100, 0xbfb8aa3b, v100
	v_mul_f32_e32 v102, 0xbfb8aa3b, v102
	v_exp_f32_e32 v100, v100
	v_exp_f32_e32 v102, v102
	v_cvt_pk_bf16_f32 v98, v98, v99
	v_cvt_pk_bf16_f32 v99, v106, v107
	global_store_dwordx4 v[118:119], v[96:99], off
	v_or_b32_e32 v104, 32, v154
	s_nop 0
	v_pk_add_f32 v[96:97], v[100:101], 1.0 op_sel_hi:[1,0]
	v_pk_add_f32 v[98:99], v[102:103], 1.0 op_sel_hi:[1,0]
	v_mov_b32_e32 v100, v97
	v_mov_b32_e32 v101, v99
	v_mov_b32_e32 v102, v96
	v_mov_b32_e32 v103, v98
	v_pk_mul_f32 v[100:101], v[100:101], v[102:103]
	s_nop 0
	v_mul_f32_e32 v102, v100, v101
	v_rcp_f32_e32 v105, v102
	v_mad_i64_i32 v[102:103], s[16:17], v104, s40, v[144:145]
	v_lshl_add_u64 v[102:103], v[102:103], 0, v[146:147]
	v_mul_f32_e32 v100, v100, v105
	v_mul_f32_e32 v104, v101, v105
	v_pk_mul_f32 v[98:99], v[98:99], v[100:101] op_sel_hi:[1,0]
	v_max_f32_e32 v100, v88, v88
	v_max_f32_e32 v105, v90, v90
	v_max_f32_e32 v100, 0xc1a00000, v100
	v_max_f32_e32 v105, 0xc1a00000, v105
	v_mul_f32_e32 v100, 0xbfb8aa3b, v100
	v_mul_f32_e32 v105, 0xbfb8aa3b, v105
	v_exp_f32_e32 v101, v100
	v_max_f32_e32 v100, v89, v89
	v_exp_f32_e32 v107, v105
	v_max_f32_e32 v105, v91, v91
	v_max_f32_e32 v100, 0xc1a00000, v100
	v_max_f32_e32 v105, 0xc1a00000, v105
	v_mul_f32_e32 v100, 0xbfb8aa3b, v100
	v_mul_f32_e32 v105, 0xbfb8aa3b, v105
	v_exp_f32_e32 v100, v100
	v_exp_f32_e32 v106, v105
	v_pk_mul_f32 v[96:97], v[96:97], v[104:105] op_sel_hi:[1,0]
	v_pk_mul_f32 v[94:95], v[94:95], v[98:99]
; __device__ __forceinline__ unsigned cvt_pk_bf16(float lo, float hi) { unsigned r; asm volatile("v_cvt_pk_bf16_f32 %0, %1, %2" : "=v"(r) : "v"(lo), "v"(hi)); return r; }
; __device__ __forceinline__ f32x4 sigmoid4(f32x4 x) {
;     f32x4 d;
; #pragma unroll
;     for (int j = 0; j < 4; ++j) d[j] = 1.0f + __expf(-fmaxf(x[j], -20.0f));
;     const float p01 = d[0] * d[1], p23 = d[2] * d[3], r = __builtin_amdgcn_rcpf(p01 * p23), r01 = r * p23, r23 = r * p01;
;     return (f32x4){r01 * d[1], r01 * d[0], r23 * d[3], r23 * d[2]};
; }
;     __device__ __forceinline__ void operator()(const f32x4 (&acc)[2][2][4][2], const Unit& u, int wr, int wc, int fr, int fq) const {
;     ...
;         for (int ai = 0; ai < 2; ++ai)
; #pragma unroll
;             for (int m = 0; m < 4; ++m) { bf16_t* rowp = O + (size_t)(row0 + ai * HALF + m * 16) * ldc + col0;
;                 f32x4 v0, v1;
; #pragma unroll
;                 for (int j = 0; j < 1; ++j) { v0 = acc[ai][0][m][0] * sigmoid4(acc[ai][0][m][0]) * acc[ai][1][m][0]; v1 = acc[ai][0][m][1] * sigmoid4(acc[ai][0][m][1]) * acc[ai][1][m][1]; }
;                 u32x4 w; w.x = cvt_pk_bf16(v0[0], v0[1]); w.y = cvt_pk_bf16(v0[2], v0[3]); w.z = cvt_pk_bf16(v1[0], v1[1]); w.w = cvt_pk_bf16(v1[2], v1[3]);
;                 *(u32x4*)rowp = w; }
	v_pk_mul_f32 v[92:93], v[92:93], v[96:97]
	v_pk_add_f32 v[96:97], v[100:101], 1.0 op_sel_hi:[1,0]
	v_pk_add_f32 v[100:101], v[106:107], 1.0 op_sel_hi:[1,0]
	v_mov_b32_e32 v104, v97
	v_mov_b32_e32 v105, v101
	v_mov_b32_e32 v106, v96
	v_mov_b32_e32 v107, v100
	v_pk_mul_f32 v[104:105], v[104:105], v[106:107]
	v_pk_mul_f32 v[86:87], v[94:95], v[86:87]
	v_mul_f32_e32 v106, v104, v105
	v_rcp_f32_e32 v106, v106
	v_pk_mul_f32 v[84:85], v[92:93], v[84:85]
	v_mul_f32_e32 v92, v105, v106
	v_mul_f32_e32 v94, v104, v106
	v_pk_mul_f32 v[94:95], v[100:101], v[94:95] op_sel_hi:[1,0]
	v_pk_mul_f32 v[92:93], v[96:97], v[92:93] op_sel_hi:[1,0]
	v_pk_mul_f32 v[90:91], v[90:91], v[94:95]
	v_pk_mul_f32 v[88:89], v[88:89], v[92:93]
	v_pk_mul_f32 v[90:91], v[90:91], v[82:83]
	v_pk_mul_f32 v[82:83], v[88:89], v[80:81]
	v_cvt_pk_bf16_f32 v80, v84, v85
	v_cvt_pk_bf16_f32 v81, v86, v87
	v_max_f32_e32 v84, v76, v76
	v_max_f32_e32 v86, v78, v78
	v_max_f32_e32 v84, 0xc1a00000, v84
	v_max_f32_e32 v86, 0xc1a00000, v86
	v_mul_f32_e32 v84, 0xbfb8aa3b, v84
	v_mul_f32_e32 v86, 0xbfb8aa3b, v86
	v_exp_f32_e32 v85, v84
	v_max_f32_e32 v84, v77, v77
	v_exp_f32_e32 v87, v86
	v_max_f32_e32 v86, v79, v79
	v_max_f32_e32 v84, 0xc1a00000, v84
	v_max_f32_e32 v86, 0xc1a00000, v86
	v_mul_f32_e32 v84, 0xbfb8aa3b, v84
	v_mul_f32_e32 v86, 0xbfb8aa3b, v86
	v_exp_f32_e32 v84, v84
	v_exp_f32_e32 v86, v86
	v_cvt_pk_bf16_f32 v82, v82, v83
	v_cvt_pk_bf16_f32 v83, v90, v91
	global_store_dwordx4 v[102:103], v[80:83], off
	v_or_b32_e32 v88, 48, v154
	s_nop 0
	v_pk_add_f32 v[80:81], v[84:85], 1.0 op_sel_hi:[1,0]
	v_pk_add_f32 v[82:83], v[86:87], 1.0 op_sel_hi:[1,0]
	v_mov_b32_e32 v84, v81
	v_mov_b32_e32 v85, v83
	v_mov_b32_e32 v86, v80
	v_mov_b32_e32 v87, v82
	v_pk_mul_f32 v[84:85], v[84:85], v[86:87]
	s_nop 0
	v_mul_f32_e32 v86, v84, v85
	v_rcp_f32_e32 v89, v86
	v_mad_i64_i32 v[86:87], s[16:17], v88, s40, v[144:145]
	v_lshl_add_u64 v[86:87], v[86:87], 0, v[146:147]
	v_mul_f32_e32 v84, v84, v89
	v_mul_f32_e32 v88, v85, v89
	v_pk_mul_f32 v[82:83], v[82:83], v[84:85] op_sel_hi:[1,0]
	v_max_f32_e32 v84, v72, v72
	v_max_f32_e32 v89, v74, v74
	v_max_f32_e32 v84, 0xc1a00000, v84
	v_max_f32_e32 v89, 0xc1a00000, v89
	v_mul_f32_e32 v84, 0xbfb8aa3b, v84
	v_mul_f32_e32 v89, 0xbfb8aa3b, v89
	v_exp_f32_e32 v85, v84
	v_max_f32_e32 v84, v73, v73
	v_exp_f32_e32 v91, v89
	v_max_f32_e32 v89, v75, v75
	v_max_f32_e32 v84, 0xc1a00000, v84
	v_max_f32_e32 v89, 0xc1a00000, v89
	v_mul_f32_e32 v84, 0xbfb8aa3b, v84
	v_mul_f32_e32 v89, 0xbfb8aa3b, v89
	v_exp_f32_e32 v84, v84
	v_exp_f32_e32 v90, v89
	v_pk_mul_f32 v[80:81], v[80:81], v[88:89] op_sel_hi:[1,0]
	v_pk_mul_f32 v[78:79], v[78:79], v[82:83]
	v_pk_mul_f32 v[76:77], v[76:77], v[80:81]
	v_pk_add_f32 v[80:81], v[84:85], 1.0 op_sel_hi:[1,0]
	v_pk_add_f32 v[84:85], v[90:91], 1.0 op_sel_hi:[1,0]
	v_mov_b32_e32 v88, v81
	v_mov_b32_e32 v89, v85
	v_mov_b32_e32 v90, v80
	v_mov_b32_e32 v91, v84
	v_pk_mul_f32 v[88:89], v[88:89], v[90:91]
	v_pk_mul_f32 v[70:71], v[78:79], v[70:71]
	v_mul_f32_e32 v90, v88, v89
	v_rcp_f32_e32 v90, v90
	v_pk_mul_f32 v[68:69], v[76:77], v[68:69]
	v_mul_f32_e32 v76, v89, v90
	v_mul_f32_e32 v78, v88, v90
	v_pk_mul_f32 v[78:79], v[84:85], v[78:79] op_sel_hi:[1,0]
	v_pk_mul_f32 v[76:77], v[80:81], v[76:77] op_sel_hi:[1,0]
	v_pk_mul_f32 v[74:75], v[74:75], v[78:79]
	v_pk_mul_f32 v[72:73], v[72:73], v[76:77]
	v_pk_mul_f32 v[74:75], v[74:75], v[66:67]
	v_pk_mul_f32 v[66:67], v[72:73], v[64:65]
	v_cvt_pk_bf16_f32 v64, v68, v69
	v_cvt_pk_bf16_f32 v65, v70, v71
	v_max_f32_e32 v68, v60, v60
	v_max_f32_e32 v70, v62, v62
	v_max_f32_e32 v68, 0xc1a00000, v68
	v_max_f32_e32 v70, 0xc1a00000, v70
	v_mul_f32_e32 v68, 0xbfb8aa3b, v68
	v_mul_f32_e32 v70, 0xbfb8aa3b, v70
	v_exp_f32_e32 v69, v68
	v_max_f32_e32 v68, v61, v61
	v_exp_f32_e32 v71, v70
	v_max_f32_e32 v70, v63, v63
	v_max_f32_e32 v68, 0xc1a00000, v68
	v_max_f32_e32 v70, 0xc1a00000, v70
	v_mul_f32_e32 v68, 0xbfb8aa3b, v68
	v_mul_f32_e32 v70, 0xbfb8aa3b, v70
	v_exp_f32_e32 v68, v68
	v_exp_f32_e32 v70, v70
	v_cvt_pk_bf16_f32 v66, v66, v67
	v_cvt_pk_bf16_f32 v67, v74, v75
	global_store_dwordx4 v[86:87], v[64:67], off
	v_add_u32_e32 v72, 0x80, v154
	s_nop 0
	v_pk_add_f32 v[64:65], v[68:69], 1.0 op_sel_hi:[1,0]
	v_pk_add_f32 v[66:67], v[70:71], 1.0 op_sel_hi:[1,0]
	v_mov_b32_e32 v68, v65
	v_mov_b32_e32 v69, v67
	v_mov_b32_e32 v70, v64
	v_mov_b32_e32 v71, v66
	v_pk_mul_f32 v[68:69], v[68:69], v[70:71]
	s_nop 0
	v_mul_f32_e32 v70, v68, v69
	v_rcp_f32_e32 v73, v70
	v_mad_i64_i32 v[70:71], s[16:17], v72, s40, v[144:145]
	v_lshl_add_u64 v[70:71], v[70:71], 0, v[146:147]
	v_mul_f32_e32 v68, v68, v73
	v_mul_f32_e32 v72, v69, v73
	v_pk_mul_f32 v[66:67], v[66:67], v[68:69] op_sel_hi:[1,0]
	v_max_f32_e32 v68, v56, v56
	v_max_f32_e32 v73, v58, v58
	v_max_f32_e32 v68, 0xc1a00000, v68
	v_max_f32_e32 v73, 0xc1a00000, v73
	v_mul_f32_e32 v68, 0xbfb8aa3b, v68
	v_mul_f32_e32 v73, 0xbfb8aa3b, v73
	v_exp_f32_e32 v69, v68
	v_max_f32_e32 v68, v57, v57
	v_exp_f32_e32 v75, v73
	v_max_f32_e32 v73, v59, v59
	v_max_f32_e32 v68, 0xc1a00000, v68
	v_max_f32_e32 v73, 0xc1a00000, v73
	v_mul_f32_e32 v68, 0xbfb8aa3b, v68
	v_mul_f32_e32 v73, 0xbfb8aa3b, v73
	v_exp_f32_e32 v68, v68
	v_exp_f32_e32 v74, v73
	v_pk_mul_f32 v[64:65], v[64:65], v[72:73] op_sel_hi:[1,0]
	v_pk_mul_f32 v[62:63], v[62:63], v[66:67]
	v_pk_mul_f32 v[60:61], v[60:61], v[64:65]
	v_pk_add_f32 v[64:65], v[68:69], 1.0 op_sel_hi:[1,0]
	v_pk_add_f32 v[68:69], v[74:75], 1.0 op_sel_hi:[1,0]
	v_mov_b32_e32 v72, v65
	v_mov_b32_e32 v73, v69
	v_mov_b32_e32 v74, v64
	v_mov_b32_e32 v75, v68
	v_pk_mul_f32 v[72:73], v[72:73], v[74:75]
	v_pk_mul_f32 v[54:55], v[62:63], v[54:55]
	v_mul_f32_e32 v74, v72, v73
; __device__ __forceinline__ unsigned cvt_pk_bf16(float lo, float hi) { unsigned r; asm volatile("v_cvt_pk_bf16_f32 %0, %1, %2" : "=v"(r) : "v"(lo), "v"(hi)); return r; }
; __device__ __forceinline__ f32x4 sigmoid4(f32x4 x) {
;     f32x4 d;
; #pragma unroll
;     for (int j = 0; j < 4; ++j) d[j] = 1.0f + __expf(-fmaxf(x[j], -20.0f));
;     const float p01 = d[0] * d[1], p23 = d[2] * d[3], r = __builtin_amdgcn_rcpf(p01 * p23), r01 = r * p23, r23 = r * p01;
;     return (f32x4){r01 * d[1], r01 * d[0], r23 * d[3], r23 * d[2]};
; }
;     __device__ __forceinline__ void operator()(const f32x4 (&acc)[2][2][4][2], const Unit& u, int wr, int wc, int fr, int fq) const {
;     ...
;         for (int ai = 0; ai < 2; ++ai)
; #pragma unroll
;             for (int m = 0; m < 4; ++m) { bf16_t* rowp = O + (size_t)(row0 + ai * HALF + m * 16) * ldc + col0;
;                 f32x4 v0, v1;
; #pragma unroll
;                 for (int j = 0; j < 1; ++j) { v0 = acc[ai][0][m][0] * sigmoid4(acc[ai][0][m][0]) * acc[ai][1][m][0]; v1 = acc[ai][0][m][1] * sigmoid4(acc[ai][0][m][1]) * acc[ai][1][m][1]; }
;                 u32x4 w; w.x = cvt_pk_bf16(v0[0], v0[1]); w.y = cvt_pk_bf16(v0[2], v0[3]); w.z = cvt_pk_bf16(v1[0], v1[1]); w.w = cvt_pk_bf16(v1[2], v1[3]);
;                 *(u32x4*)rowp = w; }
	v_rcp_f32_e32 v74, v74
	v_pk_mul_f32 v[52:53], v[60:61], v[52:53]
	v_mul_f32_e32 v60, v73, v74
	v_mul_f32_e32 v62, v72, v74
	v_pk_mul_f32 v[62:63], v[68:69], v[62:63] op_sel_hi:[1,0]
	v_pk_mul_f32 v[60:61], v[64:65], v[60:61] op_sel_hi:[1,0]
	v_pk_mul_f32 v[58:59], v[58:59], v[62:63]
	v_pk_mul_f32 v[56:57], v[56:57], v[60:61]
	v_pk_mul_f32 v[58:59], v[58:59], v[50:51]
	v_pk_mul_f32 v[50:51], v[56:57], v[48:49]
	v_cvt_pk_bf16_f32 v48, v52, v53
	v_cvt_pk_bf16_f32 v49, v54, v55
	v_max_f32_e32 v52, v44, v44
	v_max_f32_e32 v54, v46, v46
	v_max_f32_e32 v52, 0xc1a00000, v52
	v_max_f32_e32 v54, 0xc1a00000, v54
	v_mul_f32_e32 v52, 0xbfb8aa3b, v52
	v_mul_f32_e32 v54, 0xbfb8aa3b, v54
	v_exp_f32_e32 v53, v52
	v_max_f32_e32 v52, v45, v45
	v_exp_f32_e32 v55, v54
	v_max_f32_e32 v54, v47, v47
	v_max_f32_e32 v52, 0xc1a00000, v52
	v_max_f32_e32 v54, 0xc1a00000, v54
	v_mul_f32_e32 v52, 0xbfb8aa3b, v52
	v_mul_f32_e32 v54, 0xbfb8aa3b, v54
	v_exp_f32_e32 v52, v52
	v_exp_f32_e32 v54, v54
	v_cvt_pk_bf16_f32 v50, v50, v51
	v_cvt_pk_bf16_f32 v51, v58, v59
	global_store_dwordx4 v[70:71], v[48:51], off
	v_add_u32_e32 v56, 0x90, v154
	s_nop 0
	v_pk_add_f32 v[48:49], v[52:53], 1.0 op_sel_hi:[1,0]
	v_pk_add_f32 v[50:51], v[54:55], 1.0 op_sel_hi:[1,0]
	v_mov_b32_e32 v52, v49
	v_mov_b32_e32 v53, v51
	v_mov_b32_e32 v54, v48
	v_mov_b32_e32 v55, v50
	v_pk_mul_f32 v[52:53], v[52:53], v[54:55]
	s_nop 0
	v_mul_f32_e32 v54, v52, v53
	v_rcp_f32_e32 v57, v54
	v_mad_i64_i32 v[54:55], s[16:17], v56, s40, v[144:145]
	v_lshl_add_u64 v[54:55], v[54:55], 0, v[146:147]
	v_mul_f32_e32 v52, v52, v57
	v_mul_f32_e32 v56, v53, v57
	v_pk_mul_f32 v[50:51], v[50:51], v[52:53] op_sel_hi:[1,0]
	v_max_f32_e32 v52, v40, v40
	v_max_f32_e32 v57, v42, v42
	v_max_f32_e32 v52, 0xc1a00000, v52
	v_max_f32_e32 v57, 0xc1a00000, v57
	v_mul_f32_e32 v52, 0xbfb8aa3b, v52
	v_mul_f32_e32 v57, 0xbfb8aa3b, v57
	v_exp_f32_e32 v53, v52
	v_max_f32_e32 v52, v41, v41
	v_exp_f32_e32 v59, v57
	v_max_f32_e32 v57, v43, v43
	v_max_f32_e32 v52, 0xc1a00000, v52
	v_max_f32_e32 v57, 0xc1a00000, v57
	v_mul_f32_e32 v52, 0xbfb8aa3b, v52
	v_mul_f32_e32 v57, 0xbfb8aa3b, v57
	v_exp_f32_e32 v52, v52
	v_exp_f32_e32 v58, v57
	v_pk_mul_f32 v[48:49], v[48:49], v[56:57] op_sel_hi:[1,0]
	v_pk_mul_f32 v[46:47], v[46:47], v[50:51]
	v_pk_mul_f32 v[44:45], v[44:45], v[48:49]
	v_pk_add_f32 v[48:49], v[52:53], 1.0 op_sel_hi:[1,0]
	v_pk_add_f32 v[52:53], v[58:59], 1.0 op_sel_hi:[1,0]
	v_mov_b32_e32 v56, v49
	v_mov_b32_e32 v57, v53
	v_mov_b32_e32 v58, v48
	v_mov_b32_e32 v59, v52
	v_pk_mul_f32 v[56:57], v[56:57], v[58:59]
	v_pk_mul_f32 v[38:39], v[46:47], v[38:39]
	v_mul_f32_e32 v58, v56, v57
	v_rcp_f32_e32 v58, v58
	v_pk_mul_f32 v[36:37], v[44:45], v[36:37]
	v_mul_f32_e32 v44, v57, v58
	v_mul_f32_e32 v46, v56, v58
	v_pk_mul_f32 v[46:47], v[52:53], v[46:47] op_sel_hi:[1,0]
	v_pk_mul_f32 v[44:45], v[48:49], v[44:45] op_sel_hi:[1,0]
	v_pk_mul_f32 v[42:43], v[42:43], v[46:47]
	v_pk_mul_f32 v[40:41], v[40:41], v[44:45]
	v_pk_mul_f32 v[42:43], v[42:43], v[34:35]
	v_pk_mul_f32 v[34:35], v[40:41], v[32:33]
	v_cvt_pk_bf16_f32 v32, v36, v37
	v_cvt_pk_bf16_f32 v33, v38, v39
	v_max_f32_e32 v36, v28, v28
	v_max_f32_e32 v38, v30, v30
	v_max_f32_e32 v36, 0xc1a00000, v36
	v_max_f32_e32 v38, 0xc1a00000, v38
	v_mul_f32_e32 v36, 0xbfb8aa3b, v36
	v_mul_f32_e32 v38, 0xbfb8aa3b, v38
	v_exp_f32_e32 v37, v36
	v_max_f32_e32 v36, v29, v29
	v_exp_f32_e32 v39, v38
	v_max_f32_e32 v38, v31, v31
	v_max_f32_e32 v36, 0xc1a00000, v36
	v_max_f32_e32 v38, 0xc1a00000, v38
	v_mul_f32_e32 v36, 0xbfb8aa3b, v36
	v_mul_f32_e32 v38, 0xbfb8aa3b, v38
	v_exp_f32_e32 v36, v36
	v_exp_f32_e32 v38, v38
	v_cvt_pk_bf16_f32 v34, v34, v35
	v_cvt_pk_bf16_f32 v35, v42, v43
	global_store_dwordx4 v[54:55], v[32:35], off
	v_add_u32_e32 v40, 0xa0, v154
	s_nop 0
	v_pk_add_f32 v[32:33], v[36:37], 1.0 op_sel_hi:[1,0]
	v_pk_add_f32 v[34:35], v[38:39], 1.0 op_sel_hi:[1,0]
	v_mov_b32_e32 v36, v33
	v_mov_b32_e32 v37, v35
	v_mov_b32_e32 v38, v32
	v_mov_b32_e32 v39, v34
	v_pk_mul_f32 v[36:37], v[36:37], v[38:39]
	s_nop 0
	v_mul_f32_e32 v38, v36, v37
	v_rcp_f32_e32 v41, v38
	v_mad_i64_i32 v[38:39], s[16:17], v40, s40, v[144:145]
	v_lshl_add_u64 v[38:39], v[38:39], 0, v[146:147]
	v_mul_f32_e32 v36, v36, v41
	v_mul_f32_e32 v40, v37, v41
	v_pk_mul_f32 v[34:35], v[34:35], v[36:37] op_sel_hi:[1,0]
; __device__ __forceinline__ unsigned cvt_pk_bf16(float lo, float hi) { unsigned r; asm volatile("v_cvt_pk_bf16_f32 %0, %1, %2" : "=v"(r) : "v"(lo), "v"(hi)); return r; }
; __device__ __forceinline__ f32x4 sigmoid4(f32x4 x) {
;     f32x4 d;
; #pragma unroll
;     for (int j = 0; j < 4; ++j) d[j] = 1.0f + __expf(-fmaxf(x[j], -20.0f));
;     const float p01 = d[0] * d[1], p23 = d[2] * d[3], r = __builtin_amdgcn_rcpf(p01 * p23), r01 = r * p23, r23 = r * p01;
;     return (f32x4){r01 * d[1], r01 * d[0], r23 * d[3], r23 * d[2]};
; }
;     __device__ __forceinline__ void operator()(const f32x4 (&acc)[2][2][4][2], const Unit& u, int wr, int wc, int fr, int fq) const {
;     ...
;         for (int ai = 0; ai < 2; ++ai)
; #pragma unroll
;             for (int m = 0; m < 4; ++m) { bf16_t* rowp = O + (size_t)(row0 + ai * HALF + m * 16) * ldc + col0;
;                 f32x4 v0, v1;
; #pragma unroll
;                 for (int j = 0; j < 1; ++j) { v0 = acc[ai][0][m][0] * sigmoid4(acc[ai][0][m][0]) * acc[ai][1][m][0]; v1 = acc[ai][0][m][1] * sigmoid4(acc[ai][0][m][1]) * acc[ai][1][m][1]; }
;                 u32x4 w; w.x = cvt_pk_bf16(v0[0], v0[1]); w.y = cvt_pk_bf16(v0[2], v0[3]); w.z = cvt_pk_bf16(v1[0], v1[1]); w.w = cvt_pk_bf16(v1[2], v1[3]);
;                 *(u32x4*)rowp = w; }
	v_max_f32_e32 v36, v24, v24
	v_max_f32_e32 v41, v26, v26
	v_max_f32_e32 v36, 0xc1a00000, v36
	v_max_f32_e32 v41, 0xc1a00000, v41
	v_mul_f32_e32 v36, 0xbfb8aa3b, v36
	v_mul_f32_e32 v41, 0xbfb8aa3b, v41
	v_exp_f32_e32 v37, v36
	v_max_f32_e32 v36, v25, v25
	v_exp_f32_e32 v43, v41
	v_max_f32_e32 v41, v27, v27
	v_max_f32_e32 v36, 0xc1a00000, v36
	v_max_f32_e32 v41, 0xc1a00000, v41
	v_mul_f32_e32 v36, 0xbfb8aa3b, v36
	v_mul_f32_e32 v41, 0xbfb8aa3b, v41
	v_exp_f32_e32 v36, v36
	v_exp_f32_e32 v42, v41
	v_pk_mul_f32 v[32:33], v[32:33], v[40:41] op_sel_hi:[1,0]
	v_pk_mul_f32 v[30:31], v[30:31], v[34:35]
	v_pk_mul_f32 v[28:29], v[28:29], v[32:33]
	v_pk_add_f32 v[32:33], v[36:37], 1.0 op_sel_hi:[1,0]
	v_pk_add_f32 v[36:37], v[42:43], 1.0 op_sel_hi:[1,0]
	v_mov_b32_e32 v40, v33
	v_mov_b32_e32 v41, v37
	v_mov_b32_e32 v42, v32
	v_mov_b32_e32 v43, v36
	v_pk_mul_f32 v[40:41], v[40:41], v[42:43]
	v_pk_mul_f32 v[22:23], v[30:31], v[22:23]
	v_mul_f32_e32 v42, v40, v41
	v_rcp_f32_e32 v42, v42
	v_pk_mul_f32 v[20:21], v[28:29], v[20:21]
	v_mul_f32_e32 v28, v41, v42
	v_mul_f32_e32 v30, v40, v42
	v_pk_mul_f32 v[30:31], v[36:37], v[30:31] op_sel_hi:[1,0]
	v_pk_mul_f32 v[28:29], v[32:33], v[28:29] op_sel_hi:[1,0]
	v_pk_mul_f32 v[26:27], v[26:27], v[30:31]
	v_pk_mul_f32 v[24:25], v[24:25], v[28:29]
	v_pk_mul_f32 v[26:27], v[26:27], v[18:19]
	v_pk_mul_f32 v[18:19], v[24:25], v[16:17]
	v_cvt_pk_bf16_f32 v16, v20, v21
	v_cvt_pk_bf16_f32 v17, v22, v23
	v_max_f32_e32 v20, v12, v12
	v_max_f32_e32 v22, v14, v14
	v_max_f32_e32 v20, 0xc1a00000, v20
	v_max_f32_e32 v22, 0xc1a00000, v22
	v_mul_f32_e32 v20, 0xbfb8aa3b, v20
	v_mul_f32_e32 v22, 0xbfb8aa3b, v22
	v_exp_f32_e32 v21, v20
	v_max_f32_e32 v20, v13, v13
	v_exp_f32_e32 v23, v22
	v_max_f32_e32 v22, v15, v15
	v_max_f32_e32 v20, 0xc1a00000, v20
	v_max_f32_e32 v22, 0xc1a00000, v22
	v_mul_f32_e32 v20, 0xbfb8aa3b, v20
	v_mul_f32_e32 v22, 0xbfb8aa3b, v22
	v_exp_f32_e32 v20, v20
	v_exp_f32_e32 v22, v22
	v_cvt_pk_bf16_f32 v18, v18, v19
	v_cvt_pk_bf16_f32 v19, v26, v27
	global_store_dwordx4 v[38:39], v[16:19], off
	v_add_u32_e32 v24, 0xb0, v154
	s_nop 0
	v_pk_add_f32 v[16:17], v[20:21], 1.0 op_sel_hi:[1,0]
	v_pk_add_f32 v[18:19], v[22:23], 1.0 op_sel_hi:[1,0]
	v_mov_b32_e32 v20, v17
	v_mov_b32_e32 v21, v19
	v_mov_b32_e32 v22, v16
	v_mov_b32_e32 v23, v18
	v_pk_mul_f32 v[20:21], v[20:21], v[22:23]
	s_nop 0
	v_mul_f32_e32 v22, v20, v21
	v_rcp_f32_e32 v25, v22
	v_mad_i64_i32 v[22:23], s[16:17], v24, s40, v[144:145]
	v_lshl_add_u64 v[22:23], v[22:23], 0, v[146:147]
	v_mul_f32_e32 v20, v20, v25
	v_mul_f32_e32 v24, v21, v25
	v_pk_mul_f32 v[18:19], v[18:19], v[20:21] op_sel_hi:[1,0]
	v_max_f32_e32 v20, v8, v8
	v_max_f32_e32 v25, v10, v10
	v_max_f32_e32 v20, 0xc1a00000, v20
	v_max_f32_e32 v25, 0xc1a00000, v25
	v_mul_f32_e32 v20, 0xbfb8aa3b, v20
	v_mul_f32_e32 v25, 0xbfb8aa3b, v25
	v_exp_f32_e32 v21, v20
	v_max_f32_e32 v20, v9, v9
	v_exp_f32_e32 v27, v25
	v_max_f32_e32 v25, v11, v11
	v_max_f32_e32 v20, 0xc1a00000, v20
	v_max_f32_e32 v25, 0xc1a00000, v25
	v_mul_f32_e32 v20, 0xbfb8aa3b, v20
	v_mul_f32_e32 v25, 0xbfb8aa3b, v25
	v_exp_f32_e32 v20, v20
	v_exp_f32_e32 v26, v25
	v_pk_mul_f32 v[16:17], v[16:17], v[24:25] op_sel_hi:[1,0]
	v_pk_mul_f32 v[14:15], v[14:15], v[18:19]
	v_pk_mul_f32 v[12:13], v[12:13], v[16:17]
	v_pk_add_f32 v[16:17], v[20:21], 1.0 op_sel_hi:[1,0]
	v_pk_add_f32 v[20:21], v[26:27], 1.0 op_sel_hi:[1,0]
	v_mov_b32_e32 v24, v17
	v_mov_b32_e32 v25, v21
	v_mov_b32_e32 v26, v16
	v_mov_b32_e32 v27, v20
	v_pk_mul_f32 v[24:25], v[24:25], v[26:27]
	v_pk_mul_f32 v[6:7], v[14:15], v[6:7]
	v_mul_f32_e32 v26, v24, v25
	v_rcp_f32_e32 v26, v26
	v_pk_mul_f32 v[4:5], v[12:13], v[4:5]
	s_mov_b64 s[16:17], s[10:11]
	v_mul_f32_e32 v12, v25, v26
	v_mul_f32_e32 v14, v24, v26
	v_pk_mul_f32 v[14:15], v[20:21], v[14:15] op_sel_hi:[1,0]
	v_pk_mul_f32 v[12:13], v[16:17], v[12:13] op_sel_hi:[1,0]
	v_pk_mul_f32 v[10:11], v[10:11], v[14:15]
	v_pk_mul_f32 v[8:9], v[8:9], v[12:13]
	v_pk_mul_f32 v[10:11], v[10:11], v[2:3]
	v_pk_mul_f32 v[2:3], v[8:9], v[0:1]
	v_cvt_pk_bf16_f32 v0, v4, v5
	v_cvt_pk_bf16_f32 v1, v6, v7
	s_nop 0
	v_cvt_pk_bf16_f32 v2, v2, v3
	v_cvt_pk_bf16_f32 v3, v10, v11
	global_store_dwordx4 v[22:23], v[0:3], off
	s_cbranch_vccz .LBB0_1199
	s_waitcnt vmcnt(0)
	s_cmpk_gt_u32 s23, 0xff
	s_cbranch_scc1 .LBB0_1206
	s_barrier

; #define PG8_STAGE(bufoff, gbase, voff) do { _Pragma("unroll") for (int _i = 0; _i < 2; ++_i) \
;         __builtin_amdgcn_global_load_lds((const unsigned*)((const char*)(gbase) + (voff)[_i]), (PG8_LAS unsigned*)(lds + (bufoff) + ldsw + _i * 8192), 16, 0, 0); } while (0)
; #define PG8_LDA(dst, b, h) do { _Pragma("unroll") for (int m = 0; m < 4; ++m) _Pragma("unroll") for (int k = 0; k < 2; ++k) dst[m][k] = *(const PG8_LAS bf16x8*)(lds + PG8_SA(b, h) + aoff + m * 2048 + k * 1024); } while (0)
; #define PG8_LDB(dst, b, h) do { _Pragma("unroll") for (int n = 0; n < 2; ++n) _Pragma("unroll") for (int k = 0; k < 2; ++k) dst[n][k] = *(const PG8_LAS bf16x8*)(lds + PG8_SB(b, h) + boff + n * 2048 + k * 1024); } while (0)
; #define PG8_MMA(ai, bj, At, Bt) do { __builtin_amdgcn_s_setprio(1); _Pragma("unroll") for (int m = 0; m < 4; ++m) _Pragma("unroll") for (int n = 0; n < 2; ++n) _Pragma("unroll") for (int k = 0; k < 2; ++k) \
;         acc[ai][bj][m][n] = __builtin_amdgcn_mfma_f32_16x16x32_bf16(Bt[n][k], At[m][k], acc[ai][bj][m][n], 0, 0, 0); __builtin_amdgcn_s_setprio(0); } while (0)
; #define PG8_WAIT_L(n) asm volatile("s_waitcnt lgkmcnt(" #n ")" ::: "memory")
; #define PG8_BAR __builtin_amdgcn_s_barrier()
; #define PG8_SCHED __builtin_amdgcn_sched_barrier(0)
; template <class Epi, class Sched>
; __device__ __forceinline__ void gemm_phase(PG8_LAS unsigned char* lds, const Gemm g, const Sched& S, const Epi& E) {
;     ...
;             const bool last = (t == nt - 2);
;             const char* a1 = cA + (size_t)(t + 1) * kstep;
;             const char* a2 = last ? nA : cA + (size_t)(t + 2) * kstep; const char* b2 = last ? nB : cB + (size_t)(t + 2) * kstep;
;             const char* a3 = a2 + kstep; const char* b3 = b2 + kstep;
;             if (last && has_next) S.a_ready(nxt);
;             PG8_LDB(B0, 0, 0); PG8_SCHED; PG8_LDA(At, 0, 0); PG8_STAGE(PG8_SA(1, 1), a1 + hstep, voffA);
;             PG8_WAIT_L(8); PG8_BAR; PG8_WAIT_L(0); PG8_MMA(0, 0, At, B0); PG8_BAR; PG8_SCHED;
;             PG8_LDB(B1, 0, 1); PG8_STAGE(PG8_SB(0, 0), b2, voffB);
;             PG8_BAR; PG8_WAIT_L(0); PG8_MMA(0, 1, At, B1); PG8_BAR;
;             PG8_LDA(At, 0, 1); PG8_STAGE(PG8_SA(0, 0), a2, voffA);
;             PG8_BAR; PG8_WAIT_L(0); PG8_MMA(1, 0, At, B0); PG8_BAR; PG8_SCHED;
.LBB0_1278:
	ds_read_b128 v[152:155], v149
	ds_read_b128 v[156:159], v149 offset:1024
	ds_read_b128 v[160:163], v149 offset:2048
	ds_read_b128 v[164:167], v149 offset:3072
	s_add_u32 s20, s18, 0x100
	s_addc_u32 s21, s19, 0
	s_cmp_eq_u32 s54, 40
	s_cselect_b32 s25, s1, s21
	s_cselect_b32 s24, s0, s20
	s_cselect_b32 s23, s5, s53
	s_cselect_b32 s22, s4, s52
	v_lshl_add_u64 v[144:145], s[18:19], 0, v[136:137]
	s_add_i32 m0, s34, 0xc000
	ds_read_b128 v[168:171], v150
	ds_read_b128 v[172:175], v150 offset:1024
	ds_read_b128 v[182:185], v150 offset:2048
	ds_read_b128 v[190:193], v150 offset:3072
	ds_read_b128 v[194:197], v150 offset:4096
	ds_read_b128 v[198:201], v150 offset:5120
	ds_read_b128 v[202:205], v150 offset:6144
	ds_read_b128 v[206:209], v150 offset:7168
	global_load_lds_dwordx4 v[144:145], off
	v_lshl_add_u64 v[144:145], s[18:19], 0, v[138:139]
	s_add_i32 m0, s34, 0xe000
	s_nop 0
	global_load_lds_dwordx4 v[144:145], off
	ds_read_b128 v[210:213], v151
	ds_read_b128 v[214:217], v151 offset:1024
	ds_read_b128 v[218:221], v151 offset:2048
	ds_read_b128 v[222:225], v151 offset:3072
	s_waitcnt vmcnt(8) lgkmcnt(0)
	s_barrier
	v_mfma_f32_16x16x32_bf16 v[124:127], v[152:155], v[168:171], v[124:127]
	v_mfma_f32_16x16x32_bf16 v[120:123], v[160:163], v[168:171], v[120:123]
	v_mfma_f32_16x16x32_bf16 v[108:111], v[152:155], v[182:185], v[108:111]
	v_mfma_f32_16x16x32_bf16 v[104:107], v[160:163], v[182:185], v[104:107]
	v_mfma_f32_16x16x32_bf16 v[92:95], v[152:155], v[194:197], v[92:95]
	v_mfma_f32_16x16x32_bf16 v[88:91], v[160:163], v[194:197], v[88:91]
	v_mfma_f32_16x16x32_bf16 v[76:79], v[152:155], v[202:205], v[76:79]
	v_mfma_f32_16x16x32_bf16 v[72:75], v[160:163], v[202:205], v[72:75]
	v_mfma_f32_16x16x32_bf16 v[124:127], v[156:159], v[172:175], v[124:127]
	v_mfma_f32_16x16x32_bf16 v[120:123], v[164:167], v[172:175], v[120:123]
	v_mfma_f32_16x16x32_bf16 v[108:111], v[156:159], v[190:193], v[108:111]
	v_mfma_f32_16x16x32_bf16 v[104:107], v[164:167], v[190:193], v[104:107]
	v_mfma_f32_16x16x32_bf16 v[92:95], v[156:159], v[198:201], v[92:95]
	v_mfma_f32_16x16x32_bf16 v[88:91], v[164:167], v[198:201], v[88:91]
	v_mfma_f32_16x16x32_bf16 v[76:79], v[156:159], v[206:209], v[76:79]
	v_mfma_f32_16x16x32_bf16 v[72:75], v[164:167], v[206:209], v[72:75]
	v_mfma_f32_16x16x32_bf16 v[116:119], v[210:213], v[168:171], v[116:119]
	v_mfma_f32_16x16x32_bf16 v[112:115], v[218:221], v[168:171], v[112:115]
	v_mfma_f32_16x16x32_bf16 v[100:103], v[210:213], v[182:185], v[100:103]
	v_mfma_f32_16x16x32_bf16 v[96:99], v[218:221], v[182:185], v[96:99]
	v_mfma_f32_16x16x32_bf16 v[84:87], v[210:213], v[194:197], v[84:87]
	v_mfma_f32_16x16x32_bf16 v[80:83], v[218:221], v[194:197], v[80:83]
	v_mfma_f32_16x16x32_bf16 v[68:71], v[210:213], v[202:205], v[68:71]
	v_mfma_f32_16x16x32_bf16 v[64:67], v[218:221], v[202:205], v[64:67]
	v_mfma_f32_16x16x32_bf16 v[116:119], v[214:217], v[172:175], v[116:119]
	v_mfma_f32_16x16x32_bf16 v[112:115], v[222:225], v[172:175], v[112:115]
	v_mfma_f32_16x16x32_bf16 v[100:103], v[214:217], v[190:193], v[100:103]
	v_mfma_f32_16x16x32_bf16 v[96:99], v[222:225], v[190:193], v[96:99]
	v_mfma_f32_16x16x32_bf16 v[84:87], v[214:217], v[198:201], v[84:87]
	v_mfma_f32_16x16x32_bf16 v[80:83], v[222:225], v[198:201], v[80:83]
	v_mfma_f32_16x16x32_bf16 v[68:71], v[214:217], v[206:209], v[68:71]
	v_mfma_f32_16x16x32_bf16 v[64:67], v[222:225], v[206:209], v[64:67]
	s_barrier
	ds_read_b128 v[168:171], v150 offset:16384
	ds_read_b128 v[172:175], v150 offset:17408
	ds_read_b128 v[182:185], v150 offset:18432
	ds_read_b128 v[190:193], v150 offset:19456
	ds_read_b128 v[194:197], v150 offset:20480
	ds_read_b128 v[198:201], v150 offset:21504
	ds_read_b128 v[202:205], v150 offset:22528
	ds_read_b128 v[206:209], v150 offset:23552
	s_add_i32 s18, s42, s31
	v_lshl_add_u64 v[144:145], s[22:23], 0, v[130:131]
	s_mov_b32 m0, s18
	s_nop 0
	global_load_lds_dwordx4 v[144:145], off
	v_lshl_add_u64 v[186:187], s[22:23], 0, v[134:135]
	s_add_i32 m0, s18, 0x2000
	s_nop 0
	global_load_lds_dwordx4 v[186:187], off
	s_mov_b32 m0, s34
	v_lshl_add_u64 v[226:227], s[24:25], 0, v[128:129]
	global_load_lds_dwordx4 v[226:227], off
	v_lshl_add_u64 v[228:229], s[24:25], 0, v[132:133]
	s_mov_b32 m0, s35
	s_nop 0
	global_load_lds_dwordx4 v[228:229], off
	s_add_u32 s18, s22, 0xb0000
	s_addc_u32 s19, s23, 0
	s_add_i32 s55, s43, s31
	v_lshl_add_u64 v[246:247], s[18:19], 0, v[130:131]
	s_mov_b32 m0, s55
	s_nop 0
	global_load_lds_dwordx4 v[246:247], off
	v_lshl_add_u64 v[246:247], s[18:19], 0, v[134:135]
	s_add_i32 m0, s55, 0x2000
	s_nop 0
	global_load_lds_dwordx4 v[246:247], off
	s_waitcnt vmcnt(8) lgkmcnt(0)
	s_barrier
; #define PG8_STAGE(bufoff, gbase, voff) do { _Pragma("unroll") for (int _i = 0; _i < 2; ++_i) \
;         __builtin_amdgcn_global_load_lds((const unsigned*)((const char*)(gbase) + (voff)[_i]), (PG8_LAS unsigned*)(lds + (bufoff) + ldsw + _i * 8192), 16, 0, 0); } while (0)
; #define PG8_LDA(dst, b, h) do { _Pragma("unroll") for (int m = 0; m < 4; ++m) _Pragma("unroll") for (int k = 0; k < 2; ++k) dst[m][k] = *(const PG8_LAS bf16x8*)(lds + PG8_SA(b, h) + aoff + m * 2048 + k * 1024); } while (0)
; #define PG8_LDB(dst, b, h) do { _Pragma("unroll") for (int n = 0; n < 2; ++n) _Pragma("unroll") for (int k = 0; k < 2; ++k) dst[n][k] = *(const PG8_LAS bf16x8*)(lds + PG8_SB(b, h) + boff + n * 2048 + k * 1024); } while (0)
; #define PG8_MMA(ai, bj, At, Bt) do { __builtin_amdgcn_s_setprio(1); _Pragma("unroll") for (int m = 0; m < 4; ++m) _Pragma("unroll") for (int n = 0; n < 2; ++n) _Pragma("unroll") for (int k = 0; k < 2; ++k) \
;         acc[ai][bj][m][n] = __builtin_amdgcn_mfma_f32_16x16x32_bf16(Bt[n][k], At[m][k], acc[ai][bj][m][n], 0, 0, 0); __builtin_amdgcn_s_setprio(0); } while (0)
; #define PG8_WAIT_V(n) asm volatile("s_waitcnt vmcnt(" #n ")" ::: "memory")
; #define PG8_WAIT_L(n) asm volatile("s_waitcnt lgkmcnt(" #n ")" ::: "memory")
; #define PG8_BAR __builtin_amdgcn_s_barrier()
; #define PG8_SCHED __builtin_amdgcn_sched_barrier(0)
; template <class Epi, class Sched>
; __device__ __forceinline__ void gemm_phase(PG8_LAS unsigned char* lds, const Gemm g, const Sched& S, const Epi& E) {
;     ...
;             PG8_BAR; PG8_WAIT_L(0); PG8_MMA(1, 0, At, B0); PG8_BAR; PG8_SCHED;
;             PG8_STAGE(PG8_SB(0, 1), b2 + hstep, voffB);
;             PG8_WAIT_V(6); PG8_BAR; PG8_MMA(1, 1, At, B1); PG8_BAR;
;             PG8_LDB(B0, 1, 0); PG8_SCHED; PG8_LDA(At, 1, 0); PG8_STAGE(PG8_SA(0, 1), a2 + hstep, voffA);
;             PG8_WAIT_L(8); PG8_BAR; PG8_WAIT_L(0); PG8_MMA(0, 0, At, B0); PG8_BAR; PG8_SCHED;
;             PG8_LDB(B1, 1, 1); PG8_STAGE(PG8_SB(1, 0), b3, voffB);
;             PG8_BAR; PG8_WAIT_L(0); PG8_MMA(0, 1, At, B1); PG8_BAR;
;             PG8_LDA(At, 1, 1); PG8_STAGE(PG8_SA(1, 0), a3, voffA);
;             PG8_BAR; PG8_WAIT_L(0); PG8_MMA(1, 0, At, B0); PG8_BAR; PG8_SCHED;
	v_mfma_f32_16x16x32_bf16 v[60:63], v[152:155], v[168:171], v[60:63]
	v_mfma_f32_16x16x32_bf16 v[56:59], v[160:163], v[168:171], v[56:59]
	v_mfma_f32_16x16x32_bf16 v[48:51], v[152:155], v[182:185], v[48:51]
	v_mfma_f32_16x16x32_bf16 v[40:43], v[160:163], v[182:185], v[40:43]
	v_mfma_f32_16x16x32_bf16 v[32:35], v[152:155], v[194:197], v[32:35]
	v_mfma_f32_16x16x32_bf16 v[24:27], v[160:163], v[194:197], v[24:27]
	v_mfma_f32_16x16x32_bf16 v[16:19], v[152:155], v[202:205], v[16:19]
	v_mfma_f32_16x16x32_bf16 v[8:11], v[160:163], v[202:205], v[8:11]
	v_mfma_f32_16x16x32_bf16 v[60:63], v[156:159], v[172:175], v[60:63]
	v_mfma_f32_16x16x32_bf16 v[56:59], v[164:167], v[172:175], v[56:59]
	v_mfma_f32_16x16x32_bf16 v[48:51], v[156:159], v[190:193], v[48:51]
	v_mfma_f32_16x16x32_bf16 v[40:43], v[164:167], v[190:193], v[40:43]
	v_mfma_f32_16x16x32_bf16 v[32:35], v[156:159], v[198:201], v[32:35]
	v_mfma_f32_16x16x32_bf16 v[24:27], v[164:167], v[198:201], v[24:27]
	v_mfma_f32_16x16x32_bf16 v[16:19], v[156:159], v[206:209], v[16:19]
	v_mfma_f32_16x16x32_bf16 v[8:11], v[164:167], v[206:209], v[8:11]
	v_mfma_f32_16x16x32_bf16 v[52:55], v[210:213], v[168:171], v[52:55]
	v_mfma_f32_16x16x32_bf16 v[44:47], v[218:221], v[168:171], v[44:47]
	v_mfma_f32_16x16x32_bf16 v[36:39], v[210:213], v[182:185], v[36:39]
	v_mfma_f32_16x16x32_bf16 v[28:31], v[218:221], v[182:185], v[28:31]
	v_mfma_f32_16x16x32_bf16 v[20:23], v[210:213], v[194:197], v[20:23]
	v_mfma_f32_16x16x32_bf16 v[12:15], v[218:221], v[194:197], v[12:15]
	v_mfma_f32_16x16x32_bf16 v[4:7], v[210:213], v[202:205], v[4:7]
	v_mfma_f32_16x16x32_bf16 v[0:3], v[218:221], v[202:205], v[0:3]
	v_mfma_f32_16x16x32_bf16 v[52:55], v[214:217], v[172:175], v[52:55]
	v_mfma_f32_16x16x32_bf16 v[44:47], v[222:225], v[172:175], v[44:47]
	v_mfma_f32_16x16x32_bf16 v[36:39], v[214:217], v[190:193], v[36:39]
	v_mfma_f32_16x16x32_bf16 v[28:31], v[222:225], v[190:193], v[28:31]
	v_mfma_f32_16x16x32_bf16 v[20:23], v[214:217], v[198:201], v[20:23]
	v_mfma_f32_16x16x32_bf16 v[12:15], v[222:225], v[198:201], v[12:15]
	v_mfma_f32_16x16x32_bf16 v[4:7], v[214:217], v[206:209], v[4:7]
	v_mfma_f32_16x16x32_bf16 v[0:3], v[222:225], v[206:209], v[0:3]
	s_barrier
	s_add_i32 s55, 0, 0x18000
	v_add_u32_e32 v164, s55, v147
	ds_read_b128 v[152:155], v164
	ds_read_b128 v[156:159], v164 offset:1024
	ds_read_b128 v[160:163], v164 offset:2048
	ds_read_b128 v[164:167], v164 offset:3072
	s_add_u32 s18, s24, 0xb0000
	s_addc_u32 s19, s25, 0
	s_mov_b32 m0, s36
	v_lshl_add_u64 v[210:211], s[18:19], 0, v[128:129]
	ds_read_b128 v[168:171], v150 offset:32768
	ds_read_b128 v[172:175], v150 offset:33792
	ds_read_b128 v[182:185], v150 offset:34816
	ds_read_b128 v[190:193], v150 offset:35840
	ds_read_b128 v[194:197], v150 offset:36864
	ds_read_b128 v[198:201], v150 offset:37888
	ds_read_b128 v[202:205], v150 offset:38912
	ds_read_b128 v[206:209], v150 offset:39936
	global_load_lds_dwordx4 v[210:211], off
	v_lshl_add_u64 v[210:211], s[18:19], 0, v[132:133]
	s_mov_b32 m0, s37
	s_nop 0
	global_load_lds_dwordx4 v[210:211], off
	s_add_i32 s24, 0, 0x1c000
	v_add_u32_e32 v179, s24, v147
	ds_read_b128 v[210:213], v179
	ds_read_b128 v[214:217], v179 offset:1024
	ds_read_b128 v[218:221], v179 offset:2048
	ds_read_b128 v[222:225], v179 offset:3072
	s_waitcnt vmcnt(8) lgkmcnt(0)
	s_barrier
	v_mfma_f32_16x16x32_bf16 v[124:127], v[152:155], v[168:171], v[124:127]
	v_mfma_f32_16x16x32_bf16 v[120:123], v[160:163], v[168:171], v[120:123]
	v_mfma_f32_16x16x32_bf16 v[108:111], v[152:155], v[182:185], v[108:111]
	v_mfma_f32_16x16x32_bf16 v[104:107], v[160:163], v[182:185], v[104:107]
	v_mfma_f32_16x16x32_bf16 v[92:95], v[152:155], v[194:197], v[92:95]
	v_mfma_f32_16x16x32_bf16 v[88:91], v[160:163], v[194:197], v[88:91]
	v_mfma_f32_16x16x32_bf16 v[76:79], v[152:155], v[202:205], v[76:79]
	v_mfma_f32_16x16x32_bf16 v[72:75], v[160:163], v[202:205], v[72:75]
	v_mfma_f32_16x16x32_bf16 v[124:127], v[156:159], v[172:175], v[124:127]
	v_mfma_f32_16x16x32_bf16 v[120:123], v[164:167], v[172:175], v[120:123]
	v_mfma_f32_16x16x32_bf16 v[108:111], v[156:159], v[190:193], v[108:111]
	v_mfma_f32_16x16x32_bf16 v[104:107], v[164:167], v[190:193], v[104:107]
	v_mfma_f32_16x16x32_bf16 v[92:95], v[156:159], v[198:201], v[92:95]
	v_mfma_f32_16x16x32_bf16 v[88:91], v[164:167], v[198:201], v[88:91]
	v_mfma_f32_16x16x32_bf16 v[76:79], v[156:159], v[206:209], v[76:79]
	v_mfma_f32_16x16x32_bf16 v[72:75], v[164:167], v[206:209], v[72:75]
	v_mfma_f32_16x16x32_bf16 v[116:119], v[210:213], v[168:171], v[116:119]
	v_mfma_f32_16x16x32_bf16 v[112:115], v[218:221], v[168:171], v[112:115]
	v_mfma_f32_16x16x32_bf16 v[100:103], v[210:213], v[182:185], v[100:103]
	v_mfma_f32_16x16x32_bf16 v[96:99], v[218:221], v[182:185], v[96:99]
	v_mfma_f32_16x16x32_bf16 v[84:87], v[210:213], v[194:197], v[84:87]
	v_mfma_f32_16x16x32_bf16 v[80:83], v[218:221], v[194:197], v[80:83]
	v_mfma_f32_16x16x32_bf16 v[68:71], v[210:213], v[202:205], v[68:71]
	v_mfma_f32_16x16x32_bf16 v[64:67], v[218:221], v[202:205], v[64:67]
	v_mfma_f32_16x16x32_bf16 v[116:119], v[214:217], v[172:175], v[116:119]
	v_mfma_f32_16x16x32_bf16 v[112:115], v[222:225], v[172:175], v[112:115]
	v_mfma_f32_16x16x32_bf16 v[100:103], v[214:217], v[190:193], v[100:103]
	v_mfma_f32_16x16x32_bf16 v[96:99], v[222:225], v[190:193], v[96:99]
	v_mfma_f32_16x16x32_bf16 v[84:87], v[214:217], v[198:201], v[84:87]
	v_mfma_f32_16x16x32_bf16 v[80:83], v[222:225], v[198:201], v[80:83]
	v_mfma_f32_16x16x32_bf16 v[68:71], v[214:217], v[206:209], v[68:71]
	v_mfma_f32_16x16x32_bf16 v[64:67], v[222:225], v[206:209], v[64:67]
	s_barrier
; __device__ __forceinline__ unsigned cvt_pk_bf16(float lo, float hi) { unsigned r; asm volatile("v_cvt_pk_bf16_f32 %0, %1, %2" : "=v"(r) : "v"(lo), "v"(hi)); return r; }
; __device__ __forceinline__ float flogsig16(float x) { return (fminf(x, 0.f) - __logf(1.0f + __expf(-fabsf(x)))) * 0.0625f; }
; #define PG8_STAGE(bufoff, gbase, voff) do { _Pragma("unroll") for (int _i = 0; _i < 2; ++_i) \
;         __builtin_amdgcn_global_load_lds((const unsigned*)((const char*)(gbase) + (voff)[_i]), (PG8_LAS unsigned*)(lds + (bufoff) + ldsw + _i * 8192), 16, 0, 0); } while (0)
; #define PG8_LDA(dst, b, h) do { _Pragma("unroll") for (int m = 0; m < 4; ++m) _Pragma("unroll") for (int k = 0; k < 2; ++k) dst[m][k] = *(const PG8_LAS bf16x8*)(lds + PG8_SA(b, h) + aoff + m * 2048 + k * 1024); } while (0)
; #define PG8_BAR __builtin_amdgcn_s_barrier()
;     __device__ __forceinline__ void operator()(const f32x4 (&acc)[2][2][4][2], const Unit& u, int wr, int wc, int fr, int fq) const {
;     ...
;             for (int m = 0; m < 4; ++m) { bf16_t* rowp = O + (size_t)(row0 + ai * HALF + m * 16) * ldc + col0;
; #pragma unroll
;                 for (int bj = 0; bj < 2; ++bj) { f32x4 v0 = acc[ai][bj][m][0] + bv[bj][0], v1 = acc[ai][bj][m][1] + bv[bj][1];
;                     if (act == 1) {
; #pragma unroll
;                         for (int j = 0; j < 1; ++j) { v0 = v0 * sigmoid4(v0); v1 = v1 * sigmoid4(v1); } }
;                     else if (act == 2) {
; #pragma unroll
;                         for (int j = 0; j < 1; ++j) { v0 = sigmoid4(v0); v1 = sigmoid4(v1); } }
;                     else if (act == 3) {
; #pragma unroll
;                         for (int j = 0; j < 4; ++j) { v0[j] = flogsig16(v0[j]); v1[j] = flogsig16(v1[j]); } }
;                     u32x4 w; w.x = cvt_pk_bf16(v0[0], v0[1]); w.y = cvt_pk_bf16(v0[2], v0[3]); w.z = cvt_pk_bf16(v1[0], v1[1]); w.w = cvt_pk_bf16(v1[2], v1[3]);
;                     *(u32x4*)(rowp + bj * HALF) = w; } }
; template <class Epi, class Sched>
; __device__ __forceinline__ void gemm_phase(PG8_LAS unsigned char* lds, const Gemm g, const Sched& S, const Epi& E) {
;     ...
;             PG8_LDA(At, 1, 1); PG8_STAGE(PG8_SA(1, 0), a3, voffA);
;             PG8_BAR; PG8_WAIT_L(0); PG8_MMA(1, 0, At, B0); PG8_BAR; PG8_SCHED;
;             PG8_STAGE(PG8_SB(1, 1), b3 + hstep, voffB);
;             PG8_WAIT_V(6); PG8_BAR; PG8_MMA(1, 1, At, B1); PG8_BAR;
;         }
	ds_read_b128 v[168:171], v150 offset:49152
	ds_read_b128 v[172:175], v150 offset:50176
	ds_read_b128 v[182:185], v150 offset:51200
	ds_read_b128 v[190:193], v150 offset:52224
	ds_read_b128 v[194:197], v150 offset:53248
	ds_read_b128 v[198:201], v150 offset:54272
	ds_read_b128 v[202:205], v150 offset:55296
	ds_read_b128 v[206:209], v150 offset:56320
	s_add_i32 s18, s55, s31
	v_lshl_add_u64 v[144:145], v[144:145], 0, s[8:9]
	s_mov_b32 m0, s18
	s_nop 0
	global_load_lds_dwordx4 v[144:145], off
	v_lshl_add_u64 v[144:145], v[186:187], 0, s[8:9]
	s_add_i32 m0, s18, 0x2000
	s_nop 0
	global_load_lds_dwordx4 v[144:145], off
	s_mov_b32 m0, s39
	v_lshl_add_u64 v[144:145], v[226:227], 0, s[8:9]
	global_load_lds_dwordx4 v[144:145], off
	v_lshl_add_u64 v[144:145], v[228:229], 0, s[8:9]
	s_mov_b32 m0, s40
	s_nop 0
	global_load_lds_dwordx4 v[144:145], off
	s_add_u32 s18, s22, 0xb0080
	s_addc_u32 s19, s23, 0
	s_add_i32 s22, s24, s31
	v_lshl_add_u64 v[144:145], s[18:19], 0, v[130:131]
	s_mov_b32 m0, s22
	s_nop 0
	global_load_lds_dwordx4 v[144:145], off
	v_lshl_add_u64 v[144:145], s[18:19], 0, v[134:135]
	s_add_i32 m0, s22, 0x2000
	s_nop 0
	global_load_lds_dwordx4 v[144:145], off
	s_waitcnt vmcnt(8) lgkmcnt(0)
	s_barrier
	v_mfma_f32_16x16x32_bf16 v[60:63], v[152:155], v[168:171], v[60:63]
	v_mfma_f32_16x16x32_bf16 v[56:59], v[160:163], v[168:171], v[56:59]
	v_mfma_f32_16x16x32_bf16 v[48:51], v[152:155], v[182:185], v[48:51]
	v_mfma_f32_16x16x32_bf16 v[40:43], v[160:163], v[182:185], v[40:43]
	v_mfma_f32_16x16x32_bf16 v[32:35], v[152:155], v[194:197], v[32:35]
	v_mfma_f32_16x16x32_bf16 v[24:27], v[160:163], v[194:197], v[24:27]
	v_mfma_f32_16x16x32_bf16 v[16:19], v[152:155], v[202:205], v[16:19]
	v_mfma_f32_16x16x32_bf16 v[8:11], v[160:163], v[202:205], v[8:11]
	v_mfma_f32_16x16x32_bf16 v[60:63], v[156:159], v[172:175], v[60:63]
	v_mfma_f32_16x16x32_bf16 v[56:59], v[164:167], v[172:175], v[56:59]
	v_mfma_f32_16x16x32_bf16 v[48:51], v[156:159], v[190:193], v[48:51]
	v_mfma_f32_16x16x32_bf16 v[40:43], v[164:167], v[190:193], v[40:43]
	v_mfma_f32_16x16x32_bf16 v[32:35], v[156:159], v[198:201], v[32:35]
	v_mfma_f32_16x16x32_bf16 v[24:27], v[164:167], v[198:201], v[24:27]
	v_mfma_f32_16x16x32_bf16 v[16:19], v[156:159], v[206:209], v[16:19]
	v_mfma_f32_16x16x32_bf16 v[8:11], v[164:167], v[206:209], v[8:11]
	v_mfma_f32_16x16x32_bf16 v[52:55], v[210:213], v[168:171], v[52:55]
	v_mfma_f32_16x16x32_bf16 v[44:47], v[218:221], v[168:171], v[44:47]
	v_mfma_f32_16x16x32_bf16 v[36:39], v[210:213], v[182:185], v[36:39]
	v_mfma_f32_16x16x32_bf16 v[28:31], v[218:221], v[182:185], v[28:31]
	v_mfma_f32_16x16x32_bf16 v[20:23], v[210:213], v[194:197], v[20:23]
	v_mfma_f32_16x16x32_bf16 v[12:15], v[218:221], v[194:197], v[12:15]
	v_mfma_f32_16x16x32_bf16 v[4:7], v[210:213], v[202:205], v[4:7]
	v_mfma_f32_16x16x32_bf16 v[0:3], v[218:221], v[202:205], v[0:3]
	v_mfma_f32_16x16x32_bf16 v[52:55], v[214:217], v[172:175], v[52:55]
	v_mfma_f32_16x16x32_bf16 v[44:47], v[222:225], v[172:175], v[44:47]
	v_mfma_f32_16x16x32_bf16 v[36:39], v[214:217], v[190:193], v[36:39]
	v_mfma_f32_16x16x32_bf16 v[28:31], v[222:225], v[190:193], v[28:31]
	v_mfma_f32_16x16x32_bf16 v[20:23], v[214:217], v[198:201], v[20:23]
	v_mfma_f32_16x16x32_bf16 v[12:15], v[222:225], v[198:201], v[12:15]
	v_mfma_f32_16x16x32_bf16 v[4:7], v[214:217], v[206:209], v[4:7]
	v_mfma_f32_16x16x32_bf16 v[0:3], v[222:225], v[206:209], v[0:3]
	s_barrier
	s_add_i32 s54, s54, 2
	s_add_u32 s52, s52, 0x100
	s_addc_u32 s53, s53, 0
	s_cmp_gt_u32 s54, 41
	s_mov_b64 s[18:19], s[20:21]
	s_cbranch_scc0 .LBB0_1278
	v_lshl_add_u32 v152, s50, 8, v146
	v_lshl_or_b32 v144, s51, 8, v148
	v_ashrrev_i32_e32 v153, 31, v152
	v_ashrrev_i32_e32 v145, 31, v144
	v_lshlrev_b64 v[154:155], 11, v[152:153]
	v_lshl_add_u64 v[154:155], s[6:7], 0, v[154:155]
	v_lshlrev_b64 v[156:157], 1, v[144:145]
	v_lshl_add_u64 v[144:145], v[154:155], 0, v[156:157]
	v_pk_add_f32 v[126:127], v[126:127], 0 op_sel_hi:[1,0]
	v_pk_add_f32 v[124:125], v[124:125], 0 op_sel_hi:[1,0]
	v_pk_add_f32 v[154:155], v[122:123], 0 op_sel_hi:[1,0]
	v_pk_add_f32 v[122:123], v[120:121], 0 op_sel_hi:[1,0]
	v_cvt_pk_bf16_f32 v120, v124, v125
	v_cvt_pk_bf16_f32 v121, v126, v127
	v_pk_add_f32 v[116:117], v[116:117], 0 op_sel_hi:[1,0]
	v_cvt_pk_bf16_f32 v122, v122, v123
	v_cvt_pk_bf16_f32 v123, v154, v155
	global_store_dwordx4 v[144:145], v[120:123], off
	v_pk_add_f32 v[118:119], v[118:119], 0 op_sel_hi:[1,0]
	v_pk_add_f32 v[110:111], v[110:111], 0 op_sel_hi:[1,0]
	v_pk_add_f32 v[120:121], v[114:115], 0 op_sel_hi:[1,0]
	v_pk_add_f32 v[114:115], v[112:113], 0 op_sel_hi:[1,0]
	v_cvt_pk_bf16_f32 v112, v116, v117
	v_cvt_pk_bf16_f32 v113, v118, v119
	v_pk_add_f32 v[108:109], v[108:109], 0 op_sel_hi:[1,0]
	v_cvt_pk_bf16_f32 v114, v114, v115
	v_cvt_pk_bf16_f32 v115, v120, v121
	global_store_dwordx4 v[144:145], v[112:115], off offset:256
	v_pk_add_f32 v[100:101], v[100:101], 0 op_sel_hi:[1,0]
	v_pk_add_f32 v[102:103], v[102:103], 0 op_sel_hi:[1,0]
	v_or_b32_e32 v112, 16, v152
	v_ashrrev_i32_e32 v113, 31, v112
	v_lshlrev_b64 v[112:113], 11, v[112:113]
	v_lshl_add_u64 v[112:113], s[6:7], 0, v[112:113]
	v_lshl_add_u64 v[112:113], v[112:113], 0, v[156:157]
	v_pk_add_f32 v[114:115], v[106:107], 0 op_sel_hi:[1,0]
	v_pk_add_f32 v[106:107], v[104:105], 0 op_sel_hi:[1,0]
	v_cvt_pk_bf16_f32 v104, v108, v109
	v_cvt_pk_bf16_f32 v105, v110, v111
	v_pk_add_f32 v[94:95], v[94:95], 0 op_sel_hi:[1,0]
	v_cvt_pk_bf16_f32 v106, v106, v107
	v_cvt_pk_bf16_f32 v107, v114, v115
	global_store_dwordx4 v[112:113], v[104:107], off
	v_pk_add_f32 v[92:93], v[92:93], 0 op_sel_hi:[1,0]
	v_pk_add_f32 v[84:85], v[84:85], 0 op_sel_hi:[1,0]
; __device__ __forceinline__ unsigned cvt_pk_bf16(float lo, float hi) { unsigned r; asm volatile("v_cvt_pk_bf16_f32 %0, %1, %2" : "=v"(r) : "v"(lo), "v"(hi)); return r; }
; __device__ __forceinline__ float flogsig16(float x) { return (fminf(x, 0.f) - __logf(1.0f + __expf(-fabsf(x)))) * 0.0625f; }
;     __device__ __forceinline__ void operator()(const f32x4 (&acc)[2][2][4][2], const Unit& u, int wr, int wc, int fr, int fq) const {
;     ...
;             for (int m = 0; m < 4; ++m) { bf16_t* rowp = O + (size_t)(row0 + ai * HALF + m * 16) * ldc + col0;
; #pragma unroll
;                 for (int bj = 0; bj < 2; ++bj) { f32x4 v0 = acc[ai][bj][m][0] + bv[bj][0], v1 = acc[ai][bj][m][1] + bv[bj][1];
;                     if (act == 1) {
; #pragma unroll
;                         for (int j = 0; j < 1; ++j) { v0 = v0 * sigmoid4(v0); v1 = v1 * sigmoid4(v1); } }
;                     else if (act == 2) {
; #pragma unroll
;                         for (int j = 0; j < 1; ++j) { v0 = sigmoid4(v0); v1 = sigmoid4(v1); } }
;                     else if (act == 3) {
; #pragma unroll
;                         for (int j = 0; j < 4; ++j) { v0[j] = flogsig16(v0[j]); v1[j] = flogsig16(v1[j]); } }
;                     u32x4 w; w.x = cvt_pk_bf16(v0[0], v0[1]); w.y = cvt_pk_bf16(v0[2], v0[3]); w.z = cvt_pk_bf16(v1[0], v1[1]); w.w = cvt_pk_bf16(v1[2], v1[3]);
;                     *(u32x4*)(rowp + bj * HALF) = w; } }
	v_pk_add_f32 v[104:105], v[98:99], 0 op_sel_hi:[1,0]
	v_pk_add_f32 v[98:99], v[96:97], 0 op_sel_hi:[1,0]
	v_cvt_pk_bf16_f32 v96, v100, v101
	v_cvt_pk_bf16_f32 v97, v102, v103
	v_pk_add_f32 v[86:87], v[86:87], 0 op_sel_hi:[1,0]
	v_cvt_pk_bf16_f32 v98, v98, v99
	v_cvt_pk_bf16_f32 v99, v104, v105
	global_store_dwordx4 v[112:113], v[96:99], off offset:256
	v_pk_add_f32 v[78:79], v[78:79], 0 op_sel_hi:[1,0]
	v_pk_add_f32 v[76:77], v[76:77], 0 op_sel_hi:[1,0]
	v_or_b32_e32 v96, 32, v152
	v_ashrrev_i32_e32 v97, 31, v96
	v_lshlrev_b64 v[96:97], 11, v[96:97]
	v_lshl_add_u64 v[96:97], s[6:7], 0, v[96:97]
	v_lshl_add_u64 v[96:97], v[96:97], 0, v[156:157]
	v_pk_add_f32 v[98:99], v[90:91], 0 op_sel_hi:[1,0]
	v_pk_add_f32 v[90:91], v[88:89], 0 op_sel_hi:[1,0]
	v_cvt_pk_bf16_f32 v88, v92, v93
	v_cvt_pk_bf16_f32 v89, v94, v95
	v_pk_add_f32 v[70:71], v[70:71], 0 op_sel_hi:[1,0]
	v_cvt_pk_bf16_f32 v90, v90, v91
	v_cvt_pk_bf16_f32 v91, v98, v99
	global_store_dwordx4 v[96:97], v[88:91], off
	v_pk_add_f32 v[68:69], v[68:69], 0 op_sel_hi:[1,0]
	v_pk_add_f32 v[60:61], v[60:61], 0 op_sel_hi:[1,0]
	v_pk_add_f32 v[88:89], v[82:83], 0 op_sel_hi:[1,0]
	v_pk_add_f32 v[82:83], v[80:81], 0 op_sel_hi:[1,0]
	v_cvt_pk_bf16_f32 v80, v84, v85
	v_cvt_pk_bf16_f32 v81, v86, v87
	v_pk_add_f32 v[62:63], v[62:63], 0 op_sel_hi:[1,0]
	v_cvt_pk_bf16_f32 v82, v82, v83
	v_cvt_pk_bf16_f32 v83, v88, v89
	global_store_dwordx4 v[96:97], v[80:83], off offset:256
	v_pk_add_f32 v[54:55], v[54:55], 0 op_sel_hi:[1,0]
	v_pk_add_f32 v[52:53], v[52:53], 0 op_sel_hi:[1,0]
	v_or_b32_e32 v80, 48, v152
	v_ashrrev_i32_e32 v81, 31, v80
	v_lshlrev_b64 v[80:81], 11, v[80:81]
	v_lshl_add_u64 v[80:81], s[6:7], 0, v[80:81]
	v_lshl_add_u64 v[80:81], v[80:81], 0, v[156:157]
	v_pk_add_f32 v[82:83], v[74:75], 0 op_sel_hi:[1,0]
	v_pk_add_f32 v[74:75], v[72:73], 0 op_sel_hi:[1,0]
	v_cvt_pk_bf16_f32 v72, v76, v77
	v_cvt_pk_bf16_f32 v73, v78, v79
	v_pk_add_f32 v[48:49], v[48:49], 0 op_sel_hi:[1,0]
	v_cvt_pk_bf16_f32 v74, v74, v75
	v_cvt_pk_bf16_f32 v75, v82, v83
	global_store_dwordx4 v[80:81], v[72:75], off
	v_pk_add_f32 v[38:39], v[38:39], 0 op_sel_hi:[1,0]
	v_pk_add_f32 v[36:37], v[36:37], 0 op_sel_hi:[1,0]
	v_pk_add_f32 v[72:73], v[66:67], 0 op_sel_hi:[1,0]
	v_pk_add_f32 v[66:67], v[64:65], 0 op_sel_hi:[1,0]
	v_cvt_pk_bf16_f32 v64, v68, v69
	v_cvt_pk_bf16_f32 v65, v70, v71
	v_pk_add_f32 v[32:33], v[32:33], 0 op_sel_hi:[1,0]
	v_cvt_pk_bf16_f32 v66, v66, v67
	v_cvt_pk_bf16_f32 v67, v72, v73
	global_store_dwordx4 v[80:81], v[64:67], off offset:256
	v_pk_add_f32 v[22:23], v[22:23], 0 op_sel_hi:[1,0]
	v_pk_add_f32 v[20:21], v[20:21], 0 op_sel_hi:[1,0]
	v_pk_add_f32 v[66:67], v[58:59], 0 op_sel_hi:[1,0]
	v_pk_add_f32 v[58:59], v[56:57], 0 op_sel_hi:[1,0]
	v_cvt_pk_bf16_f32 v56, v60, v61
	v_add_co_u32_e32 v60, vcc, s44, v144
	v_cvt_pk_bf16_f32 v57, v62, v63
	v_cvt_pk_bf16_f32 v58, v58, v59
	v_cvt_pk_bf16_f32 v59, v66, v67
	v_lshl_add_u64 v[64:65], v[144:145], 0, s[10:11]
	s_nop 0
	v_addc_co_u32_e32 v61, vcc, 0, v145, vcc
	global_store_dwordx4 v[60:61], v[56:59], off
	v_pk_add_f32 v[16:17], v[16:17], 0 op_sel_hi:[1,0]
	s_mov_b32 s51, s48
	v_pk_add_f32 v[56:57], v[46:47], 0 op_sel_hi:[1,0]
	v_pk_add_f32 v[46:47], v[44:45], 0 op_sel_hi:[1,0]
	v_cvt_pk_bf16_f32 v44, v52, v53
	v_cvt_pk_bf16_f32 v45, v54, v55
	s_mov_b32 s50, s49
	v_cvt_pk_bf16_f32 v46, v46, v47
	v_cvt_pk_bf16_f32 v47, v56, v57
	global_store_dwordx4 v[64:65], v[44:47], off offset:256
	s_mov_b64 s[20:21], s[4:5]
	s_mov_b64 s[18:19], s[0:1]
	v_pk_add_f32 v[46:47], v[50:51], 0 op_sel_hi:[1,0]
	v_pk_add_f32 v[50:51], v[42:43], 0 op_sel_hi:[1,0]
	v_pk_add_f32 v[42:43], v[40:41], 0 op_sel_hi:[1,0]
	v_cvt_pk_bf16_f32 v40, v48, v49
	v_cvt_pk_bf16_f32 v41, v46, v47
	v_add_co_u32_e32 v46, vcc, s45, v144
	v_cvt_pk_bf16_f32 v42, v42, v43
	v_cvt_pk_bf16_f32 v43, v50, v51
	v_lshl_add_u64 v[44:45], v[144:145], 0, s[12:13]
	s_nop 0
	v_addc_co_u32_e32 v47, vcc, 0, v145, vcc
	global_store_dwordx4 v[46:47], v[40:43], off
	v_pk_add_f32 v[6:7], v[6:7], 0 op_sel_hi:[1,0]
	v_pk_add_f32 v[4:5], v[4:5], 0 op_sel_hi:[1,0]
	v_pk_add_f32 v[40:41], v[30:31], 0 op_sel_hi:[1,0]
	v_pk_add_f32 v[30:31], v[28:29], 0 op_sel_hi:[1,0]
	v_cvt_pk_bf16_f32 v28, v36, v37
	v_cvt_pk_bf16_f32 v29, v38, v39
	s_nop 0
	v_cvt_pk_bf16_f32 v30, v30, v31
	v_cvt_pk_bf16_f32 v31, v40, v41
	global_store_dwordx4 v[44:45], v[28:31], off offset:256
	s_nop 1
	v_pk_add_f32 v[30:31], v[34:35], 0 op_sel_hi:[1,0]
	v_pk_add_f32 v[34:35], v[26:27], 0 op_sel_hi:[1,0]
	v_pk_add_f32 v[26:27], v[24:25], 0 op_sel_hi:[1,0]
	v_cvt_pk_bf16_f32 v24, v32, v33
	v_cvt_pk_bf16_f32 v25, v30, v31
	v_add_co_u32_e32 v30, vcc, s46, v144
	v_cvt_pk_bf16_f32 v26, v26, v27
	v_cvt_pk_bf16_f32 v27, v34, v35
	v_lshl_add_u64 v[28:29], v[144:145], 0, s[14:15]
	s_nop 0
	v_addc_co_u32_e32 v31, vcc, 0, v145, vcc
	global_store_dwordx4 v[30:31], v[24:27], off
	s_nop 1
	v_pk_add_f32 v[24:25], v[14:15], 0 op_sel_hi:[1,0]
	v_pk_add_f32 v[14:15], v[12:13], 0 op_sel_hi:[1,0]
	v_cvt_pk_bf16_f32 v12, v20, v21
	v_cvt_pk_bf16_f32 v13, v22, v23
	s_nop 0
	v_cvt_pk_bf16_f32 v14, v14, v15
	v_cvt_pk_bf16_f32 v15, v24, v25
	global_store_dwordx4 v[28:29], v[12:15], off offset:256
	s_nop 1
	v_pk_add_f32 v[14:15], v[18:19], 0 op_sel_hi:[1,0]
	v_pk_add_f32 v[18:19], v[10:11], 0 op_sel_hi:[1,0]
	v_pk_add_f32 v[10:11], v[8:9], 0 op_sel_hi:[1,0]
	v_cvt_pk_bf16_f32 v8, v16, v17
	v_cvt_pk_bf16_f32 v9, v14, v15
	v_add_co_u32_e32 v14, vcc, s47, v144
	v_lshl_add_u64 v[12:13], v[144:145], 0, s[16:17]
	s_nop 0
	v_addc_co_u32_e32 v15, vcc, 0, v145, vcc
	v_cvt_pk_bf16_f32 v10, v10, v11
	v_cvt_pk_bf16_f32 v11, v18, v19
	global_store_dwordx4 v[14:15], v[8:11], off
	s_and_b64 vcc, exec, s[2:3]
	s_nop 0
	v_pk_add_f32 v[8:9], v[2:3], 0 op_sel_hi:[1,0]
	v_pk_add_f32 v[2:3], v[0:1], 0 op_sel_hi:[1,0]
	v_cvt_pk_bf16_f32 v0, v4, v5
	v_cvt_pk_bf16_f32 v1, v6, v7
	s_nop 0
	v_cvt_pk_bf16_f32 v2, v2, v3
	v_cvt_pk_bf16_f32 v3, v8, v9
	global_store_dwordx4 v[12:13], v[0:3], off offset:256
	s_cbranch_vccz .LBB0_1267
	s_waitcnt vmcnt(0)
	s_cmpk_gt_u32 s27, 0xff
	s_cbranch_scc1 .LBB0_1282
	s_barrier
